# speedup vs baseline: 1.0272x; 1.0272x over previous
; #define STAGE8(P, BASE, LD, OFF, br, kt) do { const bf16_t* g_ = (BASE) + (long)(br) * (LD) + (long)(kt) * 64 + (OFF); \
;     __builtin_amdgcn_global_load_lds((const unsigned*)(g_), (unsigned*)((char*)(P) + tid8 * 16), 16, 0, 0);            \
;     __builtin_amdgcn_global_load_lds((const unsigned*)(g_ + 64 * (long)(LD)), (unsigned*)((char*)(P) + tid8 * 16 + 8192), 16, 0, 0); } while (0)
; #define LDA8(dst, b, h) _Pragma("unroll") for (int m = 0; m < 4; ++m) _Pragma("unroll") for (int k = 0; k < 2; ++k) \
;     dst[m][k] = *reinterpret_cast<const bf16x8*>(SA8(b, h) + fa_off + m * 2048 + k * 1024)
; #define LDB8(dst, b, h) _Pragma("unroll") for (int n = 0; n < 2; ++n) _Pragma("unroll") for (int k = 0; k < 2; ++k) \
;     dst[n][k] = *reinterpret_cast<const bf16x8*>(SB8(b, h) + fb_off + n * 2048 + k * 1024)
; #define WAIT_V8(n) asm volatile("s_waitcnt vmcnt(" #n ")" ::: "memory")
; #define WAIT_L8(n) asm volatile("s_waitcnt lgkmcnt(" #n ")" ::: "memory")
; #define BAR8 __builtin_amdgcn_s_barrier()
; #define SCHED8 __builtin_amdgcn_sched_barrier(0)
; __device__ __forceinline__ void gemm_mainloop8(const bf16_t* __restrict__ Xg, int ldx, const bf16_t* __restrict__ Wg, int ldw, ...
;     ...
;     LDB8(B0, 0, 0); SCHED8; LDA8(At, 0, 0); STAGE8(SA8(1, 1), A, ldw, offA, 128, t + 1);
;     WAIT_L8(8); BAR8; WAIT_L8(0); MMA8(0, 0, At, B0); BAR8; SCHED8;
;     LDB8(B1, 0, 1); STAGE8(SB8(0, 0), Bt, ldx, offB, 0, t + 2);
;     BAR8; WAIT_L8(0); MMA8(0, 1, At, B1); BAR8;
;     LDA8(At, 0, 1); STAGE8(SA8(0, 0), A, ldw, offA, 0, t + 2);
;     BAR8; WAIT_L8(0); MMA8(1, 0, At, B0); BAR8; SCHED8;
;     STAGE8(SB8(0, 1), Bt, ldx, offB, 128, t + 2);
;     WAIT_V8(6); BAR8; MMA8(1, 1, At, B1); BAR8;
;     LDB8(B0, 1, 0); SCHED8; LDA8(At, 1, 0); STAGE8(SA8(0, 1), A, ldw, offA, 128, t + 2);
.LBB0_170:
	v_or_b32_e32 v152, 0x10000, v135
	v_add_u32_e32 v153, 0x10400, v135
	v_add_u32_e32 v154, 0x10800, v135
	v_add_u32_e32 v155, 0x10c00, v135
	v_or_b32_e32 v158, 0x14000, v135
	v_add_u32_e32 v159, 0x14400, v135
	v_add_u32_e32 v160, 0x14800, v135
	v_add_u32_e32 v161, 0x14c00, v135
	v_add_u32_e32 v156, 0xc000, v0
	v_add_u32_e32 v157, 0xe000, v0
	v_lshl_add_u64 v[244:245], s[28:29], 0, v[132:133]
	v_lshl_add_u64 v[246:247], s[26:27], 0, v[132:133]
	ds_read_b128 v[162:165], v152
	ds_read_b128 v[166:169], v153
	ds_read_b128 v[170:173], v154
	ds_read_b128 v[174:177], v155
	ds_read_b128 v[178:181], v134
	ds_read_b128 v[186:189], v134 offset:1024
	ds_read_b128 v[190:193], v134 offset:2048
	ds_read_b128 v[194:197], v134 offset:3072
	ds_read_b128 v[204:207], v134 offset:4096
	ds_read_b128 v[208:211], v134 offset:5120
	ds_read_b128 v[212:215], v134 offset:6144
	ds_read_b128 v[216:219], v134 offset:7168
	ds_read_b128 v[220:223], v158
	ds_read_b128 v[224:227], v159
	ds_read_b128 v[228:231], v160
	ds_read_b128 v[232:235], v161
	v_lshl_add_u64 v[236:237], v[244:245], 0, s[40:41]
	v_readfirstlane_b32 s31, v156
	s_nop 0
	s_mov_b32 m0, s31
	s_nop 0
	global_load_lds_dwordx4 v[236:237], off
	v_lshl_add_u64 v[236:237], v[244:245], 0, s[42:43]
	v_readfirstlane_b32 s31, v157
	s_nop 0
	s_mov_b32 m0, s31
	s_nop 0
	global_load_lds_dwordx4 v[236:237], off
	s_waitcnt lgkmcnt(0)
	s_barrier
	s_setprio 1
	v_mfma_f32_16x16x32_bf16 v[126:129], v[178:181], v[162:165], v[126:129]
	v_mfma_f32_16x16x32_bf16 v[122:125], v[178:181], v[170:173], v[122:125]
	v_mfma_f32_16x16x32_bf16 v[118:121], v[190:193], v[162:165], v[118:121]
	v_mfma_f32_16x16x32_bf16 v[114:117], v[190:193], v[170:173], v[114:117]
	v_mfma_f32_16x16x32_bf16 v[102:105], v[204:207], v[162:165], v[102:105]
	v_mfma_f32_16x16x32_bf16 v[98:101], v[204:207], v[170:173], v[98:101]
	v_mfma_f32_16x16x32_bf16 v[86:89], v[212:215], v[162:165], v[86:89]
	v_mfma_f32_16x16x32_bf16 v[82:85], v[212:215], v[170:173], v[82:85]
	v_mfma_f32_16x16x32_bf16 v[126:129], v[186:189], v[166:169], v[126:129]
	v_mfma_f32_16x16x32_bf16 v[122:125], v[186:189], v[174:177], v[122:125]
	v_mfma_f32_16x16x32_bf16 v[118:121], v[194:197], v[166:169], v[118:121]
	v_mfma_f32_16x16x32_bf16 v[114:117], v[194:197], v[174:177], v[114:117]
	v_mfma_f32_16x16x32_bf16 v[102:105], v[208:211], v[166:169], v[102:105]
	v_mfma_f32_16x16x32_bf16 v[98:101], v[208:211], v[174:177], v[98:101]
	v_mfma_f32_16x16x32_bf16 v[86:89], v[216:219], v[166:169], v[86:89]
	v_mfma_f32_16x16x32_bf16 v[82:85], v[216:219], v[174:177], v[82:85]
	v_mfma_f32_16x16x32_bf16 v[110:113], v[178:181], v[220:223], v[110:113]
	v_mfma_f32_16x16x32_bf16 v[106:109], v[178:181], v[228:231], v[106:109]
	v_mfma_f32_16x16x32_bf16 v[94:97], v[190:193], v[220:223], v[94:97]
	v_mfma_f32_16x16x32_bf16 v[90:93], v[190:193], v[228:231], v[90:93]
	v_mfma_f32_16x16x32_bf16 v[78:81], v[204:207], v[220:223], v[78:81]
	v_mfma_f32_16x16x32_bf16 v[74:77], v[204:207], v[228:231], v[74:77]
	v_mfma_f32_16x16x32_bf16 v[70:73], v[212:215], v[220:223], v[70:73]
	v_mfma_f32_16x16x32_bf16 v[66:69], v[212:215], v[228:231], v[66:69]
	v_mfma_f32_16x16x32_bf16 v[110:113], v[186:189], v[224:227], v[110:113]
	v_mfma_f32_16x16x32_bf16 v[106:109], v[186:189], v[232:235], v[106:109]
	v_mfma_f32_16x16x32_bf16 v[94:97], v[194:197], v[224:227], v[94:97]
	v_mfma_f32_16x16x32_bf16 v[90:93], v[194:197], v[232:235], v[90:93]
	v_mfma_f32_16x16x32_bf16 v[78:81], v[208:211], v[224:227], v[78:81]
	v_mfma_f32_16x16x32_bf16 v[74:77], v[208:211], v[232:235], v[74:77]
	v_mfma_f32_16x16x32_bf16 v[70:73], v[216:219], v[224:227], v[70:73]
	v_mfma_f32_16x16x32_bf16 v[66:69], v[216:219], v[232:235], v[66:69]
	s_setprio 0
	s_barrier
	ds_read_b128 v[178:181], v134 offset:16384
	ds_read_b128 v[186:189], v134 offset:17408
	ds_read_b128 v[190:193], v134 offset:18432
	ds_read_b128 v[194:197], v134 offset:19456
	ds_read_b128 v[204:207], v134 offset:20480
	ds_read_b128 v[208:211], v134 offset:21504
	ds_read_b128 v[212:215], v134 offset:22528
	ds_read_b128 v[216:219], v134 offset:23552
	v_lshl_add_u64 v[236:237], v[246:247], 0, s[70:71]
	v_readfirstlane_b32 s31, v151
	s_nop 0
	s_mov_b32 m0, s31
	s_nop 0
	global_load_lds_dwordx4 v[236:237], off
	v_lshl_add_u64 v[236:237], v[246:247], 0, s[48:49]
	v_readfirstlane_b32 s31, v150
	s_nop 0
	s_mov_b32 m0, s31
	s_nop 0
	global_load_lds_dwordx4 v[236:237], off
	v_lshl_add_u64 v[236:237], v[244:245], 0, s[70:71]
	v_readfirstlane_b32 s31, v0
	s_nop 0
	s_mov_b32 m0, s31
	s_nop 0
	global_load_lds_dwordx4 v[236:237], off
	v_lshl_add_u64 v[236:237], v[244:245], 0, s[48:49]
	v_readfirstlane_b32 s31, v149
	s_nop 0
	s_mov_b32 m0, s31
	s_nop 0
	global_load_lds_dwordx4 v[236:237], off
	v_lshl_add_u64 v[236:237], v[246:247], 0, s[52:53]
	v_readfirstlane_b32 s31, v148
	s_nop 0
	s_mov_b32 m0, s31
	s_nop 0
	global_load_lds_dwordx4 v[236:237], off
	v_lshl_add_u64 v[236:237], v[246:247], 0, s[54:55]
	v_readfirstlane_b32 s31, v146
	s_nop 0
	s_mov_b32 m0, s31
	s_nop 0
	global_load_lds_dwordx4 v[236:237], off
	s_waitcnt vmcnt(6)
	s_waitcnt lgkmcnt(0)
	s_barrier
; #define STAGE8(P, BASE, LD, OFF, br, kt) do { const bf16_t* g_ = (BASE) + (long)(br) * (LD) + (long)(kt) * 64 + (OFF); \
;     __builtin_amdgcn_global_load_lds((const unsigned*)(g_), (unsigned*)((char*)(P) + tid8 * 16), 16, 0, 0);            \
;     __builtin_amdgcn_global_load_lds((const unsigned*)(g_ + 64 * (long)(LD)), (unsigned*)((char*)(P) + tid8 * 16 + 8192), 16, 0, 0); } while (0)
; #define LDA8(dst, b, h) _Pragma("unroll") for (int m = 0; m < 4; ++m) _Pragma("unroll") for (int k = 0; k < 2; ++k) \
;     dst[m][k] = *reinterpret_cast<const bf16x8*>(SA8(b, h) + fa_off + m * 2048 + k * 1024)
; #define LDB8(dst, b, h) _Pragma("unroll") for (int n = 0; n < 2; ++n) _Pragma("unroll") for (int k = 0; k < 2; ++k) \
;     dst[n][k] = *reinterpret_cast<const bf16x8*>(SB8(b, h) + fb_off + n * 2048 + k * 1024)
; #define WAIT_V8(n) asm volatile("s_waitcnt vmcnt(" #n ")" ::: "memory")
; #define WAIT_L8(n) asm volatile("s_waitcnt lgkmcnt(" #n ")" ::: "memory")
; #define BAR8 __builtin_amdgcn_s_barrier()
; #define SCHED8 __builtin_amdgcn_sched_barrier(0)
; __device__ __forceinline__ void gemm_mainloop8(const bf16_t* __restrict__ Xg, int ldx, const bf16_t* __restrict__ Wg, int ldw, ...
;     ...
;     WAIT_V8(6); BAR8; MMA8(1, 1, At, B1); BAR8;
;     LDB8(B0, 1, 0); SCHED8; LDA8(At, 1, 0); STAGE8(SA8(0, 1), A, ldw, offA, 128, t + 2);
;     WAIT_L8(8); BAR8; WAIT_L8(0); MMA8(0, 0, At, B0); BAR8; SCHED8;
;     LDB8(B1, 1, 1); STAGE8(SB8(1, 0), Bt, ldx, offB, 0, t + 3);
;     BAR8; WAIT_L8(0); MMA8(0, 1, At, B1); BAR8;
;     LDA8(At, 1, 1); STAGE8(SA8(1, 0), A, ldw, offA, 0, t + 3);
;     BAR8; WAIT_L8(0); MMA8(1, 0, At, B0); BAR8; SCHED8;
	s_setprio 1
	v_mfma_f32_16x16x32_bf16 v[62:65], v[178:181], v[162:165], v[62:65]
	v_mfma_f32_16x16x32_bf16 v[58:61], v[178:181], v[170:173], v[58:61]
	v_mfma_f32_16x16x32_bf16 v[54:57], v[190:193], v[162:165], v[54:57]
	v_mfma_f32_16x16x32_bf16 v[46:49], v[190:193], v[170:173], v[46:49]
	v_mfma_f32_16x16x32_bf16 v[38:41], v[204:207], v[162:165], v[38:41]
	v_mfma_f32_16x16x32_bf16 v[30:33], v[204:207], v[170:173], v[30:33]
	v_mfma_f32_16x16x32_bf16 v[22:25], v[212:215], v[162:165], v[22:25]
	v_mfma_f32_16x16x32_bf16 v[14:17], v[212:215], v[170:173], v[14:17]
	v_mfma_f32_16x16x32_bf16 v[62:65], v[186:189], v[166:169], v[62:65]
	v_mfma_f32_16x16x32_bf16 v[58:61], v[186:189], v[174:177], v[58:61]
	v_mfma_f32_16x16x32_bf16 v[54:57], v[194:197], v[166:169], v[54:57]
	v_mfma_f32_16x16x32_bf16 v[46:49], v[194:197], v[174:177], v[46:49]
	v_mfma_f32_16x16x32_bf16 v[38:41], v[208:211], v[166:169], v[38:41]
	v_mfma_f32_16x16x32_bf16 v[30:33], v[208:211], v[174:177], v[30:33]
	v_mfma_f32_16x16x32_bf16 v[22:25], v[216:219], v[166:169], v[22:25]
	v_mfma_f32_16x16x32_bf16 v[14:17], v[216:219], v[174:177], v[14:17]
	v_mfma_f32_16x16x32_bf16 v[50:53], v[178:181], v[220:223], v[50:53]
	v_mfma_f32_16x16x32_bf16 v[42:45], v[178:181], v[228:231], v[42:45]
	v_mfma_f32_16x16x32_bf16 v[34:37], v[190:193], v[220:223], v[34:37]
	v_mfma_f32_16x16x32_bf16 v[26:29], v[190:193], v[228:231], v[26:29]
	v_mfma_f32_16x16x32_bf16 v[18:21], v[204:207], v[220:223], v[18:21]
	v_mfma_f32_16x16x32_bf16 v[10:13], v[204:207], v[228:231], v[10:13]
	v_mfma_f32_16x16x32_bf16 v[6:9], v[212:215], v[220:223], v[6:9]
	v_mfma_f32_16x16x32_bf16 v[2:5], v[212:215], v[228:231], v[2:5]
	v_mfma_f32_16x16x32_bf16 v[50:53], v[186:189], v[224:227], v[50:53]
	v_mfma_f32_16x16x32_bf16 v[42:45], v[186:189], v[232:235], v[42:45]
	v_mfma_f32_16x16x32_bf16 v[34:37], v[194:197], v[224:227], v[34:37]
	v_mfma_f32_16x16x32_bf16 v[26:29], v[194:197], v[232:235], v[26:29]
	v_mfma_f32_16x16x32_bf16 v[18:21], v[208:211], v[224:227], v[18:21]
	v_mfma_f32_16x16x32_bf16 v[10:13], v[208:211], v[232:235], v[10:13]
	v_mfma_f32_16x16x32_bf16 v[6:9], v[216:219], v[224:227], v[6:9]
	v_mfma_f32_16x16x32_bf16 v[2:5], v[216:219], v[232:235], v[2:5]
	s_setprio 0
	s_barrier
	v_or_b32_e32 v162, 0x18000, v135
	v_add_u32_e32 v163, 0x18400, v135
	v_add_u32_e32 v164, 0x18800, v135
	v_add_u32_e32 v165, 0x18c00, v135
	v_or_b32_e32 v166, 0x1c000, v135
	v_add_u32_e32 v167, 0x1c400, v135
	v_add_u32_e32 v168, 0x1c800, v135
	v_add_u32_e32 v169, 0x1cc00, v135
	ds_read_b128 v[170:173], v162
	ds_read_b128 v[174:177], v163
	ds_read_b128 v[178:181], v164
	ds_read_b128 v[186:189], v165
	ds_read_b128 v[190:193], v134 offset:32768
	ds_read_b128 v[194:197], v134 offset:33792
	ds_read_b128 v[204:207], v134 offset:34816
	ds_read_b128 v[208:211], v134 offset:35840
	ds_read_b128 v[212:215], v134 offset:36864
	ds_read_b128 v[216:219], v134 offset:37888
	ds_read_b128 v[220:223], v134 offset:38912
	ds_read_b128 v[224:227], v134 offset:39936
	ds_read_b128 v[228:231], v166
	ds_read_b128 v[232:235], v167
	ds_read_b128 v[236:239], v168
	ds_read_b128 v[240:243], v169
	v_lshl_add_u64 v[248:249], v[244:245], 0, s[52:53]
	v_readfirstlane_b32 s31, v141
	s_nop 0
	s_mov_b32 m0, s31
	s_nop 0
	global_load_lds_dwordx4 v[248:249], off
	v_lshl_add_u64 v[248:249], v[244:245], 0, s[54:55]
	v_readfirstlane_b32 s31, v140
	s_nop 0
	s_mov_b32 m0, s31
	s_nop 0
	global_load_lds_dwordx4 v[248:249], off
	s_waitcnt lgkmcnt(0)
	s_barrier
	s_setprio 1
	v_mfma_f32_16x16x32_bf16 v[126:129], v[190:193], v[170:173], v[126:129]
	v_mfma_f32_16x16x32_bf16 v[122:125], v[190:193], v[178:181], v[122:125]
	v_mfma_f32_16x16x32_bf16 v[118:121], v[204:207], v[170:173], v[118:121]
	v_mfma_f32_16x16x32_bf16 v[114:117], v[204:207], v[178:181], v[114:117]
	v_mfma_f32_16x16x32_bf16 v[102:105], v[212:215], v[170:173], v[102:105]
	v_mfma_f32_16x16x32_bf16 v[98:101], v[212:215], v[178:181], v[98:101]
	v_mfma_f32_16x16x32_bf16 v[86:89], v[220:223], v[170:173], v[86:89]
	v_mfma_f32_16x16x32_bf16 v[82:85], v[220:223], v[178:181], v[82:85]
	v_mfma_f32_16x16x32_bf16 v[126:129], v[194:197], v[174:177], v[126:129]
	v_mfma_f32_16x16x32_bf16 v[122:125], v[194:197], v[186:189], v[122:125]
	v_mfma_f32_16x16x32_bf16 v[118:121], v[208:211], v[174:177], v[118:121]
	v_mfma_f32_16x16x32_bf16 v[114:117], v[208:211], v[186:189], v[114:117]
	v_mfma_f32_16x16x32_bf16 v[102:105], v[216:219], v[174:177], v[102:105]
	v_mfma_f32_16x16x32_bf16 v[98:101], v[216:219], v[186:189], v[98:101]
	v_mfma_f32_16x16x32_bf16 v[86:89], v[224:227], v[174:177], v[86:89]
	v_mfma_f32_16x16x32_bf16 v[82:85], v[224:227], v[186:189], v[82:85]
	v_mfma_f32_16x16x32_bf16 v[110:113], v[190:193], v[228:231], v[110:113]
	v_mfma_f32_16x16x32_bf16 v[106:109], v[190:193], v[236:239], v[106:109]
	v_mfma_f32_16x16x32_bf16 v[94:97], v[204:207], v[228:231], v[94:97]
	v_mfma_f32_16x16x32_bf16 v[90:93], v[204:207], v[236:239], v[90:93]
	v_mfma_f32_16x16x32_bf16 v[78:81], v[212:215], v[228:231], v[78:81]
	v_mfma_f32_16x16x32_bf16 v[74:77], v[212:215], v[236:239], v[74:77]
	v_mfma_f32_16x16x32_bf16 v[70:73], v[220:223], v[228:231], v[70:73]
	v_mfma_f32_16x16x32_bf16 v[66:69], v[220:223], v[236:239], v[66:69]
	v_mfma_f32_16x16x32_bf16 v[110:113], v[194:197], v[232:235], v[110:113]
	v_mfma_f32_16x16x32_bf16 v[106:109], v[194:197], v[240:243], v[106:109]
	v_mfma_f32_16x16x32_bf16 v[94:97], v[208:211], v[232:235], v[94:97]
	v_mfma_f32_16x16x32_bf16 v[90:93], v[208:211], v[240:243], v[90:93]
	v_mfma_f32_16x16x32_bf16 v[78:81], v[216:219], v[232:235], v[78:81]
	v_mfma_f32_16x16x32_bf16 v[74:77], v[216:219], v[240:243], v[74:77]
	v_mfma_f32_16x16x32_bf16 v[70:73], v[224:227], v[232:235], v[70:73]
	v_mfma_f32_16x16x32_bf16 v[66:69], v[224:227], v[240:243], v[66:69]
	s_setprio 0
	s_barrier
; #define STAGE8(P, BASE, LD, OFF, br, kt) do { const bf16_t* g_ = (BASE) + (long)(br) * (LD) + (long)(kt) * 64 + (OFF); \
;     __builtin_amdgcn_global_load_lds((const unsigned*)(g_), (unsigned*)((char*)(P) + tid8 * 16), 16, 0, 0);            \
;     __builtin_amdgcn_global_load_lds((const unsigned*)(g_ + 64 * (long)(LD)), (unsigned*)((char*)(P) + tid8 * 16 + 8192), 16, 0, 0); } while (0)
; #define LDA8(dst, b, h) _Pragma("unroll") for (int m = 0; m < 4; ++m) _Pragma("unroll") for (int k = 0; k < 2; ++k) \
;     dst[m][k] = *reinterpret_cast<const bf16x8*>(SA8(b, h) + fa_off + m * 2048 + k * 1024)
; #define LDB8(dst, b, h) _Pragma("unroll") for (int n = 0; n < 2; ++n) _Pragma("unroll") for (int k = 0; k < 2; ++k) \
;     dst[n][k] = *reinterpret_cast<const bf16x8*>(SB8(b, h) + fb_off + n * 2048 + k * 1024)
; #define WAIT_V8(n) asm volatile("s_waitcnt vmcnt(" #n ")" ::: "memory")
; #define WAIT_L8(n) asm volatile("s_waitcnt lgkmcnt(" #n ")" ::: "memory")
; #define BAR8 __builtin_amdgcn_s_barrier()
; #define SCHED8 __builtin_amdgcn_sched_barrier(0)
; __device__ __forceinline__ void gemm_mainloop8(const bf16_t* __restrict__ Xg, int ldx, const bf16_t* __restrict__ Wg, int ldw, ...
;     ...
;     LDA8(At, 1, 1); STAGE8(SA8(1, 0), A, ldw, offA, 0, t + 3);
;     BAR8; WAIT_L8(0); MMA8(1, 0, At, B0); BAR8; SCHED8;
;     STAGE8(SB8(1, 1), Bt, ldx, offB, 128, t + 3);
;     WAIT_V8(6); BAR8; MMA8(1, 1, At, B1); BAR8;
;   }
;   { LDB8(B0, 0, 0); LDA8(At, 0, 0); STAGE8(SA8(1, 1), A, ldw, offA, 128, nt - 1);
;     BAR8; WAIT_L8(0); MMA8(0, 0, At, B0); BAR8;
	ds_read_b128 v[190:193], v134 offset:49152
	ds_read_b128 v[194:197], v134 offset:50176
	ds_read_b128 v[204:207], v134 offset:51200
	ds_read_b128 v[208:211], v134 offset:52224
	ds_read_b128 v[212:215], v134 offset:53248
	ds_read_b128 v[216:219], v134 offset:54272
	ds_read_b128 v[220:223], v134 offset:55296
	ds_read_b128 v[224:227], v134 offset:56320
	v_lshl_add_u64 v[248:249], v[246:247], 0, s[88:89]
	v_readfirstlane_b32 s31, v136
	s_nop 0
	s_mov_b32 m0, s31
	s_nop 0
	global_load_lds_dwordx4 v[248:249], off
	v_lshl_add_u64 v[248:249], v[246:247], 0, s[56:57]
	v_readfirstlane_b32 s31, v137
	s_nop 0
	s_mov_b32 m0, s31
	s_nop 0
	global_load_lds_dwordx4 v[248:249], off
	v_lshl_add_u64 v[248:249], v[244:245], 0, s[88:89]
	v_readfirstlane_b32 s31, v142
	s_nop 0
	s_mov_b32 m0, s31
	s_nop 0
	global_load_lds_dwordx4 v[248:249], off
	v_lshl_add_u64 v[248:249], v[244:245], 0, s[56:57]
	v_readfirstlane_b32 s31, v143
	s_nop 0
	s_mov_b32 m0, s31
	s_nop 0
	global_load_lds_dwordx4 v[248:249], off
	s_mov_b64 s[38:39], 0x160180
	v_lshl_add_u64 v[248:249], v[246:247], 0, s[38:39]
	v_readfirstlane_b32 s31, v144
	s_nop 0
	s_mov_b32 m0, s31
	s_nop 0
	global_load_lds_dwordx4 v[248:249], off
	s_mov_b64 s[38:39], 0x210180
	v_lshl_add_u64 v[248:249], v[246:247], 0, s[38:39]
	v_readfirstlane_b32 s31, v145
	s_nop 0
	s_mov_b32 m0, s31
	s_nop 0
	global_load_lds_dwordx4 v[248:249], off
	s_waitcnt vmcnt(6)
	s_waitcnt lgkmcnt(0)
	s_barrier
	s_setprio 1
	v_mfma_f32_16x16x32_bf16 v[62:65], v[190:193], v[170:173], v[62:65]
	v_mfma_f32_16x16x32_bf16 v[58:61], v[190:193], v[178:181], v[58:61]
	v_mfma_f32_16x16x32_bf16 v[54:57], v[204:207], v[170:173], v[54:57]
	v_mfma_f32_16x16x32_bf16 v[46:49], v[204:207], v[178:181], v[46:49]
	v_mfma_f32_16x16x32_bf16 v[38:41], v[212:215], v[170:173], v[38:41]
	v_mfma_f32_16x16x32_bf16 v[30:33], v[212:215], v[178:181], v[30:33]
	v_mfma_f32_16x16x32_bf16 v[22:25], v[220:223], v[170:173], v[22:25]
	v_mfma_f32_16x16x32_bf16 v[14:17], v[220:223], v[178:181], v[14:17]
	v_mfma_f32_16x16x32_bf16 v[62:65], v[194:197], v[174:177], v[62:65]
	v_mfma_f32_16x16x32_bf16 v[58:61], v[194:197], v[186:189], v[58:61]
	v_mfma_f32_16x16x32_bf16 v[54:57], v[208:211], v[174:177], v[54:57]
	v_mfma_f32_16x16x32_bf16 v[46:49], v[208:211], v[186:189], v[46:49]
	v_mfma_f32_16x16x32_bf16 v[38:41], v[216:219], v[174:177], v[38:41]
	v_mfma_f32_16x16x32_bf16 v[30:33], v[216:219], v[186:189], v[30:33]
	v_mfma_f32_16x16x32_bf16 v[22:25], v[224:227], v[174:177], v[22:25]
	v_mfma_f32_16x16x32_bf16 v[14:17], v[224:227], v[186:189], v[14:17]
	v_mfma_f32_16x16x32_bf16 v[50:53], v[190:193], v[228:231], v[50:53]
	v_mfma_f32_16x16x32_bf16 v[42:45], v[190:193], v[236:239], v[42:45]
	v_mfma_f32_16x16x32_bf16 v[34:37], v[204:207], v[228:231], v[34:37]
	v_mfma_f32_16x16x32_bf16 v[26:29], v[204:207], v[236:239], v[26:29]
	v_mfma_f32_16x16x32_bf16 v[18:21], v[212:215], v[228:231], v[18:21]
	v_mfma_f32_16x16x32_bf16 v[10:13], v[212:215], v[236:239], v[10:13]
	v_mfma_f32_16x16x32_bf16 v[6:9], v[220:223], v[228:231], v[6:9]
	v_mfma_f32_16x16x32_bf16 v[2:5], v[220:223], v[236:239], v[2:5]
	v_mfma_f32_16x16x32_bf16 v[50:53], v[194:197], v[232:235], v[50:53]
	v_mfma_f32_16x16x32_bf16 v[42:45], v[194:197], v[240:243], v[42:45]
	v_mfma_f32_16x16x32_bf16 v[34:37], v[208:211], v[232:235], v[34:37]
	v_mfma_f32_16x16x32_bf16 v[26:29], v[208:211], v[240:243], v[26:29]
	v_mfma_f32_16x16x32_bf16 v[18:21], v[216:219], v[232:235], v[18:21]
	v_mfma_f32_16x16x32_bf16 v[10:13], v[216:219], v[240:243], v[10:13]
	v_mfma_f32_16x16x32_bf16 v[6:9], v[224:227], v[232:235], v[6:9]
	v_mfma_f32_16x16x32_bf16 v[2:5], v[224:227], v[240:243], v[2:5]
	s_setprio 0
	s_add_i32 s30, s30, 2
	s_add_u32 s26, s26, 0x100
	s_addc_u32 s27, s27, 0
	s_add_u32 s28, s28, 0x100
	s_addc_u32 s29, s29, 0
	s_cmpk_lt_u32 s30, 0x54
	s_barrier
	s_cbranch_scc1 .LBB0_170
	v_lshl_add_u64 v[130:131], v[130:131], 1, s[24:25]
	s_mov_b64 s[24:25], 0x162b80
	v_lshl_add_u64 v[132:133], v[130:131], 0, s[24:25]
	v_readfirstlane_b32 s24, v156
	s_mov_b32 m0, s24
	s_mov_b64 s[24:25], 0x212b80
	v_lshl_add_u64 v[130:131], v[130:131], 0, s[24:25]
	v_readfirstlane_b32 s24, v157
	s_nop 0
	ds_read_b128 v[142:145], v152
	ds_read_b128 v[170:173], v153
	ds_read_b128 v[174:177], v154
	ds_read_b128 v[152:155], v155
	ds_read_b128 v[178:181], v134
	ds_read_b128 v[186:189], v134 offset:1024
	ds_read_b128 v[190:193], v134 offset:2048
	ds_read_b128 v[194:197], v134 offset:3072
	ds_read_b128 v[204:207], v134 offset:4096
	ds_read_b128 v[208:211], v134 offset:5120
	ds_read_b128 v[212:215], v134 offset:6144
	ds_read_b128 v[216:219], v134 offset:7168
	global_load_lds_dwordx4 v[132:133], off
	s_mov_b32 m0, s24
	s_nop 0
	global_load_lds_dwordx4 v[130:131], off
	s_barrier
	s_waitcnt lgkmcnt(0)
	s_setprio 1
	s_waitcnt lgkmcnt(0)
	v_mfma_f32_16x16x32_bf16 v[126:129], v[178:181], v[142:145], v[126:129]
	v_mfma_f32_16x16x32_bf16 v[102:105], v[204:207], v[142:145], v[102:105]
	v_mfma_f32_16x16x32_bf16 v[82:85], v[212:215], v[174:177], v[82:85]
	v_mfma_f32_16x16x32_bf16 v[126:129], v[186:189], v[170:173], v[126:129]
	v_mfma_f32_16x16x32_bf16 v[122:125], v[178:181], v[174:177], v[122:125]
	v_mfma_f32_16x16x32_bf16 v[118:121], v[190:193], v[142:145], v[118:121]
	v_mfma_f32_16x16x32_bf16 v[114:117], v[190:193], v[174:177], v[114:117]
	v_mfma_f32_16x16x32_bf16 v[130:133], v[208:211], v[170:173], v[102:105]
	v_mfma_f32_16x16x32_bf16 v[98:101], v[204:207], v[174:177], v[98:101]
	v_mfma_f32_16x16x32_bf16 v[86:89], v[212:215], v[142:145], v[86:89]
	v_mfma_f32_16x16x32_bf16 v[82:85], v[216:219], v[152:155], v[82:85]
	v_mfma_f32_16x16x32_bf16 v[122:125], v[186:189], v[152:155], v[122:125]
	v_mfma_f32_16x16x32_bf16 v[118:121], v[194:197], v[170:173], v[118:121]
	v_mfma_f32_16x16x32_bf16 v[114:117], v[194:197], v[152:155], v[114:117]
	v_mfma_f32_16x16x32_bf16 v[220:223], v[208:211], v[152:155], v[98:101]
	v_mfma_f32_16x16x32_bf16 v[224:227], v[216:219], v[170:173], v[86:89]
	s_setprio 0
	s_barrier
; #define LDA8(dst, b, h) _Pragma("unroll") for (int m = 0; m < 4; ++m) _Pragma("unroll") for (int k = 0; k < 2; ++k) \
;     dst[m][k] = *reinterpret_cast<const bf16x8*>(SA8(b, h) + fa_off + m * 2048 + k * 1024)
; #define LDB8(dst, b, h) _Pragma("unroll") for (int n = 0; n < 2; ++n) _Pragma("unroll") for (int k = 0; k < 2; ++k) \
;     dst[n][k] = *reinterpret_cast<const bf16x8*>(SB8(b, h) + fb_off + n * 2048 + k * 1024)
; #define WAIT_V8(n) asm volatile("s_waitcnt vmcnt(" #n ")" ::: "memory")
; #define WAIT_L8(n) asm volatile("s_waitcnt lgkmcnt(" #n ")" ::: "memory")
; #define BAR8 __builtin_amdgcn_s_barrier()
; __device__ __forceinline__ void gemm_mainloop8(const bf16_t* __restrict__ Xg, int ldx, const bf16_t* __restrict__ Wg, int ldw, ...
;     ...
;     BAR8; WAIT_L8(0); MMA8(0, 0, At, B0); BAR8;
;     LDB8(B1, 0, 1); BAR8; WAIT_L8(0); MMA8(0, 1, At, B1); BAR8;
;     LDA8(At, 0, 1); WAIT_V8(4); BAR8; WAIT_L8(0); MMA8(1, 0, At, B0); MMA8(1, 1, At, B1); BAR8; }
;   { LDB8(B0, 1, 0); LDA8(At, 1, 0); WAIT_V8(2); BAR8; WAIT_L8(0); MMA8(0, 0, At, B0); BAR8;
	s_nop 0
	ds_read_b128 v[86:89], v158
	ds_read_b128 v[98:101], v159
	ds_read_b128 v[102:105], v160
	ds_read_b128 v[156:159], v161
	s_barrier
	s_waitcnt lgkmcnt(0)
	s_setprio 1
	s_waitcnt lgkmcnt(1)
	v_mfma_f32_16x16x32_bf16 v[90:93], v[190:193], v[102:105], v[90:93]
	v_mfma_f32_16x16x32_bf16 v[74:77], v[204:207], v[102:105], v[74:77]
	v_mfma_f32_16x16x32_bf16 v[66:69], v[212:215], v[102:105], v[66:69]
	v_mfma_f32_16x16x32_bf16 v[110:113], v[178:181], v[86:89], v[110:113]
	v_mfma_f32_16x16x32_bf16 v[106:109], v[178:181], v[102:105], v[106:109]
	v_mfma_f32_16x16x32_bf16 v[94:97], v[190:193], v[86:89], v[94:97]
	s_waitcnt lgkmcnt(0)
	v_mfma_f32_16x16x32_bf16 v[90:93], v[194:197], v[156:159], v[90:93]
	v_mfma_f32_16x16x32_bf16 v[78:81], v[204:207], v[86:89], v[78:81]
	v_mfma_f32_16x16x32_bf16 v[74:77], v[208:211], v[156:159], v[74:77]
	v_mfma_f32_16x16x32_bf16 v[70:73], v[212:215], v[86:89], v[70:73]
	v_mfma_f32_16x16x32_bf16 v[66:69], v[216:219], v[156:159], v[66:69]
	v_mfma_f32_16x16x32_bf16 v[228:231], v[186:189], v[98:101], v[110:113]
	v_mfma_f32_16x16x32_bf16 v[178:181], v[186:189], v[156:159], v[106:109]
	v_mfma_f32_16x16x32_bf16 v[186:189], v[194:197], v[98:101], v[94:97]
	v_mfma_f32_16x16x32_bf16 v[190:193], v[208:211], v[98:101], v[78:81]
	v_mfma_f32_16x16x32_bf16 v[194:197], v[216:219], v[98:101], v[70:73]
	s_setprio 0
	s_barrier
	s_nop 0
	ds_read_b128 v[70:73], v134 offset:16384
	ds_read_b128 v[78:81], v134 offset:17408
	ds_read_b128 v[94:97], v134 offset:18432
	ds_read_b128 v[106:109], v134 offset:19456
	ds_read_b128 v[110:113], v134 offset:20480
	ds_read_b128 v[204:207], v134 offset:21504
	ds_read_b128 v[208:211], v134 offset:22528
	ds_read_b128 v[212:215], v134 offset:23552
	s_waitcnt vmcnt(4)
	s_barrier
	s_waitcnt lgkmcnt(0)
	s_setprio 1
	s_waitcnt lgkmcnt(7)
	v_mfma_f32_16x16x32_bf16 v[62:65], v[70:73], v[142:145], v[62:65]
	v_mfma_f32_16x16x32_bf16 v[58:61], v[70:73], v[174:177], v[58:61]
	s_waitcnt lgkmcnt(5)
	v_mfma_f32_16x16x32_bf16 v[54:57], v[94:97], v[142:145], v[54:57]
	s_waitcnt lgkmcnt(1)
	v_mfma_f32_16x16x32_bf16 v[22:25], v[208:211], v[142:145], v[22:25]
	v_mfma_f32_16x16x32_bf16 v[14:17], v[208:211], v[174:177], v[14:17]
	v_mfma_f32_16x16x32_bf16 v[62:65], v[78:81], v[170:173], v[62:65]
	v_mfma_f32_16x16x32_bf16 v[58:61], v[78:81], v[152:155], v[58:61]
	v_mfma_f32_16x16x32_bf16 v[54:57], v[106:109], v[170:173], v[54:57]
	v_mfma_f32_16x16x32_bf16 v[46:49], v[94:97], v[174:177], v[46:49]
	v_mfma_f32_16x16x32_bf16 v[38:41], v[110:113], v[142:145], v[38:41]
	v_mfma_f32_16x16x32_bf16 v[30:33], v[110:113], v[174:177], v[30:33]
	s_waitcnt lgkmcnt(0)
	v_mfma_f32_16x16x32_bf16 v[22:25], v[212:215], v[170:173], v[22:25]
	v_mfma_f32_16x16x32_bf16 v[14:17], v[212:215], v[152:155], v[14:17]
	v_mfma_f32_16x16x32_bf16 v[216:219], v[106:109], v[152:155], v[46:49]
	v_mfma_f32_16x16x32_bf16 v[232:235], v[204:207], v[170:173], v[38:41]
	v_mfma_f32_16x16x32_bf16 v[236:239], v[204:207], v[152:155], v[30:33]
	s_setprio 0
	s_setprio 1
	v_mfma_f32_16x16x32_bf16 v[30:33], v[70:73], v[86:89], v[50:53]
	v_mfma_f32_16x16x32_bf16 v[50:53], v[78:81], v[98:101], v[30:33]
	v_mfma_f32_16x16x32_bf16 v[30:33], v[70:73], v[102:105], v[42:45]
	v_mfma_f32_16x16x32_bf16 v[2:5], v[208:211], v[102:105], v[2:5]
	v_mfma_f32_16x16x32_bf16 v[152:155], v[78:81], v[156:159], v[30:33]
	v_mfma_f32_16x16x32_bf16 v[30:33], v[94:97], v[86:89], v[34:37]
	v_mfma_f32_16x16x32_bf16 v[26:29], v[94:97], v[102:105], v[26:29]
	v_mfma_f32_16x16x32_bf16 v[18:21], v[110:113], v[86:89], v[18:21]
	v_mfma_f32_16x16x32_bf16 v[10:13], v[110:113], v[102:105], v[10:13]
	v_mfma_f32_16x16x32_bf16 v[6:9], v[208:211], v[86:89], v[6:9]
	v_mfma_f32_16x16x32_bf16 v[2:5], v[212:215], v[156:159], v[2:5]
	v_mfma_f32_16x16x32_bf16 v[170:173], v[106:109], v[98:101], v[30:33]
	v_mfma_f32_16x16x32_bf16 v[174:177], v[106:109], v[156:159], v[26:29]
	v_mfma_f32_16x16x32_bf16 v[240:243], v[204:207], v[98:101], v[18:21]
	v_mfma_f32_16x16x32_bf16 v[204:207], v[204:207], v[156:159], v[10:13]
	v_mfma_f32_16x16x32_bf16 v[244:247], v[212:215], v[98:101], v[6:9]
	s_setprio 0
	s_barrier
	s_nop 0
	ds_read_b128 v[6:9], v162
	ds_read_b128 v[142:145], v163
	ds_read_b128 v[156:159], v164
	ds_read_b128 v[160:163], v165
	ds_read_b128 v[10:13], v134 offset:32768
	ds_read_b128 v[18:21], v134 offset:33792
	ds_read_b128 v[26:29], v134 offset:34816
	ds_read_b128 v[42:45], v134 offset:35840
	ds_read_b128 v[46:49], v134 offset:36864
	ds_read_b128 v[208:211], v134 offset:37888
	ds_read_b128 v[212:215], v134 offset:38912
	ds_read_b128 v[248:251], v134 offset:39936
	s_waitcnt vmcnt(2)
	s_barrier
; #define LDA8(dst, b, h) _Pragma("unroll") for (int m = 0; m < 4; ++m) _Pragma("unroll") for (int k = 0; k < 2; ++k) \
;     dst[m][k] = *reinterpret_cast<const bf16x8*>(SA8(b, h) + fa_off + m * 2048 + k * 1024)
; #define LDB8(dst, b, h) _Pragma("unroll") for (int n = 0; n < 2; ++n) _Pragma("unroll") for (int k = 0; k < 2; ++k) \
;     dst[n][k] = *reinterpret_cast<const bf16x8*>(SB8(b, h) + fb_off + n * 2048 + k * 1024)
; #define WAIT_V8(n) asm volatile("s_waitcnt vmcnt(" #n ")" ::: "memory")
; #define WAIT_L8(n) asm volatile("s_waitcnt lgkmcnt(" #n ")" ::: "memory")
; #define BAR8 __builtin_amdgcn_s_barrier()
; __device__ __forceinline__ void gemm_mainloop8(const bf16_t* __restrict__ Xg, int ldx, const bf16_t* __restrict__ Wg, int ldw, ...
;     ...
;   { LDB8(B0, 1, 0); LDA8(At, 1, 0); WAIT_V8(2); BAR8; WAIT_L8(0); MMA8(0, 0, At, B0); BAR8;
;     LDB8(B1, 1, 1); WAIT_V8(0); BAR8; WAIT_L8(0); MMA8(0, 1, At, B1); BAR8;
;     LDA8(At, 1, 1); BAR8; WAIT_L8(0); MMA8(1, 0, At, B0); MMA8(1, 1, At, B1); BAR8; }
;   if (wr == 0) BAR8;
	s_waitcnt lgkmcnt(0)
	s_setprio 1
	s_waitcnt lgkmcnt(7)
	v_mfma_f32_16x16x32_bf16 v[30:33], v[10:13], v[6:9], v[126:129]
	s_waitcnt lgkmcnt(6)
	v_mfma_f32_16x16x32_bf16 v[98:101], v[18:21], v[142:145], v[30:33]
	v_mfma_f32_16x16x32_bf16 v[30:33], v[10:13], v[156:159], v[122:125]
	v_mfma_f32_16x16x32_bf16 v[94:97], v[18:21], v[160:163], v[30:33]
	s_waitcnt lgkmcnt(5)
	v_mfma_f32_16x16x32_bf16 v[30:33], v[26:29], v[6:9], v[118:121]
	s_waitcnt lgkmcnt(4)
	v_mfma_f32_16x16x32_bf16 v[102:105], v[42:45], v[142:145], v[30:33]
	v_mfma_f32_16x16x32_bf16 v[30:33], v[26:29], v[156:159], v[114:117]
	v_mfma_f32_16x16x32_bf16 v[86:89], v[42:45], v[160:163], v[30:33]
	s_waitcnt lgkmcnt(3)
	v_mfma_f32_16x16x32_bf16 v[30:33], v[46:49], v[6:9], v[130:133]
	s_waitcnt lgkmcnt(2)
	v_mfma_f32_16x16x32_bf16 v[106:109], v[208:211], v[142:145], v[30:33]
	v_mfma_f32_16x16x32_bf16 v[30:33], v[46:49], v[156:159], v[220:223]
	v_mfma_f32_16x16x32_bf16 v[78:81], v[208:211], v[160:163], v[30:33]
	s_waitcnt lgkmcnt(1)
	v_mfma_f32_16x16x32_bf16 v[30:33], v[212:215], v[6:9], v[224:227]
	s_waitcnt lgkmcnt(0)
	v_mfma_f32_16x16x32_bf16 v[110:113], v[248:251], v[142:145], v[30:33]
	v_mfma_f32_16x16x32_bf16 v[30:33], v[212:215], v[156:159], v[82:85]
	v_mfma_f32_16x16x32_bf16 v[70:73], v[248:251], v[160:163], v[30:33]
	s_setprio 0
	s_barrier
	ds_read_b128 v[114:117], v166
	ds_read_b128 v[118:121], v167
	ds_read_b128 v[122:125], v168
	ds_read_b128 v[164:167], v169
	s_waitcnt vmcnt(0)
	s_barrier
	s_waitcnt lgkmcnt(0)
	s_setprio 1
	s_waitcnt lgkmcnt(3)
	v_mfma_f32_16x16x32_bf16 v[30:33], v[10:13], v[114:117], v[228:231]
	s_waitcnt lgkmcnt(1)
	v_mfma_f32_16x16x32_bf16 v[10:13], v[10:13], v[122:125], v[178:181]
	v_mfma_f32_16x16x32_bf16 v[34:37], v[18:21], v[118:121], v[30:33]
	s_waitcnt lgkmcnt(0)
	v_mfma_f32_16x16x32_bf16 v[30:33], v[18:21], v[164:167], v[10:13]
	v_mfma_f32_16x16x32_bf16 v[10:13], v[26:29], v[114:117], v[186:189]
	v_mfma_f32_16x16x32_bf16 v[38:41], v[42:45], v[118:121], v[10:13]
	v_mfma_f32_16x16x32_bf16 v[10:13], v[26:29], v[122:125], v[90:93]
	v_mfma_f32_16x16x32_bf16 v[26:29], v[42:45], v[164:167], v[10:13]
	v_mfma_f32_16x16x32_bf16 v[10:13], v[46:49], v[114:117], v[190:193]
	v_mfma_f32_16x16x32_bf16 v[42:45], v[208:211], v[118:121], v[10:13]
	v_mfma_f32_16x16x32_bf16 v[10:13], v[46:49], v[122:125], v[74:77]
	v_mfma_f32_16x16x32_bf16 v[18:21], v[208:211], v[164:167], v[10:13]
	v_mfma_f32_16x16x32_bf16 v[10:13], v[212:215], v[114:117], v[194:197]
	v_mfma_f32_16x16x32_bf16 v[46:49], v[248:251], v[118:121], v[10:13]
	v_mfma_f32_16x16x32_bf16 v[10:13], v[212:215], v[122:125], v[66:69]
	v_mfma_f32_16x16x32_bf16 v[10:13], v[248:251], v[164:167], v[10:13]
	s_setprio 0
	s_barrier
	ds_read_b128 v[178:181], v134 offset:49152
	ds_read_b128 v[186:189], v134 offset:50176
	ds_read_b128 v[190:193], v134 offset:51200
	ds_read_b128 v[194:197], v134 offset:52224
	ds_read_b128 v[208:211], v134 offset:53248
	ds_read_b128 v[212:215], v134 offset:54272
	ds_read_b128 v[220:223], v134 offset:55296
	ds_read_b128 v[224:227], v134 offset:56320
	s_barrier
	s_waitcnt lgkmcnt(0)
	s_setprio 1
	s_waitcnt lgkmcnt(5)
	v_mfma_f32_16x16x32_bf16 v[54:57], v[190:193], v[6:9], v[54:57]
	s_waitcnt lgkmcnt(4)
	v_mfma_f32_16x16x32_bf16 v[130:133], v[194:197], v[142:145], v[54:57]
	v_mfma_f32_16x16x32_bf16 v[54:57], v[190:193], v[156:159], v[216:219]
	v_mfma_f32_16x16x32_bf16 v[62:65], v[178:181], v[6:9], v[62:65]
	v_mfma_f32_16x16x32_bf16 v[82:85], v[194:197], v[160:163], v[54:57]
	s_waitcnt lgkmcnt(3)
	v_mfma_f32_16x16x32_bf16 v[54:57], v[208:211], v[6:9], v[232:235]
	s_waitcnt lgkmcnt(1)
	v_mfma_f32_16x16x32_bf16 v[6:9], v[220:223], v[6:9], v[22:25]
	v_mfma_f32_16x16x32_bf16 v[126:129], v[186:189], v[142:145], v[62:65]
	v_mfma_f32_16x16x32_bf16 v[58:61], v[178:181], v[156:159], v[58:61]
	v_mfma_f32_16x16x32_bf16 v[134:137], v[212:215], v[142:145], v[54:57]
	v_mfma_f32_16x16x32_bf16 v[54:57], v[208:211], v[156:159], v[236:239]
	s_waitcnt lgkmcnt(0)
	v_mfma_f32_16x16x32_bf16 v[142:145], v[224:227], v[142:145], v[6:9]
	v_mfma_f32_16x16x32_bf16 v[6:9], v[220:223], v[156:159], v[14:17]
	v_mfma_f32_16x16x32_bf16 v[90:93], v[186:189], v[160:163], v[58:61]
	v_mfma_f32_16x16x32_bf16 v[74:77], v[212:215], v[160:163], v[54:57]
	v_mfma_f32_16x16x32_bf16 v[66:69], v[224:227], v[160:163], v[6:9]
	s_setprio 0
	s_setprio 1
	v_mfma_f32_16x16x32_bf16 v[6:9], v[178:181], v[114:117], v[50:53]
	v_mfma_f32_16x16x32_bf16 v[50:53], v[186:189], v[118:121], v[6:9]
	v_mfma_f32_16x16x32_bf16 v[6:9], v[178:181], v[122:125], v[152:155]
	v_mfma_f32_16x16x32_bf16 v[22:25], v[186:189], v[164:167], v[6:9]
	v_mfma_f32_16x16x32_bf16 v[6:9], v[190:193], v[114:117], v[170:173]
	v_mfma_f32_16x16x32_bf16 v[54:57], v[194:197], v[118:121], v[6:9]
	v_mfma_f32_16x16x32_bf16 v[6:9], v[190:193], v[122:125], v[174:177]
	v_mfma_f32_16x16x32_bf16 v[14:17], v[194:197], v[164:167], v[6:9]
	v_mfma_f32_16x16x32_bf16 v[6:9], v[208:211], v[114:117], v[240:243]
	v_mfma_f32_16x16x32_bf16 v[58:61], v[212:215], v[118:121], v[6:9]
	v_mfma_f32_16x16x32_bf16 v[6:9], v[208:211], v[122:125], v[204:207]
	v_mfma_f32_16x16x32_bf16 v[62:65], v[220:223], v[114:117], v[244:247]
	v_mfma_f32_16x16x32_bf16 v[2:5], v[220:223], v[122:125], v[2:5]
	v_mfma_f32_16x16x32_bf16 v[6:9], v[212:215], v[164:167], v[6:9]
	v_mfma_f32_16x16x32_bf16 v[62:65], v[224:227], v[118:121], v[62:65]
	v_mfma_f32_16x16x32_bf16 v[2:5], v[224:227], v[164:167], v[2:5]
	s_setprio 0
	s_movk_i32 s24, 0x100
	v_cmp_gt_u32_e32 vcc, s24, v147
	s_barrier
	s_and_saveexec_b64 s[24:25], vcc
	s_cbranch_execz .LBB0_173
	s_barrier

; #define WAIT_V8(n) asm volatile("s_waitcnt vmcnt(" #n ")" ::: "memory")
; #define BAR8 __builtin_amdgcn_s_barrier()
; __device__ __forceinline__ void gemm_mainloop8(const bf16_t* __restrict__ Xg, int ldx, const bf16_t* __restrict__ Wg, int ldw, ...
;     ...
;   if (wr == 1) BAR8;
;   if (prefetched) { WAIT_V8(0); } else { WAIT_V8(4); }
;   BAR8;
.LBB0_185:
	s_waitcnt vmcnt(2)
	s_cbranch_execz .LBB0_168
	s_branch .LBB0_169

; #define STAGE8(P, BASE, LD, OFF, br, kt) do { const bf16_t* g_ = (BASE) + (long)(br) * (LD) + (long)(kt) * 64 + (OFF); \
;     __builtin_amdgcn_global_load_lds((const unsigned*)(g_), (unsigned*)((char*)(P) + tid8 * 16), 16, 0, 0);            \
;     __builtin_amdgcn_global_load_lds((const unsigned*)(g_ + 64 * (long)(LD)), (unsigned*)((char*)(P) + tid8 * 16 + 8192), 16, 0, 0); } while (0)
; #define WAIT_V8(n) asm volatile("s_waitcnt vmcnt(" #n ")" ::: "memory")
; #define BAR8 __builtin_amdgcn_s_barrier()
; __device__ __forceinline__ void gemm_mainloop8(const bf16_t* __restrict__ Xg, int ldx, const bf16_t* __restrict__ Wg, int ldw, ...
;     ...
;   if (wr == 1) BAR8;
;   if (prefetched) { WAIT_V8(0); } else { WAIT_V8(4); }
;   BAR8;
;   STAGE8(SB8(1, 0), Bt, ldx, offB, 0, 1); STAGE8(SA8(1, 0), A, ldw, offA, 0, 1); STAGE8(SB8(1, 1), Bt, ldx, offB, 128, 1);
;   WAIT_V8(6); BAR8;
; template <int MB>
; __device__ __forceinline__ void zero_acc(f32x4 (&acc)[8][MB]) {
; #pragma unroll
;   for (int a = 0; a < 8; ++a)
; #pragma unroll
;     for (int b = 0; b < MB; ++b) acc[a][b] = f32x4{0.f, 0.f, 0.f, 0.f};
; }
.LBB0_213:
	s_or_b64 exec, exec, s[42:43]
	v_lshlrev_b32_e32 v12, 6, v0
	v_lshlrev_b32_e32 v15, 2, v0
	v_and_b32_e32 v11, 48, v0
	v_and_b32_e32 v13, 0x3c0, v12
	v_and_b32_e32 v15, 32, v15
	v_or_b32_e32 v14, v13, v11
	v_bitop3_b32 v11, v13, v15, v11 bitop3:0x36
	s_movk_i32 s37, 0x3000
	v_add_u32_e32 v144, 0x18000, v135
	v_lshlrev_b32_e32 v10, 13, v10
	v_and_or_b32 v143, v12, s37, v11
	s_mov_b64 s[42:43], 0x80
	v_readfirstlane_b32 s37, v144
	v_add_u32_e32 v145, 0x1a000, v135
	v_bitop3_b32 v134, v14, v10, v15 bitop3:0xde
	v_lshl_add_u64 v[10:11], v[2:3], 0, s[42:43]
	s_mov_b32 m0, s37
	v_readfirstlane_b32 s37, v145
	v_add_u32_e32 v146, 0x8000, v135
	s_waitcnt vmcnt(2)
	s_barrier
	global_load_lds_dwordx4 v[10:11], off
	v_lshl_add_u64 v[2:3], v[2:3], 0, s[0:1]
	s_mov_b32 m0, s37
	v_readfirstlane_b32 s37, v146
	v_add_u32_e32 v147, 0xa000, v135
	global_load_lds_dwordx4 v[2:3], off
	v_lshl_add_u64 v[2:3], v[4:5], 0, s[42:43]
	s_mov_b32 m0, s37
	v_readfirstlane_b32 s37, v147
	global_load_lds_dwordx4 v[2:3], off
	v_lshl_add_u64 v[2:3], v[4:5], 0, s[0:1]
	s_mov_b32 m0, s37
	v_add_u32_e32 v148, 0x1c000, v135
	global_load_lds_dwordx4 v[2:3], off
	v_lshl_add_u64 v[2:3], v[130:131], 1, s[6:7]
	v_readfirstlane_b32 s37, v148
	v_add_u32_e32 v149, 0x1e000, v135
	v_lshl_add_u64 v[4:5], v[2:3], 0, s[44:45]
	s_mov_b32 m0, s37
	v_readfirstlane_b32 s37, v149
	global_load_lds_dwordx4 v[4:5], off
	v_lshl_add_u64 v[2:3], v[2:3], 0, s[82:83]
	s_mov_b32 m0, s37
	s_mov_b32 s37, -2
	global_load_lds_dwordx4 v[2:3], off
	v_lshlrev_b32_e32 v2, 14, v6
	v_and_b32_e32 v2, 0xffff8000, v2
	v_lshl_add_u32 v2, v7, 11, v2
	v_or_b32_e32 v2, v2, v8
	v_add_u32_sdwa v2, v2, sext(v9) dst_sel:DWORD dst_unused:UNUSED_PAD src0_sel:DWORD src1_sel:WORD_0
	s_waitcnt vmcnt(6)
	v_ashrrev_i32_e32 v3, 31, v2
	v_lshlrev_b64 v[132:133], 1, v[2:3]
	v_mov_b32_e32 v2, 0
	s_mov_b64 s[42:43], s[2:3]
	v_mov_b32_e32 v3, v2
	v_mov_b32_e32 v4, v2
	v_mov_b32_e32 v5, v2
	v_mov_b32_e32 v6, v2
	v_mov_b32_e32 v7, v2
	v_mov_b32_e32 v8, v2
	v_mov_b32_e32 v9, v2
	v_mov_b32_e32 v14, v2
	v_mov_b32_e32 v15, v2
	v_mov_b32_e32 v16, v2
	v_mov_b32_e32 v17, v2
	v_mov_b32_e32 v22, v2
	v_mov_b32_e32 v23, v2
	v_mov_b32_e32 v24, v2
	v_mov_b32_e32 v25, v2
	v_mov_b32_e32 v10, v2
	v_mov_b32_e32 v11, v2
	v_mov_b32_e32 v12, v2
	v_mov_b32_e32 v13, v2
	v_mov_b32_e32 v18, v2
	v_mov_b32_e32 v19, v2
	v_mov_b32_e32 v20, v2
	v_mov_b32_e32 v21, v2
	v_mov_b32_e32 v30, v2
	v_mov_b32_e32 v31, v2
	v_mov_b32_e32 v32, v2
	v_mov_b32_e32 v33, v2
	v_mov_b32_e32 v38, v2
	v_mov_b32_e32 v39, v2
	v_mov_b32_e32 v40, v2
	v_mov_b32_e32 v41, v2
	v_mov_b32_e32 v26, v2
	v_mov_b32_e32 v27, v2
	v_mov_b32_e32 v28, v2
	v_mov_b32_e32 v29, v2
	v_mov_b32_e32 v34, v2
	v_mov_b32_e32 v35, v2
	v_mov_b32_e32 v36, v2
	v_mov_b32_e32 v37, v2
	v_mov_b32_e32 v46, v2
	v_mov_b32_e32 v47, v2
	v_mov_b32_e32 v48, v2
	v_mov_b32_e32 v49, v2
	v_mov_b32_e32 v54, v2
	v_mov_b32_e32 v55, v2
	v_mov_b32_e32 v56, v2
	v_mov_b32_e32 v57, v2
	v_mov_b32_e32 v42, v2
	v_mov_b32_e32 v43, v2
	v_mov_b32_e32 v44, v2
	v_mov_b32_e32 v45, v2
	v_mov_b32_e32 v50, v2
	v_mov_b32_e32 v51, v2
	v_mov_b32_e32 v52, v2
	v_mov_b32_e32 v53, v2
	v_mov_b32_e32 v58, v2
	v_mov_b32_e32 v59, v2
	v_mov_b32_e32 v60, v2
	v_mov_b32_e32 v61, v2
	v_mov_b32_e32 v62, v2
	v_mov_b32_e32 v63, v2
	v_mov_b32_e32 v64, v2
	v_mov_b32_e32 v65, v2
	v_mov_b32_e32 v66, v2
	v_mov_b32_e32 v67, v2
	v_mov_b32_e32 v68, v2
	v_mov_b32_e32 v69, v2
	v_mov_b32_e32 v70, v2
	v_mov_b32_e32 v71, v2
	v_mov_b32_e32 v72, v2
	v_mov_b32_e32 v73, v2
	v_mov_b32_e32 v82, v2
	v_mov_b32_e32 v83, v2
	v_mov_b32_e32 v84, v2
	v_mov_b32_e32 v85, v2
	v_mov_b32_e32 v86, v2
	v_mov_b32_e32 v87, v2
	v_mov_b32_e32 v88, v2
	v_mov_b32_e32 v89, v2
	v_mov_b32_e32 v74, v2
	v_mov_b32_e32 v75, v2
	v_mov_b32_e32 v76, v2
	v_mov_b32_e32 v77, v2
	v_mov_b32_e32 v78, v2
	v_mov_b32_e32 v79, v2
	v_mov_b32_e32 v80, v2
	v_mov_b32_e32 v81, v2
	v_mov_b32_e32 v98, v2
	v_mov_b32_e32 v99, v2
	v_mov_b32_e32 v100, v2
	v_mov_b32_e32 v101, v2
	v_mov_b32_e32 v102, v2
	v_mov_b32_e32 v103, v2
	v_mov_b32_e32 v104, v2
	v_mov_b32_e32 v105, v2
	v_mov_b32_e32 v90, v2
	v_mov_b32_e32 v91, v2
	v_mov_b32_e32 v92, v2
	v_mov_b32_e32 v93, v2
	v_mov_b32_e32 v94, v2
	v_mov_b32_e32 v95, v2
	v_mov_b32_e32 v96, v2
	v_mov_b32_e32 v97, v2
	v_mov_b32_e32 v114, v2
	v_mov_b32_e32 v115, v2
	v_mov_b32_e32 v116, v2
	v_mov_b32_e32 v117, v2
	v_mov_b32_e32 v118, v2
	v_mov_b32_e32 v119, v2
	v_mov_b32_e32 v120, v2
	v_mov_b32_e32 v121, v2
	v_mov_b32_e32 v106, v2
	v_mov_b32_e32 v107, v2
	v_mov_b32_e32 v108, v2
	v_mov_b32_e32 v109, v2
	v_mov_b32_e32 v110, v2
	v_mov_b32_e32 v111, v2
	v_mov_b32_e32 v112, v2
	v_mov_b32_e32 v113, v2
	v_mov_b32_e32 v122, v2
	v_mov_b32_e32 v123, v2
	v_mov_b32_e32 v124, v2
	v_mov_b32_e32 v125, v2
	v_mov_b32_e32 v126, v2
	v_mov_b32_e32 v127, v2
	v_mov_b32_e32 v128, v2
	v_mov_b32_e32 v129, v2
	s_barrier
; #define STAGE8(P, BASE, LD, OFF, br, kt) do { const bf16_t* g_ = (BASE) + (long)(br) * (LD) + (long)(kt) * 64 + (OFF); \
;     __builtin_amdgcn_global_load_lds((const unsigned*)(g_), (unsigned*)((char*)(P) + tid8 * 16), 16, 0, 0);            \
;     __builtin_amdgcn_global_load_lds((const unsigned*)(g_ + 64 * (long)(LD)), (unsigned*)((char*)(P) + tid8 * 16 + 8192), 16, 0, 0); } while (0)
; #define LDA8(dst, b, h) _Pragma("unroll") for (int m = 0; m < 4; ++m) _Pragma("unroll") for (int k = 0; k < 2; ++k) \
;     dst[m][k] = *reinterpret_cast<const bf16x8*>(SA8(b, h) + fa_off + m * 2048 + k * 1024)
; #define LDB8(dst, b, h) _Pragma("unroll") for (int n = 0; n < 2; ++n) _Pragma("unroll") for (int k = 0; k < 2; ++k) \
;     dst[n][k] = *reinterpret_cast<const bf16x8*>(SB8(b, h) + fb_off + n * 2048 + k * 1024)
; #define WAIT_V8(n) asm volatile("s_waitcnt vmcnt(" #n ")" ::: "memory")
; #define WAIT_L8(n) asm volatile("s_waitcnt lgkmcnt(" #n ")" ::: "memory")
; #define BAR8 __builtin_amdgcn_s_barrier()
; #define SCHED8 __builtin_amdgcn_sched_barrier(0)
; __device__ __forceinline__ void gemm_mainloop8(const bf16_t* __restrict__ Xg, int ldx, const bf16_t* __restrict__ Wg, int ldw, ...
;     ...
;     LDB8(B0, 0, 0); SCHED8; LDA8(At, 0, 0); STAGE8(SA8(1, 1), A, ldw, offA, 128, t + 1);
;     WAIT_L8(8); BAR8; WAIT_L8(0); MMA8(0, 0, At, B0); BAR8; SCHED8;
;     LDB8(B1, 0, 1); STAGE8(SB8(0, 0), Bt, ldx, offB, 0, t + 2);
;     BAR8; WAIT_L8(0); MMA8(0, 1, At, B1); BAR8;
;     LDA8(At, 0, 1); STAGE8(SA8(0, 0), A, ldw, offA, 0, t + 2);
;     BAR8; WAIT_L8(0); MMA8(1, 0, At, B0); BAR8; SCHED8;
;     STAGE8(SB8(0, 1), Bt, ldx, offB, 128, t + 2);
;     WAIT_V8(6); BAR8; MMA8(1, 1, At, B1); BAR8;
;     LDB8(B0, 1, 0); SCHED8; LDA8(At, 1, 0); STAGE8(SA8(0, 1), A, ldw, offA, 128, t + 2);
.LBB0_214:
	v_or_b32_e32 v150, 0x10000, v143
	v_add_u32_e32 v151, 0x10400, v143
	v_add_u32_e32 v152, 0x10800, v143
	v_add_u32_e32 v153, 0x10c00, v143
	v_or_b32_e32 v156, 0x14000, v143
	v_add_u32_e32 v157, 0x14400, v143
	v_add_u32_e32 v158, 0x14800, v143
	v_add_u32_e32 v159, 0x14c00, v143
	v_add_u32_e32 v154, 0xc000, v135
	v_add_u32_e32 v155, 0xe000, v135
	v_lshl_add_u64 v[180:181], s[42:43], 0, v[132:133]
	v_lshl_add_u64 v[244:245], s[6:7], 0, v[132:133]
	ds_read_b128 v[160:163], v150
	ds_read_b128 v[164:167], v151
	ds_read_b128 v[168:171], v152
	ds_read_b128 v[172:175], v153
	ds_read_b128 v[176:179], v134
	ds_read_b128 v[186:189], v134 offset:1024
	ds_read_b128 v[190:193], v134 offset:2048
	ds_read_b128 v[194:197], v134 offset:3072
	ds_read_b128 v[204:207], v134 offset:4096
	ds_read_b128 v[208:211], v134 offset:5120
	ds_read_b128 v[212:215], v134 offset:6144
	ds_read_b128 v[216:219], v134 offset:7168
	ds_read_b128 v[220:223], v156
	ds_read_b128 v[224:227], v157
	ds_read_b128 v[228:231], v158
	ds_read_b128 v[232:235], v159
	v_lshl_add_u64 v[236:237], v[180:181], 0, s[44:45]
	v_readfirstlane_b32 s48, v154
	s_nop 0
	s_mov_b32 m0, s48
	s_nop 0
	global_load_lds_dwordx4 v[236:237], off
	v_lshl_add_u64 v[236:237], v[180:181], 0, s[82:83]
	v_readfirstlane_b32 s48, v155
	s_nop 0
	s_mov_b32 m0, s48
	s_nop 0
	global_load_lds_dwordx4 v[236:237], off
	s_waitcnt lgkmcnt(0)
	s_barrier
	s_setprio 1
	v_mfma_f32_16x16x32_bf16 v[126:129], v[176:179], v[160:163], v[126:129]
	v_mfma_f32_16x16x32_bf16 v[122:125], v[176:179], v[168:171], v[122:125]
	v_mfma_f32_16x16x32_bf16 v[118:121], v[190:193], v[160:163], v[118:121]
	v_mfma_f32_16x16x32_bf16 v[114:117], v[190:193], v[168:171], v[114:117]
	v_mfma_f32_16x16x32_bf16 v[102:105], v[204:207], v[160:163], v[102:105]
	v_mfma_f32_16x16x32_bf16 v[98:101], v[204:207], v[168:171], v[98:101]
	v_mfma_f32_16x16x32_bf16 v[86:89], v[212:215], v[160:163], v[86:89]
	v_mfma_f32_16x16x32_bf16 v[82:85], v[212:215], v[168:171], v[82:85]
	v_mfma_f32_16x16x32_bf16 v[126:129], v[186:189], v[164:167], v[126:129]
	v_mfma_f32_16x16x32_bf16 v[122:125], v[186:189], v[172:175], v[122:125]
	v_mfma_f32_16x16x32_bf16 v[118:121], v[194:197], v[164:167], v[118:121]
	v_mfma_f32_16x16x32_bf16 v[114:117], v[194:197], v[172:175], v[114:117]
	v_mfma_f32_16x16x32_bf16 v[102:105], v[208:211], v[164:167], v[102:105]
	v_mfma_f32_16x16x32_bf16 v[98:101], v[208:211], v[172:175], v[98:101]
	v_mfma_f32_16x16x32_bf16 v[86:89], v[216:219], v[164:167], v[86:89]
	v_mfma_f32_16x16x32_bf16 v[82:85], v[216:219], v[172:175], v[82:85]
	v_mfma_f32_16x16x32_bf16 v[110:113], v[176:179], v[220:223], v[110:113]
	v_mfma_f32_16x16x32_bf16 v[106:109], v[176:179], v[228:231], v[106:109]
	v_mfma_f32_16x16x32_bf16 v[94:97], v[190:193], v[220:223], v[94:97]
	v_mfma_f32_16x16x32_bf16 v[90:93], v[190:193], v[228:231], v[90:93]
	v_mfma_f32_16x16x32_bf16 v[78:81], v[204:207], v[220:223], v[78:81]
	v_mfma_f32_16x16x32_bf16 v[74:77], v[204:207], v[228:231], v[74:77]
	v_mfma_f32_16x16x32_bf16 v[70:73], v[212:215], v[220:223], v[70:73]
	v_mfma_f32_16x16x32_bf16 v[66:69], v[212:215], v[228:231], v[66:69]
	v_mfma_f32_16x16x32_bf16 v[110:113], v[186:189], v[224:227], v[110:113]
	v_mfma_f32_16x16x32_bf16 v[106:109], v[186:189], v[232:235], v[106:109]
	v_mfma_f32_16x16x32_bf16 v[94:97], v[194:197], v[224:227], v[94:97]
	v_mfma_f32_16x16x32_bf16 v[90:93], v[194:197], v[232:235], v[90:93]
	v_mfma_f32_16x16x32_bf16 v[78:81], v[208:211], v[224:227], v[78:81]
	v_mfma_f32_16x16x32_bf16 v[74:77], v[208:211], v[232:235], v[74:77]
	v_mfma_f32_16x16x32_bf16 v[70:73], v[216:219], v[224:227], v[70:73]
	v_mfma_f32_16x16x32_bf16 v[66:69], v[216:219], v[232:235], v[66:69]
	s_setprio 0
	s_barrier
	ds_read_b128 v[176:179], v134 offset:16384
	ds_read_b128 v[186:189], v134 offset:17408
	ds_read_b128 v[190:193], v134 offset:18432
	ds_read_b128 v[194:197], v134 offset:19456
	ds_read_b128 v[204:207], v134 offset:20480
	ds_read_b128 v[208:211], v134 offset:21504
	ds_read_b128 v[212:215], v134 offset:22528
	ds_read_b128 v[216:219], v134 offset:23552
	v_lshl_add_u64 v[236:237], v[244:245], 0, s[70:71]
	v_readfirstlane_b32 s48, v136
	s_nop 0
	s_mov_b32 m0, s48
	s_nop 0
	global_load_lds_dwordx4 v[236:237], off
	v_lshl_add_u64 v[236:237], v[244:245], 0, s[90:91]
	v_readfirstlane_b32 s48, v137
	s_nop 0
	s_mov_b32 m0, s48
	s_nop 0
	global_load_lds_dwordx4 v[236:237], off
	v_lshl_add_u64 v[236:237], v[180:181], 0, s[70:71]
	v_readfirstlane_b32 s48, v135
	s_nop 0
	s_mov_b32 m0, s48
	s_nop 0
	global_load_lds_dwordx4 v[236:237], off
	v_lshl_add_u64 v[236:237], v[180:181], 0, s[90:91]
	v_readfirstlane_b32 s48, v138
	s_nop 0
	s_mov_b32 m0, s48
	s_nop 0
	global_load_lds_dwordx4 v[236:237], off
	v_lshl_add_u64 v[236:237], v[244:245], 0, s[80:81]
	v_readfirstlane_b32 s48, v139
	s_nop 0
	s_mov_b32 m0, s48
	s_nop 0
	global_load_lds_dwordx4 v[236:237], off
	v_lshl_add_u64 v[236:237], v[244:245], 0, s[68:69]
	v_readfirstlane_b32 s48, v140
	s_nop 0
	s_mov_b32 m0, s48
	s_nop 0
	global_load_lds_dwordx4 v[236:237], off
	s_waitcnt vmcnt(6)
	s_waitcnt lgkmcnt(0)
	s_barrier
; #define STAGE8(P, BASE, LD, OFF, br, kt) do { const bf16_t* g_ = (BASE) + (long)(br) * (LD) + (long)(kt) * 64 + (OFF); \
;     __builtin_amdgcn_global_load_lds((const unsigned*)(g_), (unsigned*)((char*)(P) + tid8 * 16), 16, 0, 0);            \
;     __builtin_amdgcn_global_load_lds((const unsigned*)(g_ + 64 * (long)(LD)), (unsigned*)((char*)(P) + tid8 * 16 + 8192), 16, 0, 0); } while (0)
; #define LDA8(dst, b, h) _Pragma("unroll") for (int m = 0; m < 4; ++m) _Pragma("unroll") for (int k = 0; k < 2; ++k) \
;     dst[m][k] = *reinterpret_cast<const bf16x8*>(SA8(b, h) + fa_off + m * 2048 + k * 1024)
; #define LDB8(dst, b, h) _Pragma("unroll") for (int n = 0; n < 2; ++n) _Pragma("unroll") for (int k = 0; k < 2; ++k) \
;     dst[n][k] = *reinterpret_cast<const bf16x8*>(SB8(b, h) + fb_off + n * 2048 + k * 1024)
; #define WAIT_V8(n) asm volatile("s_waitcnt vmcnt(" #n ")" ::: "memory")
; #define WAIT_L8(n) asm volatile("s_waitcnt lgkmcnt(" #n ")" ::: "memory")
; #define BAR8 __builtin_amdgcn_s_barrier()
; #define SCHED8 __builtin_amdgcn_sched_barrier(0)
; __device__ __forceinline__ void gemm_mainloop8(const bf16_t* __restrict__ Xg, int ldx, const bf16_t* __restrict__ Wg, int ldw, ...
;     ...
;     WAIT_V8(6); BAR8; MMA8(1, 1, At, B1); BAR8;
;     LDB8(B0, 1, 0); SCHED8; LDA8(At, 1, 0); STAGE8(SA8(0, 1), A, ldw, offA, 128, t + 2);
;     WAIT_L8(8); BAR8; WAIT_L8(0); MMA8(0, 0, At, B0); BAR8; SCHED8;
;     LDB8(B1, 1, 1); STAGE8(SB8(1, 0), Bt, ldx, offB, 0, t + 3);
;     BAR8; WAIT_L8(0); MMA8(0, 1, At, B1); BAR8;
;     LDA8(At, 1, 1); STAGE8(SA8(1, 0), A, ldw, offA, 0, t + 3);
;     BAR8; WAIT_L8(0); MMA8(1, 0, At, B0); BAR8; SCHED8;
	s_setprio 1
	v_mfma_f32_16x16x32_bf16 v[62:65], v[176:179], v[160:163], v[62:65]
	v_mfma_f32_16x16x32_bf16 v[58:61], v[176:179], v[168:171], v[58:61]
	v_mfma_f32_16x16x32_bf16 v[54:57], v[190:193], v[160:163], v[54:57]
	v_mfma_f32_16x16x32_bf16 v[46:49], v[190:193], v[168:171], v[46:49]
	v_mfma_f32_16x16x32_bf16 v[38:41], v[204:207], v[160:163], v[38:41]
	v_mfma_f32_16x16x32_bf16 v[30:33], v[204:207], v[168:171], v[30:33]
	v_mfma_f32_16x16x32_bf16 v[22:25], v[212:215], v[160:163], v[22:25]
	v_mfma_f32_16x16x32_bf16 v[14:17], v[212:215], v[168:171], v[14:17]
	v_mfma_f32_16x16x32_bf16 v[62:65], v[186:189], v[164:167], v[62:65]
	v_mfma_f32_16x16x32_bf16 v[58:61], v[186:189], v[172:175], v[58:61]
	v_mfma_f32_16x16x32_bf16 v[54:57], v[194:197], v[164:167], v[54:57]
	v_mfma_f32_16x16x32_bf16 v[46:49], v[194:197], v[172:175], v[46:49]
	v_mfma_f32_16x16x32_bf16 v[38:41], v[208:211], v[164:167], v[38:41]
	v_mfma_f32_16x16x32_bf16 v[30:33], v[208:211], v[172:175], v[30:33]
	v_mfma_f32_16x16x32_bf16 v[22:25], v[216:219], v[164:167], v[22:25]
	v_mfma_f32_16x16x32_bf16 v[14:17], v[216:219], v[172:175], v[14:17]
	v_mfma_f32_16x16x32_bf16 v[50:53], v[176:179], v[220:223], v[50:53]
	v_mfma_f32_16x16x32_bf16 v[42:45], v[176:179], v[228:231], v[42:45]
	v_mfma_f32_16x16x32_bf16 v[34:37], v[190:193], v[220:223], v[34:37]
	v_mfma_f32_16x16x32_bf16 v[26:29], v[190:193], v[228:231], v[26:29]
	v_mfma_f32_16x16x32_bf16 v[18:21], v[204:207], v[220:223], v[18:21]
	v_mfma_f32_16x16x32_bf16 v[10:13], v[204:207], v[228:231], v[10:13]
	v_mfma_f32_16x16x32_bf16 v[6:9], v[212:215], v[220:223], v[6:9]
	v_mfma_f32_16x16x32_bf16 v[2:5], v[212:215], v[228:231], v[2:5]
	v_mfma_f32_16x16x32_bf16 v[50:53], v[186:189], v[224:227], v[50:53]
	v_mfma_f32_16x16x32_bf16 v[42:45], v[186:189], v[232:235], v[42:45]
	v_mfma_f32_16x16x32_bf16 v[34:37], v[194:197], v[224:227], v[34:37]
	v_mfma_f32_16x16x32_bf16 v[26:29], v[194:197], v[232:235], v[26:29]
	v_mfma_f32_16x16x32_bf16 v[18:21], v[208:211], v[224:227], v[18:21]
	v_mfma_f32_16x16x32_bf16 v[10:13], v[208:211], v[232:235], v[10:13]
	v_mfma_f32_16x16x32_bf16 v[6:9], v[216:219], v[224:227], v[6:9]
	v_mfma_f32_16x16x32_bf16 v[2:5], v[216:219], v[232:235], v[2:5]
	s_setprio 0
	s_barrier
	v_or_b32_e32 v160, 0x18000, v143
	v_add_u32_e32 v161, 0x18400, v143
	v_add_u32_e32 v162, 0x18800, v143
	v_add_u32_e32 v163, 0x18c00, v143
	v_or_b32_e32 v164, 0x1c000, v143
	v_add_u32_e32 v165, 0x1c400, v143
	v_add_u32_e32 v166, 0x1c800, v143
	v_add_u32_e32 v167, 0x1cc00, v143
	ds_read_b128 v[168:171], v160
	ds_read_b128 v[172:175], v161
	ds_read_b128 v[176:179], v162
	ds_read_b128 v[186:189], v163
	ds_read_b128 v[190:193], v134 offset:32768
	ds_read_b128 v[194:197], v134 offset:33792
	ds_read_b128 v[204:207], v134 offset:34816
	ds_read_b128 v[208:211], v134 offset:35840
	ds_read_b128 v[212:215], v134 offset:36864
	ds_read_b128 v[216:219], v134 offset:37888
	ds_read_b128 v[220:223], v134 offset:38912
	ds_read_b128 v[224:227], v134 offset:39936
	ds_read_b128 v[228:231], v164
	ds_read_b128 v[232:235], v165
	ds_read_b128 v[236:239], v166
	ds_read_b128 v[240:243], v167
	v_lshl_add_u64 v[246:247], v[180:181], 0, s[80:81]
	v_readfirstlane_b32 s48, v141
	s_nop 0
	s_mov_b32 m0, s48
	s_nop 0
	global_load_lds_dwordx4 v[246:247], off
	v_lshl_add_u64 v[246:247], v[180:181], 0, s[68:69]
	v_readfirstlane_b32 s48, v142
	s_nop 0
	s_mov_b32 m0, s48
	s_nop 0
	global_load_lds_dwordx4 v[246:247], off
	s_waitcnt lgkmcnt(0)
	s_barrier
	s_setprio 1
	v_mfma_f32_16x16x32_bf16 v[126:129], v[190:193], v[168:171], v[126:129]
	v_mfma_f32_16x16x32_bf16 v[122:125], v[190:193], v[176:179], v[122:125]
	v_mfma_f32_16x16x32_bf16 v[118:121], v[204:207], v[168:171], v[118:121]
	v_mfma_f32_16x16x32_bf16 v[114:117], v[204:207], v[176:179], v[114:117]
	v_mfma_f32_16x16x32_bf16 v[102:105], v[212:215], v[168:171], v[102:105]
	v_mfma_f32_16x16x32_bf16 v[98:101], v[212:215], v[176:179], v[98:101]
	v_mfma_f32_16x16x32_bf16 v[86:89], v[220:223], v[168:171], v[86:89]
	v_mfma_f32_16x16x32_bf16 v[82:85], v[220:223], v[176:179], v[82:85]
	v_mfma_f32_16x16x32_bf16 v[126:129], v[194:197], v[172:175], v[126:129]
	v_mfma_f32_16x16x32_bf16 v[122:125], v[194:197], v[186:189], v[122:125]
	v_mfma_f32_16x16x32_bf16 v[118:121], v[208:211], v[172:175], v[118:121]
	v_mfma_f32_16x16x32_bf16 v[114:117], v[208:211], v[186:189], v[114:117]
	v_mfma_f32_16x16x32_bf16 v[102:105], v[216:219], v[172:175], v[102:105]
	v_mfma_f32_16x16x32_bf16 v[98:101], v[216:219], v[186:189], v[98:101]
	v_mfma_f32_16x16x32_bf16 v[86:89], v[224:227], v[172:175], v[86:89]
	v_mfma_f32_16x16x32_bf16 v[82:85], v[224:227], v[186:189], v[82:85]
	v_mfma_f32_16x16x32_bf16 v[110:113], v[190:193], v[228:231], v[110:113]
	v_mfma_f32_16x16x32_bf16 v[106:109], v[190:193], v[236:239], v[106:109]
	v_mfma_f32_16x16x32_bf16 v[94:97], v[204:207], v[228:231], v[94:97]
	v_mfma_f32_16x16x32_bf16 v[90:93], v[204:207], v[236:239], v[90:93]
	v_mfma_f32_16x16x32_bf16 v[78:81], v[212:215], v[228:231], v[78:81]
	v_mfma_f32_16x16x32_bf16 v[74:77], v[212:215], v[236:239], v[74:77]
	v_mfma_f32_16x16x32_bf16 v[70:73], v[220:223], v[228:231], v[70:73]
	v_mfma_f32_16x16x32_bf16 v[66:69], v[220:223], v[236:239], v[66:69]
	v_mfma_f32_16x16x32_bf16 v[110:113], v[194:197], v[232:235], v[110:113]
	v_mfma_f32_16x16x32_bf16 v[106:109], v[194:197], v[240:243], v[106:109]
	v_mfma_f32_16x16x32_bf16 v[94:97], v[208:211], v[232:235], v[94:97]
	v_mfma_f32_16x16x32_bf16 v[90:93], v[208:211], v[240:243], v[90:93]
	v_mfma_f32_16x16x32_bf16 v[78:81], v[216:219], v[232:235], v[78:81]
	v_mfma_f32_16x16x32_bf16 v[74:77], v[216:219], v[240:243], v[74:77]
	v_mfma_f32_16x16x32_bf16 v[70:73], v[224:227], v[232:235], v[70:73]
	v_mfma_f32_16x16x32_bf16 v[66:69], v[224:227], v[240:243], v[66:69]
	s_setprio 0
	s_barrier
; #define STAGE8(P, BASE, LD, OFF, br, kt) do { const bf16_t* g_ = (BASE) + (long)(br) * (LD) + (long)(kt) * 64 + (OFF); \
;     __builtin_amdgcn_global_load_lds((const unsigned*)(g_), (unsigned*)((char*)(P) + tid8 * 16), 16, 0, 0);            \
;     __builtin_amdgcn_global_load_lds((const unsigned*)(g_ + 64 * (long)(LD)), (unsigned*)((char*)(P) + tid8 * 16 + 8192), 16, 0, 0); } while (0)
; #define LDA8(dst, b, h) _Pragma("unroll") for (int m = 0; m < 4; ++m) _Pragma("unroll") for (int k = 0; k < 2; ++k) \
;     dst[m][k] = *reinterpret_cast<const bf16x8*>(SA8(b, h) + fa_off + m * 2048 + k * 1024)
; #define LDB8(dst, b, h) _Pragma("unroll") for (int n = 0; n < 2; ++n) _Pragma("unroll") for (int k = 0; k < 2; ++k) \
;     dst[n][k] = *reinterpret_cast<const bf16x8*>(SB8(b, h) + fb_off + n * 2048 + k * 1024)
; #define WAIT_V8(n) asm volatile("s_waitcnt vmcnt(" #n ")" ::: "memory")
; #define WAIT_L8(n) asm volatile("s_waitcnt lgkmcnt(" #n ")" ::: "memory")
; #define BAR8 __builtin_amdgcn_s_barrier()
; #define SCHED8 __builtin_amdgcn_sched_barrier(0)
; __device__ __forceinline__ void gemm_mainloop8(const bf16_t* __restrict__ Xg, int ldx, const bf16_t* __restrict__ Wg, int ldw, ...
;     ...
;     LDA8(At, 1, 1); STAGE8(SA8(1, 0), A, ldw, offA, 0, t + 3);
;     BAR8; WAIT_L8(0); MMA8(1, 0, At, B0); BAR8; SCHED8;
;     STAGE8(SB8(1, 1), Bt, ldx, offB, 128, t + 3);
;     WAIT_V8(6); BAR8; MMA8(1, 1, At, B1); BAR8;
;   }
;   { LDB8(B0, 0, 0); LDA8(At, 0, 0); STAGE8(SA8(1, 1), A, ldw, offA, 128, nt - 1);
;     BAR8; WAIT_L8(0); MMA8(0, 0, At, B0); BAR8;
	ds_read_b128 v[190:193], v134 offset:49152
	ds_read_b128 v[194:197], v134 offset:50176
	ds_read_b128 v[204:207], v134 offset:51200
	ds_read_b128 v[208:211], v134 offset:52224
	ds_read_b128 v[212:215], v134 offset:53248
	ds_read_b128 v[216:219], v134 offset:54272
	ds_read_b128 v[220:223], v134 offset:55296
	ds_read_b128 v[224:227], v134 offset:56320
	v_lshl_add_u64 v[246:247], v[244:245], 0, s[88:89]
	v_readfirstlane_b32 s48, v144
	s_nop 0
	s_mov_b32 m0, s48
	s_nop 0
	global_load_lds_dwordx4 v[246:247], off
	v_lshl_add_u64 v[246:247], v[244:245], 0, s[4:5]
	v_readfirstlane_b32 s48, v145
	s_nop 0
	s_mov_b32 m0, s48
	s_nop 0
	global_load_lds_dwordx4 v[246:247], off
	v_lshl_add_u64 v[246:247], v[180:181], 0, s[88:89]
	v_readfirstlane_b32 s48, v146
	s_nop 0
	s_mov_b32 m0, s48
	s_nop 0
	global_load_lds_dwordx4 v[246:247], off
	v_lshl_add_u64 v[246:247], v[180:181], 0, s[4:5]
	v_readfirstlane_b32 s48, v147
	s_nop 0
	s_mov_b32 m0, s48
	s_nop 0
	global_load_lds_dwordx4 v[246:247], off
	v_lshl_add_u64 v[246:247], v[244:245], 0, s[92:93]
	v_readfirstlane_b32 s48, v148
	s_nop 0
	s_mov_b32 m0, s48
	s_nop 0
	global_load_lds_dwordx4 v[246:247], off
	v_lshl_add_u64 v[246:247], v[244:245], 0, s[94:95]
	v_readfirstlane_b32 s48, v149
	s_nop 0
	s_mov_b32 m0, s48
	s_nop 0
	global_load_lds_dwordx4 v[246:247], off
	s_waitcnt vmcnt(6)
	s_waitcnt lgkmcnt(0)
	s_barrier
	s_setprio 1
	v_mfma_f32_16x16x32_bf16 v[62:65], v[190:193], v[168:171], v[62:65]
	v_mfma_f32_16x16x32_bf16 v[58:61], v[190:193], v[176:179], v[58:61]
	v_mfma_f32_16x16x32_bf16 v[54:57], v[204:207], v[168:171], v[54:57]
	v_mfma_f32_16x16x32_bf16 v[46:49], v[204:207], v[176:179], v[46:49]
	v_mfma_f32_16x16x32_bf16 v[38:41], v[212:215], v[168:171], v[38:41]
	v_mfma_f32_16x16x32_bf16 v[30:33], v[212:215], v[176:179], v[30:33]
	v_mfma_f32_16x16x32_bf16 v[22:25], v[220:223], v[168:171], v[22:25]
	v_mfma_f32_16x16x32_bf16 v[14:17], v[220:223], v[176:179], v[14:17]
	v_mfma_f32_16x16x32_bf16 v[62:65], v[194:197], v[172:175], v[62:65]
	v_mfma_f32_16x16x32_bf16 v[58:61], v[194:197], v[186:189], v[58:61]
	v_mfma_f32_16x16x32_bf16 v[54:57], v[208:211], v[172:175], v[54:57]
	v_mfma_f32_16x16x32_bf16 v[46:49], v[208:211], v[186:189], v[46:49]
	v_mfma_f32_16x16x32_bf16 v[38:41], v[216:219], v[172:175], v[38:41]
	v_mfma_f32_16x16x32_bf16 v[30:33], v[216:219], v[186:189], v[30:33]
	v_mfma_f32_16x16x32_bf16 v[22:25], v[224:227], v[172:175], v[22:25]
	v_mfma_f32_16x16x32_bf16 v[14:17], v[224:227], v[186:189], v[14:17]
	v_mfma_f32_16x16x32_bf16 v[50:53], v[190:193], v[228:231], v[50:53]
	v_mfma_f32_16x16x32_bf16 v[42:45], v[190:193], v[236:239], v[42:45]
	v_mfma_f32_16x16x32_bf16 v[34:37], v[204:207], v[228:231], v[34:37]
	v_mfma_f32_16x16x32_bf16 v[26:29], v[204:207], v[236:239], v[26:29]
	v_mfma_f32_16x16x32_bf16 v[18:21], v[212:215], v[228:231], v[18:21]
	v_mfma_f32_16x16x32_bf16 v[10:13], v[212:215], v[236:239], v[10:13]
	v_mfma_f32_16x16x32_bf16 v[6:9], v[220:223], v[228:231], v[6:9]
	v_mfma_f32_16x16x32_bf16 v[2:5], v[220:223], v[236:239], v[2:5]
	v_mfma_f32_16x16x32_bf16 v[50:53], v[194:197], v[232:235], v[50:53]
	v_mfma_f32_16x16x32_bf16 v[42:45], v[194:197], v[240:243], v[42:45]
	v_mfma_f32_16x16x32_bf16 v[34:37], v[208:211], v[232:235], v[34:37]
	v_mfma_f32_16x16x32_bf16 v[26:29], v[208:211], v[240:243], v[26:29]
	v_mfma_f32_16x16x32_bf16 v[18:21], v[216:219], v[232:235], v[18:21]
	v_mfma_f32_16x16x32_bf16 v[10:13], v[216:219], v[240:243], v[10:13]
	v_mfma_f32_16x16x32_bf16 v[6:9], v[224:227], v[232:235], v[6:9]
	v_mfma_f32_16x16x32_bf16 v[2:5], v[224:227], v[240:243], v[2:5]
	s_setprio 0
	s_add_i32 s37, s37, 2
	s_add_u32 s6, s6, 0x100
	s_addc_u32 s7, s7, 0
	s_add_u32 s42, s42, 0x100
	s_addc_u32 s43, s43, 0
	s_cmp_lt_u32 s37, 28
	s_barrier
	s_cbranch_scc1 .LBB0_214
	v_lshl_add_u64 v[130:131], v[130:131], 1, s[2:3]
	s_mov_b64 s[2:3], 0x80f80
	v_lshl_add_u64 v[132:133], v[130:131], 0, s[2:3]
	v_readfirstlane_b32 s2, v154
	s_mov_b32 m0, s2
	s_mov_b64 s[2:3], 0xc0f80
	v_lshl_add_u64 v[130:131], v[130:131], 0, s[2:3]
	v_readfirstlane_b32 s2, v155
	s_nop 0
	ds_read_b128 v[136:139], v150
	ds_read_b128 v[140:143], v151
	ds_read_b128 v[144:147], v152
	ds_read_b128 v[148:151], v153
	ds_read_b128 v[168:171], v134
	ds_read_b128 v[172:175], v134 offset:1024
	ds_read_b128 v[176:179], v134 offset:2048
	ds_read_b128 v[186:189], v134 offset:3072
	ds_read_b128 v[190:193], v134 offset:4096
	ds_read_b128 v[194:197], v134 offset:5120
	ds_read_b128 v[204:207], v134 offset:6144
	ds_read_b128 v[208:211], v134 offset:7168
	global_load_lds_dwordx4 v[132:133], off
	s_mov_b32 m0, s2
	s_nop 0
	global_load_lds_dwordx4 v[130:131], off
	s_barrier
	s_waitcnt lgkmcnt(0)
	s_setprio 1
	s_waitcnt lgkmcnt(0)
	v_mfma_f32_16x16x32_bf16 v[126:129], v[168:171], v[136:139], v[126:129]
	v_mfma_f32_16x16x32_bf16 v[122:125], v[168:171], v[144:147], v[122:125]
	v_mfma_f32_16x16x32_bf16 v[118:121], v[176:179], v[136:139], v[118:121]
	v_mfma_f32_16x16x32_bf16 v[114:117], v[176:179], v[144:147], v[114:117]
	v_mfma_f32_16x16x32_bf16 v[86:89], v[204:207], v[136:139], v[86:89]
	v_mfma_f32_16x16x32_bf16 v[126:129], v[172:175], v[140:143], v[126:129]
	v_mfma_f32_16x16x32_bf16 v[122:125], v[172:175], v[148:151], v[122:125]
	v_mfma_f32_16x16x32_bf16 v[118:121], v[186:189], v[140:143], v[118:121]
	v_mfma_f32_16x16x32_bf16 v[114:117], v[186:189], v[148:151], v[114:117]
	v_mfma_f32_16x16x32_bf16 v[102:105], v[190:193], v[136:139], v[102:105]
	v_mfma_f32_16x16x32_bf16 v[98:101], v[190:193], v[144:147], v[98:101]
	v_mfma_f32_16x16x32_bf16 v[86:89], v[208:211], v[140:143], v[86:89]
	v_mfma_f32_16x16x32_bf16 v[82:85], v[204:207], v[144:147], v[82:85]
	v_mfma_f32_16x16x32_bf16 v[130:133], v[194:197], v[140:143], v[102:105]
	v_mfma_f32_16x16x32_bf16 v[152:155], v[194:197], v[148:151], v[98:101]
	v_mfma_f32_16x16x32_bf16 v[212:215], v[208:211], v[148:151], v[82:85]
	s_setprio 0
	s_barrier
; #define LDA8(dst, b, h) _Pragma("unroll") for (int m = 0; m < 4; ++m) _Pragma("unroll") for (int k = 0; k < 2; ++k) \
;     dst[m][k] = *reinterpret_cast<const bf16x8*>(SA8(b, h) + fa_off + m * 2048 + k * 1024)
; #define LDB8(dst, b, h) _Pragma("unroll") for (int n = 0; n < 2; ++n) _Pragma("unroll") for (int k = 0; k < 2; ++k) \
;     dst[n][k] = *reinterpret_cast<const bf16x8*>(SB8(b, h) + fb_off + n * 2048 + k * 1024)
; #define WAIT_V8(n) asm volatile("s_waitcnt vmcnt(" #n ")" ::: "memory")
; #define WAIT_L8(n) asm volatile("s_waitcnt lgkmcnt(" #n ")" ::: "memory")
; #define BAR8 __builtin_amdgcn_s_barrier()
; __device__ __forceinline__ void gemm_mainloop8(const bf16_t* __restrict__ Xg, int ldx, const bf16_t* __restrict__ Wg, int ldw, ...
;     ...
;     BAR8; WAIT_L8(0); MMA8(0, 0, At, B0); BAR8;
;     LDB8(B1, 0, 1); BAR8; WAIT_L8(0); MMA8(0, 1, At, B1); BAR8;
;     LDA8(At, 0, 1); WAIT_V8(4); BAR8; WAIT_L8(0); MMA8(1, 0, At, B0); MMA8(1, 1, At, B1); BAR8; }
;   { LDB8(B0, 1, 0); LDA8(At, 1, 0); WAIT_V8(2); BAR8; WAIT_L8(0); MMA8(0, 0, At, B0); BAR8;
	s_nop 0
	s_nop 1
	ds_read_b128 v[82:85], v156
	ds_read_b128 v[98:101], v157
	ds_read_b128 v[102:105], v158
	ds_read_b128 v[156:159], v159
	s_barrier
	s_waitcnt lgkmcnt(0)
	s_setprio 1
	s_waitcnt lgkmcnt(3)
	v_mfma_f32_16x16x32_bf16 v[94:97], v[176:179], v[82:85], v[94:97]
	v_mfma_f32_16x16x32_bf16 v[70:73], v[204:207], v[82:85], v[70:73]
	s_waitcnt lgkmcnt(1)
	v_mfma_f32_16x16x32_bf16 v[66:69], v[204:207], v[102:105], v[66:69]
	v_mfma_f32_16x16x32_bf16 v[110:113], v[168:171], v[82:85], v[110:113]
	v_mfma_f32_16x16x32_bf16 v[106:109], v[168:171], v[102:105], v[106:109]
	v_mfma_f32_16x16x32_bf16 v[94:97], v[186:189], v[98:101], v[94:97]
	v_mfma_f32_16x16x32_bf16 v[90:93], v[176:179], v[102:105], v[90:93]
	v_mfma_f32_16x16x32_bf16 v[78:81], v[190:193], v[82:85], v[78:81]
	v_mfma_f32_16x16x32_bf16 v[74:77], v[190:193], v[102:105], v[74:77]
	v_mfma_f32_16x16x32_bf16 v[70:73], v[208:211], v[98:101], v[70:73]
	s_waitcnt lgkmcnt(0)
	v_mfma_f32_16x16x32_bf16 v[66:69], v[208:211], v[156:159], v[66:69]
	v_mfma_f32_16x16x32_bf16 v[216:219], v[172:175], v[98:101], v[110:113]
	v_mfma_f32_16x16x32_bf16 v[168:171], v[172:175], v[156:159], v[106:109]
	v_mfma_f32_16x16x32_bf16 v[172:175], v[186:189], v[156:159], v[90:93]
	v_mfma_f32_16x16x32_bf16 v[176:179], v[194:197], v[98:101], v[78:81]
	v_mfma_f32_16x16x32_bf16 v[186:189], v[194:197], v[156:159], v[74:77]
	s_setprio 0
	s_barrier
	s_nop 0
	ds_read_b128 v[74:77], v134 offset:16384
	ds_read_b128 v[78:81], v134 offset:17408
	ds_read_b128 v[90:93], v134 offset:18432
	ds_read_b128 v[106:109], v134 offset:19456
	ds_read_b128 v[110:113], v134 offset:20480
	ds_read_b128 v[190:193], v134 offset:21504
	ds_read_b128 v[194:197], v134 offset:22528
	ds_read_b128 v[204:207], v134 offset:23552
	s_waitcnt vmcnt(4)
	s_barrier
	s_waitcnt lgkmcnt(0)
	s_setprio 1
	s_waitcnt lgkmcnt(7)
	v_mfma_f32_16x16x32_bf16 v[62:65], v[74:77], v[136:139], v[62:65]
	v_mfma_f32_16x16x32_bf16 v[58:61], v[74:77], v[144:147], v[58:61]
	s_waitcnt lgkmcnt(5)
	v_mfma_f32_16x16x32_bf16 v[54:57], v[90:93], v[136:139], v[54:57]
	s_waitcnt lgkmcnt(3)
	v_mfma_f32_16x16x32_bf16 v[30:33], v[110:113], v[144:147], v[30:33]
	s_waitcnt lgkmcnt(1)
	v_mfma_f32_16x16x32_bf16 v[22:25], v[194:197], v[136:139], v[22:25]
	v_mfma_f32_16x16x32_bf16 v[14:17], v[194:197], v[144:147], v[14:17]
	v_mfma_f32_16x16x32_bf16 v[62:65], v[78:81], v[140:143], v[62:65]
	v_mfma_f32_16x16x32_bf16 v[58:61], v[78:81], v[148:151], v[58:61]
	v_mfma_f32_16x16x32_bf16 v[54:57], v[106:109], v[140:143], v[54:57]
	v_mfma_f32_16x16x32_bf16 v[46:49], v[90:93], v[144:147], v[46:49]
	v_mfma_f32_16x16x32_bf16 v[38:41], v[110:113], v[136:139], v[38:41]
	v_mfma_f32_16x16x32_bf16 v[30:33], v[190:193], v[148:151], v[30:33]
	s_waitcnt lgkmcnt(0)
	v_mfma_f32_16x16x32_bf16 v[22:25], v[204:207], v[140:143], v[22:25]
	v_mfma_f32_16x16x32_bf16 v[14:17], v[204:207], v[148:151], v[14:17]
	v_mfma_f32_16x16x32_bf16 v[208:211], v[106:109], v[148:151], v[46:49]
	v_mfma_f32_16x16x32_bf16 v[220:223], v[190:193], v[140:143], v[38:41]
	s_setprio 0
	s_setprio 1
	v_mfma_f32_16x16x32_bf16 v[38:41], v[74:77], v[82:85], v[50:53]
	v_mfma_f32_16x16x32_bf16 v[26:29], v[90:93], v[102:105], v[26:29]
	v_mfma_f32_16x16x32_bf16 v[50:53], v[78:81], v[98:101], v[38:41]
	v_mfma_f32_16x16x32_bf16 v[38:41], v[74:77], v[102:105], v[42:45]
	v_mfma_f32_16x16x32_bf16 v[34:37], v[90:93], v[82:85], v[34:37]
	v_mfma_f32_16x16x32_bf16 v[26:29], v[106:109], v[156:159], v[26:29]
	v_mfma_f32_16x16x32_bf16 v[18:21], v[110:113], v[82:85], v[18:21]
	v_mfma_f32_16x16x32_bf16 v[10:13], v[110:113], v[102:105], v[10:13]
	v_mfma_f32_16x16x32_bf16 v[6:9], v[194:197], v[82:85], v[6:9]
	v_mfma_f32_16x16x32_bf16 v[2:5], v[194:197], v[102:105], v[2:5]
	v_mfma_f32_16x16x32_bf16 v[136:139], v[78:81], v[156:159], v[38:41]
	v_mfma_f32_16x16x32_bf16 v[140:143], v[106:109], v[98:101], v[34:37]
	v_mfma_f32_16x16x32_bf16 v[144:147], v[190:193], v[98:101], v[18:21]
	v_mfma_f32_16x16x32_bf16 v[148:151], v[190:193], v[156:159], v[10:13]
	v_mfma_f32_16x16x32_bf16 v[190:193], v[204:207], v[98:101], v[6:9]
	v_mfma_f32_16x16x32_bf16 v[156:159], v[204:207], v[156:159], v[2:5]
	s_setprio 0
	s_barrier
	ds_read_b128 v[194:197], v160
	ds_read_b128 v[204:207], v161
	ds_read_b128 v[224:227], v162
	ds_read_b128 v[160:163], v163
	ds_read_b128 v[2:5], v134 offset:32768
	ds_read_b128 v[6:9], v134 offset:33792
	ds_read_b128 v[10:13], v134 offset:34816
	ds_read_b128 v[42:45], v134 offset:35840
	ds_read_b128 v[46:49], v134 offset:36864
	ds_read_b128 v[228:231], v134 offset:37888
	ds_read_b128 v[232:235], v134 offset:38912
	ds_read_b128 v[236:239], v134 offset:39936
	s_waitcnt vmcnt(2)
	s_barrier
; #define LDA8(dst, b, h) _Pragma("unroll") for (int m = 0; m < 4; ++m) _Pragma("unroll") for (int k = 0; k < 2; ++k) \
;     dst[m][k] = *reinterpret_cast<const bf16x8*>(SA8(b, h) + fa_off + m * 2048 + k * 1024)
; #define LDB8(dst, b, h) _Pragma("unroll") for (int n = 0; n < 2; ++n) _Pragma("unroll") for (int k = 0; k < 2; ++k) \
;     dst[n][k] = *reinterpret_cast<const bf16x8*>(SB8(b, h) + fb_off + n * 2048 + k * 1024)
; #define WAIT_V8(n) asm volatile("s_waitcnt vmcnt(" #n ")" ::: "memory")
; #define WAIT_L8(n) asm volatile("s_waitcnt lgkmcnt(" #n ")" ::: "memory")
; #define BAR8 __builtin_amdgcn_s_barrier()
; __device__ __forceinline__ void gemm_mainloop8(const bf16_t* __restrict__ Xg, int ldx, const bf16_t* __restrict__ Wg, int ldw, ...
;     ...
;   { LDB8(B0, 1, 0); LDA8(At, 1, 0); WAIT_V8(2); BAR8; WAIT_L8(0); MMA8(0, 0, At, B0); BAR8;
;     LDB8(B1, 1, 1); WAIT_V8(0); BAR8; WAIT_L8(0); MMA8(0, 1, At, B1); BAR8;
;     LDA8(At, 1, 1); BAR8; WAIT_L8(0); MMA8(1, 0, At, B0); MMA8(1, 1, At, B1); BAR8; }
;   if (wr == 0) BAR8;
	s_waitcnt lgkmcnt(0)
	s_setprio 1
	s_waitcnt lgkmcnt(7)
	v_mfma_f32_16x16x32_bf16 v[18:21], v[2:5], v[194:197], v[126:129]
	s_waitcnt lgkmcnt(6)
	v_mfma_f32_16x16x32_bf16 v[98:101], v[6:9], v[204:207], v[18:21]
	v_mfma_f32_16x16x32_bf16 v[18:21], v[2:5], v[224:227], v[122:125]
	v_mfma_f32_16x16x32_bf16 v[90:93], v[6:9], v[160:163], v[18:21]
	s_waitcnt lgkmcnt(5)
	v_mfma_f32_16x16x32_bf16 v[18:21], v[10:13], v[194:197], v[118:121]
	s_waitcnt lgkmcnt(4)
	v_mfma_f32_16x16x32_bf16 v[102:105], v[42:45], v[204:207], v[18:21]
	v_mfma_f32_16x16x32_bf16 v[18:21], v[10:13], v[224:227], v[114:117]
	v_mfma_f32_16x16x32_bf16 v[82:85], v[42:45], v[160:163], v[18:21]
	s_waitcnt lgkmcnt(3)
	v_mfma_f32_16x16x32_bf16 v[18:21], v[46:49], v[194:197], v[130:133]
	s_waitcnt lgkmcnt(2)
	v_mfma_f32_16x16x32_bf16 v[106:109], v[228:231], v[204:207], v[18:21]
	v_mfma_f32_16x16x32_bf16 v[18:21], v[46:49], v[224:227], v[152:155]
	v_mfma_f32_16x16x32_bf16 v[78:81], v[228:231], v[160:163], v[18:21]
	s_waitcnt lgkmcnt(1)
	v_mfma_f32_16x16x32_bf16 v[18:21], v[232:235], v[194:197], v[86:89]
	s_waitcnt lgkmcnt(0)
	v_mfma_f32_16x16x32_bf16 v[110:113], v[236:239], v[204:207], v[18:21]
	v_mfma_f32_16x16x32_bf16 v[18:21], v[232:235], v[224:227], v[212:215]
	v_mfma_f32_16x16x32_bf16 v[74:77], v[236:239], v[160:163], v[18:21]
	s_setprio 0
	s_barrier
	ds_read_b128 v[130:133], v164
	ds_read_b128 v[152:155], v165
	ds_read_b128 v[212:215], v166
	ds_read_b128 v[164:167], v167
	s_waitcnt vmcnt(0)
	s_barrier
	s_waitcnt lgkmcnt(0)
	s_setprio 1
	s_waitcnt lgkmcnt(3)
	v_mfma_f32_16x16x32_bf16 v[18:21], v[2:5], v[130:133], v[216:219]
	s_waitcnt lgkmcnt(1)
	v_mfma_f32_16x16x32_bf16 v[2:5], v[2:5], v[212:215], v[168:171]
	v_mfma_f32_16x16x32_bf16 v[34:37], v[6:9], v[152:155], v[18:21]
	s_waitcnt lgkmcnt(0)
	v_mfma_f32_16x16x32_bf16 v[18:21], v[6:9], v[164:167], v[2:5]
	v_mfma_f32_16x16x32_bf16 v[2:5], v[10:13], v[130:133], v[94:97]
	v_mfma_f32_16x16x32_bf16 v[38:41], v[42:45], v[152:155], v[2:5]
	v_mfma_f32_16x16x32_bf16 v[2:5], v[10:13], v[212:215], v[172:175]
	v_mfma_f32_16x16x32_bf16 v[10:13], v[42:45], v[164:167], v[2:5]
	v_mfma_f32_16x16x32_bf16 v[2:5], v[46:49], v[130:133], v[176:179]
	v_mfma_f32_16x16x32_bf16 v[42:45], v[228:231], v[152:155], v[2:5]
	v_mfma_f32_16x16x32_bf16 v[2:5], v[46:49], v[212:215], v[186:189]
	v_mfma_f32_16x16x32_bf16 v[6:9], v[228:231], v[164:167], v[2:5]
	v_mfma_f32_16x16x32_bf16 v[2:5], v[232:235], v[130:133], v[70:73]
	v_mfma_f32_16x16x32_bf16 v[46:49], v[236:239], v[152:155], v[2:5]
	v_mfma_f32_16x16x32_bf16 v[2:5], v[232:235], v[212:215], v[66:69]
	v_mfma_f32_16x16x32_bf16 v[2:5], v[236:239], v[164:167], v[2:5]
	s_setprio 0
	s_barrier
	ds_read_b128 v[168:171], v134 offset:49152
	ds_read_b128 v[172:175], v134 offset:50176
	ds_read_b128 v[176:179], v134 offset:51200
	ds_read_b128 v[186:189], v134 offset:52224
	ds_read_b128 v[216:219], v134 offset:53248
	ds_read_b128 v[228:231], v134 offset:54272
	ds_read_b128 v[232:235], v134 offset:55296
	ds_read_b128 v[236:239], v134 offset:56320
	s_barrier
	s_waitcnt lgkmcnt(0)
	s_setprio 1
	s_waitcnt lgkmcnt(5)
	v_mfma_f32_16x16x32_bf16 v[54:57], v[176:179], v[194:197], v[54:57]
	s_waitcnt lgkmcnt(4)
	v_mfma_f32_16x16x32_bf16 v[118:121], v[186:189], v[204:207], v[54:57]
	v_mfma_f32_16x16x32_bf16 v[54:57], v[176:179], v[224:227], v[208:211]
	v_mfma_f32_16x16x32_bf16 v[62:65], v[168:171], v[194:197], v[62:65]
	v_mfma_f32_16x16x32_bf16 v[58:61], v[168:171], v[224:227], v[58:61]
	v_mfma_f32_16x16x32_bf16 v[86:89], v[186:189], v[160:163], v[54:57]
	s_waitcnt lgkmcnt(3)
	v_mfma_f32_16x16x32_bf16 v[54:57], v[216:219], v[194:197], v[220:223]
	v_mfma_f32_16x16x32_bf16 v[30:33], v[216:219], v[224:227], v[30:33]
	s_waitcnt lgkmcnt(1)
	v_mfma_f32_16x16x32_bf16 v[22:25], v[232:235], v[194:197], v[22:25]
	v_mfma_f32_16x16x32_bf16 v[14:17], v[232:235], v[224:227], v[14:17]
	v_mfma_f32_16x16x32_bf16 v[114:117], v[172:175], v[204:207], v[62:65]
	v_mfma_f32_16x16x32_bf16 v[94:97], v[172:175], v[160:163], v[58:61]
	v_mfma_f32_16x16x32_bf16 v[122:125], v[228:231], v[204:207], v[54:57]
	v_mfma_f32_16x16x32_bf16 v[70:73], v[228:231], v[160:163], v[30:33]
	s_waitcnt lgkmcnt(0)
	v_mfma_f32_16x16x32_bf16 v[126:129], v[236:239], v[204:207], v[22:25]
	v_mfma_f32_16x16x32_bf16 v[66:69], v[236:239], v[160:163], v[14:17]
	s_setprio 0
	s_setprio 1
	v_mfma_f32_16x16x32_bf16 v[14:17], v[168:171], v[130:133], v[50:53]
	v_mfma_f32_16x16x32_bf16 v[50:53], v[172:175], v[152:155], v[14:17]
	v_mfma_f32_16x16x32_bf16 v[14:17], v[168:171], v[212:215], v[136:139]
	v_mfma_f32_16x16x32_bf16 v[30:33], v[172:175], v[164:167], v[14:17]
	v_mfma_f32_16x16x32_bf16 v[14:17], v[176:179], v[130:133], v[140:143]
	v_mfma_f32_16x16x32_bf16 v[54:57], v[186:189], v[152:155], v[14:17]
	v_mfma_f32_16x16x32_bf16 v[14:17], v[176:179], v[212:215], v[26:29]
	v_mfma_f32_16x16x32_bf16 v[26:29], v[186:189], v[164:167], v[14:17]
	v_mfma_f32_16x16x32_bf16 v[14:17], v[216:219], v[130:133], v[144:147]
	v_mfma_f32_16x16x32_bf16 v[58:61], v[228:231], v[152:155], v[14:17]
	v_mfma_f32_16x16x32_bf16 v[14:17], v[216:219], v[212:215], v[148:151]
	v_mfma_f32_16x16x32_bf16 v[22:25], v[228:231], v[164:167], v[14:17]
	v_mfma_f32_16x16x32_bf16 v[14:17], v[232:235], v[130:133], v[190:193]
	v_mfma_f32_16x16x32_bf16 v[62:65], v[236:239], v[152:155], v[14:17]
	v_mfma_f32_16x16x32_bf16 v[14:17], v[232:235], v[212:215], v[156:159]
	v_mfma_f32_16x16x32_bf16 v[14:17], v[236:239], v[164:167], v[14:17]
	s_setprio 0
	s_movk_i32 s2, 0x100
	v_cmp_gt_u32_e32 vcc, s2, v0
	s_barrier
	s_and_saveexec_b64 s[2:3], vcc
	s_movk_i32 s48, 0x4020
	s_cbranch_execz .LBB0_217
	s_barrier

; #define STAGE8(P, BASE, LD, OFF, br, kt) do { const bf16_t* g_ = (BASE) + (long)(br) * (LD) + (long)(kt) * 64 + (OFF); \
;     __builtin_amdgcn_global_load_lds((const unsigned*)(g_), (unsigned*)((char*)(P) + tid8 * 16), 16, 0, 0);            \
;     __builtin_amdgcn_global_load_lds((const unsigned*)(g_ + 64 * (long)(LD)), (unsigned*)((char*)(P) + tid8 * 16 + 8192), 16, 0, 0); } while (0)
; #define LDA8(dst, b, h) _Pragma("unroll") for (int m = 0; m < 4; ++m) _Pragma("unroll") for (int k = 0; k < 2; ++k) \
;     dst[m][k] = *reinterpret_cast<const bf16x8*>(SA8(b, h) + fa_off + m * 2048 + k * 1024)
; #define LDB8(dst, b, h) _Pragma("unroll") for (int n = 0; n < 2; ++n) _Pragma("unroll") for (int k = 0; k < 2; ++k) \
;     dst[n][k] = *reinterpret_cast<const bf16x8*>(SB8(b, h) + fb_off + n * 2048 + k * 1024)
; #define WAIT_V8(n) asm volatile("s_waitcnt vmcnt(" #n ")" ::: "memory")
; #define WAIT_L8(n) asm volatile("s_waitcnt lgkmcnt(" #n ")" ::: "memory")
; #define BAR8 __builtin_amdgcn_s_barrier()
; #define SCHED8 __builtin_amdgcn_sched_barrier(0)
; __device__ __forceinline__ void gemm_mainloop8(const bf16_t* __restrict__ Xg, int ldx, const bf16_t* __restrict__ Wg, int ldw, ...
;     ...
;     LDB8(B0, 0, 0); SCHED8; LDA8(At, 0, 0); STAGE8(SA8(1, 1), A, ldw, offA, 128, t + 1);
;     WAIT_L8(8); BAR8; WAIT_L8(0); MMA8(0, 0, At, B0); BAR8; SCHED8;
;     LDB8(B1, 0, 1); STAGE8(SB8(0, 0), Bt, ldx, offB, 0, t + 2);
;     BAR8; WAIT_L8(0); MMA8(0, 1, At, B1); BAR8;
;     LDA8(At, 0, 1); STAGE8(SA8(0, 0), A, ldw, offA, 0, t + 2);
;     BAR8; WAIT_L8(0); MMA8(1, 0, At, B0); BAR8; SCHED8;
;     STAGE8(SB8(0, 1), Bt, ldx, offB, 128, t + 2);
;     WAIT_V8(6); BAR8; MMA8(1, 1, At, B1); BAR8;
;     LDB8(B0, 1, 0); SCHED8; LDA8(At, 1, 0); STAGE8(SA8(0, 1), A, ldw, offA, 128, t + 2);
.LBB0_255:
	v_or_b32_e32 v152, 0x10000, v135
	v_add_u32_e32 v153, 0x10400, v135
	v_add_u32_e32 v154, 0x10800, v135
	v_add_u32_e32 v155, 0x10c00, v135
	v_or_b32_e32 v158, 0x14000, v135
	v_add_u32_e32 v159, 0x14400, v135
	v_add_u32_e32 v160, 0x14800, v135
	v_add_u32_e32 v161, 0x14c00, v135
	v_add_u32_e32 v156, 0xc000, v0
	v_add_u32_e32 v157, 0xe000, v0
	v_lshl_add_u64 v[178:179], s[26:27], 0, v[132:133]
	v_lshl_add_u64 v[180:181], s[24:25], 0, v[132:133]
	ds_read_b128 v[162:165], v152
	ds_read_b128 v[166:169], v153
	ds_read_b128 v[170:173], v154
	ds_read_b128 v[174:177], v155
	ds_read_b128 v[190:193], v134
	ds_read_b128 v[194:197], v134 offset:1024
	ds_read_b128 v[204:207], v134 offset:2048
	ds_read_b128 v[208:211], v134 offset:3072
	ds_read_b128 v[212:215], v134 offset:4096
	ds_read_b128 v[216:219], v134 offset:5120
	ds_read_b128 v[220:223], v134 offset:6144
	ds_read_b128 v[224:227], v134 offset:7168
	ds_read_b128 v[228:231], v158
	ds_read_b128 v[232:235], v159
	ds_read_b128 v[236:239], v160
	ds_read_b128 v[240:243], v161
	v_lshl_add_u64 v[186:187], v[178:179], 0, s[44:45]
	v_readfirstlane_b32 s21, v156
	s_nop 0
	s_mov_b32 m0, s21
	s_nop 0
	global_load_lds_dwordx4 v[186:187], off
	v_lshl_add_u64 v[186:187], v[178:179], 0, s[82:83]
	v_readfirstlane_b32 s21, v157
	s_nop 0
	s_mov_b32 m0, s21
	s_nop 0
	global_load_lds_dwordx4 v[186:187], off
	s_waitcnt lgkmcnt(0)
	s_barrier
	s_setprio 1
	v_mfma_f32_16x16x32_bf16 v[126:129], v[190:193], v[162:165], v[126:129]
	v_mfma_f32_16x16x32_bf16 v[122:125], v[190:193], v[170:173], v[122:125]
	v_mfma_f32_16x16x32_bf16 v[118:121], v[204:207], v[162:165], v[118:121]
	v_mfma_f32_16x16x32_bf16 v[114:117], v[204:207], v[170:173], v[114:117]
	v_mfma_f32_16x16x32_bf16 v[102:105], v[212:215], v[162:165], v[102:105]
	v_mfma_f32_16x16x32_bf16 v[98:101], v[212:215], v[170:173], v[98:101]
	v_mfma_f32_16x16x32_bf16 v[86:89], v[220:223], v[162:165], v[86:89]
	v_mfma_f32_16x16x32_bf16 v[82:85], v[220:223], v[170:173], v[82:85]
	v_mfma_f32_16x16x32_bf16 v[126:129], v[194:197], v[166:169], v[126:129]
	v_mfma_f32_16x16x32_bf16 v[122:125], v[194:197], v[174:177], v[122:125]
	v_mfma_f32_16x16x32_bf16 v[118:121], v[208:211], v[166:169], v[118:121]
	v_mfma_f32_16x16x32_bf16 v[114:117], v[208:211], v[174:177], v[114:117]
	v_mfma_f32_16x16x32_bf16 v[102:105], v[216:219], v[166:169], v[102:105]
	v_mfma_f32_16x16x32_bf16 v[98:101], v[216:219], v[174:177], v[98:101]
	v_mfma_f32_16x16x32_bf16 v[86:89], v[224:227], v[166:169], v[86:89]
	v_mfma_f32_16x16x32_bf16 v[82:85], v[224:227], v[174:177], v[82:85]
	v_mfma_f32_16x16x32_bf16 v[110:113], v[190:193], v[228:231], v[110:113]
	v_mfma_f32_16x16x32_bf16 v[106:109], v[190:193], v[236:239], v[106:109]
	v_mfma_f32_16x16x32_bf16 v[94:97], v[204:207], v[228:231], v[94:97]
	v_mfma_f32_16x16x32_bf16 v[90:93], v[204:207], v[236:239], v[90:93]
	v_mfma_f32_16x16x32_bf16 v[78:81], v[212:215], v[228:231], v[78:81]
	v_mfma_f32_16x16x32_bf16 v[74:77], v[212:215], v[236:239], v[74:77]
	v_mfma_f32_16x16x32_bf16 v[70:73], v[220:223], v[228:231], v[70:73]
	v_mfma_f32_16x16x32_bf16 v[66:69], v[220:223], v[236:239], v[66:69]
	v_mfma_f32_16x16x32_bf16 v[110:113], v[194:197], v[232:235], v[110:113]
	v_mfma_f32_16x16x32_bf16 v[106:109], v[194:197], v[240:243], v[106:109]
	v_mfma_f32_16x16x32_bf16 v[94:97], v[208:211], v[232:235], v[94:97]
	v_mfma_f32_16x16x32_bf16 v[90:93], v[208:211], v[240:243], v[90:93]
	v_mfma_f32_16x16x32_bf16 v[78:81], v[216:219], v[232:235], v[78:81]
	v_mfma_f32_16x16x32_bf16 v[74:77], v[216:219], v[240:243], v[74:77]
	v_mfma_f32_16x16x32_bf16 v[70:73], v[224:227], v[232:235], v[70:73]
	v_mfma_f32_16x16x32_bf16 v[66:69], v[224:227], v[240:243], v[66:69]
	s_setprio 0
	s_barrier
	ds_read_b128 v[190:193], v134 offset:16384
	ds_read_b128 v[194:197], v134 offset:17408
	ds_read_b128 v[204:207], v134 offset:18432
	ds_read_b128 v[208:211], v134 offset:19456
	ds_read_b128 v[212:215], v134 offset:20480
	ds_read_b128 v[216:219], v134 offset:21504
	ds_read_b128 v[220:223], v134 offset:22528
	ds_read_b128 v[224:227], v134 offset:23552
	v_lshl_add_u64 v[186:187], v[180:181], 0, s[70:71]
	v_readfirstlane_b32 s21, v146
	s_nop 0
	s_mov_b32 m0, s21
	s_nop 0
	global_load_lds_dwordx4 v[186:187], off
	v_lshl_add_u64 v[186:187], v[180:181], 0, s[90:91]
	v_readfirstlane_b32 s21, v145
	s_nop 0
	s_mov_b32 m0, s21
	s_nop 0
	global_load_lds_dwordx4 v[186:187], off
	v_lshl_add_u64 v[186:187], v[178:179], 0, s[70:71]
	v_readfirstlane_b32 s21, v0
	s_nop 0
	s_mov_b32 m0, s21
	s_nop 0
	global_load_lds_dwordx4 v[186:187], off
	v_lshl_add_u64 v[186:187], v[178:179], 0, s[90:91]
	v_readfirstlane_b32 s21, v144
	s_nop 0
	s_mov_b32 m0, s21
	s_nop 0
	global_load_lds_dwordx4 v[186:187], off
	v_lshl_add_u64 v[186:187], v[180:181], 0, s[80:81]
	v_readfirstlane_b32 s21, v143
	s_nop 0
	s_mov_b32 m0, s21
	s_nop 0
	global_load_lds_dwordx4 v[186:187], off
	v_lshl_add_u64 v[186:187], v[180:181], 0, s[68:69]
	v_readfirstlane_b32 s21, v142
	s_nop 0
	s_mov_b32 m0, s21
	s_nop 0
	global_load_lds_dwordx4 v[186:187], off
	s_waitcnt vmcnt(6)
	s_waitcnt lgkmcnt(0)
	s_barrier
; #define STAGE8(P, BASE, LD, OFF, br, kt) do { const bf16_t* g_ = (BASE) + (long)(br) * (LD) + (long)(kt) * 64 + (OFF); \
;     __builtin_amdgcn_global_load_lds((const unsigned*)(g_), (unsigned*)((char*)(P) + tid8 * 16), 16, 0, 0);            \
;     __builtin_amdgcn_global_load_lds((const unsigned*)(g_ + 64 * (long)(LD)), (unsigned*)((char*)(P) + tid8 * 16 + 8192), 16, 0, 0); } while (0)
; #define LDA8(dst, b, h) _Pragma("unroll") for (int m = 0; m < 4; ++m) _Pragma("unroll") for (int k = 0; k < 2; ++k) \
;     dst[m][k] = *reinterpret_cast<const bf16x8*>(SA8(b, h) + fa_off + m * 2048 + k * 1024)
; #define LDB8(dst, b, h) _Pragma("unroll") for (int n = 0; n < 2; ++n) _Pragma("unroll") for (int k = 0; k < 2; ++k) \
;     dst[n][k] = *reinterpret_cast<const bf16x8*>(SB8(b, h) + fb_off + n * 2048 + k * 1024)
; #define WAIT_V8(n) asm volatile("s_waitcnt vmcnt(" #n ")" ::: "memory")
; #define WAIT_L8(n) asm volatile("s_waitcnt lgkmcnt(" #n ")" ::: "memory")
; #define BAR8 __builtin_amdgcn_s_barrier()
; #define SCHED8 __builtin_amdgcn_sched_barrier(0)
; __device__ __forceinline__ void gemm_mainloop8(const bf16_t* __restrict__ Xg, int ldx, const bf16_t* __restrict__ Wg, int ldw, ...
;     ...
;     WAIT_V8(6); BAR8; MMA8(1, 1, At, B1); BAR8;
;     LDB8(B0, 1, 0); SCHED8; LDA8(At, 1, 0); STAGE8(SA8(0, 1), A, ldw, offA, 128, t + 2);
;     WAIT_L8(8); BAR8; WAIT_L8(0); MMA8(0, 0, At, B0); BAR8; SCHED8;
;     LDB8(B1, 1, 1); STAGE8(SB8(1, 0), Bt, ldx, offB, 0, t + 3);
;     BAR8; WAIT_L8(0); MMA8(0, 1, At, B1); BAR8;
;     LDA8(At, 1, 1); STAGE8(SA8(1, 0), A, ldw, offA, 0, t + 3);
;     BAR8; WAIT_L8(0); MMA8(1, 0, At, B0); BAR8; SCHED8;
	s_setprio 1
	v_mfma_f32_16x16x32_bf16 v[62:65], v[190:193], v[162:165], v[62:65]
	v_mfma_f32_16x16x32_bf16 v[58:61], v[190:193], v[170:173], v[58:61]
	v_mfma_f32_16x16x32_bf16 v[54:57], v[204:207], v[162:165], v[54:57]
	v_mfma_f32_16x16x32_bf16 v[46:49], v[204:207], v[170:173], v[46:49]
	v_mfma_f32_16x16x32_bf16 v[38:41], v[212:215], v[162:165], v[38:41]
	v_mfma_f32_16x16x32_bf16 v[30:33], v[212:215], v[170:173], v[30:33]
	v_mfma_f32_16x16x32_bf16 v[22:25], v[220:223], v[162:165], v[22:25]
	v_mfma_f32_16x16x32_bf16 v[14:17], v[220:223], v[170:173], v[14:17]
	v_mfma_f32_16x16x32_bf16 v[62:65], v[194:197], v[166:169], v[62:65]
	v_mfma_f32_16x16x32_bf16 v[58:61], v[194:197], v[174:177], v[58:61]
	v_mfma_f32_16x16x32_bf16 v[54:57], v[208:211], v[166:169], v[54:57]
	v_mfma_f32_16x16x32_bf16 v[46:49], v[208:211], v[174:177], v[46:49]
	v_mfma_f32_16x16x32_bf16 v[38:41], v[216:219], v[166:169], v[38:41]
	v_mfma_f32_16x16x32_bf16 v[30:33], v[216:219], v[174:177], v[30:33]
	v_mfma_f32_16x16x32_bf16 v[22:25], v[224:227], v[166:169], v[22:25]
	v_mfma_f32_16x16x32_bf16 v[14:17], v[224:227], v[174:177], v[14:17]
	v_mfma_f32_16x16x32_bf16 v[50:53], v[190:193], v[228:231], v[50:53]
	v_mfma_f32_16x16x32_bf16 v[42:45], v[190:193], v[236:239], v[42:45]
	v_mfma_f32_16x16x32_bf16 v[34:37], v[204:207], v[228:231], v[34:37]
	v_mfma_f32_16x16x32_bf16 v[26:29], v[204:207], v[236:239], v[26:29]
	v_mfma_f32_16x16x32_bf16 v[18:21], v[212:215], v[228:231], v[18:21]
	v_mfma_f32_16x16x32_bf16 v[10:13], v[212:215], v[236:239], v[10:13]
	v_mfma_f32_16x16x32_bf16 v[6:9], v[220:223], v[228:231], v[6:9]
	v_mfma_f32_16x16x32_bf16 v[2:5], v[220:223], v[236:239], v[2:5]
	v_mfma_f32_16x16x32_bf16 v[50:53], v[194:197], v[232:235], v[50:53]
	v_mfma_f32_16x16x32_bf16 v[42:45], v[194:197], v[240:243], v[42:45]
	v_mfma_f32_16x16x32_bf16 v[34:37], v[208:211], v[232:235], v[34:37]
	v_mfma_f32_16x16x32_bf16 v[26:29], v[208:211], v[240:243], v[26:29]
	v_mfma_f32_16x16x32_bf16 v[18:21], v[216:219], v[232:235], v[18:21]
	v_mfma_f32_16x16x32_bf16 v[10:13], v[216:219], v[240:243], v[10:13]
	v_mfma_f32_16x16x32_bf16 v[6:9], v[224:227], v[232:235], v[6:9]
	v_mfma_f32_16x16x32_bf16 v[2:5], v[224:227], v[240:243], v[2:5]
	s_setprio 0
	s_barrier
	v_or_b32_e32 v162, 0x18000, v135
	v_add_u32_e32 v163, 0x18400, v135
	v_add_u32_e32 v164, 0x18800, v135
	v_add_u32_e32 v165, 0x18c00, v135
	v_or_b32_e32 v166, 0x1c000, v135
	v_add_u32_e32 v167, 0x1c400, v135
	v_add_u32_e32 v168, 0x1c800, v135
	v_add_u32_e32 v169, 0x1cc00, v135
	ds_read_b128 v[170:173], v162
	ds_read_b128 v[174:177], v163
	ds_read_b128 v[190:193], v164
	ds_read_b128 v[194:197], v165
	ds_read_b128 v[204:207], v134 offset:32768
	ds_read_b128 v[208:211], v134 offset:33792
	ds_read_b128 v[212:215], v134 offset:34816
	ds_read_b128 v[216:219], v134 offset:35840
	ds_read_b128 v[220:223], v134 offset:36864
	ds_read_b128 v[224:227], v134 offset:37888
	ds_read_b128 v[228:231], v134 offset:38912
	ds_read_b128 v[232:235], v134 offset:39936
	ds_read_b128 v[236:239], v166
	ds_read_b128 v[240:243], v167
	ds_read_b128 v[244:247], v168
	ds_read_b128 v[248:251], v169
	v_lshl_add_u64 v[186:187], v[178:179], 0, s[80:81]
	v_readfirstlane_b32 s21, v141
	s_nop 0
	s_mov_b32 m0, s21
	s_nop 0
	global_load_lds_dwordx4 v[186:187], off
	v_lshl_add_u64 v[186:187], v[178:179], 0, s[68:69]
	v_readfirstlane_b32 s21, v140
	s_nop 0
	s_mov_b32 m0, s21
	s_nop 0
	global_load_lds_dwordx4 v[186:187], off
	s_waitcnt lgkmcnt(0)
	s_barrier
	s_setprio 1
	v_mfma_f32_16x16x32_bf16 v[126:129], v[204:207], v[170:173], v[126:129]
	v_mfma_f32_16x16x32_bf16 v[122:125], v[204:207], v[190:193], v[122:125]
	v_mfma_f32_16x16x32_bf16 v[118:121], v[212:215], v[170:173], v[118:121]
	v_mfma_f32_16x16x32_bf16 v[114:117], v[212:215], v[190:193], v[114:117]
	v_mfma_f32_16x16x32_bf16 v[102:105], v[220:223], v[170:173], v[102:105]
	v_mfma_f32_16x16x32_bf16 v[98:101], v[220:223], v[190:193], v[98:101]
	v_mfma_f32_16x16x32_bf16 v[86:89], v[228:231], v[170:173], v[86:89]
	v_mfma_f32_16x16x32_bf16 v[82:85], v[228:231], v[190:193], v[82:85]
	v_mfma_f32_16x16x32_bf16 v[126:129], v[208:211], v[174:177], v[126:129]
	v_mfma_f32_16x16x32_bf16 v[122:125], v[208:211], v[194:197], v[122:125]
	v_mfma_f32_16x16x32_bf16 v[118:121], v[216:219], v[174:177], v[118:121]
	v_mfma_f32_16x16x32_bf16 v[114:117], v[216:219], v[194:197], v[114:117]
	v_mfma_f32_16x16x32_bf16 v[102:105], v[224:227], v[174:177], v[102:105]
	v_mfma_f32_16x16x32_bf16 v[98:101], v[224:227], v[194:197], v[98:101]
	v_mfma_f32_16x16x32_bf16 v[86:89], v[232:235], v[174:177], v[86:89]
	v_mfma_f32_16x16x32_bf16 v[82:85], v[232:235], v[194:197], v[82:85]
	v_mfma_f32_16x16x32_bf16 v[110:113], v[204:207], v[236:239], v[110:113]
	v_mfma_f32_16x16x32_bf16 v[106:109], v[204:207], v[244:247], v[106:109]
	v_mfma_f32_16x16x32_bf16 v[94:97], v[212:215], v[236:239], v[94:97]
	v_mfma_f32_16x16x32_bf16 v[90:93], v[212:215], v[244:247], v[90:93]
	v_mfma_f32_16x16x32_bf16 v[78:81], v[220:223], v[236:239], v[78:81]
	v_mfma_f32_16x16x32_bf16 v[74:77], v[220:223], v[244:247], v[74:77]
	v_mfma_f32_16x16x32_bf16 v[70:73], v[228:231], v[236:239], v[70:73]
	v_mfma_f32_16x16x32_bf16 v[66:69], v[228:231], v[244:247], v[66:69]
	v_mfma_f32_16x16x32_bf16 v[110:113], v[208:211], v[240:243], v[110:113]
	v_mfma_f32_16x16x32_bf16 v[106:109], v[208:211], v[248:251], v[106:109]
	v_mfma_f32_16x16x32_bf16 v[94:97], v[216:219], v[240:243], v[94:97]
	v_mfma_f32_16x16x32_bf16 v[90:93], v[216:219], v[248:251], v[90:93]
	v_mfma_f32_16x16x32_bf16 v[78:81], v[224:227], v[240:243], v[78:81]
	v_mfma_f32_16x16x32_bf16 v[74:77], v[224:227], v[248:251], v[74:77]
	v_mfma_f32_16x16x32_bf16 v[70:73], v[232:235], v[240:243], v[70:73]
	v_mfma_f32_16x16x32_bf16 v[66:69], v[232:235], v[248:251], v[66:69]
	s_setprio 0
	s_barrier
; #define STAGE8(P, BASE, LD, OFF, br, kt) do { const bf16_t* g_ = (BASE) + (long)(br) * (LD) + (long)(kt) * 64 + (OFF); \
;     __builtin_amdgcn_global_load_lds((const unsigned*)(g_), (unsigned*)((char*)(P) + tid8 * 16), 16, 0, 0);            \
;     __builtin_amdgcn_global_load_lds((const unsigned*)(g_ + 64 * (long)(LD)), (unsigned*)((char*)(P) + tid8 * 16 + 8192), 16, 0, 0); } while (0)
; #define LDA8(dst, b, h) _Pragma("unroll") for (int m = 0; m < 4; ++m) _Pragma("unroll") for (int k = 0; k < 2; ++k) \
;     dst[m][k] = *reinterpret_cast<const bf16x8*>(SA8(b, h) + fa_off + m * 2048 + k * 1024)
; #define LDB8(dst, b, h) _Pragma("unroll") for (int n = 0; n < 2; ++n) _Pragma("unroll") for (int k = 0; k < 2; ++k) \
;     dst[n][k] = *reinterpret_cast<const bf16x8*>(SB8(b, h) + fb_off + n * 2048 + k * 1024)
; #define WAIT_V8(n) asm volatile("s_waitcnt vmcnt(" #n ")" ::: "memory")
; #define WAIT_L8(n) asm volatile("s_waitcnt lgkmcnt(" #n ")" ::: "memory")
; #define BAR8 __builtin_amdgcn_s_barrier()
; #define SCHED8 __builtin_amdgcn_sched_barrier(0)
; __device__ __forceinline__ void gemm_mainloop8(const bf16_t* __restrict__ Xg, int ldx, const bf16_t* __restrict__ Wg, int ldw, ...
;     ...
;     LDA8(At, 1, 1); STAGE8(SA8(1, 0), A, ldw, offA, 0, t + 3);
;     BAR8; WAIT_L8(0); MMA8(1, 0, At, B0); BAR8; SCHED8;
;     STAGE8(SB8(1, 1), Bt, ldx, offB, 128, t + 3);
;     WAIT_V8(6); BAR8; MMA8(1, 1, At, B1); BAR8;
;   }
;   { LDB8(B0, 0, 0); LDA8(At, 0, 0); STAGE8(SA8(1, 1), A, ldw, offA, 128, nt - 1);
;     BAR8; WAIT_L8(0); MMA8(0, 0, At, B0); BAR8;
	ds_read_b128 v[204:207], v134 offset:49152
	ds_read_b128 v[208:211], v134 offset:50176
	ds_read_b128 v[212:215], v134 offset:51200
	ds_read_b128 v[216:219], v134 offset:52224
	ds_read_b128 v[220:223], v134 offset:53248
	ds_read_b128 v[224:227], v134 offset:54272
	ds_read_b128 v[228:231], v134 offset:55296
	ds_read_b128 v[232:235], v134 offset:56320
	v_lshl_add_u64 v[186:187], v[180:181], 0, s[88:89]
	v_readfirstlane_b32 s21, v136
	s_nop 0
	s_mov_b32 m0, s21
	s_nop 0
	global_load_lds_dwordx4 v[186:187], off
	v_lshl_add_u64 v[186:187], v[180:181], 0, s[4:5]
	v_readfirstlane_b32 s21, v137
	s_nop 0
	s_mov_b32 m0, s21
	s_nop 0
	global_load_lds_dwordx4 v[186:187], off
	v_lshl_add_u64 v[186:187], v[178:179], 0, s[88:89]
	v_readfirstlane_b32 s21, v148
	s_nop 0
	s_mov_b32 m0, s21
	s_nop 0
	global_load_lds_dwordx4 v[186:187], off
	v_lshl_add_u64 v[186:187], v[178:179], 0, s[4:5]
	v_readfirstlane_b32 s21, v149
	s_nop 0
	s_mov_b32 m0, s21
	s_nop 0
	global_load_lds_dwordx4 v[186:187], off
	v_lshl_add_u64 v[186:187], v[180:181], 0, s[92:93]
	v_readfirstlane_b32 s21, v150
	s_nop 0
	s_mov_b32 m0, s21
	s_nop 0
	global_load_lds_dwordx4 v[186:187], off
	v_lshl_add_u64 v[186:187], v[180:181], 0, s[94:95]
	v_readfirstlane_b32 s21, v151
	s_nop 0
	s_mov_b32 m0, s21
	s_nop 0
	global_load_lds_dwordx4 v[186:187], off
	s_waitcnt vmcnt(6)
	s_waitcnt lgkmcnt(0)
	s_barrier
	s_setprio 1
	v_mfma_f32_16x16x32_bf16 v[62:65], v[204:207], v[170:173], v[62:65]
	v_mfma_f32_16x16x32_bf16 v[58:61], v[204:207], v[190:193], v[58:61]
	v_mfma_f32_16x16x32_bf16 v[54:57], v[212:215], v[170:173], v[54:57]
	v_mfma_f32_16x16x32_bf16 v[46:49], v[212:215], v[190:193], v[46:49]
	v_mfma_f32_16x16x32_bf16 v[38:41], v[220:223], v[170:173], v[38:41]
	v_mfma_f32_16x16x32_bf16 v[30:33], v[220:223], v[190:193], v[30:33]
	v_mfma_f32_16x16x32_bf16 v[22:25], v[228:231], v[170:173], v[22:25]
	v_mfma_f32_16x16x32_bf16 v[14:17], v[228:231], v[190:193], v[14:17]
	v_mfma_f32_16x16x32_bf16 v[62:65], v[208:211], v[174:177], v[62:65]
	v_mfma_f32_16x16x32_bf16 v[58:61], v[208:211], v[194:197], v[58:61]
	v_mfma_f32_16x16x32_bf16 v[54:57], v[216:219], v[174:177], v[54:57]
	v_mfma_f32_16x16x32_bf16 v[46:49], v[216:219], v[194:197], v[46:49]
	v_mfma_f32_16x16x32_bf16 v[38:41], v[224:227], v[174:177], v[38:41]
	v_mfma_f32_16x16x32_bf16 v[30:33], v[224:227], v[194:197], v[30:33]
	v_mfma_f32_16x16x32_bf16 v[22:25], v[232:235], v[174:177], v[22:25]
	v_mfma_f32_16x16x32_bf16 v[14:17], v[232:235], v[194:197], v[14:17]
	v_mfma_f32_16x16x32_bf16 v[50:53], v[204:207], v[236:239], v[50:53]
	v_mfma_f32_16x16x32_bf16 v[42:45], v[204:207], v[244:247], v[42:45]
	v_mfma_f32_16x16x32_bf16 v[34:37], v[212:215], v[236:239], v[34:37]
	v_mfma_f32_16x16x32_bf16 v[26:29], v[212:215], v[244:247], v[26:29]
	v_mfma_f32_16x16x32_bf16 v[18:21], v[220:223], v[236:239], v[18:21]
	v_mfma_f32_16x16x32_bf16 v[10:13], v[220:223], v[244:247], v[10:13]
	v_mfma_f32_16x16x32_bf16 v[6:9], v[228:231], v[236:239], v[6:9]
	v_mfma_f32_16x16x32_bf16 v[2:5], v[228:231], v[244:247], v[2:5]
	v_mfma_f32_16x16x32_bf16 v[50:53], v[208:211], v[240:243], v[50:53]
	v_mfma_f32_16x16x32_bf16 v[42:45], v[208:211], v[248:251], v[42:45]
	v_mfma_f32_16x16x32_bf16 v[34:37], v[216:219], v[240:243], v[34:37]
	v_mfma_f32_16x16x32_bf16 v[26:29], v[216:219], v[248:251], v[26:29]
	v_mfma_f32_16x16x32_bf16 v[18:21], v[224:227], v[240:243], v[18:21]
	v_mfma_f32_16x16x32_bf16 v[10:13], v[224:227], v[248:251], v[10:13]
	v_mfma_f32_16x16x32_bf16 v[6:9], v[232:235], v[240:243], v[6:9]
	v_mfma_f32_16x16x32_bf16 v[2:5], v[232:235], v[248:251], v[2:5]
	s_setprio 0
	s_add_i32 s15, s15, 2
	s_add_u32 s24, s24, 0x100
	s_addc_u32 s25, s25, 0
	s_add_u32 s26, s26, 0x100
	s_addc_u32 s27, s27, 0
	s_cmp_lt_u32 s15, 28
	s_barrier
	s_cbranch_scc1 .LBB0_255
	v_lshl_add_u64 v[130:131], v[130:131], 1, s[22:23]
	s_mov_b64 s[22:23], 0x80f80
	v_readfirstlane_b32 s15, v156
	v_lshl_add_u64 v[132:133], v[130:131], 0, s[22:23]
	s_mov_b32 m0, s15
	s_mov_b64 s[22:23], 0xc0f80
	v_readfirstlane_b32 s15, v157
	s_nop 0
	ds_read_b128 v[148:151], v152
	ds_read_b128 v[170:173], v153
	ds_read_b128 v[174:177], v154
	ds_read_b128 v[152:155], v155
	ds_read_b128 v[190:193], v134
	ds_read_b128 v[194:197], v134 offset:1024
	ds_read_b128 v[204:207], v134 offset:2048
	ds_read_b128 v[208:211], v134 offset:3072
	ds_read_b128 v[212:215], v134 offset:4096
	ds_read_b128 v[216:219], v134 offset:5120
	ds_read_b128 v[220:223], v134 offset:6144
	ds_read_b128 v[224:227], v134 offset:7168
	global_load_lds_dwordx4 v[132:133], off
	v_lshl_add_u64 v[130:131], v[130:131], 0, s[22:23]
	s_mov_b32 m0, s15
	s_nop 0
	global_load_lds_dwordx4 v[130:131], off
	s_barrier
	s_waitcnt lgkmcnt(0)
	s_setprio 1
	s_waitcnt lgkmcnt(0)
	v_mfma_f32_16x16x32_bf16 v[126:129], v[190:193], v[148:151], v[126:129]
	v_mfma_f32_16x16x32_bf16 v[118:121], v[204:207], v[148:151], v[118:121]
	v_mfma_f32_16x16x32_bf16 v[102:105], v[212:215], v[148:151], v[102:105]
	v_mfma_f32_16x16x32_bf16 v[82:85], v[220:223], v[174:177], v[82:85]
	v_mfma_f32_16x16x32_bf16 v[126:129], v[194:197], v[170:173], v[126:129]
	v_mfma_f32_16x16x32_bf16 v[122:125], v[190:193], v[174:177], v[122:125]
	v_mfma_f32_16x16x32_bf16 v[118:121], v[208:211], v[170:173], v[118:121]
	v_mfma_f32_16x16x32_bf16 v[114:117], v[204:207], v[174:177], v[114:117]
	v_mfma_f32_16x16x32_bf16 v[130:133], v[216:219], v[170:173], v[102:105]
	v_mfma_f32_16x16x32_bf16 v[98:101], v[212:215], v[174:177], v[98:101]
	v_mfma_f32_16x16x32_bf16 v[86:89], v[220:223], v[148:151], v[86:89]
	v_mfma_f32_16x16x32_bf16 v[82:85], v[224:227], v[152:155], v[82:85]
	v_mfma_f32_16x16x32_bf16 v[122:125], v[194:197], v[152:155], v[122:125]
	v_mfma_f32_16x16x32_bf16 v[114:117], v[208:211], v[152:155], v[114:117]
	v_mfma_f32_16x16x32_bf16 v[228:231], v[216:219], v[152:155], v[98:101]
	v_mfma_f32_16x16x32_bf16 v[232:235], v[224:227], v[170:173], v[86:89]
	s_setprio 0
	s_barrier
; #define LDA8(dst, b, h) _Pragma("unroll") for (int m = 0; m < 4; ++m) _Pragma("unroll") for (int k = 0; k < 2; ++k) \
;     dst[m][k] = *reinterpret_cast<const bf16x8*>(SA8(b, h) + fa_off + m * 2048 + k * 1024)
; #define LDB8(dst, b, h) _Pragma("unroll") for (int n = 0; n < 2; ++n) _Pragma("unroll") for (int k = 0; k < 2; ++k) \
;     dst[n][k] = *reinterpret_cast<const bf16x8*>(SB8(b, h) + fb_off + n * 2048 + k * 1024)
; #define WAIT_V8(n) asm volatile("s_waitcnt vmcnt(" #n ")" ::: "memory")
; #define WAIT_L8(n) asm volatile("s_waitcnt lgkmcnt(" #n ")" ::: "memory")
; #define BAR8 __builtin_amdgcn_s_barrier()
; __device__ __forceinline__ void gemm_mainloop8(const bf16_t* __restrict__ Xg, int ldx, const bf16_t* __restrict__ Wg, int ldw, ...
;     ...
;     BAR8; WAIT_L8(0); MMA8(0, 0, At, B0); BAR8;
;     LDB8(B1, 0, 1); BAR8; WAIT_L8(0); MMA8(0, 1, At, B1); BAR8;
;     LDA8(At, 0, 1); WAIT_V8(4); BAR8; WAIT_L8(0); MMA8(1, 0, At, B0); MMA8(1, 1, At, B1); BAR8; }
;   { LDB8(B0, 1, 0); LDA8(At, 1, 0); WAIT_V8(2); BAR8; WAIT_L8(0); MMA8(0, 0, At, B0); BAR8;
	s_nop 0
	ds_read_b128 v[86:89], v158
	ds_read_b128 v[98:101], v159
	ds_read_b128 v[102:105], v160
	ds_read_b128 v[156:159], v161
	s_barrier
	s_waitcnt lgkmcnt(0)
	s_setprio 1
	s_waitcnt lgkmcnt(1)
	v_mfma_f32_16x16x32_bf16 v[90:93], v[204:207], v[102:105], v[90:93]
	v_mfma_f32_16x16x32_bf16 v[74:77], v[212:215], v[102:105], v[74:77]
	v_mfma_f32_16x16x32_bf16 v[66:69], v[220:223], v[102:105], v[66:69]
	v_mfma_f32_16x16x32_bf16 v[110:113], v[190:193], v[86:89], v[110:113]
	v_mfma_f32_16x16x32_bf16 v[106:109], v[190:193], v[102:105], v[106:109]
	v_mfma_f32_16x16x32_bf16 v[94:97], v[204:207], v[86:89], v[94:97]
	s_waitcnt lgkmcnt(0)
	v_mfma_f32_16x16x32_bf16 v[90:93], v[208:211], v[156:159], v[90:93]
	v_mfma_f32_16x16x32_bf16 v[78:81], v[212:215], v[86:89], v[78:81]
	v_mfma_f32_16x16x32_bf16 v[74:77], v[216:219], v[156:159], v[74:77]
	v_mfma_f32_16x16x32_bf16 v[70:73], v[220:223], v[86:89], v[70:73]
	v_mfma_f32_16x16x32_bf16 v[66:69], v[224:227], v[156:159], v[66:69]
	v_mfma_f32_16x16x32_bf16 v[236:239], v[194:197], v[98:101], v[110:113]
	v_mfma_f32_16x16x32_bf16 v[190:193], v[194:197], v[156:159], v[106:109]
	v_mfma_f32_16x16x32_bf16 v[194:197], v[208:211], v[98:101], v[94:97]
	v_mfma_f32_16x16x32_bf16 v[204:207], v[216:219], v[98:101], v[78:81]
	v_mfma_f32_16x16x32_bf16 v[208:211], v[224:227], v[98:101], v[70:73]
	s_setprio 0
	s_barrier
	s_nop 0
	ds_read_b128 v[70:73], v134 offset:16384
	ds_read_b128 v[78:81], v134 offset:17408
	ds_read_b128 v[94:97], v134 offset:18432
	ds_read_b128 v[106:109], v134 offset:19456
	ds_read_b128 v[110:113], v134 offset:20480
	ds_read_b128 v[212:215], v134 offset:21504
	ds_read_b128 v[216:219], v134 offset:22528
	ds_read_b128 v[220:223], v134 offset:23552
	s_waitcnt vmcnt(4)
	s_barrier
	s_waitcnt lgkmcnt(0)
	s_setprio 1
	s_waitcnt lgkmcnt(7)
	v_mfma_f32_16x16x32_bf16 v[62:65], v[70:73], v[148:151], v[62:65]
	v_mfma_f32_16x16x32_bf16 v[58:61], v[70:73], v[174:177], v[58:61]
	s_waitcnt lgkmcnt(5)
	v_mfma_f32_16x16x32_bf16 v[54:57], v[94:97], v[148:151], v[54:57]
	s_waitcnt lgkmcnt(1)
	v_mfma_f32_16x16x32_bf16 v[22:25], v[216:219], v[148:151], v[22:25]
	v_mfma_f32_16x16x32_bf16 v[14:17], v[216:219], v[174:177], v[14:17]
	v_mfma_f32_16x16x32_bf16 v[62:65], v[78:81], v[170:173], v[62:65]
	v_mfma_f32_16x16x32_bf16 v[58:61], v[78:81], v[152:155], v[58:61]
	v_mfma_f32_16x16x32_bf16 v[54:57], v[106:109], v[170:173], v[54:57]
	v_mfma_f32_16x16x32_bf16 v[46:49], v[94:97], v[174:177], v[46:49]
	v_mfma_f32_16x16x32_bf16 v[38:41], v[110:113], v[148:151], v[38:41]
	v_mfma_f32_16x16x32_bf16 v[30:33], v[110:113], v[174:177], v[30:33]
	s_waitcnt lgkmcnt(0)
	v_mfma_f32_16x16x32_bf16 v[22:25], v[220:223], v[170:173], v[22:25]
	v_mfma_f32_16x16x32_bf16 v[14:17], v[220:223], v[152:155], v[14:17]
	v_mfma_f32_16x16x32_bf16 v[224:227], v[106:109], v[152:155], v[46:49]
	v_mfma_f32_16x16x32_bf16 v[240:243], v[212:215], v[170:173], v[38:41]
	v_mfma_f32_16x16x32_bf16 v[244:247], v[212:215], v[152:155], v[30:33]
	s_setprio 0
	s_setprio 1
	v_mfma_f32_16x16x32_bf16 v[30:33], v[70:73], v[86:89], v[50:53]
	v_mfma_f32_16x16x32_bf16 v[50:53], v[78:81], v[98:101], v[30:33]
	v_mfma_f32_16x16x32_bf16 v[30:33], v[70:73], v[102:105], v[42:45]
	v_mfma_f32_16x16x32_bf16 v[2:5], v[216:219], v[102:105], v[2:5]
	v_mfma_f32_16x16x32_bf16 v[148:151], v[78:81], v[156:159], v[30:33]
	v_mfma_f32_16x16x32_bf16 v[30:33], v[94:97], v[86:89], v[34:37]
	v_mfma_f32_16x16x32_bf16 v[26:29], v[94:97], v[102:105], v[26:29]
	v_mfma_f32_16x16x32_bf16 v[18:21], v[110:113], v[86:89], v[18:21]
	v_mfma_f32_16x16x32_bf16 v[10:13], v[110:113], v[102:105], v[10:13]
	v_mfma_f32_16x16x32_bf16 v[6:9], v[216:219], v[86:89], v[6:9]
	v_mfma_f32_16x16x32_bf16 v[2:5], v[220:223], v[156:159], v[2:5]
	v_mfma_f32_16x16x32_bf16 v[152:155], v[106:109], v[98:101], v[30:33]
	v_mfma_f32_16x16x32_bf16 v[170:173], v[106:109], v[156:159], v[26:29]
	v_mfma_f32_16x16x32_bf16 v[174:177], v[212:215], v[98:101], v[18:21]
	v_mfma_f32_16x16x32_bf16 v[212:215], v[212:215], v[156:159], v[10:13]
	v_mfma_f32_16x16x32_bf16 v[248:251], v[220:223], v[98:101], v[6:9]
	s_setprio 0
	s_barrier
	s_nop 0
	ds_read_b128 v[6:9], v162
	ds_read_b128 v[156:159], v163
	ds_read_b128 v[160:163], v164
	ds_read_b128 v[216:219], v165
	ds_read_b128 v[10:13], v134 offset:32768
	ds_read_b128 v[18:21], v134 offset:33792
	ds_read_b128 v[26:29], v134 offset:34816
	ds_read_b128 v[42:45], v134 offset:35840
	ds_read_b128 v[46:49], v134 offset:36864
	ds_read_b128 v[220:223], v134 offset:37888
	ds_read_b128 v[178:181], v134 offset:38912
	ds_read_b128 v[186:189], v134 offset:39936
	s_waitcnt vmcnt(2)
	s_barrier
; #define LDA8(dst, b, h) _Pragma("unroll") for (int m = 0; m < 4; ++m) _Pragma("unroll") for (int k = 0; k < 2; ++k) \
;     dst[m][k] = *reinterpret_cast<const bf16x8*>(SA8(b, h) + fa_off + m * 2048 + k * 1024)
; #define LDB8(dst, b, h) _Pragma("unroll") for (int n = 0; n < 2; ++n) _Pragma("unroll") for (int k = 0; k < 2; ++k) \
;     dst[n][k] = *reinterpret_cast<const bf16x8*>(SB8(b, h) + fb_off + n * 2048 + k * 1024)
; #define WAIT_V8(n) asm volatile("s_waitcnt vmcnt(" #n ")" ::: "memory")
; #define WAIT_L8(n) asm volatile("s_waitcnt lgkmcnt(" #n ")" ::: "memory")
; #define BAR8 __builtin_amdgcn_s_barrier()
; __device__ __forceinline__ void gemm_mainloop8(const bf16_t* __restrict__ Xg, int ldx, const bf16_t* __restrict__ Wg, int ldw, ...
;     ...
;   { LDB8(B0, 1, 0); LDA8(At, 1, 0); WAIT_V8(2); BAR8; WAIT_L8(0); MMA8(0, 0, At, B0); BAR8;
;     LDB8(B1, 1, 1); WAIT_V8(0); BAR8; WAIT_L8(0); MMA8(0, 1, At, B1); BAR8;
;     LDA8(At, 1, 1); BAR8; WAIT_L8(0); MMA8(1, 0, At, B0); MMA8(1, 1, At, B1); BAR8; }
;   if (wr == 0) BAR8;
	s_waitcnt lgkmcnt(0)
	s_setprio 1
	s_waitcnt lgkmcnt(7)
	v_mfma_f32_16x16x32_bf16 v[30:33], v[10:13], v[6:9], v[126:129]
	s_waitcnt lgkmcnt(6)
	v_mfma_f32_16x16x32_bf16 v[98:101], v[18:21], v[156:159], v[30:33]
	v_mfma_f32_16x16x32_bf16 v[30:33], v[10:13], v[160:163], v[122:125]
	v_mfma_f32_16x16x32_bf16 v[94:97], v[18:21], v[216:219], v[30:33]
	s_waitcnt lgkmcnt(5)
	v_mfma_f32_16x16x32_bf16 v[30:33], v[26:29], v[6:9], v[118:121]
	s_waitcnt lgkmcnt(4)
	v_mfma_f32_16x16x32_bf16 v[102:105], v[42:45], v[156:159], v[30:33]
	v_mfma_f32_16x16x32_bf16 v[30:33], v[26:29], v[160:163], v[114:117]
	v_mfma_f32_16x16x32_bf16 v[86:89], v[42:45], v[216:219], v[30:33]
	s_waitcnt lgkmcnt(3)
	v_mfma_f32_16x16x32_bf16 v[30:33], v[46:49], v[6:9], v[130:133]
	s_waitcnt lgkmcnt(2)
	v_mfma_f32_16x16x32_bf16 v[106:109], v[220:223], v[156:159], v[30:33]
	v_mfma_f32_16x16x32_bf16 v[30:33], v[46:49], v[160:163], v[228:231]
	v_mfma_f32_16x16x32_bf16 v[78:81], v[220:223], v[216:219], v[30:33]
	s_waitcnt lgkmcnt(1)
	v_mfma_f32_16x16x32_bf16 v[30:33], v[178:181], v[6:9], v[232:235]
	s_waitcnt lgkmcnt(0)
	v_mfma_f32_16x16x32_bf16 v[110:113], v[186:189], v[156:159], v[30:33]
	v_mfma_f32_16x16x32_bf16 v[30:33], v[178:181], v[160:163], v[82:85]
	v_mfma_f32_16x16x32_bf16 v[70:73], v[186:189], v[216:219], v[30:33]
	s_setprio 0
	s_barrier
	ds_read_b128 v[114:117], v166
	ds_read_b128 v[122:125], v167
	ds_read_b128 v[164:167], v168
	ds_read_b128 v[228:231], v169
	s_waitcnt vmcnt(0)
	s_barrier
	s_waitcnt lgkmcnt(0)
	s_setprio 1
	s_waitcnt lgkmcnt(3)
	v_mfma_f32_16x16x32_bf16 v[30:33], v[10:13], v[114:117], v[236:239]
	s_waitcnt lgkmcnt(1)
	v_mfma_f32_16x16x32_bf16 v[10:13], v[10:13], v[164:167], v[190:193]
	v_mfma_f32_16x16x32_bf16 v[34:37], v[18:21], v[122:125], v[30:33]
	s_waitcnt lgkmcnt(0)
	v_mfma_f32_16x16x32_bf16 v[30:33], v[18:21], v[228:231], v[10:13]
	v_mfma_f32_16x16x32_bf16 v[10:13], v[26:29], v[114:117], v[194:197]
	v_mfma_f32_16x16x32_bf16 v[38:41], v[42:45], v[122:125], v[10:13]
	v_mfma_f32_16x16x32_bf16 v[10:13], v[26:29], v[164:167], v[90:93]
	v_mfma_f32_16x16x32_bf16 v[26:29], v[42:45], v[228:231], v[10:13]
	v_mfma_f32_16x16x32_bf16 v[10:13], v[46:49], v[114:117], v[204:207]
	v_mfma_f32_16x16x32_bf16 v[42:45], v[220:223], v[122:125], v[10:13]
	v_mfma_f32_16x16x32_bf16 v[10:13], v[46:49], v[164:167], v[74:77]
	v_mfma_f32_16x16x32_bf16 v[18:21], v[220:223], v[228:231], v[10:13]
	v_mfma_f32_16x16x32_bf16 v[10:13], v[178:181], v[114:117], v[208:211]
	v_mfma_f32_16x16x32_bf16 v[46:49], v[186:189], v[122:125], v[10:13]
	v_mfma_f32_16x16x32_bf16 v[10:13], v[178:181], v[164:167], v[66:69]
	v_mfma_f32_16x16x32_bf16 v[10:13], v[186:189], v[228:231], v[10:13]
	s_setprio 0
	s_barrier
	ds_read_b128 v[178:181], v134 offset:49152
	ds_read_b128 v[186:189], v134 offset:50176
	ds_read_b128 v[190:193], v134 offset:51200
	ds_read_b128 v[194:197], v134 offset:52224
	ds_read_b128 v[204:207], v134 offset:53248
	ds_read_b128 v[208:211], v134 offset:54272
	ds_read_b128 v[220:223], v134 offset:55296
	ds_read_b128 v[232:235], v134 offset:56320
	s_barrier
	s_waitcnt lgkmcnt(0)
	s_setprio 1
	s_waitcnt lgkmcnt(5)
	v_mfma_f32_16x16x32_bf16 v[54:57], v[190:193], v[6:9], v[54:57]
	s_waitcnt lgkmcnt(4)
	v_mfma_f32_16x16x32_bf16 v[126:129], v[194:197], v[156:159], v[54:57]
	v_mfma_f32_16x16x32_bf16 v[54:57], v[190:193], v[160:163], v[224:227]
	v_mfma_f32_16x16x32_bf16 v[62:65], v[178:181], v[6:9], v[62:65]
	v_mfma_f32_16x16x32_bf16 v[82:85], v[194:197], v[216:219], v[54:57]
	s_waitcnt lgkmcnt(3)
	v_mfma_f32_16x16x32_bf16 v[54:57], v[204:207], v[6:9], v[240:243]
	s_waitcnt lgkmcnt(1)
	v_mfma_f32_16x16x32_bf16 v[6:9], v[220:223], v[6:9], v[22:25]
	v_mfma_f32_16x16x32_bf16 v[58:61], v[178:181], v[160:163], v[58:61]
	v_mfma_f32_16x16x32_bf16 v[130:133], v[208:211], v[156:159], v[54:57]
	v_mfma_f32_16x16x32_bf16 v[54:57], v[204:207], v[160:163], v[244:247]
	s_waitcnt lgkmcnt(0)
	v_mfma_f32_16x16x32_bf16 v[134:137], v[232:235], v[156:159], v[6:9]
	v_mfma_f32_16x16x32_bf16 v[6:9], v[220:223], v[160:163], v[14:17]
	v_mfma_f32_16x16x32_bf16 v[118:121], v[186:189], v[156:159], v[62:65]
	v_mfma_f32_16x16x32_bf16 v[90:93], v[186:189], v[216:219], v[58:61]
	v_mfma_f32_16x16x32_bf16 v[74:77], v[208:211], v[216:219], v[54:57]
	v_mfma_f32_16x16x32_bf16 v[66:69], v[232:235], v[216:219], v[6:9]
	s_setprio 0
	s_setprio 1
	v_mfma_f32_16x16x32_bf16 v[6:9], v[178:181], v[114:117], v[50:53]
	v_mfma_f32_16x16x32_bf16 v[50:53], v[186:189], v[122:125], v[6:9]
	v_mfma_f32_16x16x32_bf16 v[6:9], v[178:181], v[164:167], v[148:151]
	v_mfma_f32_16x16x32_bf16 v[22:25], v[186:189], v[228:231], v[6:9]
	v_mfma_f32_16x16x32_bf16 v[6:9], v[190:193], v[114:117], v[152:155]
	v_mfma_f32_16x16x32_bf16 v[54:57], v[194:197], v[122:125], v[6:9]
	v_mfma_f32_16x16x32_bf16 v[6:9], v[190:193], v[164:167], v[170:173]
	v_mfma_f32_16x16x32_bf16 v[14:17], v[194:197], v[228:231], v[6:9]
	v_mfma_f32_16x16x32_bf16 v[6:9], v[204:207], v[114:117], v[174:177]
	v_mfma_f32_16x16x32_bf16 v[58:61], v[208:211], v[122:125], v[6:9]
	v_mfma_f32_16x16x32_bf16 v[6:9], v[204:207], v[164:167], v[212:215]
	v_mfma_f32_16x16x32_bf16 v[62:65], v[220:223], v[114:117], v[248:251]
	v_mfma_f32_16x16x32_bf16 v[2:5], v[220:223], v[164:167], v[2:5]
	v_mfma_f32_16x16x32_bf16 v[6:9], v[208:211], v[228:231], v[6:9]
	v_mfma_f32_16x16x32_bf16 v[62:65], v[232:235], v[122:125], v[62:65]
	v_mfma_f32_16x16x32_bf16 v[2:5], v[232:235], v[228:231], v[2:5]
	s_setprio 0
	s_movk_i32 s15, 0x100
	v_cmp_gt_u32_e32 vcc, s15, v147
	s_barrier
	s_and_saveexec_b64 s[22:23], vcc
	s_cbranch_execz .LBB0_258
	s_barrier

; #define STAGE8(P, BASE, LD, OFF, br, kt) do { const bf16_t* g_ = (BASE) + (long)(br) * (LD) + (long)(kt) * 64 + (OFF); \
;     __builtin_amdgcn_global_load_lds((const unsigned*)(g_), (unsigned*)((char*)(P) + tid8 * 16), 16, 0, 0);            \
;     __builtin_amdgcn_global_load_lds((const unsigned*)(g_ + 64 * (long)(LD)), (unsigned*)((char*)(P) + tid8 * 16 + 8192), 16, 0, 0); } while (0)
; #define WAIT_V8(n) asm volatile("s_waitcnt vmcnt(" #n ")" ::: "memory")
; #define BAR8 __builtin_amdgcn_s_barrier()
; __device__ __forceinline__ void gemm_mainloop8(const bf16_t* __restrict__ Xg, int ldx, const bf16_t* __restrict__ Wg, int ldw, ...
;     ...
;   if (wr == 1) BAR8;
;   if (prefetched) { WAIT_V8(0); } else { WAIT_V8(4); }
;   BAR8;
;   STAGE8(SB8(1, 0), Bt, ldx, offB, 0, 1); STAGE8(SA8(1, 0), A, ldw, offA, 0, 1); STAGE8(SB8(1, 1), Bt, ldx, offB, 128, 1);
;   WAIT_V8(6); BAR8;
; template <int MB>
; __device__ __forceinline__ void zero_acc(f32x4 (&acc)[8][MB]) {
; #pragma unroll
;   for (int a = 0; a < 8; ++a)
; #pragma unroll
;     for (int b = 0; b < MB; ++b) acc[a][b] = f32x4{0.f, 0.f, 0.f, 0.f};
; }
.LBB0_291:
	s_or_b64 exec, exec, s[26:27]
	v_lshlrev_b32_e32 v12, 6, v0
	v_lshlrev_b32_e32 v15, 2, v0
	v_and_b32_e32 v11, 48, v0
	v_and_b32_e32 v13, 0x3c0, v12
	v_and_b32_e32 v15, 32, v15
	v_or_b32_e32 v14, v13, v11
	v_bitop3_b32 v11, v13, v15, v11 bitop3:0x36
	s_movk_i32 s19, 0x3000
	v_add_u32_e32 v146, 0x18000, v137
	v_lshlrev_b32_e32 v10, 13, v10
	v_and_or_b32 v145, v12, s19, v11
	s_mov_b64 s[28:29], 0x80
	v_readfirstlane_b32 s19, v146
	v_add_u32_e32 v147, 0x1a000, v137
	v_bitop3_b32 v136, v14, v10, v15 bitop3:0xde
	v_lshl_add_u64 v[10:11], v[4:5], 0, s[28:29]
	s_mov_b32 m0, s19
	v_readfirstlane_b32 s19, v147
	v_add_u32_e32 v148, 0x8000, v137
	s_waitcnt vmcnt(2)
	s_barrier
	global_load_lds_dwordx4 v[10:11], off
	v_lshl_add_u64 v[10:11], v[4:5], 0, s[0:1]
	s_mov_b32 m0, s19
	v_readfirstlane_b32 s19, v148
	v_add_u32_e32 v149, 0xa000, v137
	global_load_lds_dwordx4 v[10:11], off
	v_lshl_add_u64 v[10:11], v[130:131], 0, s[28:29]
	s_mov_b32 m0, s19
	s_mov_b64 s[28:29], 0x20080
	v_readfirstlane_b32 s19, v149
	v_add_u32_e32 v150, 0x1c000, v137
	global_load_lds_dwordx4 v[10:11], off
	v_lshl_add_u64 v[10:11], v[130:131], 0, s[28:29]
	s_mov_b32 m0, s19
	v_readfirstlane_b32 s19, v150
	v_add_u32_e32 v151, 0x1e000, v137
	global_load_lds_dwordx4 v[10:11], off
	v_lshl_add_u64 v[10:11], v[4:5], 0, s[44:45]
	s_mov_b32 m0, s19
	v_readfirstlane_b32 s19, v151
	global_load_lds_dwordx4 v[10:11], off
	v_lshl_add_u64 v[4:5], v[4:5], 0, s[82:83]
	s_mov_b32 m0, s19
	s_lshl_b64 s[26:27], s[16:17], 10
	global_load_lds_dwordx4 v[4:5], off
	v_lshlrev_b32_e32 v4, 14, v6
	v_and_b32_e32 v4, 0xffff8000, v4
	v_lshl_add_u32 v4, v7, 11, v4
	v_or_b32_e32 v4, v4, v8
	v_add_u32_e32 v4, v4, v9
	s_add_u32 s28, s2, s20
	v_ashrrev_i32_e32 v5, 31, v4
	s_addc_u32 s29, s3, s21
	v_lshl_add_u64 v[132:133], v[4:5], 1, s[28:29]
	s_add_u32 s28, s8, s22
	s_waitcnt vmcnt(6)
	s_addc_u32 s29, s9, s23
	v_lshl_add_u64 v[134:135], v[2:3], 1, s[28:29]
	v_mov_b32_e32 v2, 0
	s_mov_b64 s[36:37], 0x80
	s_mov_b32 s19, -2
	s_mov_b64 s[28:29], 0
	v_mov_b32_e32 v3, v2
	v_mov_b32_e32 v4, v2
	v_mov_b32_e32 v5, v2
	v_mov_b32_e32 v6, v2
	v_mov_b32_e32 v7, v2
	v_mov_b32_e32 v8, v2
	v_mov_b32_e32 v9, v2
	v_mov_b32_e32 v14, v2
	v_mov_b32_e32 v15, v2
	v_mov_b32_e32 v16, v2
	v_mov_b32_e32 v17, v2
	v_mov_b32_e32 v22, v2
	v_mov_b32_e32 v23, v2
	v_mov_b32_e32 v24, v2
	v_mov_b32_e32 v25, v2
	v_mov_b32_e32 v10, v2
	v_mov_b32_e32 v11, v2
	v_mov_b32_e32 v12, v2
	v_mov_b32_e32 v13, v2
	v_mov_b32_e32 v18, v2
	v_mov_b32_e32 v19, v2
	v_mov_b32_e32 v20, v2
	v_mov_b32_e32 v21, v2
	v_mov_b32_e32 v30, v2
	v_mov_b32_e32 v31, v2
	v_mov_b32_e32 v32, v2
	v_mov_b32_e32 v33, v2
	v_mov_b32_e32 v38, v2
	v_mov_b32_e32 v39, v2
	v_mov_b32_e32 v40, v2
	v_mov_b32_e32 v41, v2
	v_mov_b32_e32 v26, v2
	v_mov_b32_e32 v27, v2
	v_mov_b32_e32 v28, v2
	v_mov_b32_e32 v29, v2
	v_mov_b32_e32 v34, v2
	v_mov_b32_e32 v35, v2
	v_mov_b32_e32 v36, v2
	v_mov_b32_e32 v37, v2
	v_mov_b32_e32 v46, v2
	v_mov_b32_e32 v47, v2
	v_mov_b32_e32 v48, v2
	v_mov_b32_e32 v49, v2
	v_mov_b32_e32 v54, v2
	v_mov_b32_e32 v55, v2
	v_mov_b32_e32 v56, v2
	v_mov_b32_e32 v57, v2
	v_mov_b32_e32 v42, v2
	v_mov_b32_e32 v43, v2
	v_mov_b32_e32 v44, v2
	v_mov_b32_e32 v45, v2
	v_mov_b32_e32 v50, v2
	v_mov_b32_e32 v51, v2
	v_mov_b32_e32 v52, v2
	v_mov_b32_e32 v53, v2
	v_mov_b32_e32 v58, v2
	v_mov_b32_e32 v59, v2
	v_mov_b32_e32 v60, v2
	v_mov_b32_e32 v61, v2
	v_mov_b32_e32 v62, v2
	v_mov_b32_e32 v63, v2
	v_mov_b32_e32 v64, v2
	v_mov_b32_e32 v65, v2
	v_mov_b32_e32 v66, v2
	v_mov_b32_e32 v67, v2
	v_mov_b32_e32 v68, v2
	v_mov_b32_e32 v69, v2
	v_mov_b32_e32 v70, v2
	v_mov_b32_e32 v71, v2
	v_mov_b32_e32 v72, v2
	v_mov_b32_e32 v73, v2
	v_mov_b32_e32 v82, v2
	v_mov_b32_e32 v83, v2
	v_mov_b32_e32 v84, v2
	v_mov_b32_e32 v85, v2
	v_mov_b32_e32 v86, v2
	v_mov_b32_e32 v87, v2
	v_mov_b32_e32 v88, v2
	v_mov_b32_e32 v89, v2
	v_mov_b32_e32 v74, v2
	v_mov_b32_e32 v75, v2
	v_mov_b32_e32 v76, v2
	v_mov_b32_e32 v77, v2
	v_mov_b32_e32 v78, v2
	v_mov_b32_e32 v79, v2
	v_mov_b32_e32 v80, v2
	v_mov_b32_e32 v81, v2
	v_mov_b32_e32 v98, v2
	v_mov_b32_e32 v99, v2
	v_mov_b32_e32 v100, v2
	v_mov_b32_e32 v101, v2
	v_mov_b32_e32 v102, v2
	v_mov_b32_e32 v103, v2
	v_mov_b32_e32 v104, v2
	v_mov_b32_e32 v105, v2
	v_mov_b32_e32 v90, v2
	v_mov_b32_e32 v91, v2
	v_mov_b32_e32 v92, v2
	v_mov_b32_e32 v93, v2
	v_mov_b32_e32 v94, v2
	v_mov_b32_e32 v95, v2
	v_mov_b32_e32 v96, v2
	v_mov_b32_e32 v97, v2
	v_mov_b32_e32 v114, v2
	v_mov_b32_e32 v115, v2
	v_mov_b32_e32 v116, v2
	v_mov_b32_e32 v117, v2
	v_mov_b32_e32 v118, v2
	v_mov_b32_e32 v119, v2
	v_mov_b32_e32 v120, v2
	v_mov_b32_e32 v121, v2
	v_mov_b32_e32 v106, v2
	v_mov_b32_e32 v107, v2
	v_mov_b32_e32 v108, v2
	v_mov_b32_e32 v109, v2
	v_mov_b32_e32 v110, v2
	v_mov_b32_e32 v111, v2
	v_mov_b32_e32 v112, v2
	v_mov_b32_e32 v113, v2
	v_mov_b32_e32 v122, v2
	v_mov_b32_e32 v123, v2
	v_mov_b32_e32 v124, v2
	v_mov_b32_e32 v125, v2
	v_mov_b32_e32 v126, v2
	v_mov_b32_e32 v127, v2
	v_mov_b32_e32 v128, v2
	v_mov_b32_e32 v129, v2
	s_barrier
; #define STAGE8(P, BASE, LD, OFF, br, kt) do { const bf16_t* g_ = (BASE) + (long)(br) * (LD) + (long)(kt) * 64 + (OFF); \
;     __builtin_amdgcn_global_load_lds((const unsigned*)(g_), (unsigned*)((char*)(P) + tid8 * 16), 16, 0, 0);            \
;     __builtin_amdgcn_global_load_lds((const unsigned*)(g_ + 64 * (long)(LD)), (unsigned*)((char*)(P) + tid8 * 16 + 8192), 16, 0, 0); } while (0)
; #define LDA8(dst, b, h) _Pragma("unroll") for (int m = 0; m < 4; ++m) _Pragma("unroll") for (int k = 0; k < 2; ++k) \
;     dst[m][k] = *reinterpret_cast<const bf16x8*>(SA8(b, h) + fa_off + m * 2048 + k * 1024)
; #define LDB8(dst, b, h) _Pragma("unroll") for (int n = 0; n < 2; ++n) _Pragma("unroll") for (int k = 0; k < 2; ++k) \
;     dst[n][k] = *reinterpret_cast<const bf16x8*>(SB8(b, h) + fb_off + n * 2048 + k * 1024)
; #define WAIT_V8(n) asm volatile("s_waitcnt vmcnt(" #n ")" ::: "memory")
; #define WAIT_L8(n) asm volatile("s_waitcnt lgkmcnt(" #n ")" ::: "memory")
; #define BAR8 __builtin_amdgcn_s_barrier()
; #define SCHED8 __builtin_amdgcn_sched_barrier(0)
; __device__ __forceinline__ void gemm_mainloop8(const bf16_t* __restrict__ Xg, int ldx, const bf16_t* __restrict__ Wg, int ldw, ...
;     ...
;     LDB8(B0, 0, 0); SCHED8; LDA8(At, 0, 0); STAGE8(SA8(1, 1), A, ldw, offA, 128, t + 1);
;     WAIT_L8(8); BAR8; WAIT_L8(0); MMA8(0, 0, At, B0); BAR8; SCHED8;
;     LDB8(B1, 0, 1); STAGE8(SB8(0, 0), Bt, ldx, offB, 0, t + 2);
;     BAR8; WAIT_L8(0); MMA8(0, 1, At, B1); BAR8;
;     LDA8(At, 0, 1); STAGE8(SA8(0, 0), A, ldw, offA, 0, t + 2);
;     BAR8; WAIT_L8(0); MMA8(1, 0, At, B0); BAR8; SCHED8;
;     STAGE8(SB8(0, 1), Bt, ldx, offB, 128, t + 2);
;     WAIT_V8(6); BAR8; MMA8(1, 1, At, B1); BAR8;
;     LDB8(B0, 1, 0); SCHED8; LDA8(At, 1, 0); STAGE8(SA8(0, 1), A, ldw, offA, 128, t + 2);
.LBB0_292:
	v_or_b32_e32 v152, 0x10000, v145
	v_add_u32_e32 v153, 0x10400, v145
	v_add_u32_e32 v154, 0x10800, v145
	v_add_u32_e32 v155, 0x10c00, v145
	v_or_b32_e32 v158, 0x14000, v145
	v_add_u32_e32 v159, 0x14400, v145
	v_add_u32_e32 v160, 0x14800, v145
	v_add_u32_e32 v161, 0x14c00, v145
	v_add_u32_e32 v156, 0xc000, v137
	v_add_u32_e32 v157, 0xe000, v137
	v_lshl_add_u64 v[178:179], v[134:135], 0, s[28:29]
	v_lshl_add_u64 v[180:181], v[132:133], 0, s[28:29]
	ds_read_b128 v[162:165], v152
	ds_read_b128 v[166:169], v153
	ds_read_b128 v[170:173], v154
	ds_read_b128 v[174:177], v155
	ds_read_b128 v[190:193], v136
	ds_read_b128 v[194:197], v136 offset:1024
	ds_read_b128 v[204:207], v136 offset:2048
	ds_read_b128 v[208:211], v136 offset:3072
	ds_read_b128 v[212:215], v136 offset:4096
	ds_read_b128 v[216:219], v136 offset:5120
	ds_read_b128 v[220:223], v136 offset:6144
	ds_read_b128 v[224:227], v136 offset:7168
	ds_read_b128 v[228:231], v158
	ds_read_b128 v[232:235], v159
	ds_read_b128 v[236:239], v160
	ds_read_b128 v[240:243], v161
	v_lshl_add_u64 v[186:187], v[178:179], 0, s[0:1]
	v_readfirstlane_b32 s31, v156
	s_nop 0
	s_mov_b32 m0, s31
	s_nop 0
	global_load_lds_dwordx4 v[186:187], off
	v_lshl_add_u64 v[186:187], v[178:179], 0, s[84:85]
	v_readfirstlane_b32 s31, v157
	s_nop 0
	s_mov_b32 m0, s31
	s_nop 0
	global_load_lds_dwordx4 v[186:187], off
	s_waitcnt lgkmcnt(0)
	s_barrier
	s_setprio 1
	v_mfma_f32_16x16x32_bf16 v[126:129], v[190:193], v[162:165], v[126:129]
	v_mfma_f32_16x16x32_bf16 v[122:125], v[190:193], v[170:173], v[122:125]
	v_mfma_f32_16x16x32_bf16 v[118:121], v[204:207], v[162:165], v[118:121]
	v_mfma_f32_16x16x32_bf16 v[114:117], v[204:207], v[170:173], v[114:117]
	v_mfma_f32_16x16x32_bf16 v[102:105], v[212:215], v[162:165], v[102:105]
	v_mfma_f32_16x16x32_bf16 v[98:101], v[212:215], v[170:173], v[98:101]
	v_mfma_f32_16x16x32_bf16 v[86:89], v[220:223], v[162:165], v[86:89]
	v_mfma_f32_16x16x32_bf16 v[82:85], v[220:223], v[170:173], v[82:85]
	v_mfma_f32_16x16x32_bf16 v[126:129], v[194:197], v[166:169], v[126:129]
	v_mfma_f32_16x16x32_bf16 v[122:125], v[194:197], v[174:177], v[122:125]
	v_mfma_f32_16x16x32_bf16 v[118:121], v[208:211], v[166:169], v[118:121]
	v_mfma_f32_16x16x32_bf16 v[114:117], v[208:211], v[174:177], v[114:117]
	v_mfma_f32_16x16x32_bf16 v[102:105], v[216:219], v[166:169], v[102:105]
	v_mfma_f32_16x16x32_bf16 v[98:101], v[216:219], v[174:177], v[98:101]
	v_mfma_f32_16x16x32_bf16 v[86:89], v[224:227], v[166:169], v[86:89]
	v_mfma_f32_16x16x32_bf16 v[82:85], v[224:227], v[174:177], v[82:85]
	v_mfma_f32_16x16x32_bf16 v[110:113], v[190:193], v[228:231], v[110:113]
	v_mfma_f32_16x16x32_bf16 v[106:109], v[190:193], v[236:239], v[106:109]
	v_mfma_f32_16x16x32_bf16 v[94:97], v[204:207], v[228:231], v[94:97]
	v_mfma_f32_16x16x32_bf16 v[90:93], v[204:207], v[236:239], v[90:93]
	v_mfma_f32_16x16x32_bf16 v[78:81], v[212:215], v[228:231], v[78:81]
	v_mfma_f32_16x16x32_bf16 v[74:77], v[212:215], v[236:239], v[74:77]
	v_mfma_f32_16x16x32_bf16 v[70:73], v[220:223], v[228:231], v[70:73]
	v_mfma_f32_16x16x32_bf16 v[66:69], v[220:223], v[236:239], v[66:69]
	v_mfma_f32_16x16x32_bf16 v[110:113], v[194:197], v[232:235], v[110:113]
	v_mfma_f32_16x16x32_bf16 v[106:109], v[194:197], v[240:243], v[106:109]
	v_mfma_f32_16x16x32_bf16 v[94:97], v[208:211], v[232:235], v[94:97]
	v_mfma_f32_16x16x32_bf16 v[90:93], v[208:211], v[240:243], v[90:93]
	v_mfma_f32_16x16x32_bf16 v[78:81], v[216:219], v[232:235], v[78:81]
	v_mfma_f32_16x16x32_bf16 v[74:77], v[216:219], v[240:243], v[74:77]
	v_mfma_f32_16x16x32_bf16 v[70:73], v[224:227], v[232:235], v[70:73]
	v_mfma_f32_16x16x32_bf16 v[66:69], v[224:227], v[240:243], v[66:69]
	s_setprio 0
	s_barrier
	ds_read_b128 v[190:193], v136 offset:16384
	ds_read_b128 v[194:197], v136 offset:17408
	ds_read_b128 v[204:207], v136 offset:18432
	ds_read_b128 v[208:211], v136 offset:19456
	ds_read_b128 v[212:215], v136 offset:20480
	ds_read_b128 v[216:219], v136 offset:21504
	ds_read_b128 v[220:223], v136 offset:22528
	ds_read_b128 v[224:227], v136 offset:23552
	v_lshl_add_u64 v[186:187], v[180:181], 0, s[70:71]
	v_readfirstlane_b32 s31, v138
	s_nop 0
	s_mov_b32 m0, s31
	s_nop 0
	global_load_lds_dwordx4 v[186:187], off
	v_lshl_add_u64 v[186:187], v[180:181], 0, s[90:91]
	v_readfirstlane_b32 s31, v139
	s_nop 0
	s_mov_b32 m0, s31
	s_nop 0
	global_load_lds_dwordx4 v[186:187], off
	v_lshl_add_u64 v[186:187], v[178:179], 0, s[70:71]
	v_readfirstlane_b32 s31, v137
	s_nop 0
	s_mov_b32 m0, s31
	s_nop 0
	global_load_lds_dwordx4 v[186:187], off
	v_lshl_add_u64 v[186:187], v[178:179], 0, s[64:65]
	v_readfirstlane_b32 s31, v140
	s_nop 0
	s_mov_b32 m0, s31
	s_nop 0
	global_load_lds_dwordx4 v[186:187], off
	v_lshl_add_u64 v[186:187], v[180:181], 0, s[80:81]
	v_readfirstlane_b32 s31, v141
	s_nop 0
	s_mov_b32 m0, s31
	s_nop 0
	global_load_lds_dwordx4 v[186:187], off
	v_lshl_add_u64 v[186:187], v[180:181], 0, s[68:69]
	v_readfirstlane_b32 s31, v142
	s_nop 0
	s_mov_b32 m0, s31
	s_nop 0
	global_load_lds_dwordx4 v[186:187], off
	s_waitcnt vmcnt(6)
	s_waitcnt lgkmcnt(0)
	s_barrier
; #define STAGE8(P, BASE, LD, OFF, br, kt) do { const bf16_t* g_ = (BASE) + (long)(br) * (LD) + (long)(kt) * 64 + (OFF); \
;     __builtin_amdgcn_global_load_lds((const unsigned*)(g_), (unsigned*)((char*)(P) + tid8 * 16), 16, 0, 0);            \
;     __builtin_amdgcn_global_load_lds((const unsigned*)(g_ + 64 * (long)(LD)), (unsigned*)((char*)(P) + tid8 * 16 + 8192), 16, 0, 0); } while (0)
; #define LDA8(dst, b, h) _Pragma("unroll") for (int m = 0; m < 4; ++m) _Pragma("unroll") for (int k = 0; k < 2; ++k) \
;     dst[m][k] = *reinterpret_cast<const bf16x8*>(SA8(b, h) + fa_off + m * 2048 + k * 1024)
; #define LDB8(dst, b, h) _Pragma("unroll") for (int n = 0; n < 2; ++n) _Pragma("unroll") for (int k = 0; k < 2; ++k) \
;     dst[n][k] = *reinterpret_cast<const bf16x8*>(SB8(b, h) + fb_off + n * 2048 + k * 1024)
; #define WAIT_V8(n) asm volatile("s_waitcnt vmcnt(" #n ")" ::: "memory")
; #define WAIT_L8(n) asm volatile("s_waitcnt lgkmcnt(" #n ")" ::: "memory")
; #define BAR8 __builtin_amdgcn_s_barrier()
; #define SCHED8 __builtin_amdgcn_sched_barrier(0)
; __device__ __forceinline__ void gemm_mainloop8(const bf16_t* __restrict__ Xg, int ldx, const bf16_t* __restrict__ Wg, int ldw, ...
;     ...
;   for (int t = 0; t < nt - 2; t += 2) {
;     LDB8(B0, 0, 0); SCHED8; LDA8(At, 0, 0); STAGE8(SA8(1, 1), A, ldw, offA, 128, t + 1);
;     WAIT_L8(8); BAR8; WAIT_L8(0); MMA8(0, 0, At, B0); BAR8; SCHED8;
;     LDB8(B1, 0, 1); STAGE8(SB8(0, 0), Bt, ldx, offB, 0, t + 2);
;     BAR8; WAIT_L8(0); MMA8(0, 1, At, B1); BAR8;
;     LDA8(At, 0, 1); STAGE8(SA8(0, 0), A, ldw, offA, 0, t + 2);
;     BAR8; WAIT_L8(0); MMA8(1, 0, At, B0); BAR8; SCHED8;
;     STAGE8(SB8(0, 1), Bt, ldx, offB, 128, t + 2);
;     WAIT_V8(6); BAR8; MMA8(1, 1, At, B1); BAR8;
;     LDB8(B0, 1, 0); SCHED8; LDA8(At, 1, 0); STAGE8(SA8(0, 1), A, ldw, offA, 128, t + 2);
;     WAIT_L8(8); BAR8; WAIT_L8(0); MMA8(0, 0, At, B0); BAR8; SCHED8;
;     LDB8(B1, 1, 1); STAGE8(SB8(1, 0), Bt, ldx, offB, 0, t + 3);
;     BAR8; WAIT_L8(0); MMA8(0, 1, At, B1); BAR8;
;     LDA8(At, 1, 1); STAGE8(SA8(1, 0), A, ldw, offA, 0, t + 3);
;     BAR8; WAIT_L8(0); MMA8(1, 0, At, B0); BAR8; SCHED8;
;     STAGE8(SB8(1, 1), Bt, ldx, offB, 128, t + 3);
;     WAIT_V8(6); BAR8; MMA8(1, 1, At, B1); BAR8;
;   }
	s_setprio 1
	v_mfma_f32_16x16x32_bf16 v[62:65], v[190:193], v[162:165], v[62:65]
	v_mfma_f32_16x16x32_bf16 v[58:61], v[190:193], v[170:173], v[58:61]
	v_mfma_f32_16x16x32_bf16 v[54:57], v[204:207], v[162:165], v[54:57]
	v_mfma_f32_16x16x32_bf16 v[46:49], v[204:207], v[170:173], v[46:49]
	v_mfma_f32_16x16x32_bf16 v[38:41], v[212:215], v[162:165], v[38:41]
	v_mfma_f32_16x16x32_bf16 v[30:33], v[212:215], v[170:173], v[30:33]
	v_mfma_f32_16x16x32_bf16 v[22:25], v[220:223], v[162:165], v[22:25]
	v_mfma_f32_16x16x32_bf16 v[14:17], v[220:223], v[170:173], v[14:17]
	v_mfma_f32_16x16x32_bf16 v[62:65], v[194:197], v[166:169], v[62:65]
	v_mfma_f32_16x16x32_bf16 v[58:61], v[194:197], v[174:177], v[58:61]
	v_mfma_f32_16x16x32_bf16 v[54:57], v[208:211], v[166:169], v[54:57]
	v_mfma_f32_16x16x32_bf16 v[46:49], v[208:211], v[174:177], v[46:49]
	v_mfma_f32_16x16x32_bf16 v[38:41], v[216:219], v[166:169], v[38:41]
	v_mfma_f32_16x16x32_bf16 v[30:33], v[216:219], v[174:177], v[30:33]
	v_mfma_f32_16x16x32_bf16 v[22:25], v[224:227], v[166:169], v[22:25]
	v_mfma_f32_16x16x32_bf16 v[14:17], v[224:227], v[174:177], v[14:17]
	v_mfma_f32_16x16x32_bf16 v[50:53], v[190:193], v[228:231], v[50:53]
	v_mfma_f32_16x16x32_bf16 v[42:45], v[190:193], v[236:239], v[42:45]
	v_mfma_f32_16x16x32_bf16 v[34:37], v[204:207], v[228:231], v[34:37]
	v_mfma_f32_16x16x32_bf16 v[26:29], v[204:207], v[236:239], v[26:29]
	v_mfma_f32_16x16x32_bf16 v[18:21], v[212:215], v[228:231], v[18:21]
	v_mfma_f32_16x16x32_bf16 v[10:13], v[212:215], v[236:239], v[10:13]
	v_mfma_f32_16x16x32_bf16 v[6:9], v[220:223], v[228:231], v[6:9]
	v_mfma_f32_16x16x32_bf16 v[2:5], v[220:223], v[236:239], v[2:5]
	v_mfma_f32_16x16x32_bf16 v[50:53], v[194:197], v[232:235], v[50:53]
	v_mfma_f32_16x16x32_bf16 v[42:45], v[194:197], v[240:243], v[42:45]
	v_mfma_f32_16x16x32_bf16 v[34:37], v[208:211], v[232:235], v[34:37]
	v_mfma_f32_16x16x32_bf16 v[26:29], v[208:211], v[240:243], v[26:29]
	v_mfma_f32_16x16x32_bf16 v[18:21], v[216:219], v[232:235], v[18:21]
	v_mfma_f32_16x16x32_bf16 v[10:13], v[216:219], v[240:243], v[10:13]
	v_mfma_f32_16x16x32_bf16 v[6:9], v[224:227], v[232:235], v[6:9]
	v_mfma_f32_16x16x32_bf16 v[2:5], v[224:227], v[240:243], v[2:5]
	s_setprio 0
	s_barrier
	v_or_b32_e32 v162, 0x18000, v145
	v_add_u32_e32 v163, 0x18400, v145
	v_add_u32_e32 v164, 0x18800, v145
	v_add_u32_e32 v165, 0x18c00, v145
	v_or_b32_e32 v166, 0x1c000, v145
	v_add_u32_e32 v167, 0x1c400, v145
	v_add_u32_e32 v168, 0x1c800, v145
	v_add_u32_e32 v169, 0x1cc00, v145
	ds_read_b128 v[170:173], v162
	ds_read_b128 v[174:177], v163
	ds_read_b128 v[190:193], v164
	ds_read_b128 v[194:197], v165
	ds_read_b128 v[204:207], v136 offset:32768
	ds_read_b128 v[208:211], v136 offset:33792
	ds_read_b128 v[212:215], v136 offset:34816
	ds_read_b128 v[216:219], v136 offset:35840
	ds_read_b128 v[220:223], v136 offset:36864
	ds_read_b128 v[224:227], v136 offset:37888
	ds_read_b128 v[228:231], v136 offset:38912
	ds_read_b128 v[232:235], v136 offset:39936
	ds_read_b128 v[236:239], v166
	ds_read_b128 v[240:243], v167
	ds_read_b128 v[244:247], v168
	ds_read_b128 v[248:251], v169
	v_lshl_add_u64 v[186:187], v[178:179], 0, s[90:91]
	v_readfirstlane_b32 s31, v143
	s_nop 0
	s_mov_b32 m0, s31
	s_nop 0
	global_load_lds_dwordx4 v[186:187], off
	v_lshl_add_u64 v[186:187], v[178:179], 0, s[76:77]
	v_readfirstlane_b32 s31, v144
	s_nop 0
	s_mov_b32 m0, s31
	s_nop 0
	global_load_lds_dwordx4 v[186:187], off
	s_waitcnt lgkmcnt(0)
	s_barrier
	s_setprio 1
	v_mfma_f32_16x16x32_bf16 v[126:129], v[204:207], v[170:173], v[126:129]
	v_mfma_f32_16x16x32_bf16 v[122:125], v[204:207], v[190:193], v[122:125]
	v_mfma_f32_16x16x32_bf16 v[118:121], v[212:215], v[170:173], v[118:121]
	v_mfma_f32_16x16x32_bf16 v[114:117], v[212:215], v[190:193], v[114:117]
	v_mfma_f32_16x16x32_bf16 v[102:105], v[220:223], v[170:173], v[102:105]
	v_mfma_f32_16x16x32_bf16 v[98:101], v[220:223], v[190:193], v[98:101]
	v_mfma_f32_16x16x32_bf16 v[86:89], v[228:231], v[170:173], v[86:89]
	v_mfma_f32_16x16x32_bf16 v[82:85], v[228:231], v[190:193], v[82:85]
	v_mfma_f32_16x16x32_bf16 v[126:129], v[208:211], v[174:177], v[126:129]
	v_mfma_f32_16x16x32_bf16 v[122:125], v[208:211], v[194:197], v[122:125]
	v_mfma_f32_16x16x32_bf16 v[118:121], v[216:219], v[174:177], v[118:121]
	v_mfma_f32_16x16x32_bf16 v[114:117], v[216:219], v[194:197], v[114:117]
	v_mfma_f32_16x16x32_bf16 v[102:105], v[224:227], v[174:177], v[102:105]
	v_mfma_f32_16x16x32_bf16 v[98:101], v[224:227], v[194:197], v[98:101]
	v_mfma_f32_16x16x32_bf16 v[86:89], v[232:235], v[174:177], v[86:89]
	v_mfma_f32_16x16x32_bf16 v[82:85], v[232:235], v[194:197], v[82:85]
	v_mfma_f32_16x16x32_bf16 v[110:113], v[204:207], v[236:239], v[110:113]
	v_mfma_f32_16x16x32_bf16 v[106:109], v[204:207], v[244:247], v[106:109]
	v_mfma_f32_16x16x32_bf16 v[94:97], v[212:215], v[236:239], v[94:97]
	v_mfma_f32_16x16x32_bf16 v[90:93], v[212:215], v[244:247], v[90:93]
	v_mfma_f32_16x16x32_bf16 v[78:81], v[220:223], v[236:239], v[78:81]
	v_mfma_f32_16x16x32_bf16 v[74:77], v[220:223], v[244:247], v[74:77]
	v_mfma_f32_16x16x32_bf16 v[70:73], v[228:231], v[236:239], v[70:73]
	v_mfma_f32_16x16x32_bf16 v[66:69], v[228:231], v[244:247], v[66:69]
	v_mfma_f32_16x16x32_bf16 v[110:113], v[208:211], v[240:243], v[110:113]
	v_mfma_f32_16x16x32_bf16 v[106:109], v[208:211], v[248:251], v[106:109]
	v_mfma_f32_16x16x32_bf16 v[94:97], v[216:219], v[240:243], v[94:97]
	v_mfma_f32_16x16x32_bf16 v[90:93], v[216:219], v[248:251], v[90:93]
	v_mfma_f32_16x16x32_bf16 v[78:81], v[224:227], v[240:243], v[78:81]
	v_mfma_f32_16x16x32_bf16 v[74:77], v[224:227], v[248:251], v[74:77]
	v_mfma_f32_16x16x32_bf16 v[70:73], v[232:235], v[240:243], v[70:73]
	v_mfma_f32_16x16x32_bf16 v[66:69], v[232:235], v[248:251], v[66:69]
	s_setprio 0
	s_barrier
; #define STAGE8(P, BASE, LD, OFF, br, kt) do { const bf16_t* g_ = (BASE) + (long)(br) * (LD) + (long)(kt) * 64 + (OFF); \
;     __builtin_amdgcn_global_load_lds((const unsigned*)(g_), (unsigned*)((char*)(P) + tid8 * 16), 16, 0, 0);            \
;     __builtin_amdgcn_global_load_lds((const unsigned*)(g_ + 64 * (long)(LD)), (unsigned*)((char*)(P) + tid8 * 16 + 8192), 16, 0, 0); } while (0)
; #define LDA8(dst, b, h) _Pragma("unroll") for (int m = 0; m < 4; ++m) _Pragma("unroll") for (int k = 0; k < 2; ++k) \
;     dst[m][k] = *reinterpret_cast<const bf16x8*>(SA8(b, h) + fa_off + m * 2048 + k * 1024)
; #define LDB8(dst, b, h) _Pragma("unroll") for (int n = 0; n < 2; ++n) _Pragma("unroll") for (int k = 0; k < 2; ++k) \
;     dst[n][k] = *reinterpret_cast<const bf16x8*>(SB8(b, h) + fb_off + n * 2048 + k * 1024)
; #define WAIT_V8(n) asm volatile("s_waitcnt vmcnt(" #n ")" ::: "memory")
; #define WAIT_L8(n) asm volatile("s_waitcnt lgkmcnt(" #n ")" ::: "memory")
; #define BAR8 __builtin_amdgcn_s_barrier()
; #define SCHED8 __builtin_amdgcn_sched_barrier(0)
; __device__ __forceinline__ void gemm_mainloop8(const bf16_t* __restrict__ Xg, int ldx, const bf16_t* __restrict__ Wg, int ldw, ...
;     ...
;     WAIT_V8(6); BAR8; MMA8(1, 1, At, B1); BAR8;
;     LDB8(B0, 1, 0); SCHED8; LDA8(At, 1, 0); STAGE8(SA8(0, 1), A, ldw, offA, 128, t + 2);
;     WAIT_L8(8); BAR8; WAIT_L8(0); MMA8(0, 0, At, B0); BAR8; SCHED8;
;     LDB8(B1, 1, 1); STAGE8(SB8(1, 0), Bt, ldx, offB, 0, t + 3);
;     BAR8; WAIT_L8(0); MMA8(0, 1, At, B1); BAR8;
;     LDA8(At, 1, 1); STAGE8(SA8(1, 0), A, ldw, offA, 0, t + 3);
;     BAR8; WAIT_L8(0); MMA8(1, 0, At, B0); BAR8; SCHED8;
;     STAGE8(SB8(1, 1), Bt, ldx, offB, 128, t + 3);
;     WAIT_V8(6); BAR8; MMA8(1, 1, At, B1); BAR8;
;   }
;   { LDB8(B0, 0, 0); LDA8(At, 0, 0); STAGE8(SA8(1, 1), A, ldw, offA, 128, nt - 1);
;     BAR8; WAIT_L8(0); MMA8(0, 0, At, B0); BAR8;
	ds_read_b128 v[204:207], v136 offset:49152
	ds_read_b128 v[208:211], v136 offset:50176
	ds_read_b128 v[212:215], v136 offset:51200
	ds_read_b128 v[216:219], v136 offset:52224
	ds_read_b128 v[220:223], v136 offset:53248
	ds_read_b128 v[224:227], v136 offset:54272
	ds_read_b128 v[228:231], v136 offset:55296
	ds_read_b128 v[232:235], v136 offset:56320
	v_lshl_add_u64 v[186:187], v[180:181], 0, s[88:89]
	v_readfirstlane_b32 s31, v146
	s_nop 0
	s_mov_b32 m0, s31
	s_nop 0
	global_load_lds_dwordx4 v[186:187], off
	v_lshl_add_u64 v[186:187], v[180:181], 0, s[4:5]
	v_readfirstlane_b32 s31, v147
	s_nop 0
	s_mov_b32 m0, s31
	s_nop 0
	global_load_lds_dwordx4 v[186:187], off
	v_lshl_add_u64 v[186:187], v[178:179], 0, s[88:89]
	v_readfirstlane_b32 s31, v148
	s_nop 0
	s_mov_b32 m0, s31
	s_nop 0
	global_load_lds_dwordx4 v[186:187], off
	v_lshl_add_u64 v[186:187], v[178:179], 0, s[72:73]
	v_readfirstlane_b32 s31, v149
	s_nop 0
	s_mov_b32 m0, s31
	s_nop 0
	global_load_lds_dwordx4 v[186:187], off
	v_lshl_add_u64 v[186:187], v[180:181], 0, s[92:93]
	v_readfirstlane_b32 s31, v150
	s_nop 0
	s_mov_b32 m0, s31
	s_nop 0
	global_load_lds_dwordx4 v[186:187], off
	v_lshl_add_u64 v[186:187], v[180:181], 0, s[94:95]
	v_readfirstlane_b32 s31, v151
	s_nop 0
	s_mov_b32 m0, s31
	s_nop 0
	global_load_lds_dwordx4 v[186:187], off
	s_waitcnt vmcnt(6)
	s_waitcnt lgkmcnt(0)
	s_barrier
	s_setprio 1
	v_mfma_f32_16x16x32_bf16 v[62:65], v[204:207], v[170:173], v[62:65]
	v_mfma_f32_16x16x32_bf16 v[58:61], v[204:207], v[190:193], v[58:61]
	v_mfma_f32_16x16x32_bf16 v[54:57], v[212:215], v[170:173], v[54:57]
	v_mfma_f32_16x16x32_bf16 v[46:49], v[212:215], v[190:193], v[46:49]
	v_mfma_f32_16x16x32_bf16 v[38:41], v[220:223], v[170:173], v[38:41]
	v_mfma_f32_16x16x32_bf16 v[30:33], v[220:223], v[190:193], v[30:33]
	v_mfma_f32_16x16x32_bf16 v[22:25], v[228:231], v[170:173], v[22:25]
	v_mfma_f32_16x16x32_bf16 v[14:17], v[228:231], v[190:193], v[14:17]
	v_mfma_f32_16x16x32_bf16 v[62:65], v[208:211], v[174:177], v[62:65]
	v_mfma_f32_16x16x32_bf16 v[58:61], v[208:211], v[194:197], v[58:61]
	v_mfma_f32_16x16x32_bf16 v[54:57], v[216:219], v[174:177], v[54:57]
	v_mfma_f32_16x16x32_bf16 v[46:49], v[216:219], v[194:197], v[46:49]
	v_mfma_f32_16x16x32_bf16 v[38:41], v[224:227], v[174:177], v[38:41]
	v_mfma_f32_16x16x32_bf16 v[30:33], v[224:227], v[194:197], v[30:33]
	v_mfma_f32_16x16x32_bf16 v[22:25], v[232:235], v[174:177], v[22:25]
	v_mfma_f32_16x16x32_bf16 v[14:17], v[232:235], v[194:197], v[14:17]
	v_mfma_f32_16x16x32_bf16 v[50:53], v[204:207], v[236:239], v[50:53]
	v_mfma_f32_16x16x32_bf16 v[42:45], v[204:207], v[244:247], v[42:45]
	v_mfma_f32_16x16x32_bf16 v[34:37], v[212:215], v[236:239], v[34:37]
	v_mfma_f32_16x16x32_bf16 v[26:29], v[212:215], v[244:247], v[26:29]
	v_mfma_f32_16x16x32_bf16 v[18:21], v[220:223], v[236:239], v[18:21]
	v_mfma_f32_16x16x32_bf16 v[10:13], v[220:223], v[244:247], v[10:13]
	v_mfma_f32_16x16x32_bf16 v[6:9], v[228:231], v[236:239], v[6:9]
	v_mfma_f32_16x16x32_bf16 v[2:5], v[228:231], v[244:247], v[2:5]
	v_mfma_f32_16x16x32_bf16 v[50:53], v[208:211], v[240:243], v[50:53]
	v_mfma_f32_16x16x32_bf16 v[42:45], v[208:211], v[248:251], v[42:45]
	v_mfma_f32_16x16x32_bf16 v[34:37], v[216:219], v[240:243], v[34:37]
	v_mfma_f32_16x16x32_bf16 v[26:29], v[216:219], v[248:251], v[26:29]
	v_mfma_f32_16x16x32_bf16 v[18:21], v[224:227], v[240:243], v[18:21]
	v_mfma_f32_16x16x32_bf16 v[10:13], v[224:227], v[248:251], v[10:13]
	v_mfma_f32_16x16x32_bf16 v[6:9], v[232:235], v[240:243], v[6:9]
	v_mfma_f32_16x16x32_bf16 v[2:5], v[232:235], v[248:251], v[2:5]
	s_setprio 0
	s_add_i32 s19, s19, 2
	s_add_u32 s28, s28, 0x100
	s_addc_u32 s29, s29, 0
	s_cmp_lt_u32 s19, 12
	s_barrier
	s_cbranch_scc1 .LBB0_292
	s_mov_b64 s[28:29], 0x40780
	v_readfirstlane_b32 s19, v156
	s_nop 0
	ds_read_b128 v[132:135], v152
	ds_read_b128 v[138:141], v153
	ds_read_b128 v[142:145], v154
	ds_read_b128 v[146:149], v155
	ds_read_b128 v[150:153], v136
	ds_read_b128 v[170:173], v136 offset:1024
	ds_read_b128 v[174:177], v136 offset:2048
	ds_read_b128 v[190:193], v136 offset:3072
	ds_read_b128 v[194:197], v136 offset:4096
	ds_read_b128 v[204:207], v136 offset:5120
	ds_read_b128 v[208:211], v136 offset:6144
	ds_read_b128 v[212:215], v136 offset:7168
	v_lshl_add_u64 v[154:155], v[130:131], 0, s[28:29]
	s_mov_b32 m0, s19
	s_mov_b64 s[28:29], 0x60780
	v_readfirstlane_b32 s19, v157
	global_load_lds_dwordx4 v[154:155], off
	v_lshl_add_u64 v[130:131], v[130:131], 0, s[28:29]
	s_mov_b32 m0, s19
	s_nop 0
	global_load_lds_dwordx4 v[130:131], off
	s_barrier
	s_waitcnt lgkmcnt(0)
	s_setprio 1
	s_waitcnt lgkmcnt(0)
	v_mfma_f32_16x16x32_bf16 v[126:129], v[150:153], v[132:135], v[126:129]
	v_mfma_f32_16x16x32_bf16 v[122:125], v[150:153], v[142:145], v[122:125]
	v_mfma_f32_16x16x32_bf16 v[118:121], v[174:177], v[132:135], v[118:121]
	v_mfma_f32_16x16x32_bf16 v[114:117], v[174:177], v[142:145], v[114:117]
	v_mfma_f32_16x16x32_bf16 v[102:105], v[194:197], v[132:135], v[102:105]
	v_mfma_f32_16x16x32_bf16 v[98:101], v[194:197], v[142:145], v[98:101]
	v_mfma_f32_16x16x32_bf16 v[82:85], v[208:211], v[142:145], v[82:85]
	v_mfma_f32_16x16x32_bf16 v[126:129], v[170:173], v[138:141], v[126:129]
	v_mfma_f32_16x16x32_bf16 v[122:125], v[170:173], v[146:149], v[122:125]
	v_mfma_f32_16x16x32_bf16 v[118:121], v[190:193], v[138:141], v[118:121]
	v_mfma_f32_16x16x32_bf16 v[114:117], v[190:193], v[146:149], v[114:117]
	v_mfma_f32_16x16x32_bf16 v[102:105], v[204:207], v[138:141], v[102:105]
	v_mfma_f32_16x16x32_bf16 v[98:101], v[204:207], v[146:149], v[98:101]
	v_mfma_f32_16x16x32_bf16 v[86:89], v[208:211], v[132:135], v[86:89]
	v_mfma_f32_16x16x32_bf16 v[82:85], v[212:215], v[146:149], v[82:85]
	v_mfma_f32_16x16x32_bf16 v[154:157], v[212:215], v[138:141], v[86:89]
	s_setprio 0
	s_barrier
; #define LDA8(dst, b, h) _Pragma("unroll") for (int m = 0; m < 4; ++m) _Pragma("unroll") for (int k = 0; k < 2; ++k) \
;     dst[m][k] = *reinterpret_cast<const bf16x8*>(SA8(b, h) + fa_off + m * 2048 + k * 1024)
; #define LDB8(dst, b, h) _Pragma("unroll") for (int n = 0; n < 2; ++n) _Pragma("unroll") for (int k = 0; k < 2; ++k) \
;     dst[n][k] = *reinterpret_cast<const bf16x8*>(SB8(b, h) + fb_off + n * 2048 + k * 1024)
; #define WAIT_V8(n) asm volatile("s_waitcnt vmcnt(" #n ")" ::: "memory")
; #define WAIT_L8(n) asm volatile("s_waitcnt lgkmcnt(" #n ")" ::: "memory")
; #define BAR8 __builtin_amdgcn_s_barrier()
; __device__ __forceinline__ void gemm_mainloop8(const bf16_t* __restrict__ Xg, int ldx, const bf16_t* __restrict__ Wg, int ldw, ...
;     ...
;     BAR8; WAIT_L8(0); MMA8(0, 0, At, B0); BAR8;
;     LDB8(B1, 0, 1); BAR8; WAIT_L8(0); MMA8(0, 1, At, B1); BAR8;
;     LDA8(At, 0, 1); WAIT_V8(4); BAR8; WAIT_L8(0); MMA8(1, 0, At, B0); MMA8(1, 1, At, B1); BAR8; }
;   { LDB8(B0, 1, 0); LDA8(At, 1, 0); WAIT_V8(2); BAR8; WAIT_L8(0); MMA8(0, 0, At, B0); BAR8;
	s_nop 0
	s_nop 2
	ds_read_b128 v[86:89], v158
	ds_read_b128 v[216:219], v159
	ds_read_b128 v[220:223], v160
	ds_read_b128 v[158:161], v161
	s_barrier
	s_waitcnt lgkmcnt(0)
	s_setprio 1
	s_waitcnt lgkmcnt(3)
	v_mfma_f32_16x16x32_bf16 v[110:113], v[150:153], v[86:89], v[110:113]
	s_waitcnt lgkmcnt(1)
	v_mfma_f32_16x16x32_bf16 v[106:109], v[150:153], v[220:223], v[106:109]
	v_mfma_f32_16x16x32_bf16 v[78:81], v[194:197], v[86:89], v[78:81]
	v_mfma_f32_16x16x32_bf16 v[74:77], v[194:197], v[220:223], v[74:77]
	v_mfma_f32_16x16x32_bf16 v[70:73], v[208:211], v[86:89], v[70:73]
	v_mfma_f32_16x16x32_bf16 v[66:69], v[208:211], v[220:223], v[66:69]
	v_mfma_f32_16x16x32_bf16 v[110:113], v[170:173], v[216:219], v[110:113]
	s_waitcnt lgkmcnt(0)
	v_mfma_f32_16x16x32_bf16 v[106:109], v[170:173], v[158:161], v[106:109]
	v_mfma_f32_16x16x32_bf16 v[94:97], v[174:177], v[86:89], v[94:97]
	v_mfma_f32_16x16x32_bf16 v[90:93], v[174:177], v[220:223], v[90:93]
	v_mfma_f32_16x16x32_bf16 v[78:81], v[204:207], v[216:219], v[78:81]
	v_mfma_f32_16x16x32_bf16 v[74:77], v[204:207], v[158:161], v[74:77]
	v_mfma_f32_16x16x32_bf16 v[70:73], v[212:215], v[216:219], v[70:73]
	v_mfma_f32_16x16x32_bf16 v[66:69], v[212:215], v[158:161], v[66:69]
	v_mfma_f32_16x16x32_bf16 v[150:153], v[190:193], v[216:219], v[94:97]
	v_mfma_f32_16x16x32_bf16 v[170:173], v[190:193], v[158:161], v[90:93]
	s_setprio 0
	s_barrier
	s_nop 0
	ds_read_b128 v[90:93], v136 offset:16384
	ds_read_b128 v[94:97], v136 offset:17408
	ds_read_b128 v[174:177], v136 offset:18432
	ds_read_b128 v[190:193], v136 offset:19456
	ds_read_b128 v[194:197], v136 offset:20480
	ds_read_b128 v[204:207], v136 offset:21504
	ds_read_b128 v[208:211], v136 offset:22528
	ds_read_b128 v[212:215], v136 offset:23552
	s_waitcnt vmcnt(4)
	s_barrier
	s_waitcnt lgkmcnt(0)
	s_setprio 1
	s_waitcnt lgkmcnt(5)
	v_mfma_f32_16x16x32_bf16 v[46:49], v[174:177], v[142:145], v[46:49]
	s_waitcnt lgkmcnt(3)
	v_mfma_f32_16x16x32_bf16 v[38:41], v[194:197], v[132:135], v[38:41]
	s_waitcnt lgkmcnt(1)
	v_mfma_f32_16x16x32_bf16 v[14:17], v[208:211], v[142:145], v[14:17]
	v_mfma_f32_16x16x32_bf16 v[62:65], v[90:93], v[132:135], v[62:65]
	v_mfma_f32_16x16x32_bf16 v[58:61], v[90:93], v[142:145], v[58:61]
	v_mfma_f32_16x16x32_bf16 v[54:57], v[174:177], v[132:135], v[54:57]
	v_mfma_f32_16x16x32_bf16 v[46:49], v[190:193], v[146:149], v[46:49]
	v_mfma_f32_16x16x32_bf16 v[38:41], v[204:207], v[138:141], v[38:41]
	v_mfma_f32_16x16x32_bf16 v[30:33], v[194:197], v[142:145], v[30:33]
	v_mfma_f32_16x16x32_bf16 v[22:25], v[208:211], v[132:135], v[22:25]
	s_waitcnt lgkmcnt(0)
	v_mfma_f32_16x16x32_bf16 v[14:17], v[212:215], v[146:149], v[14:17]
	v_mfma_f32_16x16x32_bf16 v[224:227], v[94:97], v[138:141], v[62:65]
	v_mfma_f32_16x16x32_bf16 v[228:231], v[94:97], v[146:149], v[58:61]
	v_mfma_f32_16x16x32_bf16 v[232:235], v[190:193], v[138:141], v[54:57]
	v_mfma_f32_16x16x32_bf16 v[236:239], v[204:207], v[146:149], v[30:33]
	v_mfma_f32_16x16x32_bf16 v[130:133], v[212:215], v[138:141], v[22:25]
	s_setprio 0
	s_setprio 1
	v_mfma_f32_16x16x32_bf16 v[22:25], v[90:93], v[86:89], v[50:53]
	v_mfma_f32_16x16x32_bf16 v[138:141], v[94:97], v[216:219], v[22:25]
	v_mfma_f32_16x16x32_bf16 v[22:25], v[90:93], v[220:223], v[42:45]
	v_mfma_f32_16x16x32_bf16 v[42:45], v[94:97], v[158:161], v[22:25]
	v_mfma_f32_16x16x32_bf16 v[22:25], v[174:177], v[86:89], v[34:37]
	v_mfma_f32_16x16x32_bf16 v[2:5], v[208:211], v[220:223], v[2:5]
	v_mfma_f32_16x16x32_bf16 v[34:37], v[190:193], v[216:219], v[22:25]
	v_mfma_f32_16x16x32_bf16 v[22:25], v[174:177], v[220:223], v[26:29]
	v_mfma_f32_16x16x32_bf16 v[18:21], v[194:197], v[86:89], v[18:21]
	v_mfma_f32_16x16x32_bf16 v[10:13], v[194:197], v[220:223], v[10:13]
	v_mfma_f32_16x16x32_bf16 v[6:9], v[208:211], v[86:89], v[6:9]
	v_mfma_f32_16x16x32_bf16 v[2:5], v[212:215], v[158:161], v[2:5]
	v_mfma_f32_16x16x32_bf16 v[142:145], v[190:193], v[158:161], v[22:25]
	v_mfma_f32_16x16x32_bf16 v[146:149], v[204:207], v[216:219], v[18:21]
	v_mfma_f32_16x16x32_bf16 v[174:177], v[204:207], v[158:161], v[10:13]
	v_mfma_f32_16x16x32_bf16 v[190:193], v[212:215], v[216:219], v[6:9]
	s_setprio 0
	s_barrier
	s_nop 0
	ds_read_b128 v[6:9], v162
	ds_read_b128 v[10:13], v163
	ds_read_b128 v[158:161], v164
	ds_read_b128 v[162:165], v165
	ds_read_b128 v[18:21], v136 offset:32768
	ds_read_b128 v[22:25], v136 offset:33792
	ds_read_b128 v[26:29], v136 offset:34816
	ds_read_b128 v[50:53], v136 offset:35840
	ds_read_b128 v[194:197], v136 offset:36864
	ds_read_b128 v[204:207], v136 offset:37888
	ds_read_b128 v[208:211], v136 offset:38912
	ds_read_b128 v[212:215], v136 offset:39936
	s_waitcnt vmcnt(2)
	s_barrier
; #define LDA8(dst, b, h) _Pragma("unroll") for (int m = 0; m < 4; ++m) _Pragma("unroll") for (int k = 0; k < 2; ++k) \
;     dst[m][k] = *reinterpret_cast<const bf16x8*>(SA8(b, h) + fa_off + m * 2048 + k * 1024)
; #define LDB8(dst, b, h) _Pragma("unroll") for (int n = 0; n < 2; ++n) _Pragma("unroll") for (int k = 0; k < 2; ++k) \
;     dst[n][k] = *reinterpret_cast<const bf16x8*>(SB8(b, h) + fb_off + n * 2048 + k * 1024)
; #define WAIT_V8(n) asm volatile("s_waitcnt vmcnt(" #n ")" ::: "memory")
; #define WAIT_L8(n) asm volatile("s_waitcnt lgkmcnt(" #n ")" ::: "memory")
; #define BAR8 __builtin_amdgcn_s_barrier()
; __device__ __forceinline__ void gemm_mainloop8(const bf16_t* __restrict__ Xg, int ldx, const bf16_t* __restrict__ Wg, int ldw, ...
;     ...
;   { LDB8(B0, 1, 0); LDA8(At, 1, 0); WAIT_V8(2); BAR8; WAIT_L8(0); MMA8(0, 0, At, B0); BAR8;
;     LDB8(B1, 1, 1); WAIT_V8(0); BAR8; WAIT_L8(0); MMA8(0, 1, At, B1); BAR8;
;     LDA8(At, 1, 1); BAR8; WAIT_L8(0); MMA8(1, 0, At, B0); MMA8(1, 1, At, B1); BAR8; }
;   if (wr == 0) BAR8;
	s_waitcnt lgkmcnt(0)
	s_setprio 1
	s_waitcnt lgkmcnt(7)
	v_mfma_f32_16x16x32_bf16 v[30:33], v[18:21], v[6:9], v[126:129]
	s_waitcnt lgkmcnt(6)
	v_mfma_f32_16x16x32_bf16 v[126:129], v[22:25], v[10:13], v[30:33]
	v_mfma_f32_16x16x32_bf16 v[30:33], v[18:21], v[158:161], v[122:125]
	v_mfma_f32_16x16x32_bf16 v[94:97], v[22:25], v[162:165], v[30:33]
	s_waitcnt lgkmcnt(5)
	v_mfma_f32_16x16x32_bf16 v[30:33], v[26:29], v[6:9], v[118:121]
	s_waitcnt lgkmcnt(4)
	v_mfma_f32_16x16x32_bf16 v[122:125], v[50:53], v[10:13], v[30:33]
	v_mfma_f32_16x16x32_bf16 v[30:33], v[26:29], v[158:161], v[114:117]
	v_mfma_f32_16x16x32_bf16 v[90:93], v[50:53], v[162:165], v[30:33]
	s_waitcnt lgkmcnt(3)
	v_mfma_f32_16x16x32_bf16 v[30:33], v[194:197], v[6:9], v[102:105]
	s_waitcnt lgkmcnt(2)
	v_mfma_f32_16x16x32_bf16 v[118:121], v[204:207], v[10:13], v[30:33]
	v_mfma_f32_16x16x32_bf16 v[30:33], v[194:197], v[158:161], v[98:101]
	v_mfma_f32_16x16x32_bf16 v[86:89], v[204:207], v[162:165], v[30:33]
	s_waitcnt lgkmcnt(1)
	v_mfma_f32_16x16x32_bf16 v[30:33], v[208:211], v[6:9], v[154:157]
	s_waitcnt lgkmcnt(0)
	v_mfma_f32_16x16x32_bf16 v[114:117], v[212:215], v[10:13], v[30:33]
	v_mfma_f32_16x16x32_bf16 v[30:33], v[208:211], v[158:161], v[82:85]
	v_mfma_f32_16x16x32_bf16 v[82:85], v[212:215], v[162:165], v[30:33]
	s_setprio 0
	s_barrier
	ds_read_b128 v[154:157], v166
	ds_read_b128 v[216:219], v167
	ds_read_b128 v[220:223], v168
	ds_read_b128 v[166:169], v169
	s_waitcnt vmcnt(0)
	s_barrier
	s_waitcnt lgkmcnt(0)
	s_setprio 1
	s_waitcnt lgkmcnt(3)
	v_mfma_f32_16x16x32_bf16 v[30:33], v[18:21], v[154:157], v[110:113]
	s_waitcnt lgkmcnt(1)
	v_mfma_f32_16x16x32_bf16 v[18:21], v[18:21], v[220:223], v[106:109]
	v_mfma_f32_16x16x32_bf16 v[62:65], v[22:25], v[216:219], v[30:33]
	s_waitcnt lgkmcnt(0)
	v_mfma_f32_16x16x32_bf16 v[30:33], v[22:25], v[166:169], v[18:21]
	v_mfma_f32_16x16x32_bf16 v[18:21], v[26:29], v[154:157], v[150:153]
	v_mfma_f32_16x16x32_bf16 v[58:61], v[50:53], v[216:219], v[18:21]
	v_mfma_f32_16x16x32_bf16 v[18:21], v[26:29], v[220:223], v[170:173]
	v_mfma_f32_16x16x32_bf16 v[26:29], v[50:53], v[166:169], v[18:21]
	v_mfma_f32_16x16x32_bf16 v[18:21], v[194:197], v[154:157], v[78:81]
	v_mfma_f32_16x16x32_bf16 v[54:57], v[204:207], v[216:219], v[18:21]
	v_mfma_f32_16x16x32_bf16 v[18:21], v[194:197], v[220:223], v[74:77]
	v_mfma_f32_16x16x32_bf16 v[22:25], v[204:207], v[166:169], v[18:21]
	v_mfma_f32_16x16x32_bf16 v[18:21], v[208:211], v[154:157], v[70:73]
	v_mfma_f32_16x16x32_bf16 v[50:53], v[212:215], v[216:219], v[18:21]
	v_mfma_f32_16x16x32_bf16 v[18:21], v[208:211], v[220:223], v[66:69]
	v_mfma_f32_16x16x32_bf16 v[18:21], v[212:215], v[166:169], v[18:21]
	s_setprio 0
	s_barrier
	ds_read_b128 v[150:153], v136 offset:49152
	ds_read_b128 v[170:173], v136 offset:50176
	ds_read_b128 v[194:197], v136 offset:51200
	ds_read_b128 v[204:207], v136 offset:52224
	ds_read_b128 v[208:211], v136 offset:53248
	ds_read_b128 v[212:215], v136 offset:54272
	ds_read_b128 v[240:243], v136 offset:55296
	ds_read_b128 v[134:137], v136 offset:56320
	s_barrier
	s_waitcnt lgkmcnt(0)
	s_setprio 1
	s_waitcnt lgkmcnt(7)
	v_mfma_f32_16x16x32_bf16 v[66:69], v[150:153], v[6:9], v[224:227]
	s_waitcnt lgkmcnt(6)
	v_mfma_f32_16x16x32_bf16 v[110:113], v[170:173], v[10:13], v[66:69]
	v_mfma_f32_16x16x32_bf16 v[66:69], v[150:153], v[158:161], v[228:231]
	v_mfma_f32_16x16x32_bf16 v[78:81], v[170:173], v[162:165], v[66:69]
	s_waitcnt lgkmcnt(5)
	v_mfma_f32_16x16x32_bf16 v[66:69], v[194:197], v[6:9], v[232:235]
	s_waitcnt lgkmcnt(3)
	v_mfma_f32_16x16x32_bf16 v[38:41], v[208:211], v[6:9], v[38:41]
	s_waitcnt lgkmcnt(1)
	v_mfma_f32_16x16x32_bf16 v[6:9], v[240:243], v[6:9], v[130:133]
	v_mfma_f32_16x16x32_bf16 v[46:49], v[194:197], v[158:161], v[46:49]
	v_mfma_f32_16x16x32_bf16 v[102:105], v[212:215], v[10:13], v[38:41]
	v_mfma_f32_16x16x32_bf16 v[38:41], v[208:211], v[158:161], v[236:239]
	s_waitcnt lgkmcnt(0)
	v_mfma_f32_16x16x32_bf16 v[98:101], v[134:137], v[10:13], v[6:9]
	v_mfma_f32_16x16x32_bf16 v[6:9], v[240:243], v[158:161], v[14:17]
	v_mfma_f32_16x16x32_bf16 v[106:109], v[204:207], v[10:13], v[66:69]
	v_mfma_f32_16x16x32_bf16 v[74:77], v[204:207], v[162:165], v[46:49]
	v_mfma_f32_16x16x32_bf16 v[70:73], v[212:215], v[162:165], v[38:41]
	v_mfma_f32_16x16x32_bf16 v[66:69], v[134:137], v[162:165], v[6:9]
	s_setprio 0
	s_setprio 1
	v_mfma_f32_16x16x32_bf16 v[6:9], v[150:153], v[154:157], v[138:141]
	v_mfma_f32_16x16x32_bf16 v[46:49], v[170:173], v[216:219], v[6:9]
	v_mfma_f32_16x16x32_bf16 v[6:9], v[150:153], v[220:223], v[42:45]
	v_mfma_f32_16x16x32_bf16 v[14:17], v[170:173], v[166:169], v[6:9]
	v_mfma_f32_16x16x32_bf16 v[6:9], v[194:197], v[154:157], v[34:37]
	v_mfma_f32_16x16x32_bf16 v[42:45], v[204:207], v[216:219], v[6:9]
	v_mfma_f32_16x16x32_bf16 v[6:9], v[194:197], v[220:223], v[142:145]
	v_mfma_f32_16x16x32_bf16 v[10:13], v[204:207], v[166:169], v[6:9]
	v_mfma_f32_16x16x32_bf16 v[6:9], v[208:211], v[154:157], v[146:149]
	v_mfma_f32_16x16x32_bf16 v[38:41], v[212:215], v[216:219], v[6:9]
	v_mfma_f32_16x16x32_bf16 v[6:9], v[208:211], v[220:223], v[174:177]
	v_mfma_f32_16x16x32_bf16 v[34:37], v[240:243], v[154:157], v[190:193]
	v_mfma_f32_16x16x32_bf16 v[2:5], v[240:243], v[220:223], v[2:5]
	v_mfma_f32_16x16x32_bf16 v[6:9], v[212:215], v[166:169], v[6:9]
	v_mfma_f32_16x16x32_bf16 v[34:37], v[134:137], v[216:219], v[34:37]
	v_mfma_f32_16x16x32_bf16 v[2:5], v[134:137], v[166:169], v[2:5]
	s_setprio 0
	s_movk_i32 s19, 0x100
	v_cmp_gt_u32_e32 vcc, s19, v0
	s_barrier
	s_and_saveexec_b64 s[28:29], vcc
	s_cbranch_execz .LBB0_295
	s_barrier

; #define STAGE8(P, BASE, LD, OFF, br, kt) do { const bf16_t* g_ = (BASE) + (long)(br) * (LD) + (long)(kt) * 64 + (OFF); \
;     __builtin_amdgcn_global_load_lds((const unsigned*)(g_), (unsigned*)((char*)(P) + tid8 * 16), 16, 0, 0);            \
;     __builtin_amdgcn_global_load_lds((const unsigned*)(g_ + 64 * (long)(LD)), (unsigned*)((char*)(P) + tid8 * 16 + 8192), 16, 0, 0); } while (0)
; #define WAIT_V8(n) asm volatile("s_waitcnt vmcnt(" #n ")" ::: "memory")
; #define BAR8 __builtin_amdgcn_s_barrier()
; __device__ __forceinline__ void gemm_mainloop8(const bf16_t* __restrict__ Xg, int ldx, const bf16_t* __restrict__ Wg, int ldw, ...
;     ...
;   const int tid8 = opaque_tid();
;   const int wid = tid8 >> 6, lane = tid8 & 63, wr = wid >> 2, wc = wid & 3, fr = lane & 15, fq = lane >> 4;
;   const bf16_t* A = Wg;
;   const bf16_t* Bt = Xg;
;   int r0_, c0_;
;   stage_rc128(tid8 * 16, r0_, c0_);
;   const int offA = r0_ * ldw + c0_, offB = r0_ * ldx + c0_;
;   const int ob_sw = (fr * 64 + fq * 16) ^ (((fr >> 3) & 1) << 5);
;   const int fa_off = wr * 8192 + ob_sw, fb_off = wc * 4096 + ob_sw;
;   asm volatile("s_waitcnt vmcnt(0)" ::: "memory");
;   bf16x8 At[4][2], B0[2][2], B1[2][2];
;   const int nt = K / 64;
;   if (!prefetched) {
;     STAGE8(SB8(0, 0), Bt, ldx, offB, 0, 0); STAGE8(SA8(0, 0), A, ldw, offA, 0, 0);
;     STAGE8(SB8(0, 1), Bt, ldx, offB, 128, 0); STAGE8(SA8(0, 1), A, ldw, offA, 128, 0);
;   }
;   if (wr == 1) BAR8;
;   if (prefetched) { WAIT_V8(0); } else { WAIT_V8(4); }
;   BAR8;
;   STAGE8(SB8(1, 0), Bt, ldx, offB, 0, 1); STAGE8(SA8(1, 0), A, ldw, offA, 0, 1); STAGE8(SB8(1, 1), Bt, ldx, offB, 128, 1);
;   WAIT_V8(6); BAR8;
; template <int MB>
; __device__ __forceinline__ void zero_acc(f32x4 (&acc)[8][MB]) {
; #pragma unroll
;   for (int a = 0; a < 8; ++a)
; #pragma unroll
;     for (int b = 0; b < MB; ++b) acc[a][b] = f32x4{0.f, 0.f, 0.f, 0.f};
.LBB0_297:
	s_or_b64 exec, exec, s[24:25]
	v_lshlrev_b32_e32 v12, 6, v0
	v_lshlrev_b32_e32 v15, 2, v0
	v_and_b32_e32 v11, 48, v0
	v_and_b32_e32 v13, 0x3c0, v12
	v_and_b32_e32 v15, 32, v15
	v_or_b32_e32 v14, v13, v11
	v_bitop3_b32 v11, v13, v15, v11 bitop3:0x36
	s_movk_i32 s19, 0x3000
	v_add_u32_e32 v146, 0x18000, v136
	v_lshlrev_b32_e32 v10, 13, v10
	v_and_or_b32 v145, v12, s19, v11
	s_mov_b64 s[24:25], 0x880
	v_readfirstlane_b32 s19, v146
	v_add_u32_e32 v147, 0x1a000, v136
	v_bitop3_b32 v141, v14, v10, v15 bitop3:0xde
	v_lshl_add_u64 v[10:11], v[4:5], 0, s[24:25]
	s_mov_b32 m0, s19
	s_mov_b64 s[24:25], 0x40880
	v_readfirstlane_b32 s19, v147
	v_add_u32_e32 v148, 0x8000, v136
	s_waitcnt vmcnt(2)
	s_barrier
	global_load_lds_dwordx4 v[10:11], off
	v_lshl_add_u64 v[10:11], v[4:5], 0, s[24:25]
	s_mov_b32 m0, s19
	v_readfirstlane_b32 s19, v148
	v_add_u32_e32 v149, 0xa000, v136
	global_load_lds_dwordx4 v[10:11], off
	v_lshl_add_u64 v[10:11], v[130:131], 0, s[36:37]
	s_mov_b32 m0, s19
	s_mov_b64 s[24:25], 0x20080
	v_readfirstlane_b32 s19, v149
	v_add_u32_e32 v150, 0x1c000, v136
	global_load_lds_dwordx4 v[10:11], off
	v_lshl_add_u64 v[10:11], v[130:131], 0, s[24:25]
	s_mov_b32 m0, s19
	s_mov_b64 s[24:25], 0x80880
	v_readfirstlane_b32 s19, v150
	v_add_u32_e32 v151, 0x1e000, v136
	global_load_lds_dwordx4 v[10:11], off
	v_lshl_add_u64 v[10:11], v[4:5], 0, s[24:25]
	s_mov_b32 m0, s19
	s_mov_b64 s[24:25], 0xc0880
	v_readfirstlane_b32 s19, v151
	global_load_lds_dwordx4 v[10:11], off
	v_lshl_add_u64 v[4:5], v[4:5], 0, s[24:25]
	s_mov_b32 m0, s19
	s_add_u32 s20, s2, s20
	global_load_lds_dwordx4 v[4:5], off
	v_lshlrev_b32_e32 v4, 14, v6
	v_and_b32_e32 v4, 0xffff8000, v4
	v_lshl_add_u32 v4, v7, 11, v4
	v_or_b32_e32 v4, v4, v8
	v_add_u32_e32 v4, v4, v9
	v_ashrrev_i32_e32 v5, 31, v4
	s_addc_u32 s21, s3, s21
	v_lshl_add_u64 v[132:133], v[4:5], 1, s[20:21]
	s_add_u32 s20, s10, s22
	s_waitcnt vmcnt(6)
	s_addc_u32 s21, s11, s23
	v_lshl_add_u64 v[134:135], v[2:3], 1, s[20:21]
	v_mov_b32_e32 v2, 0
	s_mov_b32 s19, -2
	s_mov_b64 s[20:21], 0
	v_mov_b32_e32 v3, v2
	v_mov_b32_e32 v4, v2
	v_mov_b32_e32 v5, v2
	v_mov_b32_e32 v6, v2
	v_mov_b32_e32 v7, v2
	v_mov_b32_e32 v8, v2
	v_mov_b32_e32 v9, v2
	v_mov_b32_e32 v14, v2
	v_mov_b32_e32 v15, v2
	v_mov_b32_e32 v16, v2
	v_mov_b32_e32 v17, v2
	v_mov_b32_e32 v22, v2
	v_mov_b32_e32 v23, v2
	v_mov_b32_e32 v24, v2
	v_mov_b32_e32 v25, v2
	v_mov_b32_e32 v10, v2
	v_mov_b32_e32 v11, v2
	v_mov_b32_e32 v12, v2
	v_mov_b32_e32 v13, v2
	v_mov_b32_e32 v18, v2
	v_mov_b32_e32 v19, v2
	v_mov_b32_e32 v20, v2
	v_mov_b32_e32 v21, v2
	v_mov_b32_e32 v30, v2
	v_mov_b32_e32 v31, v2
	v_mov_b32_e32 v32, v2
	v_mov_b32_e32 v33, v2
	v_mov_b32_e32 v38, v2
	v_mov_b32_e32 v39, v2
	v_mov_b32_e32 v40, v2
	v_mov_b32_e32 v41, v2
	v_mov_b32_e32 v26, v2
	v_mov_b32_e32 v27, v2
	v_mov_b32_e32 v28, v2
	v_mov_b32_e32 v29, v2
	v_mov_b32_e32 v34, v2
	v_mov_b32_e32 v35, v2
	v_mov_b32_e32 v36, v2
	v_mov_b32_e32 v37, v2
	v_mov_b32_e32 v46, v2
	v_mov_b32_e32 v47, v2
	v_mov_b32_e32 v48, v2
	v_mov_b32_e32 v49, v2
	v_mov_b32_e32 v54, v2
	v_mov_b32_e32 v55, v2
	v_mov_b32_e32 v56, v2
	v_mov_b32_e32 v57, v2
	v_mov_b32_e32 v42, v2
	v_mov_b32_e32 v43, v2
	v_mov_b32_e32 v44, v2
	v_mov_b32_e32 v45, v2
	v_mov_b32_e32 v50, v2
	v_mov_b32_e32 v51, v2
	v_mov_b32_e32 v52, v2
	v_mov_b32_e32 v53, v2
	v_mov_b32_e32 v58, v2
	v_mov_b32_e32 v59, v2
	v_mov_b32_e32 v60, v2
	v_mov_b32_e32 v61, v2
	v_mov_b32_e32 v62, v2
	v_mov_b32_e32 v63, v2
	v_mov_b32_e32 v64, v2
	v_mov_b32_e32 v65, v2
	v_mov_b32_e32 v66, v2
	v_mov_b32_e32 v67, v2
	v_mov_b32_e32 v68, v2
	v_mov_b32_e32 v69, v2
	v_mov_b32_e32 v70, v2
	v_mov_b32_e32 v71, v2
	v_mov_b32_e32 v72, v2
	v_mov_b32_e32 v73, v2
	v_mov_b32_e32 v82, v2
	v_mov_b32_e32 v83, v2
	v_mov_b32_e32 v84, v2
	v_mov_b32_e32 v85, v2
	v_mov_b32_e32 v86, v2
	v_mov_b32_e32 v87, v2
	v_mov_b32_e32 v88, v2
	v_mov_b32_e32 v89, v2
	v_mov_b32_e32 v74, v2
	v_mov_b32_e32 v75, v2
	v_mov_b32_e32 v76, v2
	v_mov_b32_e32 v77, v2
	v_mov_b32_e32 v78, v2
	v_mov_b32_e32 v79, v2
	v_mov_b32_e32 v80, v2
	v_mov_b32_e32 v81, v2
	v_mov_b32_e32 v98, v2
	v_mov_b32_e32 v99, v2
	v_mov_b32_e32 v100, v2
	v_mov_b32_e32 v101, v2
	v_mov_b32_e32 v102, v2
	v_mov_b32_e32 v103, v2
	v_mov_b32_e32 v104, v2
	v_mov_b32_e32 v105, v2
	v_mov_b32_e32 v90, v2
	v_mov_b32_e32 v91, v2
	v_mov_b32_e32 v92, v2
	v_mov_b32_e32 v93, v2
	v_mov_b32_e32 v94, v2
	v_mov_b32_e32 v95, v2
	v_mov_b32_e32 v96, v2
	v_mov_b32_e32 v97, v2
	v_mov_b32_e32 v114, v2
	v_mov_b32_e32 v115, v2
	v_mov_b32_e32 v116, v2
	v_mov_b32_e32 v117, v2
	v_mov_b32_e32 v118, v2
	v_mov_b32_e32 v119, v2
	v_mov_b32_e32 v120, v2
	v_mov_b32_e32 v121, v2
	v_mov_b32_e32 v106, v2
	v_mov_b32_e32 v107, v2
	v_mov_b32_e32 v108, v2
	v_mov_b32_e32 v109, v2
	v_mov_b32_e32 v110, v2
	v_mov_b32_e32 v111, v2
	v_mov_b32_e32 v112, v2
	v_mov_b32_e32 v113, v2
	v_mov_b32_e32 v122, v2
	v_mov_b32_e32 v123, v2
	v_mov_b32_e32 v124, v2
	v_mov_b32_e32 v125, v2
	v_mov_b32_e32 v126, v2
	v_mov_b32_e32 v127, v2
	v_mov_b32_e32 v128, v2
	v_mov_b32_e32 v129, v2
	s_barrier
; #define STAGE8(P, BASE, LD, OFF, br, kt) do { const bf16_t* g_ = (BASE) + (long)(br) * (LD) + (long)(kt) * 64 + (OFF); \
;     __builtin_amdgcn_global_load_lds((const unsigned*)(g_), (unsigned*)((char*)(P) + tid8 * 16), 16, 0, 0);            \
;     __builtin_amdgcn_global_load_lds((const unsigned*)(g_ + 64 * (long)(LD)), (unsigned*)((char*)(P) + tid8 * 16 + 8192), 16, 0, 0); } while (0)
; #define LDA8(dst, b, h) _Pragma("unroll") for (int m = 0; m < 4; ++m) _Pragma("unroll") for (int k = 0; k < 2; ++k) \
;     dst[m][k] = *reinterpret_cast<const bf16x8*>(SA8(b, h) + fa_off + m * 2048 + k * 1024)
; #define LDB8(dst, b, h) _Pragma("unroll") for (int n = 0; n < 2; ++n) _Pragma("unroll") for (int k = 0; k < 2; ++k) \
;     dst[n][k] = *reinterpret_cast<const bf16x8*>(SB8(b, h) + fb_off + n * 2048 + k * 1024)
; #define WAIT_V8(n) asm volatile("s_waitcnt vmcnt(" #n ")" ::: "memory")
; #define WAIT_L8(n) asm volatile("s_waitcnt lgkmcnt(" #n ")" ::: "memory")
; #define BAR8 __builtin_amdgcn_s_barrier()
; #define SCHED8 __builtin_amdgcn_sched_barrier(0)
; __device__ __forceinline__ void gemm_mainloop8(const bf16_t* __restrict__ Xg, int ldx, const bf16_t* __restrict__ Wg, int ldw, ...
;     ...
;   for (int t = 0; t < nt - 2; t += 2) {
;     LDB8(B0, 0, 0); SCHED8; LDA8(At, 0, 0); STAGE8(SA8(1, 1), A, ldw, offA, 128, t + 1);
;     WAIT_L8(8); BAR8; WAIT_L8(0); MMA8(0, 0, At, B0); BAR8; SCHED8;
;     LDB8(B1, 0, 1); STAGE8(SB8(0, 0), Bt, ldx, offB, 0, t + 2);
;     BAR8; WAIT_L8(0); MMA8(0, 1, At, B1); BAR8;
;     LDA8(At, 0, 1); STAGE8(SA8(0, 0), A, ldw, offA, 0, t + 2);
;     BAR8; WAIT_L8(0); MMA8(1, 0, At, B0); BAR8; SCHED8;
;     STAGE8(SB8(0, 1), Bt, ldx, offB, 128, t + 2);
;     WAIT_V8(6); BAR8; MMA8(1, 1, At, B1); BAR8;
.LBB0_298:
	v_or_b32_e32 v152, 0x10000, v145
	v_add_u32_e32 v153, 0x10400, v145
	v_add_u32_e32 v154, 0x10800, v145
	v_add_u32_e32 v155, 0x10c00, v145
	v_or_b32_e32 v158, 0x14000, v145
	v_add_u32_e32 v159, 0x14400, v145
	v_add_u32_e32 v160, 0x14800, v145
	v_add_u32_e32 v161, 0x14c00, v145
	v_add_u32_e32 v156, 0xc000, v136
	v_add_u32_e32 v157, 0xe000, v136
	v_lshl_add_u64 v[178:179], v[134:135], 0, s[20:21]
	v_lshl_add_u64 v[180:181], v[132:133], 0, s[20:21]
	ds_read_b128 v[162:165], v152
	ds_read_b128 v[166:169], v153
	ds_read_b128 v[170:173], v154
	ds_read_b128 v[174:177], v155
	ds_read_b128 v[190:193], v141
	ds_read_b128 v[194:197], v141 offset:1024
	ds_read_b128 v[204:207], v141 offset:2048
	ds_read_b128 v[208:211], v141 offset:3072
	ds_read_b128 v[212:215], v141 offset:4096
	ds_read_b128 v[216:219], v141 offset:5120
	ds_read_b128 v[220:223], v141 offset:6144
	ds_read_b128 v[224:227], v141 offset:7168
	ds_read_b128 v[228:231], v158
	ds_read_b128 v[232:235], v159
	ds_read_b128 v[236:239], v160
	ds_read_b128 v[240:243], v161
	v_lshl_add_u64 v[186:187], v[178:179], 0, s[0:1]
	v_readfirstlane_b32 s22, v156
	s_nop 0
	s_mov_b32 m0, s22
	s_nop 0
	global_load_lds_dwordx4 v[186:187], off
	v_lshl_add_u64 v[186:187], v[178:179], 0, s[84:85]
	v_readfirstlane_b32 s22, v157
	s_nop 0
	s_mov_b32 m0, s22
	s_nop 0
	global_load_lds_dwordx4 v[186:187], off
	s_waitcnt lgkmcnt(0)
	s_barrier
	s_setprio 1
	v_mfma_f32_16x16x32_bf16 v[126:129], v[190:193], v[162:165], v[126:129]
	v_mfma_f32_16x16x32_bf16 v[122:125], v[190:193], v[170:173], v[122:125]
	v_mfma_f32_16x16x32_bf16 v[118:121], v[204:207], v[162:165], v[118:121]
	v_mfma_f32_16x16x32_bf16 v[114:117], v[204:207], v[170:173], v[114:117]
	v_mfma_f32_16x16x32_bf16 v[102:105], v[212:215], v[162:165], v[102:105]
	v_mfma_f32_16x16x32_bf16 v[98:101], v[212:215], v[170:173], v[98:101]
	v_mfma_f32_16x16x32_bf16 v[86:89], v[220:223], v[162:165], v[86:89]
	v_mfma_f32_16x16x32_bf16 v[82:85], v[220:223], v[170:173], v[82:85]
	v_mfma_f32_16x16x32_bf16 v[126:129], v[194:197], v[166:169], v[126:129]
	v_mfma_f32_16x16x32_bf16 v[122:125], v[194:197], v[174:177], v[122:125]
	v_mfma_f32_16x16x32_bf16 v[118:121], v[208:211], v[166:169], v[118:121]
	v_mfma_f32_16x16x32_bf16 v[114:117], v[208:211], v[174:177], v[114:117]
	v_mfma_f32_16x16x32_bf16 v[102:105], v[216:219], v[166:169], v[102:105]
	v_mfma_f32_16x16x32_bf16 v[98:101], v[216:219], v[174:177], v[98:101]
	v_mfma_f32_16x16x32_bf16 v[86:89], v[224:227], v[166:169], v[86:89]
	v_mfma_f32_16x16x32_bf16 v[82:85], v[224:227], v[174:177], v[82:85]
	v_mfma_f32_16x16x32_bf16 v[110:113], v[190:193], v[228:231], v[110:113]
	v_mfma_f32_16x16x32_bf16 v[106:109], v[190:193], v[236:239], v[106:109]
	v_mfma_f32_16x16x32_bf16 v[94:97], v[204:207], v[228:231], v[94:97]
	v_mfma_f32_16x16x32_bf16 v[90:93], v[204:207], v[236:239], v[90:93]
	v_mfma_f32_16x16x32_bf16 v[78:81], v[212:215], v[228:231], v[78:81]
	v_mfma_f32_16x16x32_bf16 v[74:77], v[212:215], v[236:239], v[74:77]
	v_mfma_f32_16x16x32_bf16 v[70:73], v[220:223], v[228:231], v[70:73]
	v_mfma_f32_16x16x32_bf16 v[66:69], v[220:223], v[236:239], v[66:69]
	v_mfma_f32_16x16x32_bf16 v[110:113], v[194:197], v[232:235], v[110:113]
	v_mfma_f32_16x16x32_bf16 v[106:109], v[194:197], v[240:243], v[106:109]
	v_mfma_f32_16x16x32_bf16 v[94:97], v[208:211], v[232:235], v[94:97]
	v_mfma_f32_16x16x32_bf16 v[90:93], v[208:211], v[240:243], v[90:93]
	v_mfma_f32_16x16x32_bf16 v[78:81], v[216:219], v[232:235], v[78:81]
	v_mfma_f32_16x16x32_bf16 v[74:77], v[216:219], v[240:243], v[74:77]
	v_mfma_f32_16x16x32_bf16 v[70:73], v[224:227], v[232:235], v[70:73]
	v_mfma_f32_16x16x32_bf16 v[66:69], v[224:227], v[240:243], v[66:69]
	s_setprio 0
	s_barrier
	ds_read_b128 v[190:193], v141 offset:16384
	ds_read_b128 v[194:197], v141 offset:17408
	ds_read_b128 v[204:207], v141 offset:18432
	ds_read_b128 v[208:211], v141 offset:19456
	ds_read_b128 v[212:215], v141 offset:20480
	ds_read_b128 v[216:219], v141 offset:21504
	ds_read_b128 v[220:223], v141 offset:22528
	ds_read_b128 v[224:227], v141 offset:23552
	s_mov_b64 s[22:23], 0x900
	v_lshl_add_u64 v[186:187], v[180:181], 0, s[22:23]
	v_readfirstlane_b32 s22, v137
	s_nop 0
	s_mov_b32 m0, s22
	s_nop 0
	global_load_lds_dwordx4 v[186:187], off
	s_mov_b64 s[22:23], 0x40900
	v_lshl_add_u64 v[186:187], v[180:181], 0, s[22:23]
	v_readfirstlane_b32 s22, v138
	s_nop 0
	s_mov_b32 m0, s22
	s_nop 0
	global_load_lds_dwordx4 v[186:187], off
	v_lshl_add_u64 v[186:187], v[178:179], 0, s[70:71]
	v_readfirstlane_b32 s22, v136
	s_nop 0
	s_mov_b32 m0, s22
	s_nop 0
	global_load_lds_dwordx4 v[186:187], off
	v_lshl_add_u64 v[186:187], v[178:179], 0, s[64:65]
	v_readfirstlane_b32 s22, v139
	s_nop 0
	s_mov_b32 m0, s22
	s_nop 0
	global_load_lds_dwordx4 v[186:187], off
	s_mov_b64 s[22:23], 0x80900
	v_lshl_add_u64 v[186:187], v[180:181], 0, s[22:23]
	v_readfirstlane_b32 s22, v140
	s_nop 0
	s_mov_b32 m0, s22
	s_nop 0
	global_load_lds_dwordx4 v[186:187], off
	s_mov_b64 s[22:23], 0xc0900
	v_lshl_add_u64 v[186:187], v[180:181], 0, s[22:23]
	v_readfirstlane_b32 s22, v142
	s_nop 0
	s_mov_b32 m0, s22
	s_nop 0
	global_load_lds_dwordx4 v[186:187], off
	s_waitcnt vmcnt(6)
	s_waitcnt lgkmcnt(0)
	s_barrier
; #define STAGE8(P, BASE, LD, OFF, br, kt) do { const bf16_t* g_ = (BASE) + (long)(br) * (LD) + (long)(kt) * 64 + (OFF); \
;     __builtin_amdgcn_global_load_lds((const unsigned*)(g_), (unsigned*)((char*)(P) + tid8 * 16), 16, 0, 0);            \
;     __builtin_amdgcn_global_load_lds((const unsigned*)(g_ + 64 * (long)(LD)), (unsigned*)((char*)(P) + tid8 * 16 + 8192), 16, 0, 0); } while (0)
; #define LDA8(dst, b, h) _Pragma("unroll") for (int m = 0; m < 4; ++m) _Pragma("unroll") for (int k = 0; k < 2; ++k) \
;     dst[m][k] = *reinterpret_cast<const bf16x8*>(SA8(b, h) + fa_off + m * 2048 + k * 1024)
; #define LDB8(dst, b, h) _Pragma("unroll") for (int n = 0; n < 2; ++n) _Pragma("unroll") for (int k = 0; k < 2; ++k) \
;     dst[n][k] = *reinterpret_cast<const bf16x8*>(SB8(b, h) + fb_off + n * 2048 + k * 1024)
; #define WAIT_V8(n) asm volatile("s_waitcnt vmcnt(" #n ")" ::: "memory")
; #define WAIT_L8(n) asm volatile("s_waitcnt lgkmcnt(" #n ")" ::: "memory")
; #define BAR8 __builtin_amdgcn_s_barrier()
; #define SCHED8 __builtin_amdgcn_sched_barrier(0)
; __device__ __forceinline__ void gemm_mainloop8(const bf16_t* __restrict__ Xg, int ldx, const bf16_t* __restrict__ Wg, int ldw, ...
;     ...
;     WAIT_V8(6); BAR8; MMA8(1, 1, At, B1); BAR8;
;     LDB8(B0, 1, 0); SCHED8; LDA8(At, 1, 0); STAGE8(SA8(0, 1), A, ldw, offA, 128, t + 2);
;     WAIT_L8(8); BAR8; WAIT_L8(0); MMA8(0, 0, At, B0); BAR8; SCHED8;
;     LDB8(B1, 1, 1); STAGE8(SB8(1, 0), Bt, ldx, offB, 0, t + 3);
;     BAR8; WAIT_L8(0); MMA8(0, 1, At, B1); BAR8;
	s_setprio 1
	v_mfma_f32_16x16x32_bf16 v[62:65], v[190:193], v[162:165], v[62:65]
	v_mfma_f32_16x16x32_bf16 v[58:61], v[190:193], v[170:173], v[58:61]
	v_mfma_f32_16x16x32_bf16 v[54:57], v[204:207], v[162:165], v[54:57]
	v_mfma_f32_16x16x32_bf16 v[46:49], v[204:207], v[170:173], v[46:49]
	v_mfma_f32_16x16x32_bf16 v[38:41], v[212:215], v[162:165], v[38:41]
	v_mfma_f32_16x16x32_bf16 v[30:33], v[212:215], v[170:173], v[30:33]
	v_mfma_f32_16x16x32_bf16 v[22:25], v[220:223], v[162:165], v[22:25]
	v_mfma_f32_16x16x32_bf16 v[14:17], v[220:223], v[170:173], v[14:17]
	v_mfma_f32_16x16x32_bf16 v[62:65], v[194:197], v[166:169], v[62:65]
	v_mfma_f32_16x16x32_bf16 v[58:61], v[194:197], v[174:177], v[58:61]
	v_mfma_f32_16x16x32_bf16 v[54:57], v[208:211], v[166:169], v[54:57]
	v_mfma_f32_16x16x32_bf16 v[46:49], v[208:211], v[174:177], v[46:49]
	v_mfma_f32_16x16x32_bf16 v[38:41], v[216:219], v[166:169], v[38:41]
	v_mfma_f32_16x16x32_bf16 v[30:33], v[216:219], v[174:177], v[30:33]
	v_mfma_f32_16x16x32_bf16 v[22:25], v[224:227], v[166:169], v[22:25]
	v_mfma_f32_16x16x32_bf16 v[14:17], v[224:227], v[174:177], v[14:17]
	v_mfma_f32_16x16x32_bf16 v[50:53], v[190:193], v[228:231], v[50:53]
	v_mfma_f32_16x16x32_bf16 v[42:45], v[190:193], v[236:239], v[42:45]
	v_mfma_f32_16x16x32_bf16 v[34:37], v[204:207], v[228:231], v[34:37]
	v_mfma_f32_16x16x32_bf16 v[26:29], v[204:207], v[236:239], v[26:29]
	v_mfma_f32_16x16x32_bf16 v[18:21], v[212:215], v[228:231], v[18:21]
	v_mfma_f32_16x16x32_bf16 v[10:13], v[212:215], v[236:239], v[10:13]
	v_mfma_f32_16x16x32_bf16 v[6:9], v[220:223], v[228:231], v[6:9]
	v_mfma_f32_16x16x32_bf16 v[2:5], v[220:223], v[236:239], v[2:5]
	v_mfma_f32_16x16x32_bf16 v[50:53], v[194:197], v[232:235], v[50:53]
	v_mfma_f32_16x16x32_bf16 v[42:45], v[194:197], v[240:243], v[42:45]
	v_mfma_f32_16x16x32_bf16 v[34:37], v[208:211], v[232:235], v[34:37]
	v_mfma_f32_16x16x32_bf16 v[26:29], v[208:211], v[240:243], v[26:29]
	v_mfma_f32_16x16x32_bf16 v[18:21], v[216:219], v[232:235], v[18:21]
	v_mfma_f32_16x16x32_bf16 v[10:13], v[216:219], v[240:243], v[10:13]
	v_mfma_f32_16x16x32_bf16 v[6:9], v[224:227], v[232:235], v[6:9]
	v_mfma_f32_16x16x32_bf16 v[2:5], v[224:227], v[240:243], v[2:5]
	s_setprio 0
	s_barrier
	v_or_b32_e32 v162, 0x18000, v145
	v_add_u32_e32 v163, 0x18400, v145
	v_add_u32_e32 v164, 0x18800, v145
	v_add_u32_e32 v165, 0x18c00, v145
	v_or_b32_e32 v166, 0x1c000, v145
	v_add_u32_e32 v167, 0x1c400, v145
	v_add_u32_e32 v168, 0x1c800, v145
	v_add_u32_e32 v169, 0x1cc00, v145
	ds_read_b128 v[170:173], v162
	ds_read_b128 v[174:177], v163
	ds_read_b128 v[190:193], v164
	ds_read_b128 v[194:197], v165
	ds_read_b128 v[204:207], v141 offset:32768
	ds_read_b128 v[208:211], v141 offset:33792
	ds_read_b128 v[212:215], v141 offset:34816
	ds_read_b128 v[216:219], v141 offset:35840
	ds_read_b128 v[220:223], v141 offset:36864
	ds_read_b128 v[224:227], v141 offset:37888
	ds_read_b128 v[228:231], v141 offset:38912
	ds_read_b128 v[232:235], v141 offset:39936
	ds_read_b128 v[236:239], v166
	ds_read_b128 v[240:243], v167
	ds_read_b128 v[244:247], v168
	ds_read_b128 v[248:251], v169
	v_lshl_add_u64 v[186:187], v[178:179], 0, s[90:91]
	v_readfirstlane_b32 s22, v143
	s_nop 0
	s_mov_b32 m0, s22
	s_nop 0
	global_load_lds_dwordx4 v[186:187], off
	v_lshl_add_u64 v[186:187], v[178:179], 0, s[76:77]
	v_readfirstlane_b32 s22, v144
	s_nop 0
	s_mov_b32 m0, s22
	s_nop 0
	global_load_lds_dwordx4 v[186:187], off
	s_waitcnt lgkmcnt(0)
	s_barrier
	s_setprio 1
	v_mfma_f32_16x16x32_bf16 v[126:129], v[204:207], v[170:173], v[126:129]
	v_mfma_f32_16x16x32_bf16 v[122:125], v[204:207], v[190:193], v[122:125]
	v_mfma_f32_16x16x32_bf16 v[118:121], v[212:215], v[170:173], v[118:121]
	v_mfma_f32_16x16x32_bf16 v[114:117], v[212:215], v[190:193], v[114:117]
	v_mfma_f32_16x16x32_bf16 v[102:105], v[220:223], v[170:173], v[102:105]
	v_mfma_f32_16x16x32_bf16 v[98:101], v[220:223], v[190:193], v[98:101]
	v_mfma_f32_16x16x32_bf16 v[86:89], v[228:231], v[170:173], v[86:89]
	v_mfma_f32_16x16x32_bf16 v[82:85], v[228:231], v[190:193], v[82:85]
	v_mfma_f32_16x16x32_bf16 v[126:129], v[208:211], v[174:177], v[126:129]
	v_mfma_f32_16x16x32_bf16 v[122:125], v[208:211], v[194:197], v[122:125]
	v_mfma_f32_16x16x32_bf16 v[118:121], v[216:219], v[174:177], v[118:121]
	v_mfma_f32_16x16x32_bf16 v[114:117], v[216:219], v[194:197], v[114:117]
	v_mfma_f32_16x16x32_bf16 v[102:105], v[224:227], v[174:177], v[102:105]
	v_mfma_f32_16x16x32_bf16 v[98:101], v[224:227], v[194:197], v[98:101]
	v_mfma_f32_16x16x32_bf16 v[86:89], v[232:235], v[174:177], v[86:89]
	v_mfma_f32_16x16x32_bf16 v[82:85], v[232:235], v[194:197], v[82:85]
	v_mfma_f32_16x16x32_bf16 v[110:113], v[204:207], v[236:239], v[110:113]
	v_mfma_f32_16x16x32_bf16 v[106:109], v[204:207], v[244:247], v[106:109]
	v_mfma_f32_16x16x32_bf16 v[94:97], v[212:215], v[236:239], v[94:97]
	v_mfma_f32_16x16x32_bf16 v[90:93], v[212:215], v[244:247], v[90:93]
	v_mfma_f32_16x16x32_bf16 v[78:81], v[220:223], v[236:239], v[78:81]
	v_mfma_f32_16x16x32_bf16 v[74:77], v[220:223], v[244:247], v[74:77]
	v_mfma_f32_16x16x32_bf16 v[70:73], v[228:231], v[236:239], v[70:73]
	v_mfma_f32_16x16x32_bf16 v[66:69], v[228:231], v[244:247], v[66:69]
	v_mfma_f32_16x16x32_bf16 v[110:113], v[208:211], v[240:243], v[110:113]
	v_mfma_f32_16x16x32_bf16 v[106:109], v[208:211], v[248:251], v[106:109]
	v_mfma_f32_16x16x32_bf16 v[94:97], v[216:219], v[240:243], v[94:97]
	v_mfma_f32_16x16x32_bf16 v[90:93], v[216:219], v[248:251], v[90:93]
	v_mfma_f32_16x16x32_bf16 v[78:81], v[224:227], v[240:243], v[78:81]
	v_mfma_f32_16x16x32_bf16 v[74:77], v[224:227], v[248:251], v[74:77]
	v_mfma_f32_16x16x32_bf16 v[70:73], v[232:235], v[240:243], v[70:73]
	v_mfma_f32_16x16x32_bf16 v[66:69], v[232:235], v[248:251], v[66:69]
	s_setprio 0
	s_barrier
; #define STAGE8(P, BASE, LD, OFF, br, kt) do { const bf16_t* g_ = (BASE) + (long)(br) * (LD) + (long)(kt) * 64 + (OFF); \
;     __builtin_amdgcn_global_load_lds((const unsigned*)(g_), (unsigned*)((char*)(P) + tid8 * 16), 16, 0, 0);            \
;     __builtin_amdgcn_global_load_lds((const unsigned*)(g_ + 64 * (long)(LD)), (unsigned*)((char*)(P) + tid8 * 16 + 8192), 16, 0, 0); } while (0)
; #define LDA8(dst, b, h) _Pragma("unroll") for (int m = 0; m < 4; ++m) _Pragma("unroll") for (int k = 0; k < 2; ++k) \
;     dst[m][k] = *reinterpret_cast<const bf16x8*>(SA8(b, h) + fa_off + m * 2048 + k * 1024)
; #define LDB8(dst, b, h) _Pragma("unroll") for (int n = 0; n < 2; ++n) _Pragma("unroll") for (int k = 0; k < 2; ++k) \
;     dst[n][k] = *reinterpret_cast<const bf16x8*>(SB8(b, h) + fb_off + n * 2048 + k * 1024)
; #define WAIT_V8(n) asm volatile("s_waitcnt vmcnt(" #n ")" ::: "memory")
; #define WAIT_L8(n) asm volatile("s_waitcnt lgkmcnt(" #n ")" ::: "memory")
; #define BAR8 __builtin_amdgcn_s_barrier()
; #define SCHED8 __builtin_amdgcn_sched_barrier(0)
; __device__ __forceinline__ void gemm_mainloop8(const bf16_t* __restrict__ Xg, int ldx, const bf16_t* __restrict__ Wg, int ldw, ...
;     ...
;     WAIT_V8(6); BAR8; MMA8(1, 1, At, B1); BAR8;
;     LDB8(B0, 1, 0); SCHED8; LDA8(At, 1, 0); STAGE8(SA8(0, 1), A, ldw, offA, 128, t + 2);
;     WAIT_L8(8); BAR8; WAIT_L8(0); MMA8(0, 0, At, B0); BAR8; SCHED8;
;     LDB8(B1, 1, 1); STAGE8(SB8(1, 0), Bt, ldx, offB, 0, t + 3);
;     BAR8; WAIT_L8(0); MMA8(0, 1, At, B1); BAR8;
;     LDA8(At, 1, 1); STAGE8(SA8(1, 0), A, ldw, offA, 0, t + 3);
;     BAR8; WAIT_L8(0); MMA8(1, 0, At, B0); BAR8; SCHED8;
;     STAGE8(SB8(1, 1), Bt, ldx, offB, 128, t + 3);
;     WAIT_V8(6); BAR8; MMA8(1, 1, At, B1); BAR8;
;   }
;   { LDB8(B0, 0, 0); LDA8(At, 0, 0); STAGE8(SA8(1, 1), A, ldw, offA, 128, nt - 1);
;     BAR8; WAIT_L8(0); MMA8(0, 0, At, B0); BAR8;
	ds_read_b128 v[204:207], v141 offset:49152
	ds_read_b128 v[208:211], v141 offset:50176
	ds_read_b128 v[212:215], v141 offset:51200
	ds_read_b128 v[216:219], v141 offset:52224
	ds_read_b128 v[220:223], v141 offset:53248
	ds_read_b128 v[224:227], v141 offset:54272
	ds_read_b128 v[228:231], v141 offset:55296
	ds_read_b128 v[232:235], v141 offset:56320
	s_mov_b64 s[22:23], 0x980
	v_lshl_add_u64 v[186:187], v[180:181], 0, s[22:23]
	v_readfirstlane_b32 s22, v146
	s_nop 0
	s_mov_b32 m0, s22
	s_nop 0
	global_load_lds_dwordx4 v[186:187], off
	s_mov_b64 s[22:23], 0x40980
	v_lshl_add_u64 v[186:187], v[180:181], 0, s[22:23]
	v_readfirstlane_b32 s22, v147
	s_nop 0
	s_mov_b32 m0, s22
	s_nop 0
	global_load_lds_dwordx4 v[186:187], off
	v_lshl_add_u64 v[186:187], v[178:179], 0, s[88:89]
	v_readfirstlane_b32 s22, v148
	s_nop 0
	s_mov_b32 m0, s22
	s_nop 0
	global_load_lds_dwordx4 v[186:187], off
	v_lshl_add_u64 v[186:187], v[178:179], 0, s[72:73]
	v_readfirstlane_b32 s22, v149
	s_nop 0
	s_mov_b32 m0, s22
	s_nop 0
	global_load_lds_dwordx4 v[186:187], off
	s_mov_b64 s[22:23], 0x80980
	v_lshl_add_u64 v[186:187], v[180:181], 0, s[22:23]
	v_readfirstlane_b32 s22, v150
	s_nop 0
	s_mov_b32 m0, s22
	s_nop 0
	global_load_lds_dwordx4 v[186:187], off
	s_mov_b64 s[22:23], 0xc0980
	v_lshl_add_u64 v[186:187], v[180:181], 0, s[22:23]
	v_readfirstlane_b32 s22, v151
	s_nop 0
	s_mov_b32 m0, s22
	s_nop 0
	global_load_lds_dwordx4 v[186:187], off
	s_waitcnt vmcnt(6)
	s_waitcnt lgkmcnt(0)
	s_barrier
	s_setprio 1
	v_mfma_f32_16x16x32_bf16 v[62:65], v[204:207], v[170:173], v[62:65]
	v_mfma_f32_16x16x32_bf16 v[58:61], v[204:207], v[190:193], v[58:61]
	v_mfma_f32_16x16x32_bf16 v[54:57], v[212:215], v[170:173], v[54:57]
	v_mfma_f32_16x16x32_bf16 v[46:49], v[212:215], v[190:193], v[46:49]
	v_mfma_f32_16x16x32_bf16 v[38:41], v[220:223], v[170:173], v[38:41]
	v_mfma_f32_16x16x32_bf16 v[30:33], v[220:223], v[190:193], v[30:33]
	v_mfma_f32_16x16x32_bf16 v[22:25], v[228:231], v[170:173], v[22:25]
	v_mfma_f32_16x16x32_bf16 v[14:17], v[228:231], v[190:193], v[14:17]
	v_mfma_f32_16x16x32_bf16 v[62:65], v[208:211], v[174:177], v[62:65]
	v_mfma_f32_16x16x32_bf16 v[58:61], v[208:211], v[194:197], v[58:61]
	v_mfma_f32_16x16x32_bf16 v[54:57], v[216:219], v[174:177], v[54:57]
	v_mfma_f32_16x16x32_bf16 v[46:49], v[216:219], v[194:197], v[46:49]
	v_mfma_f32_16x16x32_bf16 v[38:41], v[224:227], v[174:177], v[38:41]
	v_mfma_f32_16x16x32_bf16 v[30:33], v[224:227], v[194:197], v[30:33]
	v_mfma_f32_16x16x32_bf16 v[22:25], v[232:235], v[174:177], v[22:25]
	v_mfma_f32_16x16x32_bf16 v[14:17], v[232:235], v[194:197], v[14:17]
	v_mfma_f32_16x16x32_bf16 v[50:53], v[204:207], v[236:239], v[50:53]
	v_mfma_f32_16x16x32_bf16 v[42:45], v[204:207], v[244:247], v[42:45]
	v_mfma_f32_16x16x32_bf16 v[34:37], v[212:215], v[236:239], v[34:37]
	v_mfma_f32_16x16x32_bf16 v[26:29], v[212:215], v[244:247], v[26:29]
	v_mfma_f32_16x16x32_bf16 v[18:21], v[220:223], v[236:239], v[18:21]
	v_mfma_f32_16x16x32_bf16 v[10:13], v[220:223], v[244:247], v[10:13]
	v_mfma_f32_16x16x32_bf16 v[6:9], v[228:231], v[236:239], v[6:9]
	v_mfma_f32_16x16x32_bf16 v[2:5], v[228:231], v[244:247], v[2:5]
	v_mfma_f32_16x16x32_bf16 v[50:53], v[208:211], v[240:243], v[50:53]
	v_mfma_f32_16x16x32_bf16 v[42:45], v[208:211], v[248:251], v[42:45]
	v_mfma_f32_16x16x32_bf16 v[34:37], v[216:219], v[240:243], v[34:37]
	v_mfma_f32_16x16x32_bf16 v[26:29], v[216:219], v[248:251], v[26:29]
	v_mfma_f32_16x16x32_bf16 v[18:21], v[224:227], v[240:243], v[18:21]
	v_mfma_f32_16x16x32_bf16 v[10:13], v[224:227], v[248:251], v[10:13]
	v_mfma_f32_16x16x32_bf16 v[6:9], v[232:235], v[240:243], v[6:9]
	v_mfma_f32_16x16x32_bf16 v[2:5], v[232:235], v[248:251], v[2:5]
	s_setprio 0
	s_add_i32 s19, s19, 2
	s_add_u32 s20, s20, 0x100
	s_addc_u32 s21, s21, 0
	s_cmp_lt_u32 s19, 12
	s_barrier
	s_cbranch_scc1 .LBB0_298
	s_mov_b64 s[20:21], 0x40780
	v_readfirstlane_b32 s19, v156
	s_nop 0
	ds_read_b128 v[132:135], v152
	ds_read_b128 v[136:139], v153
	ds_read_b128 v[142:145], v154
	ds_read_b128 v[146:149], v155
	ds_read_b128 v[150:153], v141
	ds_read_b128 v[170:173], v141 offset:1024
	ds_read_b128 v[174:177], v141 offset:2048
	ds_read_b128 v[190:193], v141 offset:3072
	ds_read_b128 v[194:197], v141 offset:4096
	ds_read_b128 v[204:207], v141 offset:5120
	ds_read_b128 v[208:211], v141 offset:6144
	ds_read_b128 v[212:215], v141 offset:7168
	v_lshl_add_u64 v[154:155], v[130:131], 0, s[20:21]
	s_mov_b32 m0, s19
	s_mov_b64 s[20:21], 0x60780
	v_readfirstlane_b32 s19, v157
	global_load_lds_dwordx4 v[154:155], off
	v_lshl_add_u64 v[130:131], v[130:131], 0, s[20:21]
	s_mov_b32 m0, s19
	s_nop 0
	global_load_lds_dwordx4 v[130:131], off
	s_barrier
	s_waitcnt lgkmcnt(0)
	s_setprio 1
	s_waitcnt lgkmcnt(0)
	v_mfma_f32_16x16x32_bf16 v[126:129], v[150:153], v[132:135], v[126:129]
	v_mfma_f32_16x16x32_bf16 v[122:125], v[150:153], v[142:145], v[122:125]
	v_mfma_f32_16x16x32_bf16 v[118:121], v[174:177], v[132:135], v[118:121]
	v_mfma_f32_16x16x32_bf16 v[114:117], v[174:177], v[142:145], v[114:117]
	v_mfma_f32_16x16x32_bf16 v[102:105], v[194:197], v[132:135], v[102:105]
	v_mfma_f32_16x16x32_bf16 v[98:101], v[194:197], v[142:145], v[98:101]
	v_mfma_f32_16x16x32_bf16 v[82:85], v[208:211], v[142:145], v[82:85]
	v_mfma_f32_16x16x32_bf16 v[126:129], v[170:173], v[136:139], v[126:129]
	v_mfma_f32_16x16x32_bf16 v[122:125], v[170:173], v[146:149], v[122:125]
	v_mfma_f32_16x16x32_bf16 v[118:121], v[190:193], v[136:139], v[118:121]
	v_mfma_f32_16x16x32_bf16 v[114:117], v[190:193], v[146:149], v[114:117]
	v_mfma_f32_16x16x32_bf16 v[102:105], v[204:207], v[136:139], v[102:105]
	v_mfma_f32_16x16x32_bf16 v[98:101], v[204:207], v[146:149], v[98:101]
	v_mfma_f32_16x16x32_bf16 v[86:89], v[208:211], v[132:135], v[86:89]
	v_mfma_f32_16x16x32_bf16 v[82:85], v[212:215], v[146:149], v[82:85]
	v_mfma_f32_16x16x32_bf16 v[154:157], v[212:215], v[136:139], v[86:89]
	s_setprio 0
	s_barrier
; #define LDA8(dst, b, h) _Pragma("unroll") for (int m = 0; m < 4; ++m) _Pragma("unroll") for (int k = 0; k < 2; ++k) \
;     dst[m][k] = *reinterpret_cast<const bf16x8*>(SA8(b, h) + fa_off + m * 2048 + k * 1024)
; #define LDB8(dst, b, h) _Pragma("unroll") for (int n = 0; n < 2; ++n) _Pragma("unroll") for (int k = 0; k < 2; ++k) \
;     dst[n][k] = *reinterpret_cast<const bf16x8*>(SB8(b, h) + fb_off + n * 2048 + k * 1024)
; #define WAIT_V8(n) asm volatile("s_waitcnt vmcnt(" #n ")" ::: "memory")
; #define WAIT_L8(n) asm volatile("s_waitcnt lgkmcnt(" #n ")" ::: "memory")
; #define BAR8 __builtin_amdgcn_s_barrier()
; __device__ __forceinline__ void gemm_mainloop8(const bf16_t* __restrict__ Xg, int ldx, const bf16_t* __restrict__ Wg, int ldw, ...
;     ...
;     BAR8; WAIT_L8(0); MMA8(0, 0, At, B0); BAR8;
;     LDB8(B1, 0, 1); BAR8; WAIT_L8(0); MMA8(0, 1, At, B1); BAR8;
;     LDA8(At, 0, 1); WAIT_V8(4); BAR8; WAIT_L8(0); MMA8(1, 0, At, B0); MMA8(1, 1, At, B1); BAR8; }
;   { LDB8(B0, 1, 0); LDA8(At, 1, 0); WAIT_V8(2); BAR8; WAIT_L8(0); MMA8(0, 0, At, B0); BAR8;
	s_nop 0
	s_nop 2
	ds_read_b128 v[86:89], v158
	ds_read_b128 v[216:219], v159
	ds_read_b128 v[220:223], v160
	ds_read_b128 v[158:161], v161
	s_barrier
	s_waitcnt lgkmcnt(0)
	s_setprio 1
	s_waitcnt lgkmcnt(3)
	v_mfma_f32_16x16x32_bf16 v[110:113], v[150:153], v[86:89], v[110:113]
	s_waitcnt lgkmcnt(1)
	v_mfma_f32_16x16x32_bf16 v[106:109], v[150:153], v[220:223], v[106:109]
	v_mfma_f32_16x16x32_bf16 v[78:81], v[194:197], v[86:89], v[78:81]
	v_mfma_f32_16x16x32_bf16 v[74:77], v[194:197], v[220:223], v[74:77]
	v_mfma_f32_16x16x32_bf16 v[70:73], v[208:211], v[86:89], v[70:73]
	v_mfma_f32_16x16x32_bf16 v[66:69], v[208:211], v[220:223], v[66:69]
	v_mfma_f32_16x16x32_bf16 v[110:113], v[170:173], v[216:219], v[110:113]
	s_waitcnt lgkmcnt(0)
	v_mfma_f32_16x16x32_bf16 v[106:109], v[170:173], v[158:161], v[106:109]
	v_mfma_f32_16x16x32_bf16 v[94:97], v[174:177], v[86:89], v[94:97]
	v_mfma_f32_16x16x32_bf16 v[90:93], v[174:177], v[220:223], v[90:93]
	v_mfma_f32_16x16x32_bf16 v[78:81], v[204:207], v[216:219], v[78:81]
	v_mfma_f32_16x16x32_bf16 v[74:77], v[204:207], v[158:161], v[74:77]
	v_mfma_f32_16x16x32_bf16 v[70:73], v[212:215], v[216:219], v[70:73]
	v_mfma_f32_16x16x32_bf16 v[66:69], v[212:215], v[158:161], v[66:69]
	v_mfma_f32_16x16x32_bf16 v[150:153], v[190:193], v[216:219], v[94:97]
	v_mfma_f32_16x16x32_bf16 v[170:173], v[190:193], v[158:161], v[90:93]
	s_setprio 0
	s_barrier
	s_nop 0
	ds_read_b128 v[90:93], v141 offset:16384
	ds_read_b128 v[94:97], v141 offset:17408
	ds_read_b128 v[174:177], v141 offset:18432
	ds_read_b128 v[190:193], v141 offset:19456
	ds_read_b128 v[194:197], v141 offset:20480
	ds_read_b128 v[204:207], v141 offset:21504
	ds_read_b128 v[208:211], v141 offset:22528
	ds_read_b128 v[212:215], v141 offset:23552
	s_waitcnt vmcnt(4)
	s_barrier
	s_waitcnt lgkmcnt(0)
	s_setprio 1
	s_waitcnt lgkmcnt(5)
	v_mfma_f32_16x16x32_bf16 v[46:49], v[174:177], v[142:145], v[46:49]
	s_waitcnt lgkmcnt(3)
	v_mfma_f32_16x16x32_bf16 v[38:41], v[194:197], v[132:135], v[38:41]
	s_waitcnt lgkmcnt(1)
	v_mfma_f32_16x16x32_bf16 v[14:17], v[208:211], v[142:145], v[14:17]
	v_mfma_f32_16x16x32_bf16 v[62:65], v[90:93], v[132:135], v[62:65]
	v_mfma_f32_16x16x32_bf16 v[58:61], v[90:93], v[142:145], v[58:61]
	v_mfma_f32_16x16x32_bf16 v[54:57], v[174:177], v[132:135], v[54:57]
	v_mfma_f32_16x16x32_bf16 v[46:49], v[190:193], v[146:149], v[46:49]
	v_mfma_f32_16x16x32_bf16 v[38:41], v[204:207], v[136:139], v[38:41]
	v_mfma_f32_16x16x32_bf16 v[30:33], v[194:197], v[142:145], v[30:33]
	v_mfma_f32_16x16x32_bf16 v[22:25], v[208:211], v[132:135], v[22:25]
	s_waitcnt lgkmcnt(0)
	v_mfma_f32_16x16x32_bf16 v[14:17], v[212:215], v[146:149], v[14:17]
	v_mfma_f32_16x16x32_bf16 v[224:227], v[94:97], v[136:139], v[62:65]
	v_mfma_f32_16x16x32_bf16 v[228:231], v[94:97], v[146:149], v[58:61]
	v_mfma_f32_16x16x32_bf16 v[232:235], v[190:193], v[136:139], v[54:57]
	v_mfma_f32_16x16x32_bf16 v[236:239], v[204:207], v[146:149], v[30:33]
	v_mfma_f32_16x16x32_bf16 v[130:133], v[212:215], v[136:139], v[22:25]
	s_setprio 0
	s_setprio 1
	v_mfma_f32_16x16x32_bf16 v[22:25], v[90:93], v[86:89], v[50:53]
	v_mfma_f32_16x16x32_bf16 v[134:137], v[94:97], v[216:219], v[22:25]
	v_mfma_f32_16x16x32_bf16 v[22:25], v[90:93], v[220:223], v[42:45]
	v_mfma_f32_16x16x32_bf16 v[42:45], v[94:97], v[158:161], v[22:25]
	v_mfma_f32_16x16x32_bf16 v[22:25], v[174:177], v[86:89], v[34:37]
	v_mfma_f32_16x16x32_bf16 v[2:5], v[208:211], v[220:223], v[2:5]
	v_mfma_f32_16x16x32_bf16 v[34:37], v[190:193], v[216:219], v[22:25]
	v_mfma_f32_16x16x32_bf16 v[22:25], v[174:177], v[220:223], v[26:29]
	v_mfma_f32_16x16x32_bf16 v[18:21], v[194:197], v[86:89], v[18:21]
	v_mfma_f32_16x16x32_bf16 v[10:13], v[194:197], v[220:223], v[10:13]
	v_mfma_f32_16x16x32_bf16 v[6:9], v[208:211], v[86:89], v[6:9]
	v_mfma_f32_16x16x32_bf16 v[2:5], v[212:215], v[158:161], v[2:5]
	v_mfma_f32_16x16x32_bf16 v[142:145], v[190:193], v[158:161], v[22:25]
	v_mfma_f32_16x16x32_bf16 v[146:149], v[204:207], v[216:219], v[18:21]
	v_mfma_f32_16x16x32_bf16 v[174:177], v[204:207], v[158:161], v[10:13]
	v_mfma_f32_16x16x32_bf16 v[190:193], v[212:215], v[216:219], v[6:9]
	s_setprio 0
	s_barrier
	s_nop 0
	ds_read_b128 v[6:9], v162
	ds_read_b128 v[10:13], v163
	ds_read_b128 v[158:161], v164
	ds_read_b128 v[162:165], v165
	ds_read_b128 v[18:21], v141 offset:32768
	ds_read_b128 v[22:25], v141 offset:33792
	ds_read_b128 v[26:29], v141 offset:34816
	ds_read_b128 v[50:53], v141 offset:35840
	ds_read_b128 v[194:197], v141 offset:36864
	ds_read_b128 v[204:207], v141 offset:37888
	ds_read_b128 v[208:211], v141 offset:38912
	ds_read_b128 v[212:215], v141 offset:39936
	s_waitcnt vmcnt(2)
	s_barrier
; #define LDA8(dst, b, h) _Pragma("unroll") for (int m = 0; m < 4; ++m) _Pragma("unroll") for (int k = 0; k < 2; ++k) \
;     dst[m][k] = *reinterpret_cast<const bf16x8*>(SA8(b, h) + fa_off + m * 2048 + k * 1024)
; #define LDB8(dst, b, h) _Pragma("unroll") for (int n = 0; n < 2; ++n) _Pragma("unroll") for (int k = 0; k < 2; ++k) \
;     dst[n][k] = *reinterpret_cast<const bf16x8*>(SB8(b, h) + fb_off + n * 2048 + k * 1024)
; #define WAIT_V8(n) asm volatile("s_waitcnt vmcnt(" #n ")" ::: "memory")
; #define WAIT_L8(n) asm volatile("s_waitcnt lgkmcnt(" #n ")" ::: "memory")
; #define BAR8 __builtin_amdgcn_s_barrier()
; __device__ __forceinline__ void gemm_mainloop8(const bf16_t* __restrict__ Xg, int ldx, const bf16_t* __restrict__ Wg, int ldw, ...
;     ...
;   { LDB8(B0, 1, 0); LDA8(At, 1, 0); WAIT_V8(2); BAR8; WAIT_L8(0); MMA8(0, 0, At, B0); BAR8;
;     LDB8(B1, 1, 1); WAIT_V8(0); BAR8; WAIT_L8(0); MMA8(0, 1, At, B1); BAR8;
;     LDA8(At, 1, 1); BAR8; WAIT_L8(0); MMA8(1, 0, At, B0); MMA8(1, 1, At, B1); BAR8; }
;   if (wr == 0) BAR8;
	s_waitcnt lgkmcnt(0)
	s_setprio 1
	s_waitcnt lgkmcnt(7)
	v_mfma_f32_16x16x32_bf16 v[30:33], v[18:21], v[6:9], v[126:129]
	s_waitcnt lgkmcnt(6)
	v_mfma_f32_16x16x32_bf16 v[126:129], v[22:25], v[10:13], v[30:33]
	v_mfma_f32_16x16x32_bf16 v[30:33], v[18:21], v[158:161], v[122:125]
	v_mfma_f32_16x16x32_bf16 v[94:97], v[22:25], v[162:165], v[30:33]
	s_waitcnt lgkmcnt(5)
	v_mfma_f32_16x16x32_bf16 v[30:33], v[26:29], v[6:9], v[118:121]
	s_waitcnt lgkmcnt(4)
	v_mfma_f32_16x16x32_bf16 v[122:125], v[50:53], v[10:13], v[30:33]
	v_mfma_f32_16x16x32_bf16 v[30:33], v[26:29], v[158:161], v[114:117]
	v_mfma_f32_16x16x32_bf16 v[90:93], v[50:53], v[162:165], v[30:33]
	s_waitcnt lgkmcnt(3)
	v_mfma_f32_16x16x32_bf16 v[30:33], v[194:197], v[6:9], v[102:105]
	s_waitcnt lgkmcnt(2)
	v_mfma_f32_16x16x32_bf16 v[118:121], v[204:207], v[10:13], v[30:33]
	v_mfma_f32_16x16x32_bf16 v[30:33], v[194:197], v[158:161], v[98:101]
	v_mfma_f32_16x16x32_bf16 v[86:89], v[204:207], v[162:165], v[30:33]
	s_waitcnt lgkmcnt(1)
	v_mfma_f32_16x16x32_bf16 v[30:33], v[208:211], v[6:9], v[154:157]
	s_waitcnt lgkmcnt(0)
	v_mfma_f32_16x16x32_bf16 v[114:117], v[212:215], v[10:13], v[30:33]
	v_mfma_f32_16x16x32_bf16 v[30:33], v[208:211], v[158:161], v[82:85]
	v_mfma_f32_16x16x32_bf16 v[82:85], v[212:215], v[162:165], v[30:33]
	s_setprio 0
	s_barrier
	ds_read_b128 v[154:157], v166
	ds_read_b128 v[216:219], v167
	ds_read_b128 v[220:223], v168
	ds_read_b128 v[166:169], v169
	s_waitcnt vmcnt(0)
	s_barrier
	s_waitcnt lgkmcnt(0)
	s_setprio 1
	s_waitcnt lgkmcnt(3)
	v_mfma_f32_16x16x32_bf16 v[30:33], v[18:21], v[154:157], v[110:113]
	s_waitcnt lgkmcnt(1)
	v_mfma_f32_16x16x32_bf16 v[18:21], v[18:21], v[220:223], v[106:109]
	v_mfma_f32_16x16x32_bf16 v[62:65], v[22:25], v[216:219], v[30:33]
	s_waitcnt lgkmcnt(0)
	v_mfma_f32_16x16x32_bf16 v[30:33], v[22:25], v[166:169], v[18:21]
	v_mfma_f32_16x16x32_bf16 v[18:21], v[26:29], v[154:157], v[150:153]
	v_mfma_f32_16x16x32_bf16 v[58:61], v[50:53], v[216:219], v[18:21]
	v_mfma_f32_16x16x32_bf16 v[18:21], v[26:29], v[220:223], v[170:173]
	v_mfma_f32_16x16x32_bf16 v[26:29], v[50:53], v[166:169], v[18:21]
	v_mfma_f32_16x16x32_bf16 v[18:21], v[194:197], v[154:157], v[78:81]
	v_mfma_f32_16x16x32_bf16 v[54:57], v[204:207], v[216:219], v[18:21]
	v_mfma_f32_16x16x32_bf16 v[18:21], v[194:197], v[220:223], v[74:77]
	v_mfma_f32_16x16x32_bf16 v[22:25], v[204:207], v[166:169], v[18:21]
	v_mfma_f32_16x16x32_bf16 v[18:21], v[208:211], v[154:157], v[70:73]
	v_mfma_f32_16x16x32_bf16 v[50:53], v[212:215], v[216:219], v[18:21]
	v_mfma_f32_16x16x32_bf16 v[18:21], v[208:211], v[220:223], v[66:69]
	v_mfma_f32_16x16x32_bf16 v[18:21], v[212:215], v[166:169], v[18:21]
	s_setprio 0
	s_barrier
	ds_read_b128 v[150:153], v141 offset:49152
	ds_read_b128 v[170:173], v141 offset:50176
	ds_read_b128 v[194:197], v141 offset:51200
	ds_read_b128 v[204:207], v141 offset:52224
	ds_read_b128 v[208:211], v141 offset:53248
	ds_read_b128 v[212:215], v141 offset:54272
	ds_read_b128 v[240:243], v141 offset:55296
	ds_read_b128 v[138:141], v141 offset:56320
	s_barrier
	s_waitcnt lgkmcnt(0)
	s_setprio 1
	s_waitcnt lgkmcnt(7)
	v_mfma_f32_16x16x32_bf16 v[66:69], v[150:153], v[6:9], v[224:227]
	s_waitcnt lgkmcnt(6)
	v_mfma_f32_16x16x32_bf16 v[110:113], v[170:173], v[10:13], v[66:69]
	v_mfma_f32_16x16x32_bf16 v[66:69], v[150:153], v[158:161], v[228:231]
	v_mfma_f32_16x16x32_bf16 v[78:81], v[170:173], v[162:165], v[66:69]
	s_waitcnt lgkmcnt(5)
	v_mfma_f32_16x16x32_bf16 v[66:69], v[194:197], v[6:9], v[232:235]
	s_waitcnt lgkmcnt(3)
	v_mfma_f32_16x16x32_bf16 v[38:41], v[208:211], v[6:9], v[38:41]
	s_waitcnt lgkmcnt(1)
	v_mfma_f32_16x16x32_bf16 v[6:9], v[240:243], v[6:9], v[130:133]
	v_mfma_f32_16x16x32_bf16 v[46:49], v[194:197], v[158:161], v[46:49]
	v_mfma_f32_16x16x32_bf16 v[102:105], v[212:215], v[10:13], v[38:41]
	v_mfma_f32_16x16x32_bf16 v[38:41], v[208:211], v[158:161], v[236:239]
	s_waitcnt lgkmcnt(0)
	v_mfma_f32_16x16x32_bf16 v[98:101], v[138:141], v[10:13], v[6:9]
	v_mfma_f32_16x16x32_bf16 v[6:9], v[240:243], v[158:161], v[14:17]
	v_mfma_f32_16x16x32_bf16 v[106:109], v[204:207], v[10:13], v[66:69]
	v_mfma_f32_16x16x32_bf16 v[74:77], v[204:207], v[162:165], v[46:49]
	v_mfma_f32_16x16x32_bf16 v[70:73], v[212:215], v[162:165], v[38:41]
	v_mfma_f32_16x16x32_bf16 v[66:69], v[138:141], v[162:165], v[6:9]
	s_setprio 0
	s_setprio 1
	v_mfma_f32_16x16x32_bf16 v[6:9], v[150:153], v[154:157], v[134:137]
	v_mfma_f32_16x16x32_bf16 v[46:49], v[170:173], v[216:219], v[6:9]
	v_mfma_f32_16x16x32_bf16 v[6:9], v[150:153], v[220:223], v[42:45]
	v_mfma_f32_16x16x32_bf16 v[14:17], v[170:173], v[166:169], v[6:9]
	v_mfma_f32_16x16x32_bf16 v[6:9], v[194:197], v[154:157], v[34:37]
	v_mfma_f32_16x16x32_bf16 v[42:45], v[204:207], v[216:219], v[6:9]
	v_mfma_f32_16x16x32_bf16 v[6:9], v[194:197], v[220:223], v[142:145]
	v_mfma_f32_16x16x32_bf16 v[10:13], v[204:207], v[166:169], v[6:9]
	v_mfma_f32_16x16x32_bf16 v[6:9], v[208:211], v[154:157], v[146:149]
	v_mfma_f32_16x16x32_bf16 v[38:41], v[212:215], v[216:219], v[6:9]
	v_mfma_f32_16x16x32_bf16 v[6:9], v[208:211], v[220:223], v[174:177]
	v_mfma_f32_16x16x32_bf16 v[34:37], v[240:243], v[154:157], v[190:193]
	v_mfma_f32_16x16x32_bf16 v[2:5], v[240:243], v[220:223], v[2:5]
	v_mfma_f32_16x16x32_bf16 v[6:9], v[212:215], v[166:169], v[6:9]
	v_mfma_f32_16x16x32_bf16 v[34:37], v[138:141], v[216:219], v[34:37]
	v_mfma_f32_16x16x32_bf16 v[2:5], v[138:141], v[166:169], v[2:5]
	s_setprio 0
	s_movk_i32 s19, 0x100
	v_cmp_gt_u32_e32 vcc, s19, v0
	s_barrier
	s_and_saveexec_b64 s[20:21], vcc
	s_cbranch_execz .LBB0_288
	s_barrier
	s_branch .LBB0_288

; #define STAGE8(P, BASE, LD, OFF, br, kt) do { const bf16_t* g_ = (BASE) + (long)(br) * (LD) + (long)(kt) * 64 + (OFF); \
;     __builtin_amdgcn_global_load_lds((const unsigned*)(g_), (unsigned*)((char*)(P) + tid8 * 16), 16, 0, 0);            \
;     __builtin_amdgcn_global_load_lds((const unsigned*)(g_ + 64 * (long)(LD)), (unsigned*)((char*)(P) + tid8 * 16 + 8192), 16, 0, 0); } while (0)
; #define WAIT_V8(n) asm volatile("s_waitcnt vmcnt(" #n ")" ::: "memory")
; #define BAR8 __builtin_amdgcn_s_barrier()
; __device__ __forceinline__ void gemm_mainloop8(const bf16_t* __restrict__ Xg, int ldx, const bf16_t* __restrict__ Wg, int ldw, ...
;     ...
;   const int tid8 = opaque_tid();
;   const int wid = tid8 >> 6, lane = tid8 & 63, wr = wid >> 2, wc = wid & 3, fr = lane & 15, fq = lane >> 4;
;   const bf16_t* A = Wg;
;   const bf16_t* Bt = Xg;
;   int r0_, c0_;
;   stage_rc128(tid8 * 16, r0_, c0_);
;   const int offA = r0_ * ldw + c0_, offB = r0_ * ldx + c0_;
;   const int ob_sw = (fr * 64 + fq * 16) ^ (((fr >> 3) & 1) << 5);
;   const int fa_off = wr * 8192 + ob_sw, fb_off = wc * 4096 + ob_sw;
;   asm volatile("s_waitcnt vmcnt(0)" ::: "memory");
;   bf16x8 At[4][2], B0[2][2], B1[2][2];
;   const int nt = K / 64;
;   if (!prefetched) {
;     STAGE8(SB8(0, 0), Bt, ldx, offB, 0, 0); STAGE8(SA8(0, 0), A, ldw, offA, 0, 0);
;     STAGE8(SB8(0, 1), Bt, ldx, offB, 128, 0); STAGE8(SA8(0, 1), A, ldw, offA, 128, 0);
;   }
;   if (wr == 1) BAR8;
;   if (prefetched) { WAIT_V8(0); } else { WAIT_V8(4); }
;   BAR8;
;   STAGE8(SB8(1, 0), Bt, ldx, offB, 0, 1); STAGE8(SA8(1, 0), A, ldw, offA, 0, 1); STAGE8(SB8(1, 1), Bt, ldx, offB, 128, 1);
;   WAIT_V8(6); BAR8;
; template <int MB>
; __device__ __forceinline__ void zero_acc(f32x4 (&acc)[8][MB]) {
; #pragma unroll
;   for (int a = 0; a < 8; ++a)
; #pragma unroll
;     for (int b = 0; b < MB; ++b) acc[a][b] = f32x4{0.f, 0.f, 0.f, 0.f};
.LBB0_445:
	s_or_b64 exec, exec, s[34:35]
	v_lshlrev_b32_e32 v12, 6, v0
	v_lshlrev_b32_e32 v15, 2, v0
	v_and_b32_e32 v11, 48, v0
	v_and_b32_e32 v13, 0x3c0, v12
	v_and_b32_e32 v15, 32, v15
	v_or_b32_e32 v14, v13, v11
	v_bitop3_b32 v11, v13, v15, v11 bitop3:0x36
	s_movk_i32 s3, 0x3000
	v_add_u32_e32 v144, 0x18000, v135
	v_lshlrev_b32_e32 v10, 13, v10
	v_and_or_b32 v143, v12, s3, v11
	s_mov_b64 s[34:35], 0x80
	v_readfirstlane_b32 s3, v144
	v_add_u32_e32 v145, 0x1a000, v135
	v_bitop3_b32 v134, v14, v10, v15 bitop3:0xde
	v_lshl_add_u64 v[10:11], v[4:5], 0, s[34:35]
	s_mov_b32 m0, s3
	s_mov_b64 s[40:41], 0x10080
	v_readfirstlane_b32 s3, v145
	v_add_u32_e32 v146, 0x8000, v135
	s_waitcnt vmcnt(2)
	s_barrier
	global_load_lds_dwordx4 v[10:11], off
	v_lshl_add_u64 v[4:5], v[4:5], 0, s[40:41]
	s_mov_b32 m0, s3
	v_readfirstlane_b32 s3, v146
	v_add_u32_e32 v147, 0xa000, v135
	global_load_lds_dwordx4 v[4:5], off
	v_lshl_add_u64 v[4:5], v[2:3], 0, s[34:35]
	s_mov_b32 m0, s3
	v_readfirstlane_b32 s3, v147
	global_load_lds_dwordx4 v[4:5], off
	v_lshl_add_u64 v[2:3], v[2:3], 0, s[40:41]
	s_mov_b32 m0, s3
	v_add_u32_e32 v148, 0x1c000, v135
	global_load_lds_dwordx4 v[2:3], off
	v_lshl_add_u64 v[2:3], v[130:131], 1, s[30:31]
	s_mov_b64 s[42:43], 0x20080
	v_readfirstlane_b32 s3, v148
	v_add_u32_e32 v149, 0x1e000, v135
	v_lshl_add_u64 v[4:5], v[2:3], 0, s[42:43]
	s_mov_b32 m0, s3
	s_mov_b64 s[52:53], 0x30080
	v_readfirstlane_b32 s3, v149
	global_load_lds_dwordx4 v[4:5], off
	v_lshl_add_u64 v[2:3], v[2:3], 0, s[52:53]
	s_mov_b32 m0, s3
	s_mov_b32 s3, -2
	global_load_lds_dwordx4 v[2:3], off
	v_lshlrev_b32_e32 v2, 12, v6
	v_and_b32_e32 v2, 0xffffe000, v2
	v_lshl_add_u32 v2, v7, 9, v2
	v_or_b32_e32 v2, v2, v8
	v_add_u32_sdwa v2, v2, sext(v9) dst_sel:DWORD dst_unused:UNUSED_PAD src0_sel:DWORD src1_sel:WORD_0
	s_waitcnt vmcnt(6)
	v_ashrrev_i32_e32 v3, 31, v2
	v_lshlrev_b64 v[132:133], 1, v[2:3]
	v_mov_b32_e32 v2, 0
	s_mov_b64 s[34:35], s[6:7]
	v_mov_b32_e32 v3, v2
	v_mov_b32_e32 v4, v2
	v_mov_b32_e32 v5, v2
	v_mov_b32_e32 v6, v2
	v_mov_b32_e32 v7, v2
	v_mov_b32_e32 v8, v2
	v_mov_b32_e32 v9, v2
	v_mov_b32_e32 v14, v2
	v_mov_b32_e32 v15, v2
	v_mov_b32_e32 v16, v2
	v_mov_b32_e32 v17, v2
	v_mov_b32_e32 v22, v2
	v_mov_b32_e32 v23, v2
	v_mov_b32_e32 v24, v2
	v_mov_b32_e32 v25, v2
	v_mov_b32_e32 v10, v2
	v_mov_b32_e32 v11, v2
	v_mov_b32_e32 v12, v2
	v_mov_b32_e32 v13, v2
	v_mov_b32_e32 v18, v2
	v_mov_b32_e32 v19, v2
	v_mov_b32_e32 v20, v2
	v_mov_b32_e32 v21, v2
	v_mov_b32_e32 v30, v2
	v_mov_b32_e32 v31, v2
	v_mov_b32_e32 v32, v2
	v_mov_b32_e32 v33, v2
	v_mov_b32_e32 v38, v2
	v_mov_b32_e32 v39, v2
	v_mov_b32_e32 v40, v2
	v_mov_b32_e32 v41, v2
	v_mov_b32_e32 v26, v2
	v_mov_b32_e32 v27, v2
	v_mov_b32_e32 v28, v2
	v_mov_b32_e32 v29, v2
	v_mov_b32_e32 v34, v2
	v_mov_b32_e32 v35, v2
	v_mov_b32_e32 v36, v2
	v_mov_b32_e32 v37, v2
	v_mov_b32_e32 v46, v2
	v_mov_b32_e32 v47, v2
	v_mov_b32_e32 v48, v2
	v_mov_b32_e32 v49, v2
	v_mov_b32_e32 v54, v2
	v_mov_b32_e32 v55, v2
	v_mov_b32_e32 v56, v2
	v_mov_b32_e32 v57, v2
	v_mov_b32_e32 v42, v2
	v_mov_b32_e32 v43, v2
	v_mov_b32_e32 v44, v2
	v_mov_b32_e32 v45, v2
	v_mov_b32_e32 v50, v2
	v_mov_b32_e32 v51, v2
	v_mov_b32_e32 v52, v2
	v_mov_b32_e32 v53, v2
	v_mov_b32_e32 v58, v2
	v_mov_b32_e32 v59, v2
	v_mov_b32_e32 v60, v2
	v_mov_b32_e32 v61, v2
	v_mov_b32_e32 v62, v2
	v_mov_b32_e32 v63, v2
	v_mov_b32_e32 v64, v2
	v_mov_b32_e32 v65, v2
	v_mov_b32_e32 v66, v2
	v_mov_b32_e32 v67, v2
	v_mov_b32_e32 v68, v2
	v_mov_b32_e32 v69, v2
	v_mov_b32_e32 v70, v2
	v_mov_b32_e32 v71, v2
	v_mov_b32_e32 v72, v2
	v_mov_b32_e32 v73, v2
	v_mov_b32_e32 v82, v2
	v_mov_b32_e32 v83, v2
	v_mov_b32_e32 v84, v2
	v_mov_b32_e32 v85, v2
	v_mov_b32_e32 v86, v2
	v_mov_b32_e32 v87, v2
	v_mov_b32_e32 v88, v2
	v_mov_b32_e32 v89, v2
	v_mov_b32_e32 v74, v2
	v_mov_b32_e32 v75, v2
	v_mov_b32_e32 v76, v2
	v_mov_b32_e32 v77, v2
	v_mov_b32_e32 v78, v2
	v_mov_b32_e32 v79, v2
	v_mov_b32_e32 v80, v2
	v_mov_b32_e32 v81, v2
	v_mov_b32_e32 v98, v2
	v_mov_b32_e32 v99, v2
	v_mov_b32_e32 v100, v2
	v_mov_b32_e32 v101, v2
	v_mov_b32_e32 v102, v2
	v_mov_b32_e32 v103, v2
	v_mov_b32_e32 v104, v2
	v_mov_b32_e32 v105, v2
	v_mov_b32_e32 v90, v2
	v_mov_b32_e32 v91, v2
	v_mov_b32_e32 v92, v2
	v_mov_b32_e32 v93, v2
	v_mov_b32_e32 v94, v2
	v_mov_b32_e32 v95, v2
	v_mov_b32_e32 v96, v2
	v_mov_b32_e32 v97, v2
	v_mov_b32_e32 v114, v2
	v_mov_b32_e32 v115, v2
	v_mov_b32_e32 v116, v2
	v_mov_b32_e32 v117, v2
	v_mov_b32_e32 v118, v2
	v_mov_b32_e32 v119, v2
	v_mov_b32_e32 v120, v2
	v_mov_b32_e32 v121, v2
	v_mov_b32_e32 v106, v2
	v_mov_b32_e32 v107, v2
	v_mov_b32_e32 v108, v2
	v_mov_b32_e32 v109, v2
	v_mov_b32_e32 v110, v2
	v_mov_b32_e32 v111, v2
	v_mov_b32_e32 v112, v2
	v_mov_b32_e32 v113, v2
	v_mov_b32_e32 v122, v2
	v_mov_b32_e32 v123, v2
	v_mov_b32_e32 v124, v2
	v_mov_b32_e32 v125, v2
	v_mov_b32_e32 v126, v2
	v_mov_b32_e32 v127, v2
	v_mov_b32_e32 v128, v2
	v_mov_b32_e32 v129, v2
	s_mov_b64 s[54:55], 0x10100
	s_mov_b64 s[56:57], 0x30100
	s_barrier
; #define STAGE8(P, BASE, LD, OFF, br, kt) do { const bf16_t* g_ = (BASE) + (long)(br) * (LD) + (long)(kt) * 64 + (OFF); \
;     __builtin_amdgcn_global_load_lds((const unsigned*)(g_), (unsigned*)((char*)(P) + tid8 * 16), 16, 0, 0);            \
;     __builtin_amdgcn_global_load_lds((const unsigned*)(g_ + 64 * (long)(LD)), (unsigned*)((char*)(P) + tid8 * 16 + 8192), 16, 0, 0); } while (0)
; #define LDA8(dst, b, h) _Pragma("unroll") for (int m = 0; m < 4; ++m) _Pragma("unroll") for (int k = 0; k < 2; ++k) \
;     dst[m][k] = *reinterpret_cast<const bf16x8*>(SA8(b, h) + fa_off + m * 2048 + k * 1024)
; #define LDB8(dst, b, h) _Pragma("unroll") for (int n = 0; n < 2; ++n) _Pragma("unroll") for (int k = 0; k < 2; ++k) \
;     dst[n][k] = *reinterpret_cast<const bf16x8*>(SB8(b, h) + fb_off + n * 2048 + k * 1024)
; #define WAIT_V8(n) asm volatile("s_waitcnt vmcnt(" #n ")" ::: "memory")
; #define WAIT_L8(n) asm volatile("s_waitcnt lgkmcnt(" #n ")" ::: "memory")
; #define BAR8 __builtin_amdgcn_s_barrier()
; #define SCHED8 __builtin_amdgcn_sched_barrier(0)
; __device__ __forceinline__ void gemm_mainloop8(const bf16_t* __restrict__ Xg, int ldx, const bf16_t* __restrict__ Wg, int ldw, ...
;     ...
;   for (int t = 0; t < nt - 2; t += 2) {
;     LDB8(B0, 0, 0); SCHED8; LDA8(At, 0, 0); STAGE8(SA8(1, 1), A, ldw, offA, 128, t + 1);
;     WAIT_L8(8); BAR8; WAIT_L8(0); MMA8(0, 0, At, B0); BAR8; SCHED8;
;     LDB8(B1, 0, 1); STAGE8(SB8(0, 0), Bt, ldx, offB, 0, t + 2);
;     BAR8; WAIT_L8(0); MMA8(0, 1, At, B1); BAR8;
;     LDA8(At, 0, 1); STAGE8(SA8(0, 0), A, ldw, offA, 0, t + 2);
;     BAR8; WAIT_L8(0); MMA8(1, 0, At, B0); BAR8; SCHED8;
;     STAGE8(SB8(0, 1), Bt, ldx, offB, 128, t + 2);
;     WAIT_V8(6); BAR8; MMA8(1, 1, At, B1); BAR8;
.LBB0_446:
	v_or_b32_e32 v150, 0x10000, v143
	v_add_u32_e32 v151, 0x10400, v143
	v_add_u32_e32 v152, 0x10800, v143
	v_add_u32_e32 v153, 0x10c00, v143
	v_or_b32_e32 v156, 0x14000, v143
	v_add_u32_e32 v157, 0x14400, v143
	v_add_u32_e32 v158, 0x14800, v143
	v_add_u32_e32 v159, 0x14c00, v143
	v_add_u32_e32 v154, 0xc000, v135
	v_add_u32_e32 v155, 0xe000, v135
	v_lshl_add_u64 v[180:181], s[34:35], 0, v[132:133]
	v_lshl_add_u64 v[186:187], s[30:31], 0, v[132:133]
	ds_read_b128 v[160:163], v150
	ds_read_b128 v[164:167], v151
	ds_read_b128 v[168:171], v152
	ds_read_b128 v[172:175], v153
	ds_read_b128 v[176:179], v134
	ds_read_b128 v[190:193], v134 offset:1024
	ds_read_b128 v[194:197], v134 offset:2048
	ds_read_b128 v[204:207], v134 offset:3072
	ds_read_b128 v[208:211], v134 offset:4096
	ds_read_b128 v[212:215], v134 offset:5120
	ds_read_b128 v[216:219], v134 offset:6144
	ds_read_b128 v[220:223], v134 offset:7168
	ds_read_b128 v[224:227], v156
	ds_read_b128 v[228:231], v157
	ds_read_b128 v[232:235], v158
	ds_read_b128 v[236:239], v159
	v_lshl_add_u64 v[188:189], v[180:181], 0, s[42:43]
	v_readfirstlane_b32 s29, v154
	s_nop 0
	s_mov_b32 m0, s29
	s_nop 0
	global_load_lds_dwordx4 v[188:189], off
	v_lshl_add_u64 v[188:189], v[180:181], 0, s[52:53]
	v_readfirstlane_b32 s29, v155
	s_nop 0
	s_mov_b32 m0, s29
	s_nop 0
	global_load_lds_dwordx4 v[188:189], off
	s_waitcnt lgkmcnt(0)
	s_barrier
	s_setprio 1
	v_mfma_f32_16x16x32_bf16 v[126:129], v[176:179], v[160:163], v[126:129]
	v_mfma_f32_16x16x32_bf16 v[122:125], v[176:179], v[168:171], v[122:125]
	v_mfma_f32_16x16x32_bf16 v[118:121], v[194:197], v[160:163], v[118:121]
	v_mfma_f32_16x16x32_bf16 v[114:117], v[194:197], v[168:171], v[114:117]
	v_mfma_f32_16x16x32_bf16 v[102:105], v[208:211], v[160:163], v[102:105]
	v_mfma_f32_16x16x32_bf16 v[98:101], v[208:211], v[168:171], v[98:101]
	v_mfma_f32_16x16x32_bf16 v[86:89], v[216:219], v[160:163], v[86:89]
	v_mfma_f32_16x16x32_bf16 v[82:85], v[216:219], v[168:171], v[82:85]
	v_mfma_f32_16x16x32_bf16 v[126:129], v[190:193], v[164:167], v[126:129]
	v_mfma_f32_16x16x32_bf16 v[122:125], v[190:193], v[172:175], v[122:125]
	v_mfma_f32_16x16x32_bf16 v[118:121], v[204:207], v[164:167], v[118:121]
	v_mfma_f32_16x16x32_bf16 v[114:117], v[204:207], v[172:175], v[114:117]
	v_mfma_f32_16x16x32_bf16 v[102:105], v[212:215], v[164:167], v[102:105]
	v_mfma_f32_16x16x32_bf16 v[98:101], v[212:215], v[172:175], v[98:101]
	v_mfma_f32_16x16x32_bf16 v[86:89], v[220:223], v[164:167], v[86:89]
	v_mfma_f32_16x16x32_bf16 v[82:85], v[220:223], v[172:175], v[82:85]
	v_mfma_f32_16x16x32_bf16 v[110:113], v[176:179], v[224:227], v[110:113]
	v_mfma_f32_16x16x32_bf16 v[106:109], v[176:179], v[232:235], v[106:109]
	v_mfma_f32_16x16x32_bf16 v[94:97], v[194:197], v[224:227], v[94:97]
	v_mfma_f32_16x16x32_bf16 v[90:93], v[194:197], v[232:235], v[90:93]
	v_mfma_f32_16x16x32_bf16 v[78:81], v[208:211], v[224:227], v[78:81]
	v_mfma_f32_16x16x32_bf16 v[74:77], v[208:211], v[232:235], v[74:77]
	v_mfma_f32_16x16x32_bf16 v[70:73], v[216:219], v[224:227], v[70:73]
	v_mfma_f32_16x16x32_bf16 v[66:69], v[216:219], v[232:235], v[66:69]
	v_mfma_f32_16x16x32_bf16 v[110:113], v[190:193], v[228:231], v[110:113]
	v_mfma_f32_16x16x32_bf16 v[106:109], v[190:193], v[236:239], v[106:109]
	v_mfma_f32_16x16x32_bf16 v[94:97], v[204:207], v[228:231], v[94:97]
	v_mfma_f32_16x16x32_bf16 v[90:93], v[204:207], v[236:239], v[90:93]
	v_mfma_f32_16x16x32_bf16 v[78:81], v[212:215], v[228:231], v[78:81]
	v_mfma_f32_16x16x32_bf16 v[74:77], v[212:215], v[236:239], v[74:77]
	v_mfma_f32_16x16x32_bf16 v[70:73], v[220:223], v[228:231], v[70:73]
	v_mfma_f32_16x16x32_bf16 v[66:69], v[220:223], v[236:239], v[66:69]
	s_setprio 0
	s_barrier
	ds_read_b128 v[176:179], v134 offset:16384
	ds_read_b128 v[190:193], v134 offset:17408
	ds_read_b128 v[194:197], v134 offset:18432
	ds_read_b128 v[204:207], v134 offset:19456
	ds_read_b128 v[208:211], v134 offset:20480
	ds_read_b128 v[212:215], v134 offset:21504
	ds_read_b128 v[216:219], v134 offset:22528
	ds_read_b128 v[220:223], v134 offset:23552
	v_lshl_add_u64 v[188:189], v[186:187], 0, s[70:71]
	v_readfirstlane_b32 s29, v136
	s_nop 0
	s_mov_b32 m0, s29
	s_nop 0
	global_load_lds_dwordx4 v[188:189], off
	v_lshl_add_u64 v[188:189], v[186:187], 0, s[54:55]
	v_readfirstlane_b32 s29, v137
	s_nop 0
	s_mov_b32 m0, s29
	s_nop 0
	global_load_lds_dwordx4 v[188:189], off
	v_lshl_add_u64 v[188:189], v[180:181], 0, s[70:71]
	v_readfirstlane_b32 s29, v135
	s_nop 0
	s_mov_b32 m0, s29
	s_nop 0
	global_load_lds_dwordx4 v[188:189], off
	v_lshl_add_u64 v[188:189], v[180:181], 0, s[54:55]
	v_readfirstlane_b32 s29, v138
	s_nop 0
	s_mov_b32 m0, s29
	s_nop 0
	global_load_lds_dwordx4 v[188:189], off
	v_lshl_add_u64 v[188:189], v[186:187], 0, s[64:65]
	v_readfirstlane_b32 s29, v139
	s_nop 0
	s_mov_b32 m0, s29
	s_nop 0
	global_load_lds_dwordx4 v[188:189], off
	v_lshl_add_u64 v[188:189], v[186:187], 0, s[56:57]
	v_readfirstlane_b32 s29, v140
	s_nop 0
	s_mov_b32 m0, s29
	s_nop 0
	global_load_lds_dwordx4 v[188:189], off
	s_waitcnt vmcnt(6)
	s_waitcnt lgkmcnt(0)
	s_barrier
; #define STAGE8(P, BASE, LD, OFF, br, kt) do { const bf16_t* g_ = (BASE) + (long)(br) * (LD) + (long)(kt) * 64 + (OFF); \
;     __builtin_amdgcn_global_load_lds((const unsigned*)(g_), (unsigned*)((char*)(P) + tid8 * 16), 16, 0, 0);            \
;     __builtin_amdgcn_global_load_lds((const unsigned*)(g_ + 64 * (long)(LD)), (unsigned*)((char*)(P) + tid8 * 16 + 8192), 16, 0, 0); } while (0)
; #define LDA8(dst, b, h) _Pragma("unroll") for (int m = 0; m < 4; ++m) _Pragma("unroll") for (int k = 0; k < 2; ++k) \
;     dst[m][k] = *reinterpret_cast<const bf16x8*>(SA8(b, h) + fa_off + m * 2048 + k * 1024)
; #define LDB8(dst, b, h) _Pragma("unroll") for (int n = 0; n < 2; ++n) _Pragma("unroll") for (int k = 0; k < 2; ++k) \
;     dst[n][k] = *reinterpret_cast<const bf16x8*>(SB8(b, h) + fb_off + n * 2048 + k * 1024)
; #define WAIT_V8(n) asm volatile("s_waitcnt vmcnt(" #n ")" ::: "memory")
; #define WAIT_L8(n) asm volatile("s_waitcnt lgkmcnt(" #n ")" ::: "memory")
; #define BAR8 __builtin_amdgcn_s_barrier()
; #define SCHED8 __builtin_amdgcn_sched_barrier(0)
; __device__ __forceinline__ void gemm_mainloop8(const bf16_t* __restrict__ Xg, int ldx, const bf16_t* __restrict__ Wg, int ldw, ...
;     ...
;     WAIT_V8(6); BAR8; MMA8(1, 1, At, B1); BAR8;
;     LDB8(B0, 1, 0); SCHED8; LDA8(At, 1, 0); STAGE8(SA8(0, 1), A, ldw, offA, 128, t + 2);
;     WAIT_L8(8); BAR8; WAIT_L8(0); MMA8(0, 0, At, B0); BAR8; SCHED8;
;     LDB8(B1, 1, 1); STAGE8(SB8(1, 0), Bt, ldx, offB, 0, t + 3);
;     BAR8; WAIT_L8(0); MMA8(0, 1, At, B1); BAR8;
	s_setprio 1
	v_mfma_f32_16x16x32_bf16 v[62:65], v[176:179], v[160:163], v[62:65]
	v_mfma_f32_16x16x32_bf16 v[58:61], v[176:179], v[168:171], v[58:61]
	v_mfma_f32_16x16x32_bf16 v[54:57], v[194:197], v[160:163], v[54:57]
	v_mfma_f32_16x16x32_bf16 v[46:49], v[194:197], v[168:171], v[46:49]
	v_mfma_f32_16x16x32_bf16 v[38:41], v[208:211], v[160:163], v[38:41]
	v_mfma_f32_16x16x32_bf16 v[30:33], v[208:211], v[168:171], v[30:33]
	v_mfma_f32_16x16x32_bf16 v[22:25], v[216:219], v[160:163], v[22:25]
	v_mfma_f32_16x16x32_bf16 v[14:17], v[216:219], v[168:171], v[14:17]
	v_mfma_f32_16x16x32_bf16 v[62:65], v[190:193], v[164:167], v[62:65]
	v_mfma_f32_16x16x32_bf16 v[58:61], v[190:193], v[172:175], v[58:61]
	v_mfma_f32_16x16x32_bf16 v[54:57], v[204:207], v[164:167], v[54:57]
	v_mfma_f32_16x16x32_bf16 v[46:49], v[204:207], v[172:175], v[46:49]
	v_mfma_f32_16x16x32_bf16 v[38:41], v[212:215], v[164:167], v[38:41]
	v_mfma_f32_16x16x32_bf16 v[30:33], v[212:215], v[172:175], v[30:33]
	v_mfma_f32_16x16x32_bf16 v[22:25], v[220:223], v[164:167], v[22:25]
	v_mfma_f32_16x16x32_bf16 v[14:17], v[220:223], v[172:175], v[14:17]
	v_mfma_f32_16x16x32_bf16 v[50:53], v[176:179], v[224:227], v[50:53]
	v_mfma_f32_16x16x32_bf16 v[42:45], v[176:179], v[232:235], v[42:45]
	v_mfma_f32_16x16x32_bf16 v[34:37], v[194:197], v[224:227], v[34:37]
	v_mfma_f32_16x16x32_bf16 v[26:29], v[194:197], v[232:235], v[26:29]
	v_mfma_f32_16x16x32_bf16 v[18:21], v[208:211], v[224:227], v[18:21]
	v_mfma_f32_16x16x32_bf16 v[10:13], v[208:211], v[232:235], v[10:13]
	v_mfma_f32_16x16x32_bf16 v[6:9], v[216:219], v[224:227], v[6:9]
	v_mfma_f32_16x16x32_bf16 v[2:5], v[216:219], v[232:235], v[2:5]
	v_mfma_f32_16x16x32_bf16 v[50:53], v[190:193], v[228:231], v[50:53]
	v_mfma_f32_16x16x32_bf16 v[42:45], v[190:193], v[236:239], v[42:45]
	v_mfma_f32_16x16x32_bf16 v[34:37], v[204:207], v[228:231], v[34:37]
	v_mfma_f32_16x16x32_bf16 v[26:29], v[204:207], v[236:239], v[26:29]
	v_mfma_f32_16x16x32_bf16 v[18:21], v[212:215], v[228:231], v[18:21]
	v_mfma_f32_16x16x32_bf16 v[10:13], v[212:215], v[236:239], v[10:13]
	v_mfma_f32_16x16x32_bf16 v[6:9], v[220:223], v[228:231], v[6:9]
	v_mfma_f32_16x16x32_bf16 v[2:5], v[220:223], v[236:239], v[2:5]
	s_setprio 0
	s_barrier
	v_or_b32_e32 v160, 0x18000, v143
	v_add_u32_e32 v161, 0x18400, v143
	v_add_u32_e32 v162, 0x18800, v143
	v_add_u32_e32 v163, 0x18c00, v143
	v_or_b32_e32 v164, 0x1c000, v143
	v_add_u32_e32 v165, 0x1c400, v143
	v_add_u32_e32 v166, 0x1c800, v143
	v_add_u32_e32 v167, 0x1cc00, v143
	ds_read_b128 v[168:171], v160
	ds_read_b128 v[172:175], v161
	ds_read_b128 v[176:179], v162
	ds_read_b128 v[190:193], v163
	ds_read_b128 v[194:197], v134 offset:32768
	ds_read_b128 v[204:207], v134 offset:33792
	ds_read_b128 v[208:211], v134 offset:34816
	ds_read_b128 v[212:215], v134 offset:35840
	ds_read_b128 v[216:219], v134 offset:36864
	ds_read_b128 v[220:223], v134 offset:37888
	ds_read_b128 v[224:227], v134 offset:38912
	ds_read_b128 v[228:231], v134 offset:39936
	ds_read_b128 v[232:235], v164
	ds_read_b128 v[236:239], v165
	ds_read_b128 v[240:243], v166
	ds_read_b128 v[244:247], v167
	v_lshl_add_u64 v[188:189], v[180:181], 0, s[64:65]
	v_readfirstlane_b32 s29, v141
	s_nop 0
	s_mov_b32 m0, s29
	s_nop 0
	global_load_lds_dwordx4 v[188:189], off
	v_lshl_add_u64 v[188:189], v[180:181], 0, s[56:57]
	v_readfirstlane_b32 s29, v142
	s_nop 0
	s_mov_b32 m0, s29
	s_nop 0
	global_load_lds_dwordx4 v[188:189], off
	s_waitcnt lgkmcnt(0)
	s_barrier
	s_setprio 1
	v_mfma_f32_16x16x32_bf16 v[126:129], v[194:197], v[168:171], v[126:129]
	v_mfma_f32_16x16x32_bf16 v[122:125], v[194:197], v[176:179], v[122:125]
	v_mfma_f32_16x16x32_bf16 v[118:121], v[208:211], v[168:171], v[118:121]
	v_mfma_f32_16x16x32_bf16 v[114:117], v[208:211], v[176:179], v[114:117]
	v_mfma_f32_16x16x32_bf16 v[102:105], v[216:219], v[168:171], v[102:105]
	v_mfma_f32_16x16x32_bf16 v[98:101], v[216:219], v[176:179], v[98:101]
	v_mfma_f32_16x16x32_bf16 v[86:89], v[224:227], v[168:171], v[86:89]
	v_mfma_f32_16x16x32_bf16 v[82:85], v[224:227], v[176:179], v[82:85]
	v_mfma_f32_16x16x32_bf16 v[126:129], v[204:207], v[172:175], v[126:129]
	v_mfma_f32_16x16x32_bf16 v[122:125], v[204:207], v[190:193], v[122:125]
	v_mfma_f32_16x16x32_bf16 v[118:121], v[212:215], v[172:175], v[118:121]
	v_mfma_f32_16x16x32_bf16 v[114:117], v[212:215], v[190:193], v[114:117]
	v_mfma_f32_16x16x32_bf16 v[102:105], v[220:223], v[172:175], v[102:105]
	v_mfma_f32_16x16x32_bf16 v[98:101], v[220:223], v[190:193], v[98:101]
	v_mfma_f32_16x16x32_bf16 v[86:89], v[228:231], v[172:175], v[86:89]
	v_mfma_f32_16x16x32_bf16 v[82:85], v[228:231], v[190:193], v[82:85]
	v_mfma_f32_16x16x32_bf16 v[110:113], v[194:197], v[232:235], v[110:113]
	v_mfma_f32_16x16x32_bf16 v[106:109], v[194:197], v[240:243], v[106:109]
	v_mfma_f32_16x16x32_bf16 v[94:97], v[208:211], v[232:235], v[94:97]
	v_mfma_f32_16x16x32_bf16 v[90:93], v[208:211], v[240:243], v[90:93]
	v_mfma_f32_16x16x32_bf16 v[78:81], v[216:219], v[232:235], v[78:81]
	v_mfma_f32_16x16x32_bf16 v[74:77], v[216:219], v[240:243], v[74:77]
	v_mfma_f32_16x16x32_bf16 v[70:73], v[224:227], v[232:235], v[70:73]
	v_mfma_f32_16x16x32_bf16 v[66:69], v[224:227], v[240:243], v[66:69]
	v_mfma_f32_16x16x32_bf16 v[110:113], v[204:207], v[236:239], v[110:113]
	v_mfma_f32_16x16x32_bf16 v[106:109], v[204:207], v[244:247], v[106:109]
	v_mfma_f32_16x16x32_bf16 v[94:97], v[212:215], v[236:239], v[94:97]
	v_mfma_f32_16x16x32_bf16 v[90:93], v[212:215], v[244:247], v[90:93]
	v_mfma_f32_16x16x32_bf16 v[78:81], v[220:223], v[236:239], v[78:81]
	v_mfma_f32_16x16x32_bf16 v[74:77], v[220:223], v[244:247], v[74:77]
	v_mfma_f32_16x16x32_bf16 v[70:73], v[228:231], v[236:239], v[70:73]
	v_mfma_f32_16x16x32_bf16 v[66:69], v[228:231], v[244:247], v[66:69]
	s_setprio 0
	s_barrier
; #define STAGE8(P, BASE, LD, OFF, br, kt) do { const bf16_t* g_ = (BASE) + (long)(br) * (LD) + (long)(kt) * 64 + (OFF); \
;     __builtin_amdgcn_global_load_lds((const unsigned*)(g_), (unsigned*)((char*)(P) + tid8 * 16), 16, 0, 0);            \
;     __builtin_amdgcn_global_load_lds((const unsigned*)(g_ + 64 * (long)(LD)), (unsigned*)((char*)(P) + tid8 * 16 + 8192), 16, 0, 0); } while (0)
; #define LDA8(dst, b, h) _Pragma("unroll") for (int m = 0; m < 4; ++m) _Pragma("unroll") for (int k = 0; k < 2; ++k) \
;     dst[m][k] = *reinterpret_cast<const bf16x8*>(SA8(b, h) + fa_off + m * 2048 + k * 1024)
; #define LDB8(dst, b, h) _Pragma("unroll") for (int n = 0; n < 2; ++n) _Pragma("unroll") for (int k = 0; k < 2; ++k) \
;     dst[n][k] = *reinterpret_cast<const bf16x8*>(SB8(b, h) + fb_off + n * 2048 + k * 1024)
; #define WAIT_V8(n) asm volatile("s_waitcnt vmcnt(" #n ")" ::: "memory")
; #define WAIT_L8(n) asm volatile("s_waitcnt lgkmcnt(" #n ")" ::: "memory")
; #define BAR8 __builtin_amdgcn_s_barrier()
; #define SCHED8 __builtin_amdgcn_sched_barrier(0)
; __device__ __forceinline__ void gemm_mainloop8(const bf16_t* __restrict__ Xg, int ldx, const bf16_t* __restrict__ Wg, int ldw, ...
;     ...
;     WAIT_V8(6); BAR8; MMA8(1, 1, At, B1); BAR8;
;     LDB8(B0, 1, 0); SCHED8; LDA8(At, 1, 0); STAGE8(SA8(0, 1), A, ldw, offA, 128, t + 2);
;     WAIT_L8(8); BAR8; WAIT_L8(0); MMA8(0, 0, At, B0); BAR8; SCHED8;
;     LDB8(B1, 1, 1); STAGE8(SB8(1, 0), Bt, ldx, offB, 0, t + 3);
;     BAR8; WAIT_L8(0); MMA8(0, 1, At, B1); BAR8;
;     LDA8(At, 1, 1); STAGE8(SA8(1, 0), A, ldw, offA, 0, t + 3);
;     BAR8; WAIT_L8(0); MMA8(1, 0, At, B0); BAR8; SCHED8;
;     STAGE8(SB8(1, 1), Bt, ldx, offB, 128, t + 3);
;     WAIT_V8(6); BAR8; MMA8(1, 1, At, B1); BAR8;
;   }
;   { LDB8(B0, 0, 0); LDA8(At, 0, 0); STAGE8(SA8(1, 1), A, ldw, offA, 128, nt - 1);
;     BAR8; WAIT_L8(0); MMA8(0, 0, At, B0); BAR8;
	ds_read_b128 v[194:197], v134 offset:49152
	ds_read_b128 v[204:207], v134 offset:50176
	ds_read_b128 v[208:211], v134 offset:51200
	ds_read_b128 v[212:215], v134 offset:52224
	ds_read_b128 v[216:219], v134 offset:53248
	ds_read_b128 v[220:223], v134 offset:54272
	ds_read_b128 v[224:227], v134 offset:55296
	ds_read_b128 v[228:231], v134 offset:56320
	v_lshl_add_u64 v[188:189], v[186:187], 0, s[88:89]
	v_readfirstlane_b32 s29, v144
	s_nop 0
	s_mov_b32 m0, s29
	s_nop 0
	global_load_lds_dwordx4 v[188:189], off
	v_lshl_add_u64 v[188:189], v[186:187], 0, s[50:51]
	v_readfirstlane_b32 s29, v145
	s_nop 0
	s_mov_b32 m0, s29
	s_nop 0
	global_load_lds_dwordx4 v[188:189], off
	v_lshl_add_u64 v[188:189], v[180:181], 0, s[88:89]
	v_readfirstlane_b32 s29, v146
	s_nop 0
	s_mov_b32 m0, s29
	s_nop 0
	global_load_lds_dwordx4 v[188:189], off
	v_lshl_add_u64 v[188:189], v[180:181], 0, s[50:51]
	v_readfirstlane_b32 s29, v147
	s_nop 0
	s_mov_b32 m0, s29
	s_nop 0
	global_load_lds_dwordx4 v[188:189], off
	v_lshl_add_u64 v[188:189], v[186:187], 0, s[72:73]
	v_readfirstlane_b32 s29, v148
	s_nop 0
	s_mov_b32 m0, s29
	s_nop 0
	global_load_lds_dwordx4 v[188:189], off
	s_mov_b64 s[40:41], 0x30180
	v_lshl_add_u64 v[188:189], v[186:187], 0, s[40:41]
	v_readfirstlane_b32 s29, v149
	s_nop 0
	s_mov_b32 m0, s29
	s_nop 0
	global_load_lds_dwordx4 v[188:189], off
	s_waitcnt vmcnt(6)
	s_waitcnt lgkmcnt(0)
	s_barrier
	s_setprio 1
	v_mfma_f32_16x16x32_bf16 v[62:65], v[194:197], v[168:171], v[62:65]
	v_mfma_f32_16x16x32_bf16 v[58:61], v[194:197], v[176:179], v[58:61]
	v_mfma_f32_16x16x32_bf16 v[54:57], v[208:211], v[168:171], v[54:57]
	v_mfma_f32_16x16x32_bf16 v[46:49], v[208:211], v[176:179], v[46:49]
	v_mfma_f32_16x16x32_bf16 v[38:41], v[216:219], v[168:171], v[38:41]
	v_mfma_f32_16x16x32_bf16 v[30:33], v[216:219], v[176:179], v[30:33]
	v_mfma_f32_16x16x32_bf16 v[22:25], v[224:227], v[168:171], v[22:25]
	v_mfma_f32_16x16x32_bf16 v[14:17], v[224:227], v[176:179], v[14:17]
	v_mfma_f32_16x16x32_bf16 v[62:65], v[204:207], v[172:175], v[62:65]
	v_mfma_f32_16x16x32_bf16 v[58:61], v[204:207], v[190:193], v[58:61]
	v_mfma_f32_16x16x32_bf16 v[54:57], v[212:215], v[172:175], v[54:57]
	v_mfma_f32_16x16x32_bf16 v[46:49], v[212:215], v[190:193], v[46:49]
	v_mfma_f32_16x16x32_bf16 v[38:41], v[220:223], v[172:175], v[38:41]
	v_mfma_f32_16x16x32_bf16 v[30:33], v[220:223], v[190:193], v[30:33]
	v_mfma_f32_16x16x32_bf16 v[22:25], v[228:231], v[172:175], v[22:25]
	v_mfma_f32_16x16x32_bf16 v[14:17], v[228:231], v[190:193], v[14:17]
	v_mfma_f32_16x16x32_bf16 v[50:53], v[194:197], v[232:235], v[50:53]
	v_mfma_f32_16x16x32_bf16 v[42:45], v[194:197], v[240:243], v[42:45]
	v_mfma_f32_16x16x32_bf16 v[34:37], v[208:211], v[232:235], v[34:37]
	v_mfma_f32_16x16x32_bf16 v[26:29], v[208:211], v[240:243], v[26:29]
	v_mfma_f32_16x16x32_bf16 v[18:21], v[216:219], v[232:235], v[18:21]
	v_mfma_f32_16x16x32_bf16 v[10:13], v[216:219], v[240:243], v[10:13]
	v_mfma_f32_16x16x32_bf16 v[6:9], v[224:227], v[232:235], v[6:9]
	v_mfma_f32_16x16x32_bf16 v[2:5], v[224:227], v[240:243], v[2:5]
	v_mfma_f32_16x16x32_bf16 v[50:53], v[204:207], v[236:239], v[50:53]
	v_mfma_f32_16x16x32_bf16 v[42:45], v[204:207], v[244:247], v[42:45]
	v_mfma_f32_16x16x32_bf16 v[34:37], v[212:215], v[236:239], v[34:37]
	v_mfma_f32_16x16x32_bf16 v[26:29], v[212:215], v[244:247], v[26:29]
	v_mfma_f32_16x16x32_bf16 v[18:21], v[220:223], v[236:239], v[18:21]
	v_mfma_f32_16x16x32_bf16 v[10:13], v[220:223], v[244:247], v[10:13]
	v_mfma_f32_16x16x32_bf16 v[6:9], v[228:231], v[236:239], v[6:9]
	v_mfma_f32_16x16x32_bf16 v[2:5], v[228:231], v[244:247], v[2:5]
	s_setprio 0
	s_add_i32 s3, s3, 2
	s_add_u32 s30, s30, 0x100
	s_addc_u32 s31, s31, 0
	s_add_u32 s34, s34, 0x100
	s_addc_u32 s35, s35, 0
	s_cmp_lt_u32 s3, 4
	s_barrier
	s_cbranch_scc1 .LBB0_446
	v_lshl_add_u64 v[130:131], v[130:131], 1, s[6:7]
	s_mov_b64 s[6:7], 0x20380
	v_readfirstlane_b32 s3, v154
	v_lshl_add_u64 v[132:133], v[130:131], 0, s[6:7]
	s_mov_b32 m0, s3
	s_mov_b64 s[6:7], 0x30380
	v_readfirstlane_b32 s3, v155
	s_nop 0
	ds_read_b128 v[136:139], v150
	ds_read_b128 v[140:143], v151
	ds_read_b128 v[144:147], v152
	ds_read_b128 v[148:151], v153
	ds_read_b128 v[168:171], v134
	ds_read_b128 v[172:175], v134 offset:1024
	ds_read_b128 v[176:179], v134 offset:2048
	ds_read_b128 v[190:193], v134 offset:3072
	ds_read_b128 v[194:197], v134 offset:4096
	ds_read_b128 v[204:207], v134 offset:5120
	ds_read_b128 v[208:211], v134 offset:6144
	ds_read_b128 v[212:215], v134 offset:7168
	global_load_lds_dwordx4 v[132:133], off
	v_lshl_add_u64 v[130:131], v[130:131], 0, s[6:7]
	s_mov_b32 m0, s3
	s_nop 0
	global_load_lds_dwordx4 v[130:131], off
	s_barrier
	s_waitcnt lgkmcnt(0)
	s_setprio 1
	s_waitcnt lgkmcnt(0)
	v_mfma_f32_16x16x32_bf16 v[126:129], v[168:171], v[136:139], v[126:129]
	v_mfma_f32_16x16x32_bf16 v[122:125], v[168:171], v[144:147], v[122:125]
	v_mfma_f32_16x16x32_bf16 v[118:121], v[176:179], v[136:139], v[118:121]
	v_mfma_f32_16x16x32_bf16 v[114:117], v[176:179], v[144:147], v[114:117]
	v_mfma_f32_16x16x32_bf16 v[98:101], v[194:197], v[144:147], v[98:101]
	v_mfma_f32_16x16x32_bf16 v[86:89], v[208:211], v[136:139], v[86:89]
	v_mfma_f32_16x16x32_bf16 v[82:85], v[208:211], v[144:147], v[82:85]
	v_mfma_f32_16x16x32_bf16 v[126:129], v[172:175], v[140:143], v[126:129]
	v_mfma_f32_16x16x32_bf16 v[122:125], v[172:175], v[148:151], v[122:125]
	v_mfma_f32_16x16x32_bf16 v[118:121], v[190:193], v[140:143], v[118:121]
	v_mfma_f32_16x16x32_bf16 v[114:117], v[190:193], v[148:151], v[114:117]
	v_mfma_f32_16x16x32_bf16 v[102:105], v[194:197], v[136:139], v[102:105]
	v_mfma_f32_16x16x32_bf16 v[98:101], v[204:207], v[148:151], v[98:101]
	v_mfma_f32_16x16x32_bf16 v[86:89], v[212:215], v[140:143], v[86:89]
	v_mfma_f32_16x16x32_bf16 v[82:85], v[212:215], v[148:151], v[82:85]
	v_mfma_f32_16x16x32_bf16 v[130:133], v[204:207], v[140:143], v[102:105]
	s_setprio 0
	s_barrier
; #define LDA8(dst, b, h) _Pragma("unroll") for (int m = 0; m < 4; ++m) _Pragma("unroll") for (int k = 0; k < 2; ++k) \
;     dst[m][k] = *reinterpret_cast<const bf16x8*>(SA8(b, h) + fa_off + m * 2048 + k * 1024)
; #define LDB8(dst, b, h) _Pragma("unroll") for (int n = 0; n < 2; ++n) _Pragma("unroll") for (int k = 0; k < 2; ++k) \
;     dst[n][k] = *reinterpret_cast<const bf16x8*>(SB8(b, h) + fb_off + n * 2048 + k * 1024)
; #define WAIT_V8(n) asm volatile("s_waitcnt vmcnt(" #n ")" ::: "memory")
; #define WAIT_L8(n) asm volatile("s_waitcnt lgkmcnt(" #n ")" ::: "memory")
; #define BAR8 __builtin_amdgcn_s_barrier()
; __device__ __forceinline__ void gemm_mainloop8(const bf16_t* __restrict__ Xg, int ldx, const bf16_t* __restrict__ Wg, int ldw, ...
;     ...
;     BAR8; WAIT_L8(0); MMA8(0, 0, At, B0); BAR8;
;     LDB8(B1, 0, 1); BAR8; WAIT_L8(0); MMA8(0, 1, At, B1); BAR8;
;     LDA8(At, 0, 1); WAIT_V8(4); BAR8; WAIT_L8(0); MMA8(1, 0, At, B0); MMA8(1, 1, At, B1); BAR8; }
;   { LDB8(B0, 1, 0); LDA8(At, 1, 0); WAIT_V8(2); BAR8; WAIT_L8(0); MMA8(0, 0, At, B0); BAR8;
	s_nop 0
	s_nop 0
	ds_read_b128 v[102:105], v156
	ds_read_b128 v[152:155], v157
	ds_read_b128 v[216:219], v158
	ds_read_b128 v[156:159], v159
	s_barrier
	s_waitcnt lgkmcnt(0)
	s_setprio 1
	s_waitcnt lgkmcnt(1)
	v_mfma_f32_16x16x32_bf16 v[90:93], v[176:179], v[216:219], v[90:93]
	v_mfma_f32_16x16x32_bf16 v[74:77], v[194:197], v[216:219], v[74:77]
	v_mfma_f32_16x16x32_bf16 v[66:69], v[208:211], v[216:219], v[66:69]
	v_mfma_f32_16x16x32_bf16 v[110:113], v[168:171], v[102:105], v[110:113]
	v_mfma_f32_16x16x32_bf16 v[106:109], v[168:171], v[216:219], v[106:109]
	v_mfma_f32_16x16x32_bf16 v[94:97], v[176:179], v[102:105], v[94:97]
	s_waitcnt lgkmcnt(0)
	v_mfma_f32_16x16x32_bf16 v[90:93], v[190:193], v[156:159], v[90:93]
	v_mfma_f32_16x16x32_bf16 v[78:81], v[194:197], v[102:105], v[78:81]
	v_mfma_f32_16x16x32_bf16 v[74:77], v[204:207], v[156:159], v[74:77]
	v_mfma_f32_16x16x32_bf16 v[70:73], v[208:211], v[102:105], v[70:73]
	v_mfma_f32_16x16x32_bf16 v[66:69], v[212:215], v[156:159], v[66:69]
	v_mfma_f32_16x16x32_bf16 v[220:223], v[172:175], v[152:155], v[110:113]
	v_mfma_f32_16x16x32_bf16 v[168:171], v[172:175], v[156:159], v[106:109]
	v_mfma_f32_16x16x32_bf16 v[172:175], v[190:193], v[152:155], v[94:97]
	v_mfma_f32_16x16x32_bf16 v[176:179], v[204:207], v[152:155], v[78:81]
	v_mfma_f32_16x16x32_bf16 v[190:193], v[212:215], v[152:155], v[70:73]
	s_setprio 0
	s_barrier
	s_nop 0
	ds_read_b128 v[70:73], v134 offset:16384
	ds_read_b128 v[78:81], v134 offset:17408
	ds_read_b128 v[94:97], v134 offset:18432
	ds_read_b128 v[106:109], v134 offset:19456
	ds_read_b128 v[110:113], v134 offset:20480
	ds_read_b128 v[194:197], v134 offset:21504
	ds_read_b128 v[204:207], v134 offset:22528
	ds_read_b128 v[208:211], v134 offset:23552
	s_waitcnt vmcnt(4)
	s_barrier
	s_waitcnt lgkmcnt(0)
	s_setprio 1
	s_waitcnt lgkmcnt(7)
	v_mfma_f32_16x16x32_bf16 v[62:65], v[70:73], v[136:139], v[62:65]
	v_mfma_f32_16x16x32_bf16 v[58:61], v[70:73], v[144:147], v[58:61]
	s_waitcnt lgkmcnt(5)
	v_mfma_f32_16x16x32_bf16 v[54:57], v[94:97], v[136:139], v[54:57]
	s_waitcnt lgkmcnt(3)
	v_mfma_f32_16x16x32_bf16 v[30:33], v[110:113], v[144:147], v[30:33]
	s_waitcnt lgkmcnt(1)
	v_mfma_f32_16x16x32_bf16 v[22:25], v[204:207], v[136:139], v[22:25]
	v_mfma_f32_16x16x32_bf16 v[14:17], v[204:207], v[144:147], v[14:17]
	v_mfma_f32_16x16x32_bf16 v[62:65], v[78:81], v[140:143], v[62:65]
	v_mfma_f32_16x16x32_bf16 v[58:61], v[78:81], v[148:151], v[58:61]
	v_mfma_f32_16x16x32_bf16 v[54:57], v[106:109], v[140:143], v[54:57]
	v_mfma_f32_16x16x32_bf16 v[46:49], v[94:97], v[144:147], v[46:49]
	v_mfma_f32_16x16x32_bf16 v[38:41], v[110:113], v[136:139], v[38:41]
	v_mfma_f32_16x16x32_bf16 v[30:33], v[194:197], v[148:151], v[30:33]
	s_waitcnt lgkmcnt(0)
	v_mfma_f32_16x16x32_bf16 v[22:25], v[208:211], v[140:143], v[22:25]
	v_mfma_f32_16x16x32_bf16 v[14:17], v[208:211], v[148:151], v[14:17]
	v_mfma_f32_16x16x32_bf16 v[212:215], v[106:109], v[148:151], v[46:49]
	v_mfma_f32_16x16x32_bf16 v[224:227], v[194:197], v[140:143], v[38:41]
	s_setprio 0
	s_setprio 1
	v_mfma_f32_16x16x32_bf16 v[38:41], v[70:73], v[102:105], v[50:53]
	v_mfma_f32_16x16x32_bf16 v[26:29], v[94:97], v[216:219], v[26:29]
	v_mfma_f32_16x16x32_bf16 v[18:21], v[110:113], v[102:105], v[18:21]
	v_mfma_f32_16x16x32_bf16 v[10:13], v[110:113], v[216:219], v[10:13]
	v_mfma_f32_16x16x32_bf16 v[2:5], v[204:207], v[216:219], v[2:5]
	v_mfma_f32_16x16x32_bf16 v[136:139], v[78:81], v[152:155], v[38:41]
	v_mfma_f32_16x16x32_bf16 v[38:41], v[70:73], v[216:219], v[42:45]
	v_mfma_f32_16x16x32_bf16 v[34:37], v[94:97], v[102:105], v[34:37]
	v_mfma_f32_16x16x32_bf16 v[26:29], v[106:109], v[156:159], v[26:29]
	v_mfma_f32_16x16x32_bf16 v[18:21], v[194:197], v[152:155], v[18:21]
	v_mfma_f32_16x16x32_bf16 v[10:13], v[194:197], v[156:159], v[10:13]
	v_mfma_f32_16x16x32_bf16 v[6:9], v[204:207], v[102:105], v[6:9]
	v_mfma_f32_16x16x32_bf16 v[2:5], v[208:211], v[156:159], v[2:5]
	v_mfma_f32_16x16x32_bf16 v[140:143], v[78:81], v[156:159], v[38:41]
	v_mfma_f32_16x16x32_bf16 v[144:147], v[106:109], v[152:155], v[34:37]
	v_mfma_f32_16x16x32_bf16 v[148:151], v[208:211], v[152:155], v[6:9]
	s_setprio 0
	s_barrier
	s_nop 1
	ds_read_b128 v[6:9], v160
	ds_read_b128 v[34:37], v161
	ds_read_b128 v[152:155], v162
	ds_read_b128 v[156:159], v163
	ds_read_b128 v[38:41], v134 offset:32768
	ds_read_b128 v[42:45], v134 offset:33792
	ds_read_b128 v[46:49], v134 offset:34816
	ds_read_b128 v[50:53], v134 offset:35840
	ds_read_b128 v[160:163], v134 offset:36864
	ds_read_b128 v[194:197], v134 offset:37888
	ds_read_b128 v[204:207], v134 offset:38912
	ds_read_b128 v[208:211], v134 offset:39936
	s_waitcnt vmcnt(2)
	s_barrier
; #define LDA8(dst, b, h) _Pragma("unroll") for (int m = 0; m < 4; ++m) _Pragma("unroll") for (int k = 0; k < 2; ++k) \
;     dst[m][k] = *reinterpret_cast<const bf16x8*>(SA8(b, h) + fa_off + m * 2048 + k * 1024)
; #define LDB8(dst, b, h) _Pragma("unroll") for (int n = 0; n < 2; ++n) _Pragma("unroll") for (int k = 0; k < 2; ++k) \
;     dst[n][k] = *reinterpret_cast<const bf16x8*>(SB8(b, h) + fb_off + n * 2048 + k * 1024)
; #define WAIT_V8(n) asm volatile("s_waitcnt vmcnt(" #n ")" ::: "memory")
; #define WAIT_L8(n) asm volatile("s_waitcnt lgkmcnt(" #n ")" ::: "memory")
; #define BAR8 __builtin_amdgcn_s_barrier()
; __device__ __forceinline__ void gemm_mainloop8(const bf16_t* __restrict__ Xg, int ldx, const bf16_t* __restrict__ Wg, int ldw, ...
;     ...
;   { LDB8(B0, 1, 0); LDA8(At, 1, 0); WAIT_V8(2); BAR8; WAIT_L8(0); MMA8(0, 0, At, B0); BAR8;
;     LDB8(B1, 1, 1); WAIT_V8(0); BAR8; WAIT_L8(0); MMA8(0, 1, At, B1); BAR8;
;     LDA8(At, 1, 1); BAR8; WAIT_L8(0); MMA8(1, 0, At, B0); MMA8(1, 1, At, B1); BAR8; }
;   if (wr == 0) BAR8;
	s_waitcnt lgkmcnt(0)
	s_setprio 1
	s_waitcnt lgkmcnt(7)
	v_mfma_f32_16x16x32_bf16 v[70:73], v[38:41], v[6:9], v[126:129]
	s_waitcnt lgkmcnt(6)
	v_mfma_f32_16x16x32_bf16 v[126:129], v[42:45], v[34:37], v[70:73]
	v_mfma_f32_16x16x32_bf16 v[70:73], v[38:41], v[152:155], v[122:125]
	v_mfma_f32_16x16x32_bf16 v[110:113], v[42:45], v[156:159], v[70:73]
	s_waitcnt lgkmcnt(5)
	v_mfma_f32_16x16x32_bf16 v[70:73], v[46:49], v[6:9], v[118:121]
	s_waitcnt lgkmcnt(4)
	v_mfma_f32_16x16x32_bf16 v[118:121], v[50:53], v[34:37], v[70:73]
	v_mfma_f32_16x16x32_bf16 v[70:73], v[46:49], v[152:155], v[114:117]
	v_mfma_f32_16x16x32_bf16 v[102:105], v[50:53], v[156:159], v[70:73]
	s_waitcnt lgkmcnt(3)
	v_mfma_f32_16x16x32_bf16 v[70:73], v[160:163], v[6:9], v[130:133]
	s_waitcnt lgkmcnt(2)
	v_mfma_f32_16x16x32_bf16 v[122:125], v[194:197], v[34:37], v[70:73]
	v_mfma_f32_16x16x32_bf16 v[70:73], v[160:163], v[152:155], v[98:101]
	v_mfma_f32_16x16x32_bf16 v[106:109], v[194:197], v[156:159], v[70:73]
	s_waitcnt lgkmcnt(1)
	v_mfma_f32_16x16x32_bf16 v[70:73], v[204:207], v[6:9], v[86:89]
	s_waitcnt lgkmcnt(0)
	v_mfma_f32_16x16x32_bf16 v[114:117], v[208:211], v[34:37], v[70:73]
	v_mfma_f32_16x16x32_bf16 v[70:73], v[204:207], v[152:155], v[82:85]
	v_mfma_f32_16x16x32_bf16 v[98:101], v[208:211], v[156:159], v[70:73]
	s_setprio 0
	s_barrier
	ds_read_b128 v[130:133], v164
	ds_read_b128 v[216:219], v165
	ds_read_b128 v[228:231], v166
	ds_read_b128 v[164:167], v167
	s_waitcnt vmcnt(0)
	s_barrier
	s_waitcnt lgkmcnt(0)
	s_setprio 1
	s_waitcnt lgkmcnt(3)
	v_mfma_f32_16x16x32_bf16 v[70:73], v[38:41], v[130:133], v[220:223]
	s_waitcnt lgkmcnt(1)
	v_mfma_f32_16x16x32_bf16 v[38:41], v[38:41], v[228:231], v[168:171]
	s_waitcnt lgkmcnt(0)
	v_mfma_f32_16x16x32_bf16 v[78:81], v[42:45], v[164:167], v[38:41]
	v_mfma_f32_16x16x32_bf16 v[38:41], v[46:49], v[130:133], v[172:175]
	v_mfma_f32_16x16x32_bf16 v[86:89], v[50:53], v[216:219], v[38:41]
	v_mfma_f32_16x16x32_bf16 v[38:41], v[46:49], v[228:231], v[90:93]
	v_mfma_f32_16x16x32_bf16 v[94:97], v[42:45], v[216:219], v[70:73]
	v_mfma_f32_16x16x32_bf16 v[70:73], v[50:53], v[164:167], v[38:41]
	v_mfma_f32_16x16x32_bf16 v[38:41], v[160:163], v[130:133], v[176:179]
	v_mfma_f32_16x16x32_bf16 v[90:93], v[194:197], v[216:219], v[38:41]
	v_mfma_f32_16x16x32_bf16 v[38:41], v[160:163], v[228:231], v[74:77]
	v_mfma_f32_16x16x32_bf16 v[74:77], v[194:197], v[164:167], v[38:41]
	v_mfma_f32_16x16x32_bf16 v[38:41], v[204:207], v[130:133], v[190:193]
	v_mfma_f32_16x16x32_bf16 v[82:85], v[208:211], v[216:219], v[38:41]
	v_mfma_f32_16x16x32_bf16 v[38:41], v[204:207], v[228:231], v[66:69]
	v_mfma_f32_16x16x32_bf16 v[66:69], v[208:211], v[164:167], v[38:41]
	s_setprio 0
	s_barrier
	ds_read_b128 v[160:163], v134 offset:49152
	ds_read_b128 v[168:171], v134 offset:50176
	ds_read_b128 v[172:175], v134 offset:51200
	ds_read_b128 v[176:179], v134 offset:52224
	ds_read_b128 v[190:193], v134 offset:53248
	ds_read_b128 v[194:197], v134 offset:54272
	ds_read_b128 v[204:207], v134 offset:55296
	ds_read_b128 v[208:211], v134 offset:56320
	s_barrier
	s_waitcnt lgkmcnt(0)
	s_setprio 1
	s_waitcnt lgkmcnt(7)
	v_mfma_f32_16x16x32_bf16 v[38:41], v[160:163], v[6:9], v[62:65]
	s_waitcnt lgkmcnt(6)
	v_mfma_f32_16x16x32_bf16 v[62:65], v[168:171], v[34:37], v[38:41]
	v_mfma_f32_16x16x32_bf16 v[38:41], v[160:163], v[152:155], v[58:61]
	v_mfma_f32_16x16x32_bf16 v[46:49], v[168:171], v[156:159], v[38:41]
	s_waitcnt lgkmcnt(5)
	v_mfma_f32_16x16x32_bf16 v[38:41], v[172:175], v[6:9], v[54:57]
	s_waitcnt lgkmcnt(3)
	v_mfma_f32_16x16x32_bf16 v[42:45], v[190:193], v[6:9], v[224:227]
	s_waitcnt lgkmcnt(1)
	v_mfma_f32_16x16x32_bf16 v[6:9], v[204:207], v[6:9], v[22:25]
	v_mfma_f32_16x16x32_bf16 v[54:57], v[176:179], v[34:37], v[38:41]
	v_mfma_f32_16x16x32_bf16 v[38:41], v[172:175], v[152:155], v[212:215]
	v_mfma_f32_16x16x32_bf16 v[30:33], v[190:193], v[152:155], v[30:33]
	s_waitcnt lgkmcnt(0)
	v_mfma_f32_16x16x32_bf16 v[50:53], v[208:211], v[34:37], v[6:9]
	v_mfma_f32_16x16x32_bf16 v[6:9], v[204:207], v[152:155], v[14:17]
	v_mfma_f32_16x16x32_bf16 v[38:41], v[176:179], v[156:159], v[38:41]
	v_mfma_f32_16x16x32_bf16 v[58:61], v[194:197], v[34:37], v[42:45]
	v_mfma_f32_16x16x32_bf16 v[42:45], v[194:197], v[156:159], v[30:33]
	v_mfma_f32_16x16x32_bf16 v[34:37], v[208:211], v[156:159], v[6:9]
	s_setprio 0
	s_setprio 1
	v_mfma_f32_16x16x32_bf16 v[6:9], v[160:163], v[130:133], v[136:139]
	v_mfma_f32_16x16x32_bf16 v[30:33], v[168:171], v[216:219], v[6:9]
	v_mfma_f32_16x16x32_bf16 v[6:9], v[160:163], v[228:231], v[140:143]
	v_mfma_f32_16x16x32_bf16 v[14:17], v[168:171], v[164:167], v[6:9]
	v_mfma_f32_16x16x32_bf16 v[6:9], v[172:175], v[130:133], v[144:147]
	v_mfma_f32_16x16x32_bf16 v[18:21], v[190:193], v[130:133], v[18:21]
	v_mfma_f32_16x16x32_bf16 v[22:25], v[176:179], v[216:219], v[6:9]
	v_mfma_f32_16x16x32_bf16 v[6:9], v[172:175], v[228:231], v[26:29]
	v_mfma_f32_16x16x32_bf16 v[26:29], v[194:197], v[216:219], v[18:21]
	v_mfma_f32_16x16x32_bf16 v[10:13], v[190:193], v[228:231], v[10:13]
	v_mfma_f32_16x16x32_bf16 v[18:21], v[204:207], v[130:133], v[148:151]
	v_mfma_f32_16x16x32_bf16 v[2:5], v[204:207], v[228:231], v[2:5]
	v_mfma_f32_16x16x32_bf16 v[6:9], v[176:179], v[164:167], v[6:9]
	v_mfma_f32_16x16x32_bf16 v[10:13], v[194:197], v[164:167], v[10:13]
	v_mfma_f32_16x16x32_bf16 v[18:21], v[208:211], v[216:219], v[18:21]
	v_mfma_f32_16x16x32_bf16 v[2:5], v[208:211], v[164:167], v[2:5]
	s_setprio 0
	s_movk_i32 s3, 0x100
	v_cmp_gt_u32_e32 vcc, s3, v0
	s_barrier
	s_and_saveexec_b64 s[6:7], vcc
	s_cbranch_execz .LBB0_449
	s_barrier

; #define STAGE8(P, BASE, LD, OFF, br, kt) do { const bf16_t* g_ = (BASE) + (long)(br) * (LD) + (long)(kt) * 64 + (OFF); \
;     __builtin_amdgcn_global_load_lds((const unsigned*)(g_), (unsigned*)((char*)(P) + tid8 * 16), 16, 0, 0);            \
;     __builtin_amdgcn_global_load_lds((const unsigned*)(g_ + 64 * (long)(LD)), (unsigned*)((char*)(P) + tid8 * 16 + 8192), 16, 0, 0); } while (0)
; #define LDA8(dst, b, h) _Pragma("unroll") for (int m = 0; m < 4; ++m) _Pragma("unroll") for (int k = 0; k < 2; ++k) \
;     dst[m][k] = *reinterpret_cast<const bf16x8*>(SA8(b, h) + fa_off + m * 2048 + k * 1024)
; #define LDB8(dst, b, h) _Pragma("unroll") for (int n = 0; n < 2; ++n) _Pragma("unroll") for (int k = 0; k < 2; ++k) \
;     dst[n][k] = *reinterpret_cast<const bf16x8*>(SB8(b, h) + fb_off + n * 2048 + k * 1024)
; #define WAIT_V8(n) asm volatile("s_waitcnt vmcnt(" #n ")" ::: "memory")
; #define WAIT_L8(n) asm volatile("s_waitcnt lgkmcnt(" #n ")" ::: "memory")
; #define BAR8 __builtin_amdgcn_s_barrier()
; #define SCHED8 __builtin_amdgcn_sched_barrier(0)
; __device__ __forceinline__ void gemm_mainloop8(const bf16_t* __restrict__ Xg, int ldx, const bf16_t* __restrict__ Wg, int ldw, ...
;     ...
;   for (int t = 0; t < nt - 2; t += 2) {
;     LDB8(B0, 0, 0); SCHED8; LDA8(At, 0, 0); STAGE8(SA8(1, 1), A, ldw, offA, 128, t + 1);
;     WAIT_L8(8); BAR8; WAIT_L8(0); MMA8(0, 0, At, B0); BAR8; SCHED8;
;     LDB8(B1, 0, 1); STAGE8(SB8(0, 0), Bt, ldx, offB, 0, t + 2);
;     BAR8; WAIT_L8(0); MMA8(0, 1, At, B1); BAR8;
;     LDA8(At, 0, 1); STAGE8(SA8(0, 0), A, ldw, offA, 0, t + 2);
;     BAR8; WAIT_L8(0); MMA8(1, 0, At, B0); BAR8; SCHED8;
;     STAGE8(SB8(0, 1), Bt, ldx, offB, 128, t + 2);
;     WAIT_V8(6); BAR8; MMA8(1, 1, At, B1); BAR8;
.LBB0_536:
	v_or_b32_e32 v152, 0x10000, v145
	v_add_u32_e32 v153, 0x10400, v145
	v_add_u32_e32 v154, 0x10800, v145
	v_add_u32_e32 v155, 0x10c00, v145
	v_or_b32_e32 v158, 0x14000, v145
	v_add_u32_e32 v159, 0x14400, v145
	v_add_u32_e32 v160, 0x14800, v145
	v_add_u32_e32 v161, 0x14c00, v145
	v_add_u32_e32 v156, 0xc000, v0
	v_add_u32_e32 v157, 0xe000, v0
	v_lshl_add_u64 v[178:179], s[12:13], 0, v[134:135]
	v_lshl_add_u64 v[180:181], s[10:11], 0, v[134:135]
	ds_read_b128 v[162:165], v152
	ds_read_b128 v[166:169], v153
	ds_read_b128 v[170:173], v154
	ds_read_b128 v[174:177], v155
	ds_read_b128 v[204:207], v144
	ds_read_b128 v[208:211], v144 offset:1024
	ds_read_b128 v[212:215], v144 offset:2048
	ds_read_b128 v[216:219], v144 offset:3072
	ds_read_b128 v[220:223], v144 offset:4096
	ds_read_b128 v[224:227], v144 offset:5120
	ds_read_b128 v[228:231], v144 offset:6144
	ds_read_b128 v[232:235], v144 offset:7168
	ds_read_b128 v[236:239], v158
	ds_read_b128 v[240:243], v159
	ds_read_b128 v[244:247], v160
	ds_read_b128 v[248:251], v161
	v_lshl_add_u64 v[186:187], v[178:179], 0, s[44:45]
	v_readfirstlane_b32 s3, v156
	s_nop 0
	s_mov_b32 m0, s3
	s_nop 0
	global_load_lds_dwordx4 v[186:187], off
	v_lshl_add_u64 v[186:187], v[178:179], 0, s[82:83]
	v_readfirstlane_b32 s3, v157
	s_nop 0
	s_mov_b32 m0, s3
	s_nop 0
	global_load_lds_dwordx4 v[186:187], off
	s_waitcnt lgkmcnt(0)
	s_barrier
	s_setprio 1
	v_mfma_f32_16x16x32_bf16 v[126:129], v[204:207], v[162:165], v[126:129]
	v_mfma_f32_16x16x32_bf16 v[122:125], v[204:207], v[170:173], v[122:125]
	v_mfma_f32_16x16x32_bf16 v[118:121], v[212:215], v[162:165], v[118:121]
	v_mfma_f32_16x16x32_bf16 v[114:117], v[212:215], v[170:173], v[114:117]
	v_mfma_f32_16x16x32_bf16 v[102:105], v[220:223], v[162:165], v[102:105]
	v_mfma_f32_16x16x32_bf16 v[98:101], v[220:223], v[170:173], v[98:101]
	v_mfma_f32_16x16x32_bf16 v[86:89], v[228:231], v[162:165], v[86:89]
	v_mfma_f32_16x16x32_bf16 v[82:85], v[228:231], v[170:173], v[82:85]
	v_mfma_f32_16x16x32_bf16 v[126:129], v[208:211], v[166:169], v[126:129]
	v_mfma_f32_16x16x32_bf16 v[122:125], v[208:211], v[174:177], v[122:125]
	v_mfma_f32_16x16x32_bf16 v[118:121], v[216:219], v[166:169], v[118:121]
	v_mfma_f32_16x16x32_bf16 v[114:117], v[216:219], v[174:177], v[114:117]
	v_mfma_f32_16x16x32_bf16 v[102:105], v[224:227], v[166:169], v[102:105]
	v_mfma_f32_16x16x32_bf16 v[98:101], v[224:227], v[174:177], v[98:101]
	v_mfma_f32_16x16x32_bf16 v[86:89], v[232:235], v[166:169], v[86:89]
	v_mfma_f32_16x16x32_bf16 v[82:85], v[232:235], v[174:177], v[82:85]
	v_mfma_f32_16x16x32_bf16 v[110:113], v[204:207], v[236:239], v[110:113]
	v_mfma_f32_16x16x32_bf16 v[106:109], v[204:207], v[244:247], v[106:109]
	v_mfma_f32_16x16x32_bf16 v[94:97], v[212:215], v[236:239], v[94:97]
	v_mfma_f32_16x16x32_bf16 v[90:93], v[212:215], v[244:247], v[90:93]
	v_mfma_f32_16x16x32_bf16 v[78:81], v[220:223], v[236:239], v[78:81]
	v_mfma_f32_16x16x32_bf16 v[74:77], v[220:223], v[244:247], v[74:77]
	v_mfma_f32_16x16x32_bf16 v[70:73], v[228:231], v[236:239], v[70:73]
	v_mfma_f32_16x16x32_bf16 v[66:69], v[228:231], v[244:247], v[66:69]
	v_mfma_f32_16x16x32_bf16 v[110:113], v[208:211], v[240:243], v[110:113]
	v_mfma_f32_16x16x32_bf16 v[106:109], v[208:211], v[248:251], v[106:109]
	v_mfma_f32_16x16x32_bf16 v[94:97], v[216:219], v[240:243], v[94:97]
	v_mfma_f32_16x16x32_bf16 v[90:93], v[216:219], v[248:251], v[90:93]
	v_mfma_f32_16x16x32_bf16 v[78:81], v[224:227], v[240:243], v[78:81]
	v_mfma_f32_16x16x32_bf16 v[74:77], v[224:227], v[248:251], v[74:77]
	v_mfma_f32_16x16x32_bf16 v[70:73], v[232:235], v[240:243], v[70:73]
	v_mfma_f32_16x16x32_bf16 v[66:69], v[232:235], v[248:251], v[66:69]
	s_setprio 0
	s_barrier
	ds_read_b128 v[204:207], v144 offset:16384
	ds_read_b128 v[208:211], v144 offset:17408
	ds_read_b128 v[212:215], v144 offset:18432
	ds_read_b128 v[216:219], v144 offset:19456
	ds_read_b128 v[220:223], v144 offset:20480
	ds_read_b128 v[224:227], v144 offset:21504
	ds_read_b128 v[228:231], v144 offset:22528
	ds_read_b128 v[232:235], v144 offset:23552
	v_lshl_add_u64 v[186:187], v[180:181], 0, s[70:71]
	v_readfirstlane_b32 s3, v142
	s_nop 0
	s_mov_b32 m0, s3
	s_nop 0
	global_load_lds_dwordx4 v[186:187], off
	v_lshl_add_u64 v[186:187], v[180:181], 0, s[90:91]
	v_readfirstlane_b32 s3, v141
	s_nop 0
	s_mov_b32 m0, s3
	s_nop 0
	global_load_lds_dwordx4 v[186:187], off
	v_lshl_add_u64 v[186:187], v[178:179], 0, s[70:71]
	v_readfirstlane_b32 s3, v0
	s_nop 0
	s_mov_b32 m0, s3
	s_nop 0
	global_load_lds_dwordx4 v[186:187], off
	v_lshl_add_u64 v[186:187], v[178:179], 0, s[90:91]
	v_readfirstlane_b32 s3, v140
	s_nop 0
	s_mov_b32 m0, s3
	s_nop 0
	global_load_lds_dwordx4 v[186:187], off
	v_lshl_add_u64 v[186:187], v[180:181], 0, s[80:81]
	v_readfirstlane_b32 s3, v139
	s_nop 0
	s_mov_b32 m0, s3
	s_nop 0
	global_load_lds_dwordx4 v[186:187], off
	v_lshl_add_u64 v[186:187], v[180:181], 0, s[68:69]
	v_readfirstlane_b32 s3, v138
	s_nop 0
	s_mov_b32 m0, s3
	s_nop 0
	global_load_lds_dwordx4 v[186:187], off
	s_waitcnt vmcnt(6)
	s_waitcnt lgkmcnt(0)
	s_barrier
; #define STAGE8(P, BASE, LD, OFF, br, kt) do { const bf16_t* g_ = (BASE) + (long)(br) * (LD) + (long)(kt) * 64 + (OFF); \
;     __builtin_amdgcn_global_load_lds((const unsigned*)(g_), (unsigned*)((char*)(P) + tid8 * 16), 16, 0, 0);            \
;     __builtin_amdgcn_global_load_lds((const unsigned*)(g_ + 64 * (long)(LD)), (unsigned*)((char*)(P) + tid8 * 16 + 8192), 16, 0, 0); } while (0)
; #define LDA8(dst, b, h) _Pragma("unroll") for (int m = 0; m < 4; ++m) _Pragma("unroll") for (int k = 0; k < 2; ++k) \
;     dst[m][k] = *reinterpret_cast<const bf16x8*>(SA8(b, h) + fa_off + m * 2048 + k * 1024)
; #define LDB8(dst, b, h) _Pragma("unroll") for (int n = 0; n < 2; ++n) _Pragma("unroll") for (int k = 0; k < 2; ++k) \
;     dst[n][k] = *reinterpret_cast<const bf16x8*>(SB8(b, h) + fb_off + n * 2048 + k * 1024)
; #define WAIT_V8(n) asm volatile("s_waitcnt vmcnt(" #n ")" ::: "memory")
; #define WAIT_L8(n) asm volatile("s_waitcnt lgkmcnt(" #n ")" ::: "memory")
; #define BAR8 __builtin_amdgcn_s_barrier()
; #define SCHED8 __builtin_amdgcn_sched_barrier(0)
; __device__ __forceinline__ void gemm_mainloop8(const bf16_t* __restrict__ Xg, int ldx, const bf16_t* __restrict__ Wg, int ldw, ...
;     ...
;     WAIT_V8(6); BAR8; MMA8(1, 1, At, B1); BAR8;
;     LDB8(B0, 1, 0); SCHED8; LDA8(At, 1, 0); STAGE8(SA8(0, 1), A, ldw, offA, 128, t + 2);
;     WAIT_L8(8); BAR8; WAIT_L8(0); MMA8(0, 0, At, B0); BAR8; SCHED8;
;     LDB8(B1, 1, 1); STAGE8(SB8(1, 0), Bt, ldx, offB, 0, t + 3);
;     BAR8; WAIT_L8(0); MMA8(0, 1, At, B1); BAR8;
	s_setprio 1
	v_mfma_f32_16x16x32_bf16 v[62:65], v[204:207], v[162:165], v[62:65]
	v_mfma_f32_16x16x32_bf16 v[58:61], v[204:207], v[170:173], v[58:61]
	v_mfma_f32_16x16x32_bf16 v[54:57], v[212:215], v[162:165], v[54:57]
	v_mfma_f32_16x16x32_bf16 v[46:49], v[212:215], v[170:173], v[46:49]
	v_mfma_f32_16x16x32_bf16 v[38:41], v[220:223], v[162:165], v[38:41]
	v_mfma_f32_16x16x32_bf16 v[30:33], v[220:223], v[170:173], v[30:33]
	v_mfma_f32_16x16x32_bf16 v[22:25], v[228:231], v[162:165], v[22:25]
	v_mfma_f32_16x16x32_bf16 v[14:17], v[228:231], v[170:173], v[14:17]
	v_mfma_f32_16x16x32_bf16 v[62:65], v[208:211], v[166:169], v[62:65]
	v_mfma_f32_16x16x32_bf16 v[58:61], v[208:211], v[174:177], v[58:61]
	v_mfma_f32_16x16x32_bf16 v[54:57], v[216:219], v[166:169], v[54:57]
	v_mfma_f32_16x16x32_bf16 v[46:49], v[216:219], v[174:177], v[46:49]
	v_mfma_f32_16x16x32_bf16 v[38:41], v[224:227], v[166:169], v[38:41]
	v_mfma_f32_16x16x32_bf16 v[30:33], v[224:227], v[174:177], v[30:33]
	v_mfma_f32_16x16x32_bf16 v[22:25], v[232:235], v[166:169], v[22:25]
	v_mfma_f32_16x16x32_bf16 v[14:17], v[232:235], v[174:177], v[14:17]
	v_mfma_f32_16x16x32_bf16 v[50:53], v[204:207], v[236:239], v[50:53]
	v_mfma_f32_16x16x32_bf16 v[42:45], v[204:207], v[244:247], v[42:45]
	v_mfma_f32_16x16x32_bf16 v[34:37], v[212:215], v[236:239], v[34:37]
	v_mfma_f32_16x16x32_bf16 v[26:29], v[212:215], v[244:247], v[26:29]
	v_mfma_f32_16x16x32_bf16 v[18:21], v[220:223], v[236:239], v[18:21]
	v_mfma_f32_16x16x32_bf16 v[10:13], v[220:223], v[244:247], v[10:13]
	v_mfma_f32_16x16x32_bf16 v[6:9], v[228:231], v[236:239], v[6:9]
	v_mfma_f32_16x16x32_bf16 v[2:5], v[228:231], v[244:247], v[2:5]
	v_mfma_f32_16x16x32_bf16 v[50:53], v[208:211], v[240:243], v[50:53]
	v_mfma_f32_16x16x32_bf16 v[42:45], v[208:211], v[248:251], v[42:45]
	v_mfma_f32_16x16x32_bf16 v[34:37], v[216:219], v[240:243], v[34:37]
	v_mfma_f32_16x16x32_bf16 v[26:29], v[216:219], v[248:251], v[26:29]
	v_mfma_f32_16x16x32_bf16 v[18:21], v[224:227], v[240:243], v[18:21]
	v_mfma_f32_16x16x32_bf16 v[10:13], v[224:227], v[248:251], v[10:13]
	v_mfma_f32_16x16x32_bf16 v[6:9], v[232:235], v[240:243], v[6:9]
	v_mfma_f32_16x16x32_bf16 v[2:5], v[232:235], v[248:251], v[2:5]
	s_setprio 0
	s_barrier
	v_or_b32_e32 v162, 0x18000, v145
	v_add_u32_e32 v163, 0x18400, v145
	v_add_u32_e32 v164, 0x18800, v145
	v_add_u32_e32 v165, 0x18c00, v145
	v_or_b32_e32 v166, 0x1c000, v145
	v_add_u32_e32 v167, 0x1c400, v145
	v_add_u32_e32 v168, 0x1c800, v145
	v_add_u32_e32 v169, 0x1cc00, v145
	ds_read_b128 v[170:173], v162
	ds_read_b128 v[174:177], v163
	ds_read_b128 v[204:207], v164
	ds_read_b128 v[208:211], v165
	ds_read_b128 v[212:215], v144 offset:32768
	ds_read_b128 v[216:219], v144 offset:33792
	ds_read_b128 v[220:223], v144 offset:34816
	ds_read_b128 v[224:227], v144 offset:35840
	ds_read_b128 v[228:231], v144 offset:36864
	ds_read_b128 v[232:235], v144 offset:37888
	ds_read_b128 v[236:239], v144 offset:38912
	ds_read_b128 v[240:243], v144 offset:39936
	ds_read_b128 v[244:247], v166
	ds_read_b128 v[248:251], v167
	ds_read_b128 v[190:193], v168
	ds_read_b128 v[194:197], v169
	v_lshl_add_u64 v[186:187], v[178:179], 0, s[80:81]
	v_readfirstlane_b32 s3, v137
	s_nop 0
	s_mov_b32 m0, s3
	s_nop 0
	global_load_lds_dwordx4 v[186:187], off
	v_lshl_add_u64 v[186:187], v[178:179], 0, s[68:69]
	v_readfirstlane_b32 s3, v136
	s_nop 0
	s_mov_b32 m0, s3
	s_nop 0
	global_load_lds_dwordx4 v[186:187], off
	s_waitcnt lgkmcnt(0)
	s_barrier
	s_setprio 1
	v_mfma_f32_16x16x32_bf16 v[126:129], v[212:215], v[170:173], v[126:129]
	v_mfma_f32_16x16x32_bf16 v[122:125], v[212:215], v[204:207], v[122:125]
	v_mfma_f32_16x16x32_bf16 v[118:121], v[220:223], v[170:173], v[118:121]
	v_mfma_f32_16x16x32_bf16 v[114:117], v[220:223], v[204:207], v[114:117]
	v_mfma_f32_16x16x32_bf16 v[102:105], v[228:231], v[170:173], v[102:105]
	v_mfma_f32_16x16x32_bf16 v[98:101], v[228:231], v[204:207], v[98:101]
	v_mfma_f32_16x16x32_bf16 v[86:89], v[236:239], v[170:173], v[86:89]
	v_mfma_f32_16x16x32_bf16 v[82:85], v[236:239], v[204:207], v[82:85]
	v_mfma_f32_16x16x32_bf16 v[126:129], v[216:219], v[174:177], v[126:129]
	v_mfma_f32_16x16x32_bf16 v[122:125], v[216:219], v[208:211], v[122:125]
	v_mfma_f32_16x16x32_bf16 v[118:121], v[224:227], v[174:177], v[118:121]
	v_mfma_f32_16x16x32_bf16 v[114:117], v[224:227], v[208:211], v[114:117]
	v_mfma_f32_16x16x32_bf16 v[102:105], v[232:235], v[174:177], v[102:105]
	v_mfma_f32_16x16x32_bf16 v[98:101], v[232:235], v[208:211], v[98:101]
	v_mfma_f32_16x16x32_bf16 v[86:89], v[240:243], v[174:177], v[86:89]
	v_mfma_f32_16x16x32_bf16 v[82:85], v[240:243], v[208:211], v[82:85]
	v_mfma_f32_16x16x32_bf16 v[110:113], v[212:215], v[244:247], v[110:113]
	v_mfma_f32_16x16x32_bf16 v[106:109], v[212:215], v[190:193], v[106:109]
	v_mfma_f32_16x16x32_bf16 v[94:97], v[220:223], v[244:247], v[94:97]
	v_mfma_f32_16x16x32_bf16 v[90:93], v[220:223], v[190:193], v[90:93]
	v_mfma_f32_16x16x32_bf16 v[78:81], v[228:231], v[244:247], v[78:81]
	v_mfma_f32_16x16x32_bf16 v[74:77], v[228:231], v[190:193], v[74:77]
	v_mfma_f32_16x16x32_bf16 v[70:73], v[236:239], v[244:247], v[70:73]
	v_mfma_f32_16x16x32_bf16 v[66:69], v[236:239], v[190:193], v[66:69]
	v_mfma_f32_16x16x32_bf16 v[110:113], v[216:219], v[248:251], v[110:113]
	v_mfma_f32_16x16x32_bf16 v[106:109], v[216:219], v[194:197], v[106:109]
	v_mfma_f32_16x16x32_bf16 v[94:97], v[224:227], v[248:251], v[94:97]
	v_mfma_f32_16x16x32_bf16 v[90:93], v[224:227], v[194:197], v[90:93]
	v_mfma_f32_16x16x32_bf16 v[78:81], v[232:235], v[248:251], v[78:81]
	v_mfma_f32_16x16x32_bf16 v[74:77], v[232:235], v[194:197], v[74:77]
	v_mfma_f32_16x16x32_bf16 v[70:73], v[240:243], v[248:251], v[70:73]
	v_mfma_f32_16x16x32_bf16 v[66:69], v[240:243], v[194:197], v[66:69]
	s_setprio 0
	s_barrier
; #define STAGE8(P, BASE, LD, OFF, br, kt) do { const bf16_t* g_ = (BASE) + (long)(br) * (LD) + (long)(kt) * 64 + (OFF); \
;     __builtin_amdgcn_global_load_lds((const unsigned*)(g_), (unsigned*)((char*)(P) + tid8 * 16), 16, 0, 0);            \
;     __builtin_amdgcn_global_load_lds((const unsigned*)(g_ + 64 * (long)(LD)), (unsigned*)((char*)(P) + tid8 * 16 + 8192), 16, 0, 0); } while (0)
; #define LDA8(dst, b, h) _Pragma("unroll") for (int m = 0; m < 4; ++m) _Pragma("unroll") for (int k = 0; k < 2; ++k) \
;     dst[m][k] = *reinterpret_cast<const bf16x8*>(SA8(b, h) + fa_off + m * 2048 + k * 1024)
; #define LDB8(dst, b, h) _Pragma("unroll") for (int n = 0; n < 2; ++n) _Pragma("unroll") for (int k = 0; k < 2; ++k) \
;     dst[n][k] = *reinterpret_cast<const bf16x8*>(SB8(b, h) + fb_off + n * 2048 + k * 1024)
; #define WAIT_V8(n) asm volatile("s_waitcnt vmcnt(" #n ")" ::: "memory")
; #define WAIT_L8(n) asm volatile("s_waitcnt lgkmcnt(" #n ")" ::: "memory")
; #define BAR8 __builtin_amdgcn_s_barrier()
; #define SCHED8 __builtin_amdgcn_sched_barrier(0)
; __device__ __forceinline__ void gemm_mainloop8(const bf16_t* __restrict__ Xg, int ldx, const bf16_t* __restrict__ Wg, int ldw, ...
;     ...
;     WAIT_V8(6); BAR8; MMA8(1, 1, At, B1); BAR8;
;     LDB8(B0, 1, 0); SCHED8; LDA8(At, 1, 0); STAGE8(SA8(0, 1), A, ldw, offA, 128, t + 2);
;     WAIT_L8(8); BAR8; WAIT_L8(0); MMA8(0, 0, At, B0); BAR8; SCHED8;
;     LDB8(B1, 1, 1); STAGE8(SB8(1, 0), Bt, ldx, offB, 0, t + 3);
;     BAR8; WAIT_L8(0); MMA8(0, 1, At, B1); BAR8;
;     LDA8(At, 1, 1); STAGE8(SA8(1, 0), A, ldw, offA, 0, t + 3);
;     BAR8; WAIT_L8(0); MMA8(1, 0, At, B0); BAR8; SCHED8;
;     STAGE8(SB8(1, 1), Bt, ldx, offB, 128, t + 3);
;     WAIT_V8(6); BAR8; MMA8(1, 1, At, B1); BAR8;
;   }
;   { LDB8(B0, 0, 0); LDA8(At, 0, 0); STAGE8(SA8(1, 1), A, ldw, offA, 128, nt - 1);
;     BAR8; WAIT_L8(0); MMA8(0, 0, At, B0); BAR8;
	ds_read_b128 v[212:215], v144 offset:49152
	ds_read_b128 v[216:219], v144 offset:50176
	ds_read_b128 v[220:223], v144 offset:51200
	ds_read_b128 v[224:227], v144 offset:52224
	ds_read_b128 v[228:231], v144 offset:53248
	ds_read_b128 v[232:235], v144 offset:54272
	ds_read_b128 v[236:239], v144 offset:55296
	ds_read_b128 v[240:243], v144 offset:56320
	v_lshl_add_u64 v[186:187], v[180:181], 0, s[88:89]
	v_readfirstlane_b32 s3, v146
	s_nop 0
	s_mov_b32 m0, s3
	s_nop 0
	global_load_lds_dwordx4 v[186:187], off
	v_lshl_add_u64 v[186:187], v[180:181], 0, s[4:5]
	v_readfirstlane_b32 s3, v147
	s_nop 0
	s_mov_b32 m0, s3
	s_nop 0
	global_load_lds_dwordx4 v[186:187], off
	v_lshl_add_u64 v[186:187], v[178:179], 0, s[88:89]
	v_readfirstlane_b32 s3, v148
	s_nop 0
	s_mov_b32 m0, s3
	s_nop 0
	global_load_lds_dwordx4 v[186:187], off
	v_lshl_add_u64 v[186:187], v[178:179], 0, s[4:5]
	v_readfirstlane_b32 s3, v149
	s_nop 0
	s_mov_b32 m0, s3
	s_nop 0
	global_load_lds_dwordx4 v[186:187], off
	v_lshl_add_u64 v[186:187], v[180:181], 0, s[92:93]
	v_readfirstlane_b32 s3, v150
	s_nop 0
	s_mov_b32 m0, s3
	s_nop 0
	global_load_lds_dwordx4 v[186:187], off
	v_lshl_add_u64 v[186:187], v[180:181], 0, s[94:95]
	v_readfirstlane_b32 s3, v151
	s_nop 0
	s_mov_b32 m0, s3
	s_nop 0
	global_load_lds_dwordx4 v[186:187], off
	s_waitcnt vmcnt(6)
	s_waitcnt lgkmcnt(0)
	s_barrier
	s_setprio 1
	v_mfma_f32_16x16x32_bf16 v[62:65], v[212:215], v[170:173], v[62:65]
	v_mfma_f32_16x16x32_bf16 v[58:61], v[212:215], v[204:207], v[58:61]
	v_mfma_f32_16x16x32_bf16 v[54:57], v[220:223], v[170:173], v[54:57]
	v_mfma_f32_16x16x32_bf16 v[46:49], v[220:223], v[204:207], v[46:49]
	v_mfma_f32_16x16x32_bf16 v[38:41], v[228:231], v[170:173], v[38:41]
	v_mfma_f32_16x16x32_bf16 v[30:33], v[228:231], v[204:207], v[30:33]
	v_mfma_f32_16x16x32_bf16 v[22:25], v[236:239], v[170:173], v[22:25]
	v_mfma_f32_16x16x32_bf16 v[14:17], v[236:239], v[204:207], v[14:17]
	v_mfma_f32_16x16x32_bf16 v[62:65], v[216:219], v[174:177], v[62:65]
	v_mfma_f32_16x16x32_bf16 v[58:61], v[216:219], v[208:211], v[58:61]
	v_mfma_f32_16x16x32_bf16 v[54:57], v[224:227], v[174:177], v[54:57]
	v_mfma_f32_16x16x32_bf16 v[46:49], v[224:227], v[208:211], v[46:49]
	v_mfma_f32_16x16x32_bf16 v[38:41], v[232:235], v[174:177], v[38:41]
	v_mfma_f32_16x16x32_bf16 v[30:33], v[232:235], v[208:211], v[30:33]
	v_mfma_f32_16x16x32_bf16 v[22:25], v[240:243], v[174:177], v[22:25]
	v_mfma_f32_16x16x32_bf16 v[14:17], v[240:243], v[208:211], v[14:17]
	v_mfma_f32_16x16x32_bf16 v[50:53], v[212:215], v[244:247], v[50:53]
	v_mfma_f32_16x16x32_bf16 v[42:45], v[212:215], v[190:193], v[42:45]
	v_mfma_f32_16x16x32_bf16 v[34:37], v[220:223], v[244:247], v[34:37]
	v_mfma_f32_16x16x32_bf16 v[26:29], v[220:223], v[190:193], v[26:29]
	v_mfma_f32_16x16x32_bf16 v[18:21], v[228:231], v[244:247], v[18:21]
	v_mfma_f32_16x16x32_bf16 v[10:13], v[228:231], v[190:193], v[10:13]
	v_mfma_f32_16x16x32_bf16 v[6:9], v[236:239], v[244:247], v[6:9]
	v_mfma_f32_16x16x32_bf16 v[2:5], v[236:239], v[190:193], v[2:5]
	v_mfma_f32_16x16x32_bf16 v[50:53], v[216:219], v[248:251], v[50:53]
	v_mfma_f32_16x16x32_bf16 v[42:45], v[216:219], v[194:197], v[42:45]
	v_mfma_f32_16x16x32_bf16 v[34:37], v[224:227], v[248:251], v[34:37]
	v_mfma_f32_16x16x32_bf16 v[26:29], v[224:227], v[194:197], v[26:29]
	v_mfma_f32_16x16x32_bf16 v[18:21], v[232:235], v[248:251], v[18:21]
	v_mfma_f32_16x16x32_bf16 v[10:13], v[232:235], v[194:197], v[10:13]
	v_mfma_f32_16x16x32_bf16 v[6:9], v[240:243], v[248:251], v[6:9]
	v_mfma_f32_16x16x32_bf16 v[2:5], v[240:243], v[194:197], v[2:5]
	s_setprio 0
	s_add_i32 s2, s2, 2
	s_add_u32 s10, s10, 0x100
	s_addc_u32 s11, s11, 0
	s_add_u32 s12, s12, 0x100
	s_addc_u32 s13, s13, 0
	s_cmp_lt_u32 s2, 28
	s_barrier
	s_cbranch_scc1 .LBB0_536
	v_lshl_add_u64 v[132:133], v[132:133], 1, s[8:9]
	s_mov_b64 s[2:3], 0x80f80
	v_lshl_add_u64 v[134:135], v[132:133], 0, s[2:3]
	v_readfirstlane_b32 s2, v156
	s_mov_b32 m0, s2
	s_mov_b64 s[2:3], 0xc0f80
	v_lshl_add_u64 v[132:133], v[132:133], 0, s[2:3]
	v_readfirstlane_b32 s2, v157
	s_nop 0
	ds_read_b128 v[146:149], v152
	ds_read_b128 v[150:153], v153
	ds_read_b128 v[170:173], v154
	ds_read_b128 v[174:177], v155
	ds_read_b128 v[190:193], v144
	ds_read_b128 v[194:197], v144 offset:1024
	ds_read_b128 v[204:207], v144 offset:2048
	ds_read_b128 v[208:211], v144 offset:3072
	ds_read_b128 v[212:215], v144 offset:4096
	ds_read_b128 v[216:219], v144 offset:5120
	ds_read_b128 v[220:223], v144 offset:6144
	ds_read_b128 v[224:227], v144 offset:7168
	global_load_lds_dwordx4 v[134:135], off
	s_mov_b32 m0, s2
	s_nop 0
	global_load_lds_dwordx4 v[132:133], off
	s_barrier
	s_waitcnt lgkmcnt(0)
	s_setprio 1
	s_waitcnt lgkmcnt(0)
	v_mfma_f32_16x16x32_bf16 v[126:129], v[190:193], v[146:149], v[126:129]
	v_mfma_f32_16x16x32_bf16 v[122:125], v[190:193], v[170:173], v[122:125]
	v_mfma_f32_16x16x32_bf16 v[118:121], v[204:207], v[146:149], v[118:121]
	v_mfma_f32_16x16x32_bf16 v[114:117], v[204:207], v[170:173], v[114:117]
	v_mfma_f32_16x16x32_bf16 v[102:105], v[212:215], v[146:149], v[102:105]
	v_mfma_f32_16x16x32_bf16 v[98:101], v[212:215], v[170:173], v[98:101]
	v_mfma_f32_16x16x32_bf16 v[86:89], v[220:223], v[146:149], v[86:89]
	v_mfma_f32_16x16x32_bf16 v[82:85], v[220:223], v[170:173], v[82:85]
	v_mfma_f32_16x16x32_bf16 v[126:129], v[194:197], v[150:153], v[126:129]
	v_mfma_f32_16x16x32_bf16 v[122:125], v[194:197], v[174:177], v[122:125]
	v_mfma_f32_16x16x32_bf16 v[118:121], v[208:211], v[150:153], v[118:121]
	v_mfma_f32_16x16x32_bf16 v[114:117], v[208:211], v[174:177], v[114:117]
	v_mfma_f32_16x16x32_bf16 v[102:105], v[216:219], v[150:153], v[102:105]
	v_mfma_f32_16x16x32_bf16 v[98:101], v[216:219], v[174:177], v[98:101]
	v_mfma_f32_16x16x32_bf16 v[86:89], v[224:227], v[150:153], v[86:89]
	v_mfma_f32_16x16x32_bf16 v[82:85], v[224:227], v[174:177], v[82:85]
	s_setprio 0
	s_barrier
; #define LDA8(dst, b, h) _Pragma("unroll") for (int m = 0; m < 4; ++m) _Pragma("unroll") for (int k = 0; k < 2; ++k) \
;     dst[m][k] = *reinterpret_cast<const bf16x8*>(SA8(b, h) + fa_off + m * 2048 + k * 1024)
; #define LDB8(dst, b, h) _Pragma("unroll") for (int n = 0; n < 2; ++n) _Pragma("unroll") for (int k = 0; k < 2; ++k) \
;     dst[n][k] = *reinterpret_cast<const bf16x8*>(SB8(b, h) + fb_off + n * 2048 + k * 1024)
; #define WAIT_V8(n) asm volatile("s_waitcnt vmcnt(" #n ")" ::: "memory")
; #define WAIT_L8(n) asm volatile("s_waitcnt lgkmcnt(" #n ")" ::: "memory")
; #define BAR8 __builtin_amdgcn_s_barrier()
; __device__ __forceinline__ void gemm_mainloop8(const bf16_t* __restrict__ Xg, int ldx, const bf16_t* __restrict__ Wg, int ldw, ...
;     ...
;     BAR8; WAIT_L8(0); MMA8(0, 0, At, B0); BAR8;
;     LDB8(B1, 0, 1); BAR8; WAIT_L8(0); MMA8(0, 1, At, B1); BAR8;
;     LDA8(At, 0, 1); WAIT_V8(4); BAR8; WAIT_L8(0); MMA8(1, 0, At, B0); MMA8(1, 1, At, B1); BAR8; }
;   { LDB8(B0, 1, 0); LDA8(At, 1, 0); WAIT_V8(2); BAR8; WAIT_L8(0); MMA8(0, 0, At, B0); BAR8;
	s_nop 0
	ds_read_b128 v[132:135], v158
	ds_read_b128 v[154:157], v159
	ds_read_b128 v[228:231], v160
	ds_read_b128 v[158:161], v161
	s_barrier
	s_waitcnt lgkmcnt(0)
	s_setprio 1
	s_waitcnt lgkmcnt(1)
	v_mfma_f32_16x16x32_bf16 v[66:69], v[220:223], v[228:231], v[66:69]
	v_mfma_f32_16x16x32_bf16 v[110:113], v[190:193], v[132:135], v[110:113]
	v_mfma_f32_16x16x32_bf16 v[106:109], v[190:193], v[228:231], v[106:109]
	v_mfma_f32_16x16x32_bf16 v[94:97], v[204:207], v[132:135], v[94:97]
	v_mfma_f32_16x16x32_bf16 v[90:93], v[204:207], v[228:231], v[90:93]
	v_mfma_f32_16x16x32_bf16 v[78:81], v[212:215], v[132:135], v[78:81]
	v_mfma_f32_16x16x32_bf16 v[74:77], v[212:215], v[228:231], v[74:77]
	v_mfma_f32_16x16x32_bf16 v[70:73], v[220:223], v[132:135], v[70:73]
	s_waitcnt lgkmcnt(0)
	v_mfma_f32_16x16x32_bf16 v[66:69], v[224:227], v[158:161], v[66:69]
	v_mfma_f32_16x16x32_bf16 v[232:235], v[194:197], v[154:157], v[110:113]
	v_mfma_f32_16x16x32_bf16 v[190:193], v[194:197], v[158:161], v[106:109]
	v_mfma_f32_16x16x32_bf16 v[194:197], v[208:211], v[154:157], v[94:97]
	v_mfma_f32_16x16x32_bf16 v[204:207], v[208:211], v[158:161], v[90:93]
	v_mfma_f32_16x16x32_bf16 v[208:211], v[216:219], v[154:157], v[78:81]
	v_mfma_f32_16x16x32_bf16 v[212:215], v[216:219], v[158:161], v[74:77]
	v_mfma_f32_16x16x32_bf16 v[216:219], v[224:227], v[154:157], v[70:73]
	s_setprio 0
	s_barrier
	s_nop 0
	ds_read_b128 v[70:73], v144 offset:16384
	ds_read_b128 v[74:77], v144 offset:17408
	ds_read_b128 v[78:81], v144 offset:18432
	ds_read_b128 v[90:93], v144 offset:19456
	ds_read_b128 v[94:97], v144 offset:20480
	ds_read_b128 v[106:109], v144 offset:21504
	ds_read_b128 v[110:113], v144 offset:22528
	ds_read_b128 v[220:223], v144 offset:23552
	s_waitcnt vmcnt(4)
	s_barrier
	s_waitcnt lgkmcnt(0)
	s_setprio 1
	s_waitcnt lgkmcnt(7)
	v_mfma_f32_16x16x32_bf16 v[62:65], v[70:73], v[146:149], v[62:65]
	v_mfma_f32_16x16x32_bf16 v[58:61], v[70:73], v[170:173], v[58:61]
	s_waitcnt lgkmcnt(5)
	v_mfma_f32_16x16x32_bf16 v[54:57], v[78:81], v[146:149], v[54:57]
	s_waitcnt lgkmcnt(3)
	v_mfma_f32_16x16x32_bf16 v[38:41], v[94:97], v[146:149], v[38:41]
	v_mfma_f32_16x16x32_bf16 v[30:33], v[94:97], v[170:173], v[30:33]
	s_waitcnt lgkmcnt(1)
	v_mfma_f32_16x16x32_bf16 v[22:25], v[110:113], v[146:149], v[22:25]
	v_mfma_f32_16x16x32_bf16 v[14:17], v[110:113], v[170:173], v[14:17]
	v_mfma_f32_16x16x32_bf16 v[62:65], v[74:77], v[150:153], v[62:65]
	v_mfma_f32_16x16x32_bf16 v[58:61], v[74:77], v[174:177], v[58:61]
	v_mfma_f32_16x16x32_bf16 v[54:57], v[90:93], v[150:153], v[54:57]
	v_mfma_f32_16x16x32_bf16 v[46:49], v[78:81], v[170:173], v[46:49]
	v_mfma_f32_16x16x32_bf16 v[38:41], v[106:109], v[150:153], v[38:41]
	v_mfma_f32_16x16x32_bf16 v[30:33], v[106:109], v[174:177], v[30:33]
	s_waitcnt lgkmcnt(0)
	v_mfma_f32_16x16x32_bf16 v[22:25], v[220:223], v[150:153], v[22:25]
	v_mfma_f32_16x16x32_bf16 v[14:17], v[220:223], v[174:177], v[14:17]
	v_mfma_f32_16x16x32_bf16 v[224:227], v[90:93], v[174:177], v[46:49]
	s_setprio 0
	s_setprio 1
	v_mfma_f32_16x16x32_bf16 v[18:21], v[94:97], v[132:135], v[18:21]
	v_mfma_f32_16x16x32_bf16 v[2:5], v[110:113], v[228:231], v[2:5]
	v_mfma_f32_16x16x32_bf16 v[46:49], v[70:73], v[132:135], v[50:53]
	v_mfma_f32_16x16x32_bf16 v[42:45], v[70:73], v[228:231], v[42:45]
	v_mfma_f32_16x16x32_bf16 v[34:37], v[78:81], v[132:135], v[34:37]
	v_mfma_f32_16x16x32_bf16 v[26:29], v[78:81], v[228:231], v[26:29]
	v_mfma_f32_16x16x32_bf16 v[18:21], v[106:109], v[154:157], v[18:21]
	v_mfma_f32_16x16x32_bf16 v[10:13], v[94:97], v[228:231], v[10:13]
	v_mfma_f32_16x16x32_bf16 v[6:9], v[110:113], v[132:135], v[6:9]
	v_mfma_f32_16x16x32_bf16 v[2:5], v[220:223], v[158:161], v[2:5]
	v_mfma_f32_16x16x32_bf16 v[146:149], v[74:77], v[154:157], v[46:49]
	v_mfma_f32_16x16x32_bf16 v[150:153], v[74:77], v[158:161], v[42:45]
	v_mfma_f32_16x16x32_bf16 v[170:173], v[90:93], v[154:157], v[34:37]
	v_mfma_f32_16x16x32_bf16 v[174:177], v[90:93], v[158:161], v[26:29]
	v_mfma_f32_16x16x32_bf16 v[236:239], v[106:109], v[158:161], v[10:13]
	v_mfma_f32_16x16x32_bf16 v[132:135], v[220:223], v[154:157], v[6:9]
	s_setprio 0
	s_barrier
	s_nop 0
	ds_read_b128 v[6:9], v162
	ds_read_b128 v[10:13], v163
	ds_read_b128 v[26:29], v164
	ds_read_b128 v[34:37], v165
	ds_read_b128 v[42:45], v144 offset:32768
	ds_read_b128 v[46:49], v144 offset:33792
	ds_read_b128 v[50:53], v144 offset:34816
	ds_read_b128 v[70:73], v144 offset:35840
	ds_read_b128 v[154:157], v144 offset:36864
	ds_read_b128 v[158:161], v144 offset:37888
	ds_read_b128 v[162:165], v144 offset:38912
	ds_read_b128 v[220:223], v144 offset:39936
	s_waitcnt vmcnt(2)
	s_barrier
; #define LDA8(dst, b, h) _Pragma("unroll") for (int m = 0; m < 4; ++m) _Pragma("unroll") for (int k = 0; k < 2; ++k) \
;     dst[m][k] = *reinterpret_cast<const bf16x8*>(SA8(b, h) + fa_off + m * 2048 + k * 1024)
; #define LDB8(dst, b, h) _Pragma("unroll") for (int n = 0; n < 2; ++n) _Pragma("unroll") for (int k = 0; k < 2; ++k) \
;     dst[n][k] = *reinterpret_cast<const bf16x8*>(SB8(b, h) + fb_off + n * 2048 + k * 1024)
; #define WAIT_V8(n) asm volatile("s_waitcnt vmcnt(" #n ")" ::: "memory")
; #define WAIT_L8(n) asm volatile("s_waitcnt lgkmcnt(" #n ")" ::: "memory")
; #define BAR8 __builtin_amdgcn_s_barrier()
; __device__ __forceinline__ void gemm_mainloop8(const bf16_t* __restrict__ Xg, int ldx, const bf16_t* __restrict__ Wg, int ldw, ...
;     ...
;   { LDB8(B0, 1, 0); LDA8(At, 1, 0); WAIT_V8(2); BAR8; WAIT_L8(0); MMA8(0, 0, At, B0); BAR8;
;     LDB8(B1, 1, 1); WAIT_V8(0); BAR8; WAIT_L8(0); MMA8(0, 1, At, B1); BAR8;
;     LDA8(At, 1, 1); BAR8; WAIT_L8(0); MMA8(1, 0, At, B0); MMA8(1, 1, At, B1); BAR8; }
;   if (wr == 0) BAR8;
	s_waitcnt lgkmcnt(0)
	s_setprio 1
	s_waitcnt lgkmcnt(7)
	v_mfma_f32_16x16x32_bf16 v[74:77], v[42:45], v[6:9], v[126:129]
	s_waitcnt lgkmcnt(6)
	v_mfma_f32_16x16x32_bf16 v[126:129], v[46:49], v[10:13], v[74:77]
	v_mfma_f32_16x16x32_bf16 v[74:77], v[42:45], v[26:29], v[122:125]
	v_mfma_f32_16x16x32_bf16 v[110:113], v[46:49], v[34:37], v[74:77]
	s_waitcnt lgkmcnt(5)
	v_mfma_f32_16x16x32_bf16 v[74:77], v[50:53], v[6:9], v[118:121]
	s_waitcnt lgkmcnt(4)
	v_mfma_f32_16x16x32_bf16 v[122:125], v[70:73], v[10:13], v[74:77]
	v_mfma_f32_16x16x32_bf16 v[74:77], v[50:53], v[26:29], v[114:117]
	v_mfma_f32_16x16x32_bf16 v[106:109], v[70:73], v[34:37], v[74:77]
	s_waitcnt lgkmcnt(3)
	v_mfma_f32_16x16x32_bf16 v[74:77], v[154:157], v[6:9], v[102:105]
	s_waitcnt lgkmcnt(2)
	v_mfma_f32_16x16x32_bf16 v[118:121], v[158:161], v[10:13], v[74:77]
	v_mfma_f32_16x16x32_bf16 v[74:77], v[154:157], v[26:29], v[98:101]
	v_mfma_f32_16x16x32_bf16 v[102:105], v[158:161], v[34:37], v[74:77]
	s_waitcnt lgkmcnt(1)
	v_mfma_f32_16x16x32_bf16 v[74:77], v[162:165], v[6:9], v[86:89]
	s_waitcnt lgkmcnt(0)
	v_mfma_f32_16x16x32_bf16 v[114:117], v[220:223], v[10:13], v[74:77]
	v_mfma_f32_16x16x32_bf16 v[74:77], v[162:165], v[26:29], v[82:85]
	v_mfma_f32_16x16x32_bf16 v[98:101], v[220:223], v[34:37], v[74:77]
	s_setprio 0
	s_barrier
	ds_read_b128 v[228:231], v166
	ds_read_b128 v[240:243], v167
	ds_read_b128 v[244:247], v168
	ds_read_b128 v[166:169], v169
	s_waitcnt vmcnt(0)
	s_barrier
	s_waitcnt lgkmcnt(0)
	s_setprio 1
	s_waitcnt lgkmcnt(3)
	v_mfma_f32_16x16x32_bf16 v[74:77], v[42:45], v[228:231], v[232:235]
	s_waitcnt lgkmcnt(1)
	v_mfma_f32_16x16x32_bf16 v[42:45], v[42:45], v[244:247], v[190:193]
	s_waitcnt lgkmcnt(0)
	v_mfma_f32_16x16x32_bf16 v[78:81], v[46:49], v[166:169], v[42:45]
	v_mfma_f32_16x16x32_bf16 v[42:45], v[50:53], v[228:231], v[194:197]
	v_mfma_f32_16x16x32_bf16 v[90:93], v[70:73], v[240:243], v[42:45]
	v_mfma_f32_16x16x32_bf16 v[42:45], v[50:53], v[244:247], v[204:207]
	v_mfma_f32_16x16x32_bf16 v[94:97], v[46:49], v[240:243], v[74:77]
	v_mfma_f32_16x16x32_bf16 v[74:77], v[70:73], v[166:169], v[42:45]
	v_mfma_f32_16x16x32_bf16 v[42:45], v[154:157], v[228:231], v[208:211]
	v_mfma_f32_16x16x32_bf16 v[86:89], v[158:161], v[240:243], v[42:45]
	v_mfma_f32_16x16x32_bf16 v[42:45], v[154:157], v[244:247], v[212:215]
	v_mfma_f32_16x16x32_bf16 v[70:73], v[158:161], v[166:169], v[42:45]
	v_mfma_f32_16x16x32_bf16 v[42:45], v[162:165], v[228:231], v[216:219]
	v_mfma_f32_16x16x32_bf16 v[82:85], v[220:223], v[240:243], v[42:45]
	v_mfma_f32_16x16x32_bf16 v[42:45], v[162:165], v[244:247], v[66:69]
	v_mfma_f32_16x16x32_bf16 v[66:69], v[220:223], v[166:169], v[42:45]
	s_setprio 0
	s_barrier
	ds_read_b128 v[154:157], v144 offset:49152
	ds_read_b128 v[158:161], v144 offset:50176
	ds_read_b128 v[162:165], v144 offset:51200
	ds_read_b128 v[190:193], v144 offset:52224
	ds_read_b128 v[194:197], v144 offset:53248
	ds_read_b128 v[204:207], v144 offset:54272
	ds_read_b128 v[208:211], v144 offset:55296
	ds_read_b128 v[212:215], v144 offset:56320
	s_barrier
	s_waitcnt lgkmcnt(0)
	s_setprio 1
	s_waitcnt lgkmcnt(7)
	v_mfma_f32_16x16x32_bf16 v[42:45], v[154:157], v[6:9], v[62:65]
	s_waitcnt lgkmcnt(6)
	v_mfma_f32_16x16x32_bf16 v[62:65], v[158:161], v[10:13], v[42:45]
	v_mfma_f32_16x16x32_bf16 v[42:45], v[154:157], v[26:29], v[58:61]
	v_mfma_f32_16x16x32_bf16 v[46:49], v[158:161], v[34:37], v[42:45]
	s_waitcnt lgkmcnt(5)
	v_mfma_f32_16x16x32_bf16 v[42:45], v[162:165], v[6:9], v[54:57]
	s_waitcnt lgkmcnt(3)
	v_mfma_f32_16x16x32_bf16 v[38:41], v[194:197], v[6:9], v[38:41]
	s_waitcnt lgkmcnt(1)
	v_mfma_f32_16x16x32_bf16 v[6:9], v[208:211], v[6:9], v[22:25]
	v_mfma_f32_16x16x32_bf16 v[58:61], v[190:193], v[10:13], v[42:45]
	v_mfma_f32_16x16x32_bf16 v[42:45], v[162:165], v[26:29], v[224:227]
	v_mfma_f32_16x16x32_bf16 v[30:33], v[194:197], v[26:29], v[30:33]
	s_waitcnt lgkmcnt(0)
	v_mfma_f32_16x16x32_bf16 v[50:53], v[212:215], v[10:13], v[6:9]
	v_mfma_f32_16x16x32_bf16 v[6:9], v[208:211], v[26:29], v[14:17]
	v_mfma_f32_16x16x32_bf16 v[42:45], v[190:193], v[34:37], v[42:45]
	v_mfma_f32_16x16x32_bf16 v[54:57], v[204:207], v[10:13], v[38:41]
	v_mfma_f32_16x16x32_bf16 v[38:41], v[204:207], v[34:37], v[30:33]
	v_mfma_f32_16x16x32_bf16 v[34:37], v[212:215], v[34:37], v[6:9]
	s_setprio 0
	s_setprio 1
	v_mfma_f32_16x16x32_bf16 v[6:9], v[154:157], v[228:231], v[146:149]
	v_mfma_f32_16x16x32_bf16 v[30:33], v[158:161], v[240:243], v[6:9]
	v_mfma_f32_16x16x32_bf16 v[6:9], v[154:157], v[244:247], v[150:153]
	v_mfma_f32_16x16x32_bf16 v[14:17], v[158:161], v[166:169], v[6:9]
	v_mfma_f32_16x16x32_bf16 v[6:9], v[162:165], v[228:231], v[170:173]
	v_mfma_f32_16x16x32_bf16 v[26:29], v[190:193], v[240:243], v[6:9]
	v_mfma_f32_16x16x32_bf16 v[6:9], v[162:165], v[244:247], v[174:177]
	v_mfma_f32_16x16x32_bf16 v[10:13], v[190:193], v[166:169], v[6:9]
	v_mfma_f32_16x16x32_bf16 v[6:9], v[194:197], v[228:231], v[18:21]
	v_mfma_f32_16x16x32_bf16 v[22:25], v[204:207], v[240:243], v[6:9]
	v_mfma_f32_16x16x32_bf16 v[6:9], v[194:197], v[244:247], v[236:239]
	v_mfma_f32_16x16x32_bf16 v[18:21], v[208:211], v[228:231], v[132:135]
	v_mfma_f32_16x16x32_bf16 v[2:5], v[208:211], v[244:247], v[2:5]
	v_mfma_f32_16x16x32_bf16 v[6:9], v[204:207], v[166:169], v[6:9]
	v_mfma_f32_16x16x32_bf16 v[18:21], v[212:215], v[240:243], v[18:21]
	v_mfma_f32_16x16x32_bf16 v[2:5], v[212:215], v[166:169], v[2:5]
	s_setprio 0
	s_movk_i32 s2, 0x100
	v_cmp_gt_u32_e32 vcc, s2, v143
	s_barrier
	s_and_saveexec_b64 s[2:3], vcc
	s_cbranch_execz .LBB0_539
	s_barrier
